# GEMM loops: first K-iteration peeled with C=0 (no accumulator zeroing); P_up epilogue relu folded to one max
# speedup vs baseline: 1.0324x; 1.0018x over previous
; #define PG8_STAGE(bufoff, gbase, voff) do { _Pragma("unroll") for (int _i = 0; _i < 2; ++_i) \
;         __builtin_amdgcn_global_load_lds((const unsigned*)((const char*)(gbase) + (voff)[_i]), (LAS unsigned*)(lds + (bufoff) + ldsw + _i * 8192), 16, 0, 0); } while (0)
; #define PG8_LDA(dst, b, h) do { _Pragma("unroll") for (int m = 0; m < 4; ++m) _Pragma("unroll") for (int k = 0; k < 2; ++k) dst[m][k] = *(const LAS bf16x8*)(lds + PG8_SA(b, h) + aoff + m * 2048 + k * 1024); } while (0)
; #define PG8_LDB(dst, b, h) do { _Pragma("unroll") for (int n = 0; n < 2; ++n) _Pragma("unroll") for (int k = 0; k < 2; ++k) dst[n][k] = *(const LAS bf16x8*)(lds + PG8_SB(b, h) + boff + n * 2048 + k * 1024); } while (0)
; #define PG8_MMA(ai, bj, At, Bt) do { __builtin_amdgcn_s_setprio(1); _Pragma("unroll") for (int m = 0; m < 4; ++m) _Pragma("unroll") for (int n = 0; n < 2; ++n) _Pragma("unroll") for (int k = 0; k < 2; ++k) \
;         acc[ai][bj][m][n] = __builtin_amdgcn_mfma_f32_16x16x32_bf16(Bt[n][k], At[m][k], acc[ai][bj][m][n], 0, 0, 0); __builtin_amdgcn_s_setprio(0); } while (0)
; #define PG8_BAR __builtin_amdgcn_s_barrier()
; template <class Epi, bool MID = false>
; __device__ __forceinline__ void gemm_phase(LAS unsigned char* lds, const Gemm g, const StaticOrder& S, const Epi& E) {
;     ...
;         const bool has_next = S.next(ui + 1, nxt);
;         const char* nA = has_next ? (const char*)g.A + (size_t)nxt.pm * tstepA : cA; const char* nB = has_next ? (const char*)g.Bt + (size_t)nxt.pn * tstepB : cB;
; #pragma nounroll
;         for (int t = 0; t < nt; t += 2) {
;             const bool last = (t == nt - 2);
;             const char* a1 = cA + (size_t)(t + 1) * kstep;
;             const char* a2 = last ? nA : cA + (size_t)(t + 2) * kstep; const char* b2 = last ? nB : cB + (size_t)(t + 2) * kstep;
;             const char* a3 = a2 + kstep; const char* b3 = b2 + kstep;
;             PG8_LDB(B0, 0, 0); PG8_LDB(B1, 0, 1); PG8_SCHED; PG8_LDA(At, 0, 0); PG8_STAGE(PG8_SA(1, 1), a1 + hstepA, voffA);
;             PG8_WAIT_V(8); PG8_WAIT_L(0); PG8_BAR; PG8_MMA(0, 0, At, B0); PG8_MMA(0, 1, At, B1); PG8_BAR; PG8_SCHED;
;             PG8_LDA(At, 0, 1); PG8_STAGE(PG8_SB(0, 0), b2, voffB); PG8_STAGE(PG8_SB(0, 1), b2 + hstepB, voffB); PG8_STAGE(PG8_SA(0, 0), a2, voffA);
;             PG8_WAIT_V(8); PG8_WAIT_L(0); PG8_BAR; PG8_MMA(1, 0, At, B0); PG8_MMA(1, 1, At, B1); PG8_BAR; PG8_SCHED;
.LBB0_353:
	s_ashr_i32 s63, s62, 31
	s_lshl_b64 s[42:43], s[62:63], 19
	s_add_u32 s64, s85, s42
	s_addc_u32 s65, s84, s43
	s_ashr_i32 s61, s60, 31
	s_lshl_b64 s[42:43], s[60:61], 19
	s_add_u32 s66, s82, s42
	s_addc_u32 s67, s83, s43
	s_andn2_b64 vcc, exec, s[52:53]
	s_cbranch_vccnz .LBB0_371
	s_and_b64 s[42:43], s[40:41], exec
	s_cselect_b32 s45, s65, s79
	s_cselect_b32 s48, s64, s78
	s_cselect_b32 s61, s67, s71
	s_cselect_b32 s63, s66, s70
	s_add_u32 s42, s78, 0x40080
	s_addc_u32 s43, s79, 0
	s_add_u32 s72, s70, 0x100
	s_addc_u32 s73, s71, 0
	s_mov_b32 s70, 0
	s_waitcnt lgkmcnt(0)
	s_add_i32 s97, s70, 2
	s_add_u32 s4, s42, 0xfffc0080
	s_addc_u32 s5, s43, -1
	s_add_i32 vcc_lo, 0, 0x10000
	s_cmp_eq_u32 s95, s70
	s_cselect_b32 s79, s45, s5
	s_cselect_b32 s78, s48, s4
	v_add_u32_e32 v0, vcc_lo, v229
	s_cselect_b32 s71, s61, s73
	s_cselect_b32 s70, s63, s72
	s_add_i32 s4, 0, 0x14000
	ds_read_b128 v[130:133], v0
	ds_read_b128 v[134:137], v0 offset:1024
	ds_read_b128 v[138:141], v0 offset:2048
	ds_read_b128 v[142:145], v0 offset:3072
	v_add_u32_e32 v0, s4, v229
	ds_read_b128 v[172:175], v0
	ds_read_b128 v[176:179], v0 offset:1024
	ds_read_b128 v[180:183], v0 offset:2048
	ds_read_b128 v[184:187], v0 offset:3072
	v_lshl_add_u64 v[216:217], s[42:43], 0, v[168:169]
	s_add_i32 m0, s69, 0xc000
	ds_read_b128 v[188:191], v231
	ds_read_b128 v[192:195], v231 offset:1024
	ds_read_b128 v[196:199], v231 offset:2048
	ds_read_b128 v[200:203], v231 offset:3072
	ds_read_b128 v[204:207], v231 offset:4096
	ds_read_b128 v[208:211], v231 offset:5120
	ds_read_b128 v[212:215], v231 offset:6144
	ds_read_b128 v[232:235], v231 offset:7168
	global_load_lds_dwordx4 v[216:217], off
	v_lshl_add_u64 v[216:217], s[42:43], 0, v[170:171]
	s_add_i32 m0, s69, 0xe000
	s_nop 0
	global_load_lds_dwordx4 v[216:217], off
	s_waitcnt vmcnt(8)
	s_waitcnt lgkmcnt(0)
	s_barrier
	s_setprio 1
	s_waitcnt lgkmcnt(0)
	v_mfma_f32_16x16x32_bf16 v[126:129], v[130:133], v[188:191], 0
	v_mfma_f32_16x16x32_bf16 v[118:121], v[138:141], v[188:191], 0
	v_mfma_f32_16x16x32_bf16 v[110:113], v[130:133], v[196:199], 0
	v_mfma_f32_16x16x32_bf16 v[102:105], v[138:141], v[196:199], 0
	v_mfma_f32_16x16x32_bf16 v[94:97], v[130:133], v[204:207], 0
	v_mfma_f32_16x16x32_bf16 v[86:89], v[138:141], v[204:207], 0
	v_mfma_f32_16x16x32_bf16 v[78:81], v[130:133], v[212:215], 0
	v_mfma_f32_16x16x32_bf16 v[70:73], v[138:141], v[212:215], 0
	v_mfma_f32_16x16x32_bf16 v[126:129], v[134:137], v[192:195], v[126:129]
	v_mfma_f32_16x16x32_bf16 v[118:121], v[142:145], v[192:195], v[118:121]
	v_mfma_f32_16x16x32_bf16 v[110:113], v[134:137], v[200:203], v[110:113]
	v_mfma_f32_16x16x32_bf16 v[102:105], v[142:145], v[200:203], v[102:105]
	v_mfma_f32_16x16x32_bf16 v[94:97], v[134:137], v[208:211], v[94:97]
	v_mfma_f32_16x16x32_bf16 v[86:89], v[142:145], v[208:211], v[86:89]
	v_mfma_f32_16x16x32_bf16 v[78:81], v[134:137], v[232:235], v[78:81]
	v_mfma_f32_16x16x32_bf16 v[70:73], v[142:145], v[232:235], v[70:73]
	s_setprio 0
	s_setprio 1
	v_mfma_f32_16x16x32_bf16 v[122:125], v[172:175], v[188:191], 0
	v_mfma_f32_16x16x32_bf16 v[114:117], v[180:183], v[188:191], 0
	v_mfma_f32_16x16x32_bf16 v[106:109], v[172:175], v[196:199], 0
	v_mfma_f32_16x16x32_bf16 v[98:101], v[180:183], v[196:199], 0
	v_mfma_f32_16x16x32_bf16 v[90:93], v[172:175], v[204:207], 0
	v_mfma_f32_16x16x32_bf16 v[82:85], v[180:183], v[204:207], 0
	v_mfma_f32_16x16x32_bf16 v[74:77], v[172:175], v[212:215], 0
	v_mfma_f32_16x16x32_bf16 v[66:69], v[180:183], v[212:215], 0
	v_mfma_f32_16x16x32_bf16 v[122:125], v[176:179], v[192:195], v[122:125]
	v_mfma_f32_16x16x32_bf16 v[114:117], v[184:187], v[192:195], v[114:117]
	v_mfma_f32_16x16x32_bf16 v[106:109], v[176:179], v[200:203], v[106:109]
	v_mfma_f32_16x16x32_bf16 v[98:101], v[184:187], v[200:203], v[98:101]
	v_mfma_f32_16x16x32_bf16 v[90:93], v[176:179], v[208:211], v[90:93]
	v_mfma_f32_16x16x32_bf16 v[82:85], v[184:187], v[208:211], v[82:85]
	v_mfma_f32_16x16x32_bf16 v[74:77], v[176:179], v[232:235], v[74:77]
	v_mfma_f32_16x16x32_bf16 v[66:69], v[184:187], v[232:235], v[66:69]
	s_setprio 0
	s_barrier
	s_add_i32 s5, vcc_lo, s86
	v_lshl_add_u64 v[216:217], s[70:71], 0, v[148:149]
	s_mov_b32 m0, s5
	ds_read_b128 v[188:191], v231 offset:16384
	ds_read_b128 v[192:195], v231 offset:17408
	ds_read_b128 v[196:199], v231 offset:18432
	ds_read_b128 v[200:203], v231 offset:19456
	ds_read_b128 v[204:207], v231 offset:20480
	ds_read_b128 v[208:211], v231 offset:21504
	ds_read_b128 v[212:215], v231 offset:22528
	ds_read_b128 v[232:235], v231 offset:23552
	global_load_lds_dwordx4 v[216:217], off
	s_add_i32 m0, s5, 0x2000
	s_add_u32 vcc_lo, s70, 0x40000
	v_lshl_add_u64 v[236:237], s[70:71], 0, v[152:153]
	s_addc_u32 vcc_hi, s71, 0
	s_add_i32 s4, s4, s86
	global_load_lds_dwordx4 v[236:237], off
	v_lshl_add_u64 v[238:239], vcc, 0, v[148:149]
	s_mov_b32 m0, s4
	v_lshl_add_u64 v[240:241], s[78:79], 0, v[150:151]
	global_load_lds_dwordx4 v[238:239], off
	v_lshl_add_u64 v[238:239], vcc, 0, v[152:153]
	s_add_i32 m0, s4, 0x2000
	s_nop 0
	global_load_lds_dwordx4 v[238:239], off
	v_lshl_add_u64 v[238:239], s[78:79], 0, v[146:147]
	s_mov_b32 m0, s69
	s_nop 0
	global_load_lds_dwordx4 v[238:239], off
	s_mov_b32 m0, s87
	s_nop 0
	global_load_lds_dwordx4 v[240:241], off
	s_waitcnt vmcnt(8)
	s_waitcnt lgkmcnt(0)
	s_barrier
; #define PG8_STAGE(bufoff, gbase, voff) do { _Pragma("unroll") for (int _i = 0; _i < 2; ++_i) \
;         __builtin_amdgcn_global_load_lds((const unsigned*)((const char*)(gbase) + (voff)[_i]), (LAS unsigned*)(lds + (bufoff) + ldsw + _i * 8192), 16, 0, 0); } while (0)
; #define PG8_LDA(dst, b, h) do { _Pragma("unroll") for (int m = 0; m < 4; ++m) _Pragma("unroll") for (int k = 0; k < 2; ++k) dst[m][k] = *(const LAS bf16x8*)(lds + PG8_SA(b, h) + aoff + m * 2048 + k * 1024); } while (0)
; #define PG8_LDB(dst, b, h) do { _Pragma("unroll") for (int n = 0; n < 2; ++n) _Pragma("unroll") for (int k = 0; k < 2; ++k) dst[n][k] = *(const LAS bf16x8*)(lds + PG8_SB(b, h) + boff + n * 2048 + k * 1024); } while (0)
; #define PG8_MMA(ai, bj, At, Bt) do { __builtin_amdgcn_s_setprio(1); _Pragma("unroll") for (int m = 0; m < 4; ++m) _Pragma("unroll") for (int n = 0; n < 2; ++n) _Pragma("unroll") for (int k = 0; k < 2; ++k) \
;         acc[ai][bj][m][n] = __builtin_amdgcn_mfma_f32_16x16x32_bf16(Bt[n][k], At[m][k], acc[ai][bj][m][n], 0, 0, 0); __builtin_amdgcn_s_setprio(0); } while (0)
; #define PG8_WAIT_V(n) asm volatile("s_waitcnt vmcnt(" #n ")" ::: "memory")
; #define PG8_WAIT_L(n) asm volatile("s_waitcnt lgkmcnt(" #n ")" ::: "memory")
; #define PG8_BAR __builtin_amdgcn_s_barrier()
; #define PG8_SCHED __builtin_amdgcn_sched_barrier(0)
; template <class Epi, bool MID = false>
; __device__ __forceinline__ void gemm_phase(LAS unsigned char* lds, const Gemm g, const StaticOrder& S, const Epi& E) {
;     ...
;             PG8_WAIT_V(8); PG8_WAIT_L(0); PG8_BAR; PG8_MMA(1, 0, At, B0); PG8_MMA(1, 1, At, B1); PG8_BAR; PG8_SCHED;
;             PG8_LDB(B0, 1, 0); PG8_LDB(B1, 1, 1); PG8_SCHED; PG8_LDA(At, 1, 0); PG8_STAGE(PG8_SA(0, 1), a2 + hstepA, voffA);
;             PG8_WAIT_V(8); PG8_WAIT_L(0); PG8_BAR; PG8_MMA(0, 0, At, B0); PG8_MMA(0, 1, At, B1); PG8_BAR; PG8_SCHED;
	s_setprio 1
	s_waitcnt lgkmcnt(0)
	v_mfma_f32_16x16x32_bf16 v[62:65], v[130:133], v[188:191], 0
	v_mfma_f32_16x16x32_bf16 v[54:57], v[138:141], v[188:191], 0
	v_mfma_f32_16x16x32_bf16 v[46:49], v[130:133], v[196:199], 0
	v_mfma_f32_16x16x32_bf16 v[38:41], v[138:141], v[196:199], 0
	v_mfma_f32_16x16x32_bf16 v[30:33], v[130:133], v[204:207], 0
	v_mfma_f32_16x16x32_bf16 v[22:25], v[138:141], v[204:207], 0
	v_mfma_f32_16x16x32_bf16 v[14:17], v[130:133], v[212:215], 0
	v_mfma_f32_16x16x32_bf16 v[6:9], v[138:141], v[212:215], 0
	v_mfma_f32_16x16x32_bf16 v[62:65], v[134:137], v[192:195], v[62:65]
	v_mfma_f32_16x16x32_bf16 v[54:57], v[142:145], v[192:195], v[54:57]
	v_mfma_f32_16x16x32_bf16 v[46:49], v[134:137], v[200:203], v[46:49]
	v_mfma_f32_16x16x32_bf16 v[38:41], v[142:145], v[200:203], v[38:41]
	v_mfma_f32_16x16x32_bf16 v[30:33], v[134:137], v[208:211], v[30:33]
	v_mfma_f32_16x16x32_bf16 v[22:25], v[142:145], v[208:211], v[22:25]
	v_mfma_f32_16x16x32_bf16 v[14:17], v[134:137], v[232:235], v[14:17]
	v_mfma_f32_16x16x32_bf16 v[6:9], v[142:145], v[232:235], v[6:9]
	s_setprio 0
	s_setprio 1
	v_mfma_f32_16x16x32_bf16 v[58:61], v[172:175], v[188:191], 0
	v_mfma_f32_16x16x32_bf16 v[50:53], v[180:183], v[188:191], 0
	v_mfma_f32_16x16x32_bf16 v[42:45], v[172:175], v[196:199], 0
	v_mfma_f32_16x16x32_bf16 v[34:37], v[180:183], v[196:199], 0
	v_mfma_f32_16x16x32_bf16 v[26:29], v[172:175], v[204:207], 0
	v_mfma_f32_16x16x32_bf16 v[18:21], v[180:183], v[204:207], 0
	v_mfma_f32_16x16x32_bf16 v[10:13], v[172:175], v[212:215], 0
	v_mfma_f32_16x16x32_bf16 v[2:5], v[180:183], v[212:215], 0
	v_mfma_f32_16x16x32_bf16 v[58:61], v[176:179], v[192:195], v[58:61]
	v_mfma_f32_16x16x32_bf16 v[50:53], v[184:187], v[192:195], v[50:53]
	v_mfma_f32_16x16x32_bf16 v[42:45], v[176:179], v[200:203], v[42:45]
	v_mfma_f32_16x16x32_bf16 v[34:37], v[184:187], v[200:203], v[34:37]
	v_mfma_f32_16x16x32_bf16 v[26:29], v[176:179], v[208:211], v[26:29]
	v_mfma_f32_16x16x32_bf16 v[18:21], v[184:187], v[208:211], v[18:21]
	v_mfma_f32_16x16x32_bf16 v[10:13], v[176:179], v[232:235], v[10:13]
	v_mfma_f32_16x16x32_bf16 v[2:5], v[184:187], v[232:235], v[2:5]
	s_setprio 0
	s_barrier
	s_add_i32 s4, 0, 0x18000
	v_add_u32_e32 v0, s4, v229
	s_add_i32 s5, 0, 0x1c000
	ds_read_b128 v[130:133], v0
	ds_read_b128 v[134:137], v0 offset:1024
	ds_read_b128 v[138:141], v0 offset:2048
	ds_read_b128 v[142:145], v0 offset:3072
	v_add_u32_e32 v0, s5, v229
	ds_read_b128 v[172:175], v0
	ds_read_b128 v[176:179], v0 offset:1024
	ds_read_b128 v[180:183], v0 offset:2048
	ds_read_b128 v[184:187], v0 offset:3072
	s_add_u32 s78, s78, 0x40000
	s_addc_u32 s79, s79, 0
	s_mov_b32 m0, s88
	v_lshl_add_u64 v[242:243], s[78:79], 0, v[146:147]
	ds_read_b128 v[188:191], v231 offset:32768
	ds_read_b128 v[192:195], v231 offset:33792
	ds_read_b128 v[196:199], v231 offset:34816
	ds_read_b128 v[200:203], v231 offset:35840
	ds_read_b128 v[204:207], v231 offset:36864
	ds_read_b128 v[208:211], v231 offset:37888
	ds_read_b128 v[212:215], v231 offset:38912
	ds_read_b128 v[232:235], v231 offset:39936
	global_load_lds_dwordx4 v[242:243], off
	v_lshl_add_u64 v[242:243], s[78:79], 0, v[150:151]
	s_mov_b32 m0, s89
	s_nop 0
	global_load_lds_dwordx4 v[242:243], off
	s_waitcnt vmcnt(8)
	s_waitcnt lgkmcnt(0)
	s_barrier
	s_setprio 1
	s_waitcnt lgkmcnt(0)
	v_mfma_f32_16x16x32_bf16 v[126:129], v[130:133], v[188:191], v[126:129]
	v_mfma_f32_16x16x32_bf16 v[118:121], v[138:141], v[188:191], v[118:121]
	v_mfma_f32_16x16x32_bf16 v[110:113], v[130:133], v[196:199], v[110:113]
	v_mfma_f32_16x16x32_bf16 v[102:105], v[138:141], v[196:199], v[102:105]
	v_mfma_f32_16x16x32_bf16 v[94:97], v[130:133], v[204:207], v[94:97]
	v_mfma_f32_16x16x32_bf16 v[86:89], v[138:141], v[204:207], v[86:89]
	v_mfma_f32_16x16x32_bf16 v[78:81], v[130:133], v[212:215], v[78:81]
	v_mfma_f32_16x16x32_bf16 v[70:73], v[138:141], v[212:215], v[70:73]
	v_mfma_f32_16x16x32_bf16 v[126:129], v[134:137], v[192:195], v[126:129]
	v_mfma_f32_16x16x32_bf16 v[118:121], v[142:145], v[192:195], v[118:121]
	v_mfma_f32_16x16x32_bf16 v[110:113], v[134:137], v[200:203], v[110:113]
	v_mfma_f32_16x16x32_bf16 v[102:105], v[142:145], v[200:203], v[102:105]
	v_mfma_f32_16x16x32_bf16 v[94:97], v[134:137], v[208:211], v[94:97]
	v_mfma_f32_16x16x32_bf16 v[86:89], v[142:145], v[208:211], v[86:89]
	v_mfma_f32_16x16x32_bf16 v[78:81], v[134:137], v[232:235], v[78:81]
	v_mfma_f32_16x16x32_bf16 v[70:73], v[142:145], v[232:235], v[70:73]
	s_setprio 0
	s_setprio 1
	v_mfma_f32_16x16x32_bf16 v[122:125], v[172:175], v[188:191], v[122:125]
	v_mfma_f32_16x16x32_bf16 v[114:117], v[180:183], v[188:191], v[114:117]
	v_mfma_f32_16x16x32_bf16 v[106:109], v[172:175], v[196:199], v[106:109]
	v_mfma_f32_16x16x32_bf16 v[98:101], v[180:183], v[196:199], v[98:101]
	v_mfma_f32_16x16x32_bf16 v[90:93], v[172:175], v[204:207], v[90:93]
	v_mfma_f32_16x16x32_bf16 v[82:85], v[180:183], v[204:207], v[82:85]
	v_mfma_f32_16x16x32_bf16 v[74:77], v[172:175], v[212:215], v[74:77]
	v_mfma_f32_16x16x32_bf16 v[66:69], v[180:183], v[212:215], v[66:69]
	v_mfma_f32_16x16x32_bf16 v[122:125], v[176:179], v[192:195], v[122:125]
	v_mfma_f32_16x16x32_bf16 v[114:117], v[184:187], v[192:195], v[114:117]
	v_mfma_f32_16x16x32_bf16 v[106:109], v[176:179], v[200:203], v[106:109]
	v_mfma_f32_16x16x32_bf16 v[98:101], v[184:187], v[200:203], v[98:101]
	v_mfma_f32_16x16x32_bf16 v[90:93], v[176:179], v[208:211], v[90:93]
	v_mfma_f32_16x16x32_bf16 v[82:85], v[184:187], v[208:211], v[82:85]
	v_mfma_f32_16x16x32_bf16 v[74:77], v[176:179], v[232:235], v[74:77]
	v_mfma_f32_16x16x32_bf16 v[66:69], v[184:187], v[232:235], v[66:69]
	s_setprio 0
	s_barrier
; #define PG8_STAGE(bufoff, gbase, voff) do { _Pragma("unroll") for (int _i = 0; _i < 2; ++_i) \
;         __builtin_amdgcn_global_load_lds((const unsigned*)((const char*)(gbase) + (voff)[_i]), (LAS unsigned*)(lds + (bufoff) + ldsw + _i * 8192), 16, 0, 0); } while (0)
; #define PG8_LDA(dst, b, h) do { _Pragma("unroll") for (int m = 0; m < 4; ++m) _Pragma("unroll") for (int k = 0; k < 2; ++k) dst[m][k] = *(const LAS bf16x8*)(lds + PG8_SA(b, h) + aoff + m * 2048 + k * 1024); } while (0)
; #define PG8_MMA(ai, bj, At, Bt) do { __builtin_amdgcn_s_setprio(1); _Pragma("unroll") for (int m = 0; m < 4; ++m) _Pragma("unroll") for (int n = 0; n < 2; ++n) _Pragma("unroll") for (int k = 0; k < 2; ++k) \
;         acc[ai][bj][m][n] = __builtin_amdgcn_mfma_f32_16x16x32_bf16(Bt[n][k], At[m][k], acc[ai][bj][m][n], 0, 0, 0); __builtin_amdgcn_s_setprio(0); } while (0)
; #define PG8_WAIT_V(n) asm volatile("s_waitcnt vmcnt(" #n ")" ::: "memory")
; #define PG8_WAIT_L(n) asm volatile("s_waitcnt lgkmcnt(" #n ")" ::: "memory")
; #define PG8_BAR __builtin_amdgcn_s_barrier()
; #define PG8_SCHED __builtin_amdgcn_sched_barrier(0)
; template <class Epi, bool MID = false>
; __device__ __forceinline__ void gemm_phase(LAS unsigned char* lds, const Gemm g, const StaticOrder& S, const Epi& E) {
;     ...
;         for (int t = 0; t < nt; t += 2) {
;             const bool last = (t == nt - 2);
;             const char* a1 = cA + (size_t)(t + 1) * kstep;
;             const char* a2 = last ? nA : cA + (size_t)(t + 2) * kstep; const char* b2 = last ? nB : cB + (size_t)(t + 2) * kstep;
;     ...
;             PG8_LDA(At, 1, 1); PG8_STAGE(PG8_SB(1, 0), b3, voffB); PG8_STAGE(PG8_SB(1, 1), b3 + hstepB, voffB); PG8_STAGE(PG8_SA(1, 0), a3, voffA);
;             PG8_WAIT_V(8); PG8_WAIT_L(0); PG8_BAR; PG8_MMA(1, 0, At, B0); PG8_MMA(1, 1, At, B1); PG8_BAR; PG8_SCHED;
	s_add_i32 s4, s4, s86
	v_lshl_add_u64 v[216:217], v[216:217], 0, s[24:25]
	s_mov_b32 m0, s4
	ds_read_b128 v[188:191], v231 offset:49152
	ds_read_b128 v[192:195], v231 offset:50176
	ds_read_b128 v[196:199], v231 offset:51200
	ds_read_b128 v[200:203], v231 offset:52224
	ds_read_b128 v[204:207], v231 offset:53248
	ds_read_b128 v[208:211], v231 offset:54272
	ds_read_b128 v[212:215], v231 offset:55296
	ds_read_b128 v[232:235], v231 offset:56320
	global_load_lds_dwordx4 v[216:217], off
	s_add_i32 m0, s4, 0x2000
	s_add_u32 s70, s70, 0x40080
	v_lshl_add_u64 v[216:217], v[236:237], 0, s[24:25]
	s_addc_u32 s71, s71, 0
	s_add_i32 s4, s5, s86
	global_load_lds_dwordx4 v[216:217], off
	v_lshl_add_u64 v[216:217], s[70:71], 0, v[148:149]
	s_mov_b32 m0, s4
	s_nop 0
	global_load_lds_dwordx4 v[216:217], off
	v_lshl_add_u64 v[216:217], s[70:71], 0, v[152:153]
	s_add_i32 m0, s4, 0x2000
	s_nop 0
	global_load_lds_dwordx4 v[216:217], off
	v_lshl_add_u64 v[216:217], v[238:239], 0, s[24:25]
	s_mov_b32 m0, s92
	s_nop 0
	global_load_lds_dwordx4 v[216:217], off
	v_lshl_add_u64 v[216:217], v[240:241], 0, s[24:25]
	s_mov_b32 m0, s93
	s_nop 0
	global_load_lds_dwordx4 v[216:217], off
	s_waitcnt vmcnt(8)
	s_waitcnt lgkmcnt(0)
	s_barrier
	s_setprio 1
	s_waitcnt lgkmcnt(0)
	v_mfma_f32_16x16x32_bf16 v[62:65], v[130:133], v[188:191], v[62:65]
	v_mfma_f32_16x16x32_bf16 v[54:57], v[138:141], v[188:191], v[54:57]
	v_mfma_f32_16x16x32_bf16 v[46:49], v[130:133], v[196:199], v[46:49]
	v_mfma_f32_16x16x32_bf16 v[38:41], v[138:141], v[196:199], v[38:41]
	v_mfma_f32_16x16x32_bf16 v[30:33], v[130:133], v[204:207], v[30:33]
	v_mfma_f32_16x16x32_bf16 v[22:25], v[138:141], v[204:207], v[22:25]
	v_mfma_f32_16x16x32_bf16 v[14:17], v[130:133], v[212:215], v[14:17]
	v_mfma_f32_16x16x32_bf16 v[6:9], v[138:141], v[212:215], v[6:9]
	v_mfma_f32_16x16x32_bf16 v[62:65], v[134:137], v[192:195], v[62:65]
	v_mfma_f32_16x16x32_bf16 v[54:57], v[142:145], v[192:195], v[54:57]
	v_mfma_f32_16x16x32_bf16 v[46:49], v[134:137], v[200:203], v[46:49]
	v_mfma_f32_16x16x32_bf16 v[38:41], v[142:145], v[200:203], v[38:41]
	v_mfma_f32_16x16x32_bf16 v[30:33], v[134:137], v[208:211], v[30:33]
	v_mfma_f32_16x16x32_bf16 v[22:25], v[142:145], v[208:211], v[22:25]
	v_mfma_f32_16x16x32_bf16 v[14:17], v[134:137], v[232:235], v[14:17]
	v_mfma_f32_16x16x32_bf16 v[6:9], v[142:145], v[232:235], v[6:9]
	s_setprio 0
	s_setprio 1
	v_mfma_f32_16x16x32_bf16 v[58:61], v[172:175], v[188:191], v[58:61]
	v_mfma_f32_16x16x32_bf16 v[50:53], v[180:183], v[188:191], v[50:53]
	v_mfma_f32_16x16x32_bf16 v[42:45], v[172:175], v[196:199], v[42:45]
	v_mfma_f32_16x16x32_bf16 v[34:37], v[180:183], v[196:199], v[34:37]
	v_mfma_f32_16x16x32_bf16 v[26:29], v[172:175], v[204:207], v[26:29]
	v_mfma_f32_16x16x32_bf16 v[18:21], v[180:183], v[204:207], v[18:21]
	v_mfma_f32_16x16x32_bf16 v[10:13], v[172:175], v[212:215], v[10:13]
	v_mfma_f32_16x16x32_bf16 v[2:5], v[180:183], v[212:215], v[2:5]
	v_mfma_f32_16x16x32_bf16 v[58:61], v[176:179], v[192:195], v[58:61]
	v_mfma_f32_16x16x32_bf16 v[50:53], v[184:187], v[192:195], v[50:53]
	v_mfma_f32_16x16x32_bf16 v[42:45], v[176:179], v[200:203], v[42:45]
	v_mfma_f32_16x16x32_bf16 v[34:37], v[184:187], v[200:203], v[34:37]
	v_mfma_f32_16x16x32_bf16 v[26:29], v[176:179], v[208:211], v[26:29]
	v_mfma_f32_16x16x32_bf16 v[18:21], v[184:187], v[208:211], v[18:21]
	v_mfma_f32_16x16x32_bf16 v[10:13], v[176:179], v[232:235], v[10:13]
	v_mfma_f32_16x16x32_bf16 v[2:5], v[184:187], v[232:235], v[2:5]
	s_setprio 0
	s_barrier
	s_add_u32 s42, s42, 0x100
	s_addc_u32 s43, s43, 0
	s_add_u32 s72, s72, 0x100
	s_addc_u32 s73, s73, 0
	s_cmp_ge_i32 s97, s81
	s_mov_b32 s70, s97
	s_cbranch_scc0 .LBB0_355
	s_branch .Lpk_355_exit

; #define PG8_BAR __builtin_amdgcn_s_barrier()
; template <class Epi, bool MID = false>
; __device__ __forceinline__ void gemm_phase(LAS unsigned char* lds, const Gemm g, const StaticOrder& S, const Epi& E) {
;     ...
;         if (wr == 0) PG8_BAR;
.Lpk_355_exit:
	s_and_b64 vcc, exec, s[54:55]
	s_cbranch_vccz .LBB0_358

; #define PG8_STAGE(bufoff, gbase, voff) do { _Pragma("unroll") for (int _i = 0; _i < 2; ++_i) \
;         __builtin_amdgcn_global_load_lds((const unsigned*)((const char*)(gbase) + (voff)[_i]), (LAS unsigned*)(lds + (bufoff) + ldsw + _i * 8192), 16, 0, 0); } while (0)
; #define PG8_LDA(dst, b, h) do { _Pragma("unroll") for (int m = 0; m < 4; ++m) _Pragma("unroll") for (int k = 0; k < 2; ++k) dst[m][k] = *(const LAS bf16x8*)(lds + PG8_SA(b, h) + aoff + m * 2048 + k * 1024); } while (0)
; #define PG8_LDB(dst, b, h) do { _Pragma("unroll") for (int n = 0; n < 2; ++n) _Pragma("unroll") for (int k = 0; k < 2; ++k) dst[n][k] = *(const LAS bf16x8*)(lds + PG8_SB(b, h) + boff + n * 2048 + k * 1024); } while (0)
; #define PG8_MMA(ai, bj, At, Bt) do { __builtin_amdgcn_s_setprio(1); _Pragma("unroll") for (int m = 0; m < 4; ++m) _Pragma("unroll") for (int n = 0; n < 2; ++n) _Pragma("unroll") for (int k = 0; k < 2; ++k) \
;         acc[ai][bj][m][n] = __builtin_amdgcn_mfma_f32_16x16x32_bf16(Bt[n][k], At[m][k], acc[ai][bj][m][n], 0, 0, 0); __builtin_amdgcn_s_setprio(0); } while (0)
; #define PG8_BAR __builtin_amdgcn_s_barrier()
; template <class Epi, bool MID = false>
; __device__ __forceinline__ void gemm_phase(LAS unsigned char* lds, const Gemm g, const StaticOrder& S, const Epi& E) {
;     ...
;         const bool has_next = S.next(ui + 1, nxt);
;         const char* nA = has_next ? (const char*)g.A + (size_t)nxt.pm * tstepA : cA; const char* nB = has_next ? (const char*)g.Bt + (size_t)nxt.pn * tstepB : cB;
; #pragma nounroll
;         for (int t = 0; t < nt; t += 2) {
;             const bool last = (t == nt - 2);
;             const char* a1 = cA + (size_t)(t + 1) * kstep;
;             const char* a2 = last ? nA : cA + (size_t)(t + 2) * kstep; const char* b2 = last ? nB : cB + (size_t)(t + 2) * kstep;
;             const char* a3 = a2 + kstep; const char* b3 = b2 + kstep;
;             PG8_LDB(B0, 0, 0); PG8_LDB(B1, 0, 1); PG8_SCHED; PG8_LDA(At, 0, 0); PG8_STAGE(PG8_SA(1, 1), a1 + hstepA, voffA);
;             PG8_WAIT_V(8); PG8_WAIT_L(0); PG8_BAR; PG8_MMA(0, 0, At, B0); PG8_MMA(0, 1, At, B1); PG8_BAR; PG8_SCHED;
;             PG8_LDA(At, 0, 1); PG8_STAGE(PG8_SB(0, 0), b2, voffB); PG8_STAGE(PG8_SB(0, 1), b2 + hstepB, voffB); PG8_STAGE(PG8_SA(0, 0), a2, voffA);
;             PG8_WAIT_V(8); PG8_WAIT_L(0); PG8_BAR; PG8_MMA(1, 0, At, B0); PG8_MMA(1, 1, At, B1); PG8_BAR; PG8_SCHED;
.LBB0_594:
	s_add_u32 s72, s44, 0x100
	s_addc_u32 s73, s45, 0
	s_mov_b32 s42, 0
	s_add_i32 s91, s42, 2
	s_add_u32 s0, s18, 0x100
	s_addc_u32 s1, s19, 0
	s_add_i32 s4, 0, 0x10000
	s_cmp_eq_u32 s87, s42
	s_cselect_b32 s45, s61, s1
	s_cselect_b32 s44, s60, s0
	v_add_u32_e32 v0, s4, v199
	s_cselect_b32 s43, s63, s73
	s_cselect_b32 s42, s62, s72
	s_add_i32 s5, 0, 0x14000
	ds_read_b128 v[130:133], v0
	ds_read_b128 v[134:137], v0 offset:1024
	ds_read_b128 v[138:141], v0 offset:2048
	ds_read_b128 v[142:145], v0 offset:3072
	v_add_u32_e32 v0, s5, v199
	ds_read_b128 v[146:149], v0
	ds_read_b128 v[150:153], v0 offset:1024
	ds_read_b128 v[184:187], v0 offset:2048
	ds_read_b128 v[188:191], v0 offset:3072
	v_lshl_add_u64 v[154:155], s[18:19], 0, v[180:181]
	s_add_i32 m0, s81, 0xc000
	ds_read_b128 v[192:195], v208
	ds_read_b128 v[200:203], v208 offset:1024
	ds_read_b128 v[204:207], v208 offset:2048
	ds_read_b128 v[210:213], v208 offset:3072
	ds_read_b128 v[214:217], v208 offset:4096
	ds_read_b128 v[230:233], v208 offset:5120
	ds_read_b128 v[234:237], v208 offset:6144
	ds_read_b128 v[238:241], v208 offset:7168
	global_load_lds_dwordx4 v[154:155], off
	v_lshl_add_u64 v[154:155], s[18:19], 0, v[182:183]
	s_add_i32 m0, s81, 0xe000
	s_nop 0
	global_load_lds_dwordx4 v[154:155], off
	s_waitcnt vmcnt(8)
	s_waitcnt lgkmcnt(0)
	s_barrier
	s_setprio 1
	s_waitcnt lgkmcnt(0)
	v_mfma_f32_16x16x32_bf16 v[126:129], v[130:133], v[192:195], 0
	v_mfma_f32_16x16x32_bf16 v[122:125], v[138:141], v[192:195], 0
	v_mfma_f32_16x16x32_bf16 v[110:113], v[130:133], v[204:207], 0
	v_mfma_f32_16x16x32_bf16 v[106:109], v[138:141], v[204:207], 0
	v_mfma_f32_16x16x32_bf16 v[94:97], v[130:133], v[214:217], 0
	v_mfma_f32_16x16x32_bf16 v[90:93], v[138:141], v[214:217], 0
	v_mfma_f32_16x16x32_bf16 v[78:81], v[130:133], v[234:237], 0
	v_mfma_f32_16x16x32_bf16 v[74:77], v[138:141], v[234:237], 0
	v_mfma_f32_16x16x32_bf16 v[126:129], v[134:137], v[200:203], v[126:129]
	v_mfma_f32_16x16x32_bf16 v[122:125], v[142:145], v[200:203], v[122:125]
	v_mfma_f32_16x16x32_bf16 v[110:113], v[134:137], v[210:213], v[110:113]
	v_mfma_f32_16x16x32_bf16 v[106:109], v[142:145], v[210:213], v[106:109]
	v_mfma_f32_16x16x32_bf16 v[94:97], v[134:137], v[230:233], v[94:97]
	v_mfma_f32_16x16x32_bf16 v[90:93], v[142:145], v[230:233], v[90:93]
	v_mfma_f32_16x16x32_bf16 v[78:81], v[134:137], v[238:241], v[78:81]
	v_mfma_f32_16x16x32_bf16 v[74:77], v[142:145], v[238:241], v[74:77]
	s_setprio 0
	s_setprio 1
	v_mfma_f32_16x16x32_bf16 v[118:121], v[146:149], v[192:195], 0
	v_mfma_f32_16x16x32_bf16 v[114:117], v[184:187], v[192:195], 0
	v_mfma_f32_16x16x32_bf16 v[102:105], v[146:149], v[204:207], 0
	v_mfma_f32_16x16x32_bf16 v[98:101], v[184:187], v[204:207], 0
	v_mfma_f32_16x16x32_bf16 v[86:89], v[146:149], v[214:217], 0
	v_mfma_f32_16x16x32_bf16 v[82:85], v[184:187], v[214:217], 0
	v_mfma_f32_16x16x32_bf16 v[70:73], v[146:149], v[234:237], 0
	v_mfma_f32_16x16x32_bf16 v[66:69], v[184:187], v[234:237], 0
	v_mfma_f32_16x16x32_bf16 v[118:121], v[150:153], v[200:203], v[118:121]
	v_mfma_f32_16x16x32_bf16 v[114:117], v[188:191], v[200:203], v[114:117]
	v_mfma_f32_16x16x32_bf16 v[102:105], v[150:153], v[210:213], v[102:105]
	v_mfma_f32_16x16x32_bf16 v[98:101], v[188:191], v[210:213], v[98:101]
	v_mfma_f32_16x16x32_bf16 v[86:89], v[150:153], v[230:233], v[86:89]
	v_mfma_f32_16x16x32_bf16 v[82:85], v[188:191], v[230:233], v[82:85]
	v_mfma_f32_16x16x32_bf16 v[70:73], v[150:153], v[238:241], v[70:73]
	v_mfma_f32_16x16x32_bf16 v[66:69], v[188:191], v[238:241], v[66:69]
	s_setprio 0
	s_barrier
	s_add_i32 s4, s4, s79
	v_lshl_add_u64 v[154:155], s[42:43], 0, v[158:159]
	s_mov_b32 m0, s4
	ds_read_b128 v[192:195], v208 offset:16384
	ds_read_b128 v[200:203], v208 offset:17408
	ds_read_b128 v[204:207], v208 offset:18432
	ds_read_b128 v[210:213], v208 offset:19456
	ds_read_b128 v[214:217], v208 offset:20480
	ds_read_b128 v[230:233], v208 offset:21504
	ds_read_b128 v[234:237], v208 offset:22528
	ds_read_b128 v[238:241], v208 offset:23552
	global_load_lds_dwordx4 v[154:155], off
	s_add_i32 m0, s4, 0x2000
	s_add_u32 s18, s42, 0x18000
	v_lshl_add_u64 v[196:197], s[42:43], 0, v[164:165]
	s_addc_u32 s19, s43, 0
	s_add_i32 s4, s5, s79
	global_load_lds_dwordx4 v[196:197], off
	v_lshl_add_u64 v[242:243], s[18:19], 0, v[158:159]
	s_mov_b32 m0, s4
	v_lshl_add_u64 v[244:245], s[44:45], 0, v[160:161]
	global_load_lds_dwordx4 v[242:243], off
	v_lshl_add_u64 v[242:243], s[18:19], 0, v[164:165]
	s_add_i32 m0, s4, 0x2000
	s_nop 0
	global_load_lds_dwordx4 v[242:243], off
	v_lshl_add_u64 v[242:243], s[44:45], 0, v[156:157]
	s_mov_b32 m0, s81
	s_nop 0
	global_load_lds_dwordx4 v[242:243], off
	s_mov_b32 m0, s80
	s_nop 0
	global_load_lds_dwordx4 v[244:245], off
	s_waitcnt vmcnt(8)
	s_waitcnt lgkmcnt(0)
	s_barrier
; #define PG8_STAGE(bufoff, gbase, voff) do { _Pragma("unroll") for (int _i = 0; _i < 2; ++_i) \
;         __builtin_amdgcn_global_load_lds((const unsigned*)((const char*)(gbase) + (voff)[_i]), (LAS unsigned*)(lds + (bufoff) + ldsw + _i * 8192), 16, 0, 0); } while (0)
; #define PG8_LDA(dst, b, h) do { _Pragma("unroll") for (int m = 0; m < 4; ++m) _Pragma("unroll") for (int k = 0; k < 2; ++k) dst[m][k] = *(const LAS bf16x8*)(lds + PG8_SA(b, h) + aoff + m * 2048 + k * 1024); } while (0)
; #define PG8_LDB(dst, b, h) do { _Pragma("unroll") for (int n = 0; n < 2; ++n) _Pragma("unroll") for (int k = 0; k < 2; ++k) dst[n][k] = *(const LAS bf16x8*)(lds + PG8_SB(b, h) + boff + n * 2048 + k * 1024); } while (0)
; #define PG8_MMA(ai, bj, At, Bt) do { __builtin_amdgcn_s_setprio(1); _Pragma("unroll") for (int m = 0; m < 4; ++m) _Pragma("unroll") for (int n = 0; n < 2; ++n) _Pragma("unroll") for (int k = 0; k < 2; ++k) \
;         acc[ai][bj][m][n] = __builtin_amdgcn_mfma_f32_16x16x32_bf16(Bt[n][k], At[m][k], acc[ai][bj][m][n], 0, 0, 0); __builtin_amdgcn_s_setprio(0); } while (0)
; #define PG8_WAIT_V(n) asm volatile("s_waitcnt vmcnt(" #n ")" ::: "memory")
; #define PG8_WAIT_L(n) asm volatile("s_waitcnt lgkmcnt(" #n ")" ::: "memory")
; #define PG8_BAR __builtin_amdgcn_s_barrier()
; #define PG8_SCHED __builtin_amdgcn_sched_barrier(0)
; template <class Epi, bool MID = false>
; __device__ __forceinline__ void gemm_phase(LAS unsigned char* lds, const Gemm g, const StaticOrder& S, const Epi& E) {
;     ...
;             PG8_WAIT_V(8); PG8_WAIT_L(0); PG8_BAR; PG8_MMA(1, 0, At, B0); PG8_MMA(1, 1, At, B1); PG8_BAR; PG8_SCHED;
;             PG8_LDB(B0, 1, 0); PG8_LDB(B1, 1, 1); PG8_SCHED; PG8_LDA(At, 1, 0); PG8_STAGE(PG8_SA(0, 1), a2 + hstepA, voffA);
;             PG8_WAIT_V(8); PG8_WAIT_L(0); PG8_BAR; PG8_MMA(0, 0, At, B0); PG8_MMA(0, 1, At, B1); PG8_BAR; PG8_SCHED;
	s_setprio 1
	s_waitcnt lgkmcnt(0)
	v_mfma_f32_16x16x32_bf16 v[62:65], v[130:133], v[192:195], 0
	v_mfma_f32_16x16x32_bf16 v[58:61], v[138:141], v[192:195], 0
	v_mfma_f32_16x16x32_bf16 v[46:49], v[130:133], v[204:207], 0
	v_mfma_f32_16x16x32_bf16 v[42:45], v[138:141], v[204:207], 0
	v_mfma_f32_16x16x32_bf16 v[30:33], v[130:133], v[214:217], 0
	v_mfma_f32_16x16x32_bf16 v[26:29], v[138:141], v[214:217], 0
	v_mfma_f32_16x16x32_bf16 v[14:17], v[130:133], v[234:237], 0
	v_mfma_f32_16x16x32_bf16 v[10:13], v[138:141], v[234:237], 0
	v_mfma_f32_16x16x32_bf16 v[62:65], v[134:137], v[200:203], v[62:65]
	v_mfma_f32_16x16x32_bf16 v[58:61], v[142:145], v[200:203], v[58:61]
	v_mfma_f32_16x16x32_bf16 v[46:49], v[134:137], v[210:213], v[46:49]
	v_mfma_f32_16x16x32_bf16 v[42:45], v[142:145], v[210:213], v[42:45]
	v_mfma_f32_16x16x32_bf16 v[30:33], v[134:137], v[230:233], v[30:33]
	v_mfma_f32_16x16x32_bf16 v[26:29], v[142:145], v[230:233], v[26:29]
	v_mfma_f32_16x16x32_bf16 v[14:17], v[134:137], v[238:241], v[14:17]
	v_mfma_f32_16x16x32_bf16 v[10:13], v[142:145], v[238:241], v[10:13]
	s_setprio 0
	s_setprio 1
	v_mfma_f32_16x16x32_bf16 v[54:57], v[146:149], v[192:195], 0
	v_mfma_f32_16x16x32_bf16 v[50:53], v[184:187], v[192:195], 0
	v_mfma_f32_16x16x32_bf16 v[38:41], v[146:149], v[204:207], 0
	v_mfma_f32_16x16x32_bf16 v[34:37], v[184:187], v[204:207], 0
	v_mfma_f32_16x16x32_bf16 v[22:25], v[146:149], v[214:217], 0
	v_mfma_f32_16x16x32_bf16 v[18:21], v[184:187], v[214:217], 0
	v_mfma_f32_16x16x32_bf16 v[6:9], v[146:149], v[234:237], 0
	v_mfma_f32_16x16x32_bf16 v[2:5], v[184:187], v[234:237], 0
	v_mfma_f32_16x16x32_bf16 v[54:57], v[150:153], v[200:203], v[54:57]
	v_mfma_f32_16x16x32_bf16 v[50:53], v[188:191], v[200:203], v[50:53]
	v_mfma_f32_16x16x32_bf16 v[38:41], v[150:153], v[210:213], v[38:41]
	v_mfma_f32_16x16x32_bf16 v[34:37], v[188:191], v[210:213], v[34:37]
	v_mfma_f32_16x16x32_bf16 v[22:25], v[150:153], v[230:233], v[22:25]
	v_mfma_f32_16x16x32_bf16 v[18:21], v[188:191], v[230:233], v[18:21]
	v_mfma_f32_16x16x32_bf16 v[6:9], v[150:153], v[238:241], v[6:9]
	v_mfma_f32_16x16x32_bf16 v[2:5], v[188:191], v[238:241], v[2:5]
	s_setprio 0
	s_barrier
	s_add_i32 s4, 0, 0x18000
	v_add_u32_e32 v0, s4, v199
	s_add_i32 s5, 0, 0x1c000
	ds_read_b128 v[130:133], v0
	ds_read_b128 v[134:137], v0 offset:1024
	ds_read_b128 v[138:141], v0 offset:2048
	ds_read_b128 v[142:145], v0 offset:3072
	v_add_u32_e32 v0, s5, v199
	ds_read_b128 v[146:149], v0
	ds_read_b128 v[150:153], v0 offset:1024
	ds_read_b128 v[184:187], v0 offset:2048
	ds_read_b128 v[188:191], v0 offset:3072
	s_add_u32 s18, s44, 0x90000
	s_addc_u32 s19, s45, 0
	s_mov_b32 m0, s75
	v_lshl_add_u64 v[246:247], s[18:19], 0, v[156:157]
	ds_read_b128 v[192:195], v208 offset:32768
	ds_read_b128 v[200:203], v208 offset:33792
	ds_read_b128 v[204:207], v208 offset:34816
	ds_read_b128 v[210:213], v208 offset:35840
	ds_read_b128 v[214:217], v208 offset:36864
	ds_read_b128 v[230:233], v208 offset:37888
	ds_read_b128 v[234:237], v208 offset:38912
	ds_read_b128 v[238:241], v208 offset:39936
	global_load_lds_dwordx4 v[246:247], off
	v_lshl_add_u64 v[246:247], s[18:19], 0, v[160:161]
	s_mov_b32 m0, s82
	s_nop 0
	global_load_lds_dwordx4 v[246:247], off
	s_waitcnt vmcnt(8)
	s_waitcnt lgkmcnt(0)
	s_barrier
	s_setprio 1
	s_waitcnt lgkmcnt(0)
	v_mfma_f32_16x16x32_bf16 v[126:129], v[130:133], v[192:195], v[126:129]
	v_mfma_f32_16x16x32_bf16 v[122:125], v[138:141], v[192:195], v[122:125]
	v_mfma_f32_16x16x32_bf16 v[110:113], v[130:133], v[204:207], v[110:113]
	v_mfma_f32_16x16x32_bf16 v[106:109], v[138:141], v[204:207], v[106:109]
	v_mfma_f32_16x16x32_bf16 v[94:97], v[130:133], v[214:217], v[94:97]
	v_mfma_f32_16x16x32_bf16 v[90:93], v[138:141], v[214:217], v[90:93]
	v_mfma_f32_16x16x32_bf16 v[78:81], v[130:133], v[234:237], v[78:81]
	v_mfma_f32_16x16x32_bf16 v[74:77], v[138:141], v[234:237], v[74:77]
	v_mfma_f32_16x16x32_bf16 v[126:129], v[134:137], v[200:203], v[126:129]
	v_mfma_f32_16x16x32_bf16 v[122:125], v[142:145], v[200:203], v[122:125]
	v_mfma_f32_16x16x32_bf16 v[110:113], v[134:137], v[210:213], v[110:113]
	v_mfma_f32_16x16x32_bf16 v[106:109], v[142:145], v[210:213], v[106:109]
	v_mfma_f32_16x16x32_bf16 v[94:97], v[134:137], v[230:233], v[94:97]
	v_mfma_f32_16x16x32_bf16 v[90:93], v[142:145], v[230:233], v[90:93]
	v_mfma_f32_16x16x32_bf16 v[78:81], v[134:137], v[238:241], v[78:81]
	v_mfma_f32_16x16x32_bf16 v[74:77], v[142:145], v[238:241], v[74:77]
	s_setprio 0
	s_setprio 1
	v_mfma_f32_16x16x32_bf16 v[118:121], v[146:149], v[192:195], v[118:121]
	v_mfma_f32_16x16x32_bf16 v[114:117], v[184:187], v[192:195], v[114:117]
	v_mfma_f32_16x16x32_bf16 v[102:105], v[146:149], v[204:207], v[102:105]
	v_mfma_f32_16x16x32_bf16 v[98:101], v[184:187], v[204:207], v[98:101]
	v_mfma_f32_16x16x32_bf16 v[86:89], v[146:149], v[214:217], v[86:89]
	v_mfma_f32_16x16x32_bf16 v[82:85], v[184:187], v[214:217], v[82:85]
	v_mfma_f32_16x16x32_bf16 v[70:73], v[146:149], v[234:237], v[70:73]
	v_mfma_f32_16x16x32_bf16 v[66:69], v[184:187], v[234:237], v[66:69]
	v_mfma_f32_16x16x32_bf16 v[118:121], v[150:153], v[200:203], v[118:121]
	v_mfma_f32_16x16x32_bf16 v[114:117], v[188:191], v[200:203], v[114:117]
	v_mfma_f32_16x16x32_bf16 v[102:105], v[150:153], v[210:213], v[102:105]
	v_mfma_f32_16x16x32_bf16 v[98:101], v[188:191], v[210:213], v[98:101]
	v_mfma_f32_16x16x32_bf16 v[86:89], v[150:153], v[230:233], v[86:89]
	v_mfma_f32_16x16x32_bf16 v[82:85], v[188:191], v[230:233], v[82:85]
	v_mfma_f32_16x16x32_bf16 v[70:73], v[150:153], v[238:241], v[70:73]
	v_mfma_f32_16x16x32_bf16 v[66:69], v[188:191], v[238:241], v[66:69]
	s_setprio 0
	s_barrier
; #define PG8_STAGE(bufoff, gbase, voff) do { _Pragma("unroll") for (int _i = 0; _i < 2; ++_i) \
;         __builtin_amdgcn_global_load_lds((const unsigned*)((const char*)(gbase) + (voff)[_i]), (LAS unsigned*)(lds + (bufoff) + ldsw + _i * 8192), 16, 0, 0); } while (0)
; #define PG8_LDA(dst, b, h) do { _Pragma("unroll") for (int m = 0; m < 4; ++m) _Pragma("unroll") for (int k = 0; k < 2; ++k) dst[m][k] = *(const LAS bf16x8*)(lds + PG8_SA(b, h) + aoff + m * 2048 + k * 1024); } while (0)
; #define PG8_MMA(ai, bj, At, Bt) do { __builtin_amdgcn_s_setprio(1); _Pragma("unroll") for (int m = 0; m < 4; ++m) _Pragma("unroll") for (int n = 0; n < 2; ++n) _Pragma("unroll") for (int k = 0; k < 2; ++k) \
;         acc[ai][bj][m][n] = __builtin_amdgcn_mfma_f32_16x16x32_bf16(Bt[n][k], At[m][k], acc[ai][bj][m][n], 0, 0, 0); __builtin_amdgcn_s_setprio(0); } while (0)
; #define PG8_WAIT_V(n) asm volatile("s_waitcnt vmcnt(" #n ")" ::: "memory")
; #define PG8_WAIT_L(n) asm volatile("s_waitcnt lgkmcnt(" #n ")" ::: "memory")
; #define PG8_BAR __builtin_amdgcn_s_barrier()
; #define PG8_SCHED __builtin_amdgcn_sched_barrier(0)
; template <class Epi, bool MID = false>
; __device__ __forceinline__ void gemm_phase(LAS unsigned char* lds, const Gemm g, const StaticOrder& S, const Epi& E) {
;     ...
;         for (int t = 0; t < nt; t += 2) {
;             const bool last = (t == nt - 2);
;             const char* a1 = cA + (size_t)(t + 1) * kstep;
;             const char* a2 = last ? nA : cA + (size_t)(t + 2) * kstep; const char* b2 = last ? nB : cB + (size_t)(t + 2) * kstep;
;     ...
;             PG8_LDA(At, 1, 1); PG8_STAGE(PG8_SB(1, 0), b3, voffB); PG8_STAGE(PG8_SB(1, 1), b3 + hstepB, voffB); PG8_STAGE(PG8_SA(1, 0), a3, voffA);
;             PG8_WAIT_V(8); PG8_WAIT_L(0); PG8_BAR; PG8_MMA(1, 0, At, B0); PG8_MMA(1, 1, At, B1); PG8_BAR; PG8_SCHED;
	s_add_i32 s4, s4, s79
	v_lshl_add_u64 v[154:155], v[154:155], 0, s[24:25]
	s_mov_b32 m0, s4
	ds_read_b128 v[192:195], v208 offset:49152
	ds_read_b128 v[200:203], v208 offset:50176
	ds_read_b128 v[204:207], v208 offset:51200
	ds_read_b128 v[210:213], v208 offset:52224
	ds_read_b128 v[214:217], v208 offset:53248
	ds_read_b128 v[230:233], v208 offset:54272
	ds_read_b128 v[234:237], v208 offset:55296
	ds_read_b128 v[238:241], v208 offset:56320
	global_load_lds_dwordx4 v[154:155], off
	s_add_i32 m0, s4, 0x2000
	s_add_u32 s18, s42, 0x18080
	v_lshl_add_u64 v[154:155], v[196:197], 0, s[24:25]
	s_addc_u32 s19, s43, 0
	s_add_i32 s4, s5, s79
	global_load_lds_dwordx4 v[154:155], off
	v_lshl_add_u64 v[154:155], s[18:19], 0, v[158:159]
	s_mov_b32 m0, s4
	s_nop 0
	global_load_lds_dwordx4 v[154:155], off
	v_lshl_add_u64 v[154:155], s[18:19], 0, v[164:165]
	s_add_i32 m0, s4, 0x2000
	s_nop 0
	global_load_lds_dwordx4 v[154:155], off
	v_lshl_add_u64 v[154:155], v[242:243], 0, s[24:25]
	s_mov_b32 m0, s84
	s_nop 0
	global_load_lds_dwordx4 v[154:155], off
	v_lshl_add_u64 v[154:155], v[244:245], 0, s[24:25]
	s_mov_b32 m0, s85
	s_nop 0
	global_load_lds_dwordx4 v[154:155], off
	s_waitcnt vmcnt(8)
	s_waitcnt lgkmcnt(0)
	s_barrier
	s_setprio 1
	s_waitcnt lgkmcnt(0)
	v_mfma_f32_16x16x32_bf16 v[62:65], v[130:133], v[192:195], v[62:65]
	v_mfma_f32_16x16x32_bf16 v[58:61], v[138:141], v[192:195], v[58:61]
	v_mfma_f32_16x16x32_bf16 v[46:49], v[130:133], v[204:207], v[46:49]
	v_mfma_f32_16x16x32_bf16 v[42:45], v[138:141], v[204:207], v[42:45]
	v_mfma_f32_16x16x32_bf16 v[30:33], v[130:133], v[214:217], v[30:33]
	v_mfma_f32_16x16x32_bf16 v[26:29], v[138:141], v[214:217], v[26:29]
	v_mfma_f32_16x16x32_bf16 v[14:17], v[130:133], v[234:237], v[14:17]
	v_mfma_f32_16x16x32_bf16 v[10:13], v[138:141], v[234:237], v[10:13]
	v_mfma_f32_16x16x32_bf16 v[62:65], v[134:137], v[200:203], v[62:65]
	v_mfma_f32_16x16x32_bf16 v[58:61], v[142:145], v[200:203], v[58:61]
	v_mfma_f32_16x16x32_bf16 v[46:49], v[134:137], v[210:213], v[46:49]
	v_mfma_f32_16x16x32_bf16 v[42:45], v[142:145], v[210:213], v[42:45]
	v_mfma_f32_16x16x32_bf16 v[30:33], v[134:137], v[230:233], v[30:33]
	v_mfma_f32_16x16x32_bf16 v[26:29], v[142:145], v[230:233], v[26:29]
	v_mfma_f32_16x16x32_bf16 v[14:17], v[134:137], v[238:241], v[14:17]
	v_mfma_f32_16x16x32_bf16 v[10:13], v[142:145], v[238:241], v[10:13]
	s_setprio 0
	s_setprio 1
	v_mfma_f32_16x16x32_bf16 v[54:57], v[146:149], v[192:195], v[54:57]
	v_mfma_f32_16x16x32_bf16 v[50:53], v[184:187], v[192:195], v[50:53]
	v_mfma_f32_16x16x32_bf16 v[38:41], v[146:149], v[204:207], v[38:41]
	v_mfma_f32_16x16x32_bf16 v[34:37], v[184:187], v[204:207], v[34:37]
	v_mfma_f32_16x16x32_bf16 v[22:25], v[146:149], v[214:217], v[22:25]
	v_mfma_f32_16x16x32_bf16 v[18:21], v[184:187], v[214:217], v[18:21]
	v_mfma_f32_16x16x32_bf16 v[6:9], v[146:149], v[234:237], v[6:9]
	v_mfma_f32_16x16x32_bf16 v[2:5], v[184:187], v[234:237], v[2:5]
	v_mfma_f32_16x16x32_bf16 v[54:57], v[150:153], v[200:203], v[54:57]
	v_mfma_f32_16x16x32_bf16 v[50:53], v[188:191], v[200:203], v[50:53]
	v_mfma_f32_16x16x32_bf16 v[38:41], v[150:153], v[210:213], v[38:41]
	v_mfma_f32_16x16x32_bf16 v[34:37], v[188:191], v[210:213], v[34:37]
	v_mfma_f32_16x16x32_bf16 v[22:25], v[150:153], v[230:233], v[22:25]
	v_mfma_f32_16x16x32_bf16 v[18:21], v[188:191], v[230:233], v[18:21]
	v_mfma_f32_16x16x32_bf16 v[6:9], v[150:153], v[238:241], v[6:9]
	v_mfma_f32_16x16x32_bf16 v[2:5], v[188:191], v[238:241], v[2:5]
	s_setprio 0
	s_barrier
	s_add_u32 s72, s72, 0x100
	s_addc_u32 s73, s73, 0
	s_cmp_ge_i32 s91, s68
	s_mov_b64 s[18:19], s[0:1]
	s_mov_b32 s42, s91
	s_cbranch_scc0 .LBB0_595
	s_branch .Lpk_595_exit

; #define PG8_STAGE(bufoff, gbase, voff) do { _Pragma("unroll") for (int _i = 0; _i < 2; ++_i) \
;         __builtin_amdgcn_global_load_lds((const unsigned*)((const char*)(gbase) + (voff)[_i]), (LAS unsigned*)(lds + (bufoff) + ldsw + _i * 8192), 16, 0, 0); } while (0)
; #define PG8_LDA(dst, b, h) do { _Pragma("unroll") for (int m = 0; m < 4; ++m) _Pragma("unroll") for (int k = 0; k < 2; ++k) dst[m][k] = *(const LAS bf16x8*)(lds + PG8_SA(b, h) + aoff + m * 2048 + k * 1024); } while (0)
; #define PG8_LDB(dst, b, h) do { _Pragma("unroll") for (int n = 0; n < 2; ++n) _Pragma("unroll") for (int k = 0; k < 2; ++k) dst[n][k] = *(const LAS bf16x8*)(lds + PG8_SB(b, h) + boff + n * 2048 + k * 1024); } while (0)
; #define PG8_MMA(ai, bj, At, Bt) do { __builtin_amdgcn_s_setprio(1); _Pragma("unroll") for (int m = 0; m < 4; ++m) _Pragma("unroll") for (int n = 0; n < 2; ++n) _Pragma("unroll") for (int k = 0; k < 2; ++k) \
;         acc[ai][bj][m][n] = __builtin_amdgcn_mfma_f32_16x16x32_bf16(Bt[n][k], At[m][k], acc[ai][bj][m][n], 0, 0, 0); __builtin_amdgcn_s_setprio(0); } while (0)
; #define PG8_BAR __builtin_amdgcn_s_barrier()
; template <class Epi, bool MID = false>
; __device__ __forceinline__ void gemm_phase(LAS unsigned char* lds, const Gemm g, const StaticOrder& S, const Epi& E) {
;     ...
;         const bool has_next = S.next(ui + 1, nxt);
;         const char* nA = has_next ? (const char*)g.A + (size_t)nxt.pm * tstepA : cA; const char* nB = has_next ? (const char*)g.Bt + (size_t)nxt.pn * tstepB : cB;
; #pragma nounroll
;         for (int t = 0; t < nt; t += 2) {
;             const bool last = (t == nt - 2);
;             const char* a1 = cA + (size_t)(t + 1) * kstep;
;             const char* a2 = last ? nA : cA + (size_t)(t + 2) * kstep; const char* b2 = last ? nB : cB + (size_t)(t + 2) * kstep;
;             const char* a3 = a2 + kstep; const char* b3 = b2 + kstep;
;             PG8_LDB(B0, 0, 0); PG8_LDB(B1, 0, 1); PG8_SCHED; PG8_LDA(At, 0, 0); PG8_STAGE(PG8_SA(1, 1), a1 + hstepA, voffA);
;             PG8_WAIT_V(8); PG8_WAIT_L(0); PG8_BAR; PG8_MMA(0, 0, At, B0); PG8_MMA(0, 1, At, B1); PG8_BAR; PG8_SCHED;
;             PG8_LDA(At, 0, 1); PG8_STAGE(PG8_SB(0, 0), b2, voffB); PG8_STAGE(PG8_SB(0, 1), b2 + hstepB, voffB); PG8_STAGE(PG8_SA(0, 0), a2, voffA);
;             PG8_WAIT_V(8); PG8_WAIT_L(0); PG8_BAR; PG8_MMA(1, 0, At, B0); PG8_MMA(1, 1, At, B1); PG8_BAR; PG8_SCHED;
.LBB0_673:
	s_ashr_i32 s57, s56, 31
	s_lshl_b64 s[60:61], s[56:57], 17
	s_add_u32 s60, s78, s60
	s_addc_u32 s61, s79, s61
	s_andn2_b64 vcc, exec, s[50:51]
	s_cbranch_vccnz .LBB0_729
	s_and_b64 s[42:43], s[42:43], exec
	s_cselect_b32 s45, s61, s65
	s_cselect_b32 s48, s60, s64
	s_add_u32 s57, s64, 0x100
	s_addc_u32 s73, s65, 0
	s_mov_b32 s64, 0
	s_add_i32 s93, s64, 2
	s_add_u32 s42, s62, 0x100
	s_addc_u32 s43, s63, 0
	s_add_i32 s4, 0, 0x10000
	s_cmp_eq_u32 s89, s64
	s_cselect_b32 s67, s59, s43
	s_cselect_b32 s66, s58, s42
	v_add_u32_e32 v0, s4, v196
	s_cselect_b32 s65, s45, s73
	s_cselect_b32 s64, s48, s57
	s_add_i32 s5, 0, 0x14000
	ds_read_b128 v[130:133], v0
	ds_read_b128 v[134:137], v0 offset:1024
	ds_read_b128 v[138:141], v0 offset:2048
	ds_read_b128 v[142:145], v0 offset:3072
	v_add_u32_e32 v0, s5, v196
	ds_read_b128 v[146:149], v0
	ds_read_b128 v[150:153], v0 offset:1024
	ds_read_b128 v[176:179], v0 offset:2048
	ds_read_b128 v[180:183], v0 offset:3072
	v_lshl_add_u64 v[154:155], s[62:63], 0, v[172:173]
	s_add_i32 m0, s81, 0xc000
	ds_read_b128 v[184:187], v197
	ds_read_b128 v[188:191], v197 offset:1024
	ds_read_b128 v[192:195], v197 offset:2048
	ds_read_b128 v[198:201], v197 offset:3072
	ds_read_b128 v[202:205], v197 offset:4096
	ds_read_b128 v[206:209], v197 offset:5120
	ds_read_b128 v[210:213], v197 offset:6144
	ds_read_b128 v[214:217], v197 offset:7168
	global_load_lds_dwordx4 v[154:155], off
	v_lshl_add_u64 v[154:155], s[62:63], 0, v[174:175]
	s_add_i32 m0, s81, 0xe000
	s_nop 0
	global_load_lds_dwordx4 v[154:155], off
	s_waitcnt vmcnt(8)
	s_waitcnt lgkmcnt(0)
	s_barrier
	s_setprio 1
	s_waitcnt lgkmcnt(0)
	v_mfma_f32_16x16x32_bf16 v[126:129], v[130:133], v[184:187], 0
	v_mfma_f32_16x16x32_bf16 v[122:125], v[138:141], v[184:187], 0
	v_mfma_f32_16x16x32_bf16 v[110:113], v[130:133], v[192:195], 0
	v_mfma_f32_16x16x32_bf16 v[106:109], v[138:141], v[192:195], 0
	v_mfma_f32_16x16x32_bf16 v[94:97], v[130:133], v[202:205], 0
	v_mfma_f32_16x16x32_bf16 v[90:93], v[138:141], v[202:205], 0
	v_mfma_f32_16x16x32_bf16 v[78:81], v[130:133], v[210:213], 0
	v_mfma_f32_16x16x32_bf16 v[74:77], v[138:141], v[210:213], 0
	v_mfma_f32_16x16x32_bf16 v[126:129], v[134:137], v[188:191], v[126:129]
	v_mfma_f32_16x16x32_bf16 v[122:125], v[142:145], v[188:191], v[122:125]
	v_mfma_f32_16x16x32_bf16 v[110:113], v[134:137], v[198:201], v[110:113]
	v_mfma_f32_16x16x32_bf16 v[106:109], v[142:145], v[198:201], v[106:109]
	v_mfma_f32_16x16x32_bf16 v[94:97], v[134:137], v[206:209], v[94:97]
	v_mfma_f32_16x16x32_bf16 v[90:93], v[142:145], v[206:209], v[90:93]
	v_mfma_f32_16x16x32_bf16 v[78:81], v[134:137], v[214:217], v[78:81]
	v_mfma_f32_16x16x32_bf16 v[74:77], v[142:145], v[214:217], v[74:77]
	s_setprio 0
	s_setprio 1
	v_mfma_f32_16x16x32_bf16 v[118:121], v[146:149], v[184:187], 0
	v_mfma_f32_16x16x32_bf16 v[114:117], v[176:179], v[184:187], 0
	v_mfma_f32_16x16x32_bf16 v[102:105], v[146:149], v[192:195], 0
	v_mfma_f32_16x16x32_bf16 v[98:101], v[176:179], v[192:195], 0
	v_mfma_f32_16x16x32_bf16 v[86:89], v[146:149], v[202:205], 0
	v_mfma_f32_16x16x32_bf16 v[82:85], v[176:179], v[202:205], 0
	v_mfma_f32_16x16x32_bf16 v[70:73], v[146:149], v[210:213], 0
	v_mfma_f32_16x16x32_bf16 v[66:69], v[176:179], v[210:213], 0
	v_mfma_f32_16x16x32_bf16 v[118:121], v[150:153], v[188:191], v[118:121]
	v_mfma_f32_16x16x32_bf16 v[114:117], v[180:183], v[188:191], v[114:117]
	v_mfma_f32_16x16x32_bf16 v[102:105], v[150:153], v[198:201], v[102:105]
	v_mfma_f32_16x16x32_bf16 v[98:101], v[180:183], v[198:201], v[98:101]
	v_mfma_f32_16x16x32_bf16 v[86:89], v[150:153], v[206:209], v[86:89]
	v_mfma_f32_16x16x32_bf16 v[82:85], v[180:183], v[206:209], v[82:85]
	v_mfma_f32_16x16x32_bf16 v[70:73], v[150:153], v[214:217], v[70:73]
	v_mfma_f32_16x16x32_bf16 v[66:69], v[180:183], v[214:217], v[66:69]
	s_setprio 0
	s_barrier
	s_add_i32 s4, s4, s80
	v_lshl_add_u64 v[154:155], s[64:65], 0, v[158:159]
	s_mov_b32 m0, s4
	ds_read_b128 v[184:187], v197 offset:16384
	ds_read_b128 v[188:191], v197 offset:17408
	ds_read_b128 v[192:195], v197 offset:18432
	ds_read_b128 v[198:201], v197 offset:19456
	ds_read_b128 v[202:205], v197 offset:20480
	ds_read_b128 v[206:209], v197 offset:21504
	ds_read_b128 v[210:213], v197 offset:22528
	ds_read_b128 v[214:217], v197 offset:23552
	global_load_lds_dwordx4 v[154:155], off
	s_add_i32 m0, s4, 0x2000
	s_add_u32 s62, s64, 0x10000
	v_lshl_add_u64 v[230:231], s[64:65], 0, v[164:165]
	s_addc_u32 s63, s65, 0
	s_add_i32 s4, s5, s80
	global_load_lds_dwordx4 v[230:231], off
	v_lshl_add_u64 v[232:233], s[62:63], 0, v[158:159]
	s_mov_b32 m0, s4
	v_lshl_add_u64 v[234:235], s[66:67], 0, v[160:161]
	global_load_lds_dwordx4 v[232:233], off
	v_lshl_add_u64 v[232:233], s[62:63], 0, v[164:165]
	s_add_i32 m0, s4, 0x2000
	s_nop 0
	global_load_lds_dwordx4 v[232:233], off
	v_lshl_add_u64 v[232:233], s[66:67], 0, v[156:157]
	s_mov_b32 m0, s81
	s_nop 0
	global_load_lds_dwordx4 v[232:233], off
	s_mov_b32 m0, s82
	s_nop 0
	global_load_lds_dwordx4 v[234:235], off
	s_waitcnt vmcnt(8)
	s_waitcnt lgkmcnt(0)
	s_barrier
; #define PG8_STAGE(bufoff, gbase, voff) do { _Pragma("unroll") for (int _i = 0; _i < 2; ++_i) \
;         __builtin_amdgcn_global_load_lds((const unsigned*)((const char*)(gbase) + (voff)[_i]), (LAS unsigned*)(lds + (bufoff) + ldsw + _i * 8192), 16, 0, 0); } while (0)
; #define PG8_LDA(dst, b, h) do { _Pragma("unroll") for (int m = 0; m < 4; ++m) _Pragma("unroll") for (int k = 0; k < 2; ++k) dst[m][k] = *(const LAS bf16x8*)(lds + PG8_SA(b, h) + aoff + m * 2048 + k * 1024); } while (0)
; #define PG8_LDB(dst, b, h) do { _Pragma("unroll") for (int n = 0; n < 2; ++n) _Pragma("unroll") for (int k = 0; k < 2; ++k) dst[n][k] = *(const LAS bf16x8*)(lds + PG8_SB(b, h) + boff + n * 2048 + k * 1024); } while (0)
; #define PG8_MMA(ai, bj, At, Bt) do { __builtin_amdgcn_s_setprio(1); _Pragma("unroll") for (int m = 0; m < 4; ++m) _Pragma("unroll") for (int n = 0; n < 2; ++n) _Pragma("unroll") for (int k = 0; k < 2; ++k) \
;         acc[ai][bj][m][n] = __builtin_amdgcn_mfma_f32_16x16x32_bf16(Bt[n][k], At[m][k], acc[ai][bj][m][n], 0, 0, 0); __builtin_amdgcn_s_setprio(0); } while (0)
; #define PG8_WAIT_V(n) asm volatile("s_waitcnt vmcnt(" #n ")" ::: "memory")
; #define PG8_WAIT_L(n) asm volatile("s_waitcnt lgkmcnt(" #n ")" ::: "memory")
; #define PG8_BAR __builtin_amdgcn_s_barrier()
; #define PG8_SCHED __builtin_amdgcn_sched_barrier(0)
; template <class Epi, bool MID = false>
; __device__ __forceinline__ void gemm_phase(LAS unsigned char* lds, const Gemm g, const StaticOrder& S, const Epi& E) {
;     ...
;             PG8_WAIT_V(8); PG8_WAIT_L(0); PG8_BAR; PG8_MMA(1, 0, At, B0); PG8_MMA(1, 1, At, B1); PG8_BAR; PG8_SCHED;
;             PG8_LDB(B0, 1, 0); PG8_LDB(B1, 1, 1); PG8_SCHED; PG8_LDA(At, 1, 0); PG8_STAGE(PG8_SA(0, 1), a2 + hstepA, voffA);
;             PG8_WAIT_V(8); PG8_WAIT_L(0); PG8_BAR; PG8_MMA(0, 0, At, B0); PG8_MMA(0, 1, At, B1); PG8_BAR; PG8_SCHED;
	s_setprio 1
	s_waitcnt lgkmcnt(0)
	v_mfma_f32_16x16x32_bf16 v[62:65], v[130:133], v[184:187], 0
	v_mfma_f32_16x16x32_bf16 v[58:61], v[138:141], v[184:187], 0
	v_mfma_f32_16x16x32_bf16 v[46:49], v[130:133], v[192:195], 0
	v_mfma_f32_16x16x32_bf16 v[42:45], v[138:141], v[192:195], 0
	v_mfma_f32_16x16x32_bf16 v[30:33], v[130:133], v[202:205], 0
	v_mfma_f32_16x16x32_bf16 v[26:29], v[138:141], v[202:205], 0
	v_mfma_f32_16x16x32_bf16 v[14:17], v[130:133], v[210:213], 0
	v_mfma_f32_16x16x32_bf16 v[10:13], v[138:141], v[210:213], 0
	v_mfma_f32_16x16x32_bf16 v[62:65], v[134:137], v[188:191], v[62:65]
	v_mfma_f32_16x16x32_bf16 v[58:61], v[142:145], v[188:191], v[58:61]
	v_mfma_f32_16x16x32_bf16 v[46:49], v[134:137], v[198:201], v[46:49]
	v_mfma_f32_16x16x32_bf16 v[42:45], v[142:145], v[198:201], v[42:45]
	v_mfma_f32_16x16x32_bf16 v[30:33], v[134:137], v[206:209], v[30:33]
	v_mfma_f32_16x16x32_bf16 v[26:29], v[142:145], v[206:209], v[26:29]
	v_mfma_f32_16x16x32_bf16 v[14:17], v[134:137], v[214:217], v[14:17]
	v_mfma_f32_16x16x32_bf16 v[10:13], v[142:145], v[214:217], v[10:13]
	s_setprio 0
	s_setprio 1
	v_mfma_f32_16x16x32_bf16 v[54:57], v[146:149], v[184:187], 0
	v_mfma_f32_16x16x32_bf16 v[50:53], v[176:179], v[184:187], 0
	v_mfma_f32_16x16x32_bf16 v[38:41], v[146:149], v[192:195], 0
	v_mfma_f32_16x16x32_bf16 v[34:37], v[176:179], v[192:195], 0
	v_mfma_f32_16x16x32_bf16 v[22:25], v[146:149], v[202:205], 0
	v_mfma_f32_16x16x32_bf16 v[18:21], v[176:179], v[202:205], 0
	v_mfma_f32_16x16x32_bf16 v[6:9], v[146:149], v[210:213], 0
	v_mfma_f32_16x16x32_bf16 v[2:5], v[176:179], v[210:213], 0
	v_mfma_f32_16x16x32_bf16 v[54:57], v[150:153], v[188:191], v[54:57]
	v_mfma_f32_16x16x32_bf16 v[50:53], v[180:183], v[188:191], v[50:53]
	v_mfma_f32_16x16x32_bf16 v[38:41], v[150:153], v[198:201], v[38:41]
	v_mfma_f32_16x16x32_bf16 v[34:37], v[180:183], v[198:201], v[34:37]
	v_mfma_f32_16x16x32_bf16 v[22:25], v[150:153], v[206:209], v[22:25]
	v_mfma_f32_16x16x32_bf16 v[18:21], v[180:183], v[206:209], v[18:21]
	v_mfma_f32_16x16x32_bf16 v[6:9], v[150:153], v[214:217], v[6:9]
	v_mfma_f32_16x16x32_bf16 v[2:5], v[180:183], v[214:217], v[2:5]
	s_setprio 0
	s_barrier
	s_add_i32 s4, 0, 0x18000
	v_add_u32_e32 v0, s4, v196
	s_add_i32 s5, 0, 0x1c000
	ds_read_b128 v[130:133], v0
	ds_read_b128 v[134:137], v0 offset:1024
	ds_read_b128 v[138:141], v0 offset:2048
	ds_read_b128 v[142:145], v0 offset:3072
	v_add_u32_e32 v0, s5, v196
	ds_read_b128 v[146:149], v0
	ds_read_b128 v[150:153], v0 offset:1024
	ds_read_b128 v[176:179], v0 offset:2048
	ds_read_b128 v[180:183], v0 offset:3072
	s_add_u32 s62, s66, 0x90000
	s_addc_u32 s63, s67, 0
	s_mov_b32 m0, s83
	v_lshl_add_u64 v[236:237], s[62:63], 0, v[156:157]
	ds_read_b128 v[184:187], v197 offset:32768
	ds_read_b128 v[188:191], v197 offset:33792
	ds_read_b128 v[192:195], v197 offset:34816
	ds_read_b128 v[198:201], v197 offset:35840
	ds_read_b128 v[202:205], v197 offset:36864
	ds_read_b128 v[206:209], v197 offset:37888
	ds_read_b128 v[210:213], v197 offset:38912
	ds_read_b128 v[214:217], v197 offset:39936
	global_load_lds_dwordx4 v[236:237], off
	v_lshl_add_u64 v[236:237], s[62:63], 0, v[160:161]
	s_mov_b32 m0, s84
	s_nop 0
	global_load_lds_dwordx4 v[236:237], off
	s_waitcnt vmcnt(8)
	s_waitcnt lgkmcnt(0)
	s_barrier
	s_setprio 1
	s_waitcnt lgkmcnt(0)
	v_mfma_f32_16x16x32_bf16 v[126:129], v[130:133], v[184:187], v[126:129]
	v_mfma_f32_16x16x32_bf16 v[122:125], v[138:141], v[184:187], v[122:125]
	v_mfma_f32_16x16x32_bf16 v[110:113], v[130:133], v[192:195], v[110:113]
	v_mfma_f32_16x16x32_bf16 v[106:109], v[138:141], v[192:195], v[106:109]
	v_mfma_f32_16x16x32_bf16 v[94:97], v[130:133], v[202:205], v[94:97]
	v_mfma_f32_16x16x32_bf16 v[90:93], v[138:141], v[202:205], v[90:93]
	v_mfma_f32_16x16x32_bf16 v[78:81], v[130:133], v[210:213], v[78:81]
	v_mfma_f32_16x16x32_bf16 v[74:77], v[138:141], v[210:213], v[74:77]
	v_mfma_f32_16x16x32_bf16 v[126:129], v[134:137], v[188:191], v[126:129]
	v_mfma_f32_16x16x32_bf16 v[122:125], v[142:145], v[188:191], v[122:125]
	v_mfma_f32_16x16x32_bf16 v[110:113], v[134:137], v[198:201], v[110:113]
	v_mfma_f32_16x16x32_bf16 v[106:109], v[142:145], v[198:201], v[106:109]
	v_mfma_f32_16x16x32_bf16 v[94:97], v[134:137], v[206:209], v[94:97]
	v_mfma_f32_16x16x32_bf16 v[90:93], v[142:145], v[206:209], v[90:93]
	v_mfma_f32_16x16x32_bf16 v[78:81], v[134:137], v[214:217], v[78:81]
	v_mfma_f32_16x16x32_bf16 v[74:77], v[142:145], v[214:217], v[74:77]
	s_setprio 0
	s_setprio 1
	v_mfma_f32_16x16x32_bf16 v[118:121], v[146:149], v[184:187], v[118:121]
	v_mfma_f32_16x16x32_bf16 v[114:117], v[176:179], v[184:187], v[114:117]
	v_mfma_f32_16x16x32_bf16 v[102:105], v[146:149], v[192:195], v[102:105]
	v_mfma_f32_16x16x32_bf16 v[98:101], v[176:179], v[192:195], v[98:101]
	v_mfma_f32_16x16x32_bf16 v[86:89], v[146:149], v[202:205], v[86:89]
	v_mfma_f32_16x16x32_bf16 v[82:85], v[176:179], v[202:205], v[82:85]
	v_mfma_f32_16x16x32_bf16 v[70:73], v[146:149], v[210:213], v[70:73]
	v_mfma_f32_16x16x32_bf16 v[66:69], v[176:179], v[210:213], v[66:69]
	v_mfma_f32_16x16x32_bf16 v[118:121], v[150:153], v[188:191], v[118:121]
	v_mfma_f32_16x16x32_bf16 v[114:117], v[180:183], v[188:191], v[114:117]
	v_mfma_f32_16x16x32_bf16 v[102:105], v[150:153], v[198:201], v[102:105]
	v_mfma_f32_16x16x32_bf16 v[98:101], v[180:183], v[198:201], v[98:101]
	v_mfma_f32_16x16x32_bf16 v[86:89], v[150:153], v[206:209], v[86:89]
	v_mfma_f32_16x16x32_bf16 v[82:85], v[180:183], v[206:209], v[82:85]
	v_mfma_f32_16x16x32_bf16 v[70:73], v[150:153], v[214:217], v[70:73]
	v_mfma_f32_16x16x32_bf16 v[66:69], v[180:183], v[214:217], v[66:69]
	s_setprio 0
	s_barrier
; #define PG8_STAGE(bufoff, gbase, voff) do { _Pragma("unroll") for (int _i = 0; _i < 2; ++_i) \
;         __builtin_amdgcn_global_load_lds((const unsigned*)((const char*)(gbase) + (voff)[_i]), (LAS unsigned*)(lds + (bufoff) + ldsw + _i * 8192), 16, 0, 0); } while (0)
; #define PG8_LDA(dst, b, h) do { _Pragma("unroll") for (int m = 0; m < 4; ++m) _Pragma("unroll") for (int k = 0; k < 2; ++k) dst[m][k] = *(const LAS bf16x8*)(lds + PG8_SA(b, h) + aoff + m * 2048 + k * 1024); } while (0)
; #define PG8_LDB(dst, b, h) do { _Pragma("unroll") for (int n = 0; n < 2; ++n) _Pragma("unroll") for (int k = 0; k < 2; ++k) dst[n][k] = *(const LAS bf16x8*)(lds + PG8_SB(b, h) + boff + n * 2048 + k * 1024); } while (0)
; #define PG8_MMA(ai, bj, At, Bt) do { __builtin_amdgcn_s_setprio(1); _Pragma("unroll") for (int m = 0; m < 4; ++m) _Pragma("unroll") for (int n = 0; n < 2; ++n) _Pragma("unroll") for (int k = 0; k < 2; ++k) \
;         acc[ai][bj][m][n] = __builtin_amdgcn_mfma_f32_16x16x32_bf16(Bt[n][k], At[m][k], acc[ai][bj][m][n], 0, 0, 0); __builtin_amdgcn_s_setprio(0); } while (0)
; #define PG8_WAIT_V(n) asm volatile("s_waitcnt vmcnt(" #n ")" ::: "memory")
; #define PG8_BAR __builtin_amdgcn_s_barrier()
; template <class Epi, bool MID = false>
; __device__ __forceinline__ void gemm_phase(LAS unsigned char* lds, const Gemm g, const StaticOrder& S, const Epi& E) {
;     ...
;         for (int t = 0; t < nt; t += 2) {
;             const bool last = (t == nt - 2);
;             const char* a1 = cA + (size_t)(t + 1) * kstep;
;             const char* a2 = last ? nA : cA + (size_t)(t + 2) * kstep; const char* b2 = last ? nB : cB + (size_t)(t + 2) * kstep;
;             const char* a3 = a2 + kstep; const char* b3 = b2 + kstep;
;             PG8_LDB(B0, 0, 0); PG8_LDB(B1, 0, 1); PG8_SCHED; PG8_LDA(At, 0, 0); PG8_STAGE(PG8_SA(1, 1), a1 + hstepA, voffA);
;             PG8_WAIT_V(8); PG8_WAIT_L(0); PG8_BAR; PG8_MMA(0, 0, At, B0); PG8_MMA(0, 1, At, B1); PG8_BAR; PG8_SCHED;
;             PG8_LDA(At, 0, 1); PG8_STAGE(PG8_SB(0, 0), b2, voffB); PG8_STAGE(PG8_SB(0, 1), b2 + hstepB, voffB); PG8_STAGE(PG8_SA(0, 0), a2, voffA);
;     ...
;             PG8_LDA(At, 1, 1); PG8_STAGE(PG8_SB(1, 0), b3, voffB); PG8_STAGE(PG8_SB(1, 1), b3 + hstepB, voffB); PG8_STAGE(PG8_SA(1, 0), a3, voffA);
;             PG8_WAIT_V(8); PG8_WAIT_L(0); PG8_BAR; PG8_MMA(1, 0, At, B0); PG8_MMA(1, 1, At, B1); PG8_BAR; PG8_SCHED;
	s_add_i32 s4, s4, s80
	v_lshl_add_u64 v[154:155], v[154:155], 0, s[24:25]
	s_mov_b32 m0, s4
	ds_read_b128 v[184:187], v197 offset:49152
	ds_read_b128 v[188:191], v197 offset:50176
	ds_read_b128 v[192:195], v197 offset:51200
	ds_read_b128 v[198:201], v197 offset:52224
	ds_read_b128 v[202:205], v197 offset:53248
	ds_read_b128 v[206:209], v197 offset:54272
	ds_read_b128 v[210:213], v197 offset:55296
	ds_read_b128 v[214:217], v197 offset:56320
	global_load_lds_dwordx4 v[154:155], off
	s_add_i32 m0, s4, 0x2000
	s_add_u32 s62, s64, 0x10080
	v_lshl_add_u64 v[154:155], v[230:231], 0, s[24:25]
	s_addc_u32 s63, s65, 0
	s_add_i32 s4, s5, s80
	global_load_lds_dwordx4 v[154:155], off
	v_lshl_add_u64 v[154:155], s[62:63], 0, v[158:159]
	s_mov_b32 m0, s4
	s_nop 0
	global_load_lds_dwordx4 v[154:155], off
	v_lshl_add_u64 v[154:155], s[62:63], 0, v[164:165]
	s_add_i32 m0, s4, 0x2000
	s_nop 0
	global_load_lds_dwordx4 v[154:155], off
	v_lshl_add_u64 v[154:155], v[232:233], 0, s[24:25]
	s_mov_b32 m0, s86
	s_nop 0
	global_load_lds_dwordx4 v[154:155], off
	v_lshl_add_u64 v[154:155], v[234:235], 0, s[24:25]
	s_mov_b32 m0, s87
	s_nop 0
	global_load_lds_dwordx4 v[154:155], off
	s_waitcnt vmcnt(8)
	s_waitcnt lgkmcnt(0)
	s_barrier
	s_setprio 1
	s_waitcnt lgkmcnt(0)
	v_mfma_f32_16x16x32_bf16 v[62:65], v[130:133], v[184:187], v[62:65]
	v_mfma_f32_16x16x32_bf16 v[58:61], v[138:141], v[184:187], v[58:61]
	v_mfma_f32_16x16x32_bf16 v[46:49], v[130:133], v[192:195], v[46:49]
	v_mfma_f32_16x16x32_bf16 v[42:45], v[138:141], v[192:195], v[42:45]
	v_mfma_f32_16x16x32_bf16 v[30:33], v[130:133], v[202:205], v[30:33]
	v_mfma_f32_16x16x32_bf16 v[26:29], v[138:141], v[202:205], v[26:29]
	v_mfma_f32_16x16x32_bf16 v[14:17], v[130:133], v[210:213], v[14:17]
	v_mfma_f32_16x16x32_bf16 v[10:13], v[138:141], v[210:213], v[10:13]
	v_mfma_f32_16x16x32_bf16 v[62:65], v[134:137], v[188:191], v[62:65]
	v_mfma_f32_16x16x32_bf16 v[58:61], v[142:145], v[188:191], v[58:61]
	v_mfma_f32_16x16x32_bf16 v[46:49], v[134:137], v[198:201], v[46:49]
	v_mfma_f32_16x16x32_bf16 v[42:45], v[142:145], v[198:201], v[42:45]
	v_mfma_f32_16x16x32_bf16 v[30:33], v[134:137], v[206:209], v[30:33]
	v_mfma_f32_16x16x32_bf16 v[26:29], v[142:145], v[206:209], v[26:29]
	v_mfma_f32_16x16x32_bf16 v[14:17], v[134:137], v[214:217], v[14:17]
	v_mfma_f32_16x16x32_bf16 v[10:13], v[142:145], v[214:217], v[10:13]
	s_setprio 0
	s_setprio 1
	v_mfma_f32_16x16x32_bf16 v[54:57], v[146:149], v[184:187], v[54:57]
	v_mfma_f32_16x16x32_bf16 v[50:53], v[176:179], v[184:187], v[50:53]
	v_mfma_f32_16x16x32_bf16 v[38:41], v[146:149], v[192:195], v[38:41]
	v_mfma_f32_16x16x32_bf16 v[34:37], v[176:179], v[192:195], v[34:37]
	v_mfma_f32_16x16x32_bf16 v[22:25], v[146:149], v[202:205], v[22:25]
	v_mfma_f32_16x16x32_bf16 v[18:21], v[176:179], v[202:205], v[18:21]
	v_mfma_f32_16x16x32_bf16 v[6:9], v[146:149], v[210:213], v[6:9]
	v_mfma_f32_16x16x32_bf16 v[2:5], v[176:179], v[210:213], v[2:5]
	v_mfma_f32_16x16x32_bf16 v[54:57], v[150:153], v[188:191], v[54:57]
	v_mfma_f32_16x16x32_bf16 v[50:53], v[180:183], v[188:191], v[50:53]
	v_mfma_f32_16x16x32_bf16 v[38:41], v[150:153], v[198:201], v[38:41]
	v_mfma_f32_16x16x32_bf16 v[34:37], v[180:183], v[198:201], v[34:37]
	v_mfma_f32_16x16x32_bf16 v[22:25], v[150:153], v[206:209], v[22:25]
	v_mfma_f32_16x16x32_bf16 v[18:21], v[180:183], v[206:209], v[18:21]
	v_mfma_f32_16x16x32_bf16 v[6:9], v[150:153], v[214:217], v[6:9]
	v_mfma_f32_16x16x32_bf16 v[2:5], v[180:183], v[214:217], v[2:5]
	s_setprio 0
	s_barrier
	s_add_u32 s57, s57, 0x100
	s_addc_u32 s73, s73, 0
	s_cmp_ge_i32 s93, s70
	s_mov_b64 s[62:63], s[42:43]
	s_mov_b32 s64, s93
	s_cbranch_scc0 .LBB0_675
	s_branch .Lpk_675_exit
.LBB0_675:
	s_add_i32 s93, s64, 2
	s_add_u32 s42, s62, 0x100
	s_addc_u32 s43, s63, 0
	s_add_i32 s4, 0, 0x10000
	s_cmp_eq_u32 s89, s64
	s_cselect_b32 s67, s59, s43
	s_cselect_b32 s66, s58, s42
	v_add_u32_e32 v0, s4, v196
	s_cselect_b32 s65, s45, s73
	s_cselect_b32 s64, s48, s57
	s_add_i32 s5, 0, 0x14000
	ds_read_b128 v[130:133], v0
	ds_read_b128 v[134:137], v0 offset:1024
	ds_read_b128 v[138:141], v0 offset:2048
	ds_read_b128 v[142:145], v0 offset:3072
	v_add_u32_e32 v0, s5, v196
	ds_read_b128 v[146:149], v0
	ds_read_b128 v[150:153], v0 offset:1024
	ds_read_b128 v[176:179], v0 offset:2048
	ds_read_b128 v[180:183], v0 offset:3072
	v_lshl_add_u64 v[154:155], s[62:63], 0, v[172:173]
	s_add_i32 m0, s81, 0xc000
	ds_read_b128 v[184:187], v197
	ds_read_b128 v[188:191], v197 offset:1024
	ds_read_b128 v[192:195], v197 offset:2048
	ds_read_b128 v[198:201], v197 offset:3072
	ds_read_b128 v[202:205], v197 offset:4096
	ds_read_b128 v[206:209], v197 offset:5120
	ds_read_b128 v[210:213], v197 offset:6144
	ds_read_b128 v[214:217], v197 offset:7168
	global_load_lds_dwordx4 v[154:155], off
	v_lshl_add_u64 v[154:155], s[62:63], 0, v[174:175]
	s_add_i32 m0, s81, 0xe000
	s_nop 0
	global_load_lds_dwordx4 v[154:155], off
	s_waitcnt vmcnt(8)
	s_waitcnt lgkmcnt(0)
	s_barrier
; #define PG8_STAGE(bufoff, gbase, voff) do { _Pragma("unroll") for (int _i = 0; _i < 2; ++_i) \
;         __builtin_amdgcn_global_load_lds((const unsigned*)((const char*)(gbase) + (voff)[_i]), (LAS unsigned*)(lds + (bufoff) + ldsw + _i * 8192), 16, 0, 0); } while (0)
; #define PG8_LDA(dst, b, h) do { _Pragma("unroll") for (int m = 0; m < 4; ++m) _Pragma("unroll") for (int k = 0; k < 2; ++k) dst[m][k] = *(const LAS bf16x8*)(lds + PG8_SA(b, h) + aoff + m * 2048 + k * 1024); } while (0)
; #define PG8_LDB(dst, b, h) do { _Pragma("unroll") for (int n = 0; n < 2; ++n) _Pragma("unroll") for (int k = 0; k < 2; ++k) dst[n][k] = *(const LAS bf16x8*)(lds + PG8_SB(b, h) + boff + n * 2048 + k * 1024); } while (0)
; #define PG8_MMA(ai, bj, At, Bt) do { __builtin_amdgcn_s_setprio(1); _Pragma("unroll") for (int m = 0; m < 4; ++m) _Pragma("unroll") for (int n = 0; n < 2; ++n) _Pragma("unroll") for (int k = 0; k < 2; ++k) \
;         acc[ai][bj][m][n] = __builtin_amdgcn_mfma_f32_16x16x32_bf16(Bt[n][k], At[m][k], acc[ai][bj][m][n], 0, 0, 0); __builtin_amdgcn_s_setprio(0); } while (0)
; #define PG8_WAIT_V(n) asm volatile("s_waitcnt vmcnt(" #n ")" ::: "memory")
; #define PG8_WAIT_L(n) asm volatile("s_waitcnt lgkmcnt(" #n ")" ::: "memory")
; #define PG8_BAR __builtin_amdgcn_s_barrier()
; #define PG8_SCHED __builtin_amdgcn_sched_barrier(0)
; template <class Epi, bool MID = false>
; __device__ __forceinline__ void gemm_phase(LAS unsigned char* lds, const Gemm g, const StaticOrder& S, const Epi& E) {
;     ...
;             PG8_LDB(B0, 0, 0); PG8_LDB(B1, 0, 1); PG8_SCHED; PG8_LDA(At, 0, 0); PG8_STAGE(PG8_SA(1, 1), a1 + hstepA, voffA);
;             PG8_WAIT_V(8); PG8_WAIT_L(0); PG8_BAR; PG8_MMA(0, 0, At, B0); PG8_MMA(0, 1, At, B1); PG8_BAR; PG8_SCHED;
;             PG8_LDA(At, 0, 1); PG8_STAGE(PG8_SB(0, 0), b2, voffB); PG8_STAGE(PG8_SB(0, 1), b2 + hstepB, voffB); PG8_STAGE(PG8_SA(0, 0), a2, voffA);
;             PG8_WAIT_V(8); PG8_WAIT_L(0); PG8_BAR; PG8_MMA(1, 0, At, B0); PG8_MMA(1, 1, At, B1); PG8_BAR; PG8_SCHED;
	s_setprio 1
	s_waitcnt lgkmcnt(0)
	v_mfma_f32_16x16x32_bf16 v[126:129], v[130:133], v[184:187], v[126:129]
	v_mfma_f32_16x16x32_bf16 v[122:125], v[138:141], v[184:187], v[122:125]
	v_mfma_f32_16x16x32_bf16 v[110:113], v[130:133], v[192:195], v[110:113]
	v_mfma_f32_16x16x32_bf16 v[106:109], v[138:141], v[192:195], v[106:109]
	v_mfma_f32_16x16x32_bf16 v[94:97], v[130:133], v[202:205], v[94:97]
	v_mfma_f32_16x16x32_bf16 v[90:93], v[138:141], v[202:205], v[90:93]
	v_mfma_f32_16x16x32_bf16 v[78:81], v[130:133], v[210:213], v[78:81]
	v_mfma_f32_16x16x32_bf16 v[74:77], v[138:141], v[210:213], v[74:77]
	v_mfma_f32_16x16x32_bf16 v[126:129], v[134:137], v[188:191], v[126:129]
	v_mfma_f32_16x16x32_bf16 v[122:125], v[142:145], v[188:191], v[122:125]
	v_mfma_f32_16x16x32_bf16 v[110:113], v[134:137], v[198:201], v[110:113]
	v_mfma_f32_16x16x32_bf16 v[106:109], v[142:145], v[198:201], v[106:109]
	v_mfma_f32_16x16x32_bf16 v[94:97], v[134:137], v[206:209], v[94:97]
	v_mfma_f32_16x16x32_bf16 v[90:93], v[142:145], v[206:209], v[90:93]
	v_mfma_f32_16x16x32_bf16 v[78:81], v[134:137], v[214:217], v[78:81]
	v_mfma_f32_16x16x32_bf16 v[74:77], v[142:145], v[214:217], v[74:77]
	s_setprio 0
	s_setprio 1
	v_mfma_f32_16x16x32_bf16 v[118:121], v[146:149], v[184:187], v[118:121]
	v_mfma_f32_16x16x32_bf16 v[114:117], v[176:179], v[184:187], v[114:117]
	v_mfma_f32_16x16x32_bf16 v[102:105], v[146:149], v[192:195], v[102:105]
	v_mfma_f32_16x16x32_bf16 v[98:101], v[176:179], v[192:195], v[98:101]
	v_mfma_f32_16x16x32_bf16 v[86:89], v[146:149], v[202:205], v[86:89]
	v_mfma_f32_16x16x32_bf16 v[82:85], v[176:179], v[202:205], v[82:85]
	v_mfma_f32_16x16x32_bf16 v[70:73], v[146:149], v[210:213], v[70:73]
	v_mfma_f32_16x16x32_bf16 v[66:69], v[176:179], v[210:213], v[66:69]
	v_mfma_f32_16x16x32_bf16 v[118:121], v[150:153], v[188:191], v[118:121]
	v_mfma_f32_16x16x32_bf16 v[114:117], v[180:183], v[188:191], v[114:117]
	v_mfma_f32_16x16x32_bf16 v[102:105], v[150:153], v[198:201], v[102:105]
	v_mfma_f32_16x16x32_bf16 v[98:101], v[180:183], v[198:201], v[98:101]
	v_mfma_f32_16x16x32_bf16 v[86:89], v[150:153], v[206:209], v[86:89]
	v_mfma_f32_16x16x32_bf16 v[82:85], v[180:183], v[206:209], v[82:85]
	v_mfma_f32_16x16x32_bf16 v[70:73], v[150:153], v[214:217], v[70:73]
	v_mfma_f32_16x16x32_bf16 v[66:69], v[180:183], v[214:217], v[66:69]
	s_setprio 0
	s_barrier
	s_add_i32 s4, s4, s80
	v_lshl_add_u64 v[154:155], s[64:65], 0, v[158:159]
	s_mov_b32 m0, s4
	ds_read_b128 v[184:187], v197 offset:16384
	ds_read_b128 v[188:191], v197 offset:17408
	ds_read_b128 v[192:195], v197 offset:18432
	ds_read_b128 v[198:201], v197 offset:19456
	ds_read_b128 v[202:205], v197 offset:20480
	ds_read_b128 v[206:209], v197 offset:21504
	ds_read_b128 v[210:213], v197 offset:22528
	ds_read_b128 v[214:217], v197 offset:23552
	global_load_lds_dwordx4 v[154:155], off
	s_add_i32 m0, s4, 0x2000
	s_add_u32 s62, s64, 0x10000
	v_lshl_add_u64 v[230:231], s[64:65], 0, v[164:165]
	s_addc_u32 s63, s65, 0
	s_add_i32 s4, s5, s80
	global_load_lds_dwordx4 v[230:231], off
	v_lshl_add_u64 v[232:233], s[62:63], 0, v[158:159]
	s_mov_b32 m0, s4
	v_lshl_add_u64 v[234:235], s[66:67], 0, v[160:161]
	global_load_lds_dwordx4 v[232:233], off
	v_lshl_add_u64 v[232:233], s[62:63], 0, v[164:165]
	s_add_i32 m0, s4, 0x2000
	s_nop 0
	global_load_lds_dwordx4 v[232:233], off
	v_lshl_add_u64 v[232:233], s[66:67], 0, v[156:157]
	s_mov_b32 m0, s81
	s_nop 0
	global_load_lds_dwordx4 v[232:233], off
	s_mov_b32 m0, s82
	s_nop 0
	global_load_lds_dwordx4 v[234:235], off
	s_waitcnt vmcnt(8)
	s_waitcnt lgkmcnt(0)
	s_barrier
	s_setprio 1
	s_waitcnt lgkmcnt(0)
	v_mfma_f32_16x16x32_bf16 v[62:65], v[130:133], v[184:187], v[62:65]
	v_mfma_f32_16x16x32_bf16 v[58:61], v[138:141], v[184:187], v[58:61]
	v_mfma_f32_16x16x32_bf16 v[46:49], v[130:133], v[192:195], v[46:49]
	v_mfma_f32_16x16x32_bf16 v[42:45], v[138:141], v[192:195], v[42:45]
	v_mfma_f32_16x16x32_bf16 v[30:33], v[130:133], v[202:205], v[30:33]
	v_mfma_f32_16x16x32_bf16 v[26:29], v[138:141], v[202:205], v[26:29]
	v_mfma_f32_16x16x32_bf16 v[14:17], v[130:133], v[210:213], v[14:17]
	v_mfma_f32_16x16x32_bf16 v[10:13], v[138:141], v[210:213], v[10:13]
	v_mfma_f32_16x16x32_bf16 v[62:65], v[134:137], v[188:191], v[62:65]
	v_mfma_f32_16x16x32_bf16 v[58:61], v[142:145], v[188:191], v[58:61]
	v_mfma_f32_16x16x32_bf16 v[46:49], v[134:137], v[198:201], v[46:49]
	v_mfma_f32_16x16x32_bf16 v[42:45], v[142:145], v[198:201], v[42:45]
	v_mfma_f32_16x16x32_bf16 v[30:33], v[134:137], v[206:209], v[30:33]
	v_mfma_f32_16x16x32_bf16 v[26:29], v[142:145], v[206:209], v[26:29]
	v_mfma_f32_16x16x32_bf16 v[14:17], v[134:137], v[214:217], v[14:17]
	v_mfma_f32_16x16x32_bf16 v[10:13], v[142:145], v[214:217], v[10:13]
	s_setprio 0
	s_setprio 1
	v_mfma_f32_16x16x32_bf16 v[54:57], v[146:149], v[184:187], v[54:57]
	v_mfma_f32_16x16x32_bf16 v[50:53], v[176:179], v[184:187], v[50:53]
	v_mfma_f32_16x16x32_bf16 v[38:41], v[146:149], v[192:195], v[38:41]
	v_mfma_f32_16x16x32_bf16 v[34:37], v[176:179], v[192:195], v[34:37]
	v_mfma_f32_16x16x32_bf16 v[22:25], v[146:149], v[202:205], v[22:25]
	v_mfma_f32_16x16x32_bf16 v[18:21], v[176:179], v[202:205], v[18:21]
	v_mfma_f32_16x16x32_bf16 v[6:9], v[146:149], v[210:213], v[6:9]
	v_mfma_f32_16x16x32_bf16 v[2:5], v[176:179], v[210:213], v[2:5]
	v_mfma_f32_16x16x32_bf16 v[54:57], v[150:153], v[188:191], v[54:57]
	v_mfma_f32_16x16x32_bf16 v[50:53], v[180:183], v[188:191], v[50:53]
	v_mfma_f32_16x16x32_bf16 v[38:41], v[150:153], v[198:201], v[38:41]
	v_mfma_f32_16x16x32_bf16 v[34:37], v[180:183], v[198:201], v[34:37]
	v_mfma_f32_16x16x32_bf16 v[22:25], v[150:153], v[206:209], v[22:25]
	v_mfma_f32_16x16x32_bf16 v[18:21], v[180:183], v[206:209], v[18:21]
	v_mfma_f32_16x16x32_bf16 v[6:9], v[150:153], v[214:217], v[6:9]
	v_mfma_f32_16x16x32_bf16 v[2:5], v[180:183], v[214:217], v[2:5]
	s_setprio 0
	s_barrier
; #define PG8_STAGE(bufoff, gbase, voff) do { _Pragma("unroll") for (int _i = 0; _i < 2; ++_i) \
;         __builtin_amdgcn_global_load_lds((const unsigned*)((const char*)(gbase) + (voff)[_i]), (LAS unsigned*)(lds + (bufoff) + ldsw + _i * 8192), 16, 0, 0); } while (0)
; #define PG8_LDA(dst, b, h) do { _Pragma("unroll") for (int m = 0; m < 4; ++m) _Pragma("unroll") for (int k = 0; k < 2; ++k) dst[m][k] = *(const LAS bf16x8*)(lds + PG8_SA(b, h) + aoff + m * 2048 + k * 1024); } while (0)
; #define PG8_LDB(dst, b, h) do { _Pragma("unroll") for (int n = 0; n < 2; ++n) _Pragma("unroll") for (int k = 0; k < 2; ++k) dst[n][k] = *(const LAS bf16x8*)(lds + PG8_SB(b, h) + boff + n * 2048 + k * 1024); } while (0)
; #define PG8_MMA(ai, bj, At, Bt) do { __builtin_amdgcn_s_setprio(1); _Pragma("unroll") for (int m = 0; m < 4; ++m) _Pragma("unroll") for (int n = 0; n < 2; ++n) _Pragma("unroll") for (int k = 0; k < 2; ++k) \
;         acc[ai][bj][m][n] = __builtin_amdgcn_mfma_f32_16x16x32_bf16(Bt[n][k], At[m][k], acc[ai][bj][m][n], 0, 0, 0); __builtin_amdgcn_s_setprio(0); } while (0)
; #define PG8_WAIT_V(n) asm volatile("s_waitcnt vmcnt(" #n ")" ::: "memory")
; #define PG8_WAIT_L(n) asm volatile("s_waitcnt lgkmcnt(" #n ")" ::: "memory")
; #define PG8_BAR __builtin_amdgcn_s_barrier()
; #define PG8_SCHED __builtin_amdgcn_sched_barrier(0)
; template <class Epi, bool MID = false>
; __device__ __forceinline__ void gemm_phase(LAS unsigned char* lds, const Gemm g, const StaticOrder& S, const Epi& E) {
;     ...
;             PG8_LDB(B0, 1, 0); PG8_LDB(B1, 1, 1); PG8_SCHED; PG8_LDA(At, 1, 0); PG8_STAGE(PG8_SA(0, 1), a2 + hstepA, voffA);
;             PG8_WAIT_V(8); PG8_WAIT_L(0); PG8_BAR; PG8_MMA(0, 0, At, B0); PG8_MMA(0, 1, At, B1); PG8_BAR; PG8_SCHED;
	s_add_i32 s4, 0, 0x18000
	v_add_u32_e32 v0, s4, v196
	s_add_i32 s5, 0, 0x1c000
	ds_read_b128 v[130:133], v0
	ds_read_b128 v[134:137], v0 offset:1024
	ds_read_b128 v[138:141], v0 offset:2048
	ds_read_b128 v[142:145], v0 offset:3072
	v_add_u32_e32 v0, s5, v196
	ds_read_b128 v[146:149], v0
	ds_read_b128 v[150:153], v0 offset:1024
	ds_read_b128 v[176:179], v0 offset:2048
	ds_read_b128 v[180:183], v0 offset:3072
	s_add_u32 s62, s66, 0x90000
	s_addc_u32 s63, s67, 0
	s_mov_b32 m0, s83
	v_lshl_add_u64 v[236:237], s[62:63], 0, v[156:157]
	ds_read_b128 v[184:187], v197 offset:32768
	ds_read_b128 v[188:191], v197 offset:33792
	ds_read_b128 v[192:195], v197 offset:34816
	ds_read_b128 v[198:201], v197 offset:35840
	ds_read_b128 v[202:205], v197 offset:36864
	ds_read_b128 v[206:209], v197 offset:37888
	ds_read_b128 v[210:213], v197 offset:38912
	ds_read_b128 v[214:217], v197 offset:39936
	global_load_lds_dwordx4 v[236:237], off
	v_lshl_add_u64 v[236:237], s[62:63], 0, v[160:161]
	s_mov_b32 m0, s84
	s_nop 0
	global_load_lds_dwordx4 v[236:237], off
	s_waitcnt vmcnt(8)
	s_waitcnt lgkmcnt(0)
	s_barrier
	s_setprio 1
	s_waitcnt lgkmcnt(0)
	v_mfma_f32_16x16x32_bf16 v[126:129], v[130:133], v[184:187], v[126:129]
	v_mfma_f32_16x16x32_bf16 v[122:125], v[138:141], v[184:187], v[122:125]
	v_mfma_f32_16x16x32_bf16 v[110:113], v[130:133], v[192:195], v[110:113]
	v_mfma_f32_16x16x32_bf16 v[106:109], v[138:141], v[192:195], v[106:109]
	v_mfma_f32_16x16x32_bf16 v[94:97], v[130:133], v[202:205], v[94:97]
	v_mfma_f32_16x16x32_bf16 v[90:93], v[138:141], v[202:205], v[90:93]
	v_mfma_f32_16x16x32_bf16 v[78:81], v[130:133], v[210:213], v[78:81]
	v_mfma_f32_16x16x32_bf16 v[74:77], v[138:141], v[210:213], v[74:77]
	v_mfma_f32_16x16x32_bf16 v[126:129], v[134:137], v[188:191], v[126:129]
	v_mfma_f32_16x16x32_bf16 v[122:125], v[142:145], v[188:191], v[122:125]
	v_mfma_f32_16x16x32_bf16 v[110:113], v[134:137], v[198:201], v[110:113]
	v_mfma_f32_16x16x32_bf16 v[106:109], v[142:145], v[198:201], v[106:109]
	v_mfma_f32_16x16x32_bf16 v[94:97], v[134:137], v[206:209], v[94:97]
	v_mfma_f32_16x16x32_bf16 v[90:93], v[142:145], v[206:209], v[90:93]
	v_mfma_f32_16x16x32_bf16 v[78:81], v[134:137], v[214:217], v[78:81]
	v_mfma_f32_16x16x32_bf16 v[74:77], v[142:145], v[214:217], v[74:77]
	s_setprio 0
	s_setprio 1
	v_mfma_f32_16x16x32_bf16 v[118:121], v[146:149], v[184:187], v[118:121]
	v_mfma_f32_16x16x32_bf16 v[114:117], v[176:179], v[184:187], v[114:117]
	v_mfma_f32_16x16x32_bf16 v[102:105], v[146:149], v[192:195], v[102:105]
	v_mfma_f32_16x16x32_bf16 v[98:101], v[176:179], v[192:195], v[98:101]
	v_mfma_f32_16x16x32_bf16 v[86:89], v[146:149], v[202:205], v[86:89]
	v_mfma_f32_16x16x32_bf16 v[82:85], v[176:179], v[202:205], v[82:85]
	v_mfma_f32_16x16x32_bf16 v[70:73], v[146:149], v[210:213], v[70:73]
	v_mfma_f32_16x16x32_bf16 v[66:69], v[176:179], v[210:213], v[66:69]
	v_mfma_f32_16x16x32_bf16 v[118:121], v[150:153], v[188:191], v[118:121]
	v_mfma_f32_16x16x32_bf16 v[114:117], v[180:183], v[188:191], v[114:117]
	v_mfma_f32_16x16x32_bf16 v[102:105], v[150:153], v[198:201], v[102:105]
	v_mfma_f32_16x16x32_bf16 v[98:101], v[180:183], v[198:201], v[98:101]
	v_mfma_f32_16x16x32_bf16 v[86:89], v[150:153], v[206:209], v[86:89]
	v_mfma_f32_16x16x32_bf16 v[82:85], v[180:183], v[206:209], v[82:85]
	v_mfma_f32_16x16x32_bf16 v[70:73], v[150:153], v[214:217], v[70:73]
	v_mfma_f32_16x16x32_bf16 v[66:69], v[180:183], v[214:217], v[66:69]
	s_setprio 0
	s_barrier
; #define PG8_STAGE(bufoff, gbase, voff) do { _Pragma("unroll") for (int _i = 0; _i < 2; ++_i) \
;         __builtin_amdgcn_global_load_lds((const unsigned*)((const char*)(gbase) + (voff)[_i]), (LAS unsigned*)(lds + (bufoff) + ldsw + _i * 8192), 16, 0, 0); } while (0)
; #define PG8_LDA(dst, b, h) do { _Pragma("unroll") for (int m = 0; m < 4; ++m) _Pragma("unroll") for (int k = 0; k < 2; ++k) dst[m][k] = *(const LAS bf16x8*)(lds + PG8_SA(b, h) + aoff + m * 2048 + k * 1024); } while (0)
; #define PG8_MMA(ai, bj, At, Bt) do { __builtin_amdgcn_s_setprio(1); _Pragma("unroll") for (int m = 0; m < 4; ++m) _Pragma("unroll") for (int n = 0; n < 2; ++n) _Pragma("unroll") for (int k = 0; k < 2; ++k) \
;         acc[ai][bj][m][n] = __builtin_amdgcn_mfma_f32_16x16x32_bf16(Bt[n][k], At[m][k], acc[ai][bj][m][n], 0, 0, 0); __builtin_amdgcn_s_setprio(0); } while (0)
; #define PG8_WAIT_V(n) asm volatile("s_waitcnt vmcnt(" #n ")" ::: "memory")
; #define PG8_WAIT_L(n) asm volatile("s_waitcnt lgkmcnt(" #n ")" ::: "memory")
; #define PG8_BAR __builtin_amdgcn_s_barrier()
; #define PG8_SCHED __builtin_amdgcn_sched_barrier(0)
; template <class Epi, bool MID = false>
; __device__ __forceinline__ void gemm_phase(LAS unsigned char* lds, const Gemm g, const StaticOrder& S, const Epi& E) {
;     ...
;             PG8_LDA(At, 1, 1); PG8_STAGE(PG8_SB(1, 0), b3, voffB); PG8_STAGE(PG8_SB(1, 1), b3 + hstepB, voffB); PG8_STAGE(PG8_SA(1, 0), a3, voffA);
;             PG8_WAIT_V(8); PG8_WAIT_L(0); PG8_BAR; PG8_MMA(1, 0, At, B0); PG8_MMA(1, 1, At, B1); PG8_BAR; PG8_SCHED;
;             if constexpr (MID) { if (t == 6) E.mid(acc, cur, wr, wc, fr, fq); }
;         }
;         if (wr == 0) PG8_BAR;
	s_add_i32 s4, s4, s80
	v_lshl_add_u64 v[154:155], v[154:155], 0, s[24:25]
	s_mov_b32 m0, s4
	ds_read_b128 v[184:187], v197 offset:49152
	ds_read_b128 v[188:191], v197 offset:50176
	ds_read_b128 v[192:195], v197 offset:51200
	ds_read_b128 v[198:201], v197 offset:52224
	ds_read_b128 v[202:205], v197 offset:53248
	ds_read_b128 v[206:209], v197 offset:54272
	ds_read_b128 v[210:213], v197 offset:55296
	ds_read_b128 v[214:217], v197 offset:56320
	global_load_lds_dwordx4 v[154:155], off
	s_add_i32 m0, s4, 0x2000
	s_add_u32 s62, s64, 0x10080
	v_lshl_add_u64 v[154:155], v[230:231], 0, s[24:25]
	s_addc_u32 s63, s65, 0
	s_add_i32 s4, s5, s80
	global_load_lds_dwordx4 v[154:155], off
	v_lshl_add_u64 v[154:155], s[62:63], 0, v[158:159]
	s_mov_b32 m0, s4
	s_nop 0
	global_load_lds_dwordx4 v[154:155], off
	v_lshl_add_u64 v[154:155], s[62:63], 0, v[164:165]
	s_add_i32 m0, s4, 0x2000
	s_nop 0
	global_load_lds_dwordx4 v[154:155], off
	v_lshl_add_u64 v[154:155], v[232:233], 0, s[24:25]
	s_mov_b32 m0, s86
	s_nop 0
	global_load_lds_dwordx4 v[154:155], off
	v_lshl_add_u64 v[154:155], v[234:235], 0, s[24:25]
	s_mov_b32 m0, s87
	s_nop 0
	global_load_lds_dwordx4 v[154:155], off
	s_waitcnt vmcnt(8)
	s_waitcnt lgkmcnt(0)
	s_barrier
	s_setprio 1
	s_waitcnt lgkmcnt(0)
	v_mfma_f32_16x16x32_bf16 v[62:65], v[130:133], v[184:187], v[62:65]
	v_mfma_f32_16x16x32_bf16 v[58:61], v[138:141], v[184:187], v[58:61]
	v_mfma_f32_16x16x32_bf16 v[46:49], v[130:133], v[192:195], v[46:49]
	v_mfma_f32_16x16x32_bf16 v[42:45], v[138:141], v[192:195], v[42:45]
	v_mfma_f32_16x16x32_bf16 v[30:33], v[130:133], v[202:205], v[30:33]
	v_mfma_f32_16x16x32_bf16 v[26:29], v[138:141], v[202:205], v[26:29]
	v_mfma_f32_16x16x32_bf16 v[14:17], v[130:133], v[210:213], v[14:17]
	v_mfma_f32_16x16x32_bf16 v[10:13], v[138:141], v[210:213], v[10:13]
	v_mfma_f32_16x16x32_bf16 v[62:65], v[134:137], v[188:191], v[62:65]
	v_mfma_f32_16x16x32_bf16 v[58:61], v[142:145], v[188:191], v[58:61]
	v_mfma_f32_16x16x32_bf16 v[46:49], v[134:137], v[198:201], v[46:49]
	v_mfma_f32_16x16x32_bf16 v[42:45], v[142:145], v[198:201], v[42:45]
	v_mfma_f32_16x16x32_bf16 v[30:33], v[134:137], v[206:209], v[30:33]
	v_mfma_f32_16x16x32_bf16 v[26:29], v[142:145], v[206:209], v[26:29]
	v_mfma_f32_16x16x32_bf16 v[14:17], v[134:137], v[214:217], v[14:17]
	v_mfma_f32_16x16x32_bf16 v[10:13], v[142:145], v[214:217], v[10:13]
	s_setprio 0
	s_setprio 1
	v_mfma_f32_16x16x32_bf16 v[54:57], v[146:149], v[184:187], v[54:57]
	v_mfma_f32_16x16x32_bf16 v[50:53], v[176:179], v[184:187], v[50:53]
	v_mfma_f32_16x16x32_bf16 v[38:41], v[146:149], v[192:195], v[38:41]
	v_mfma_f32_16x16x32_bf16 v[34:37], v[176:179], v[192:195], v[34:37]
	v_mfma_f32_16x16x32_bf16 v[22:25], v[146:149], v[202:205], v[22:25]
	v_mfma_f32_16x16x32_bf16 v[18:21], v[176:179], v[202:205], v[18:21]
	v_mfma_f32_16x16x32_bf16 v[6:9], v[146:149], v[210:213], v[6:9]
	v_mfma_f32_16x16x32_bf16 v[2:5], v[176:179], v[210:213], v[2:5]
	v_mfma_f32_16x16x32_bf16 v[54:57], v[150:153], v[188:191], v[54:57]
	v_mfma_f32_16x16x32_bf16 v[50:53], v[180:183], v[188:191], v[50:53]
	v_mfma_f32_16x16x32_bf16 v[38:41], v[150:153], v[198:201], v[38:41]
	v_mfma_f32_16x16x32_bf16 v[34:37], v[180:183], v[198:201], v[34:37]
	v_mfma_f32_16x16x32_bf16 v[22:25], v[150:153], v[206:209], v[22:25]
	v_mfma_f32_16x16x32_bf16 v[18:21], v[180:183], v[206:209], v[18:21]
	v_mfma_f32_16x16x32_bf16 v[6:9], v[150:153], v[214:217], v[6:9]
	v_mfma_f32_16x16x32_bf16 v[2:5], v[180:183], v[214:217], v[2:5]
	s_setprio 0
	s_barrier
	s_add_u32 s57, s57, 0x100
	s_addc_u32 s73, s73, 0
	s_cmp_ge_i32 s93, s70
	s_mov_b64 s[62:63], s[42:43]
	s_mov_b32 s64, s93
	s_cbranch_scc0 .LBB0_675
.Lpk_675_exit:
	s_and_b64 vcc, exec, s[52:53]
	s_cbranch_vccz .LBB0_678
.LBB0_677:
	s_barrier

; #define PG8_STAGE(bufoff, gbase, voff) do { _Pragma("unroll") for (int _i = 0; _i < 2; ++_i) \
;         __builtin_amdgcn_global_load_lds((const unsigned*)((const char*)(gbase) + (voff)[_i]), (LAS unsigned*)(lds + (bufoff) + ldsw + _i * 8192), 16, 0, 0); } while (0)
; #define PG8_LDA(dst, b, h) do { _Pragma("unroll") for (int m = 0; m < 4; ++m) _Pragma("unroll") for (int k = 0; k < 2; ++k) dst[m][k] = *(const LAS bf16x8*)(lds + PG8_SA(b, h) + aoff + m * 2048 + k * 1024); } while (0)
; #define PG8_LDB(dst, b, h) do { _Pragma("unroll") for (int n = 0; n < 2; ++n) _Pragma("unroll") for (int k = 0; k < 2; ++k) dst[n][k] = *(const LAS bf16x8*)(lds + PG8_SB(b, h) + boff + n * 2048 + k * 1024); } while (0)
; #define PG8_MMA(ai, bj, At, Bt) do { __builtin_amdgcn_s_setprio(1); _Pragma("unroll") for (int m = 0; m < 4; ++m) _Pragma("unroll") for (int n = 0; n < 2; ++n) _Pragma("unroll") for (int k = 0; k < 2; ++k) \
;         acc[ai][bj][m][n] = __builtin_amdgcn_mfma_f32_16x16x32_bf16(Bt[n][k], At[m][k], acc[ai][bj][m][n], 0, 0, 0); __builtin_amdgcn_s_setprio(0); } while (0)
; #define PG8_BAR __builtin_amdgcn_s_barrier()
; template <class Epi, bool MID = false>
; __device__ __forceinline__ void gemm_phase(LAS unsigned char* lds, const Gemm g, const StaticOrder& S, const Epi& E) {
;     ...
;         const bool has_next = S.next(ui + 1, nxt);
;         const char* nA = has_next ? (const char*)g.A + (size_t)nxt.pm * tstepA : cA; const char* nB = has_next ? (const char*)g.Bt + (size_t)nxt.pn * tstepB : cB;
; #pragma nounroll
;         for (int t = 0; t < nt; t += 2) {
;             const bool last = (t == nt - 2);
;             const char* a1 = cA + (size_t)(t + 1) * kstep;
;             const char* a2 = last ? nA : cA + (size_t)(t + 2) * kstep; const char* b2 = last ? nB : cB + (size_t)(t + 2) * kstep;
;             const char* a3 = a2 + kstep; const char* b3 = b2 + kstep;
;             PG8_LDB(B0, 0, 0); PG8_LDB(B1, 0, 1); PG8_SCHED; PG8_LDA(At, 0, 0); PG8_STAGE(PG8_SA(1, 1), a1 + hstepA, voffA);
;             PG8_WAIT_V(8); PG8_WAIT_L(0); PG8_BAR; PG8_MMA(0, 0, At, B0); PG8_MMA(0, 1, At, B1); PG8_BAR; PG8_SCHED;
;             PG8_LDA(At, 0, 1); PG8_STAGE(PG8_SB(0, 0), b2, voffB); PG8_STAGE(PG8_SB(0, 1), b2 + hstepB, voffB); PG8_STAGE(PG8_SA(0, 0), a2, voffA);
;             PG8_WAIT_V(8); PG8_WAIT_L(0); PG8_BAR; PG8_MMA(1, 0, At, B0); PG8_MMA(1, 1, At, B1); PG8_BAR; PG8_SCHED;
.LBB0_1457:
	s_ashr_i32 s51, s50, 31
	s_lshl_b64 s[52:53], s[50:51], 19
	s_add_u32 s52, s66, s52
	s_addc_u32 s53, s67, s53
	s_ashr_i32 s47, s46, 31
	s_lshl_b64 s[54:55], s[46:47], 19
	s_add_u32 s54, s68, s54
	s_addc_u32 s55, s69, s55
	s_andn2_b64 vcc, exec, s[40:41]
	s_cbranch_vccnz .LBB0_1465
	s_and_b64 s[62:63], s[38:39], exec
	s_cselect_b32 s47, s53, s59
	s_cselect_b32 s51, s52, s58
	s_cselect_b32 s73, s55, s61
	s_cselect_b32 s84, s54, s60
	s_add_u32 s58, s58, 0x40080
	s_addc_u32 s59, s59, 0
	s_add_u32 s85, s60, 0x100
	s_addc_u32 s86, s61, 0
	s_mov_b32 s60, 0
	s_add_i32 s87, s60, 2
	s_add_u32 s4, s58, 0xfffc0080
	s_addc_u32 s5, s59, -1
	s_add_i32 s88, 0, 0x10000
	s_cmp_eq_u32 s82, s60
	s_cselect_b32 s63, s47, s5
	s_cselect_b32 s62, s51, s4
	v_add_u32_e32 v140, s88, v143
	s_cselect_b32 s61, s73, s86
	s_cselect_b32 s60, s84, s85
	s_add_i32 s4, 0, 0x14000
	ds_read_b128 v[146:149], v140
	ds_read_b128 v[150:153], v140 offset:1024
	ds_read_b128 v[154:157], v140 offset:2048
	ds_read_b128 v[158:161], v140 offset:3072
	v_add_u32_e32 v140, s4, v143
	ds_read_b128 v[164:167], v140
	ds_read_b128 v[168:171], v140 offset:1024
	ds_read_b128 v[172:175], v140 offset:2048
	ds_read_b128 v[176:179], v140 offset:3072
	v_lshl_add_u64 v[140:141], s[58:59], 0, v[136:137]
	s_add_i32 m0, s57, 0xc000
	ds_read_b128 v[180:183], v145
	ds_read_b128 v[184:187], v145 offset:1024
	ds_read_b128 v[188:191], v145 offset:2048
	ds_read_b128 v[192:195], v145 offset:3072
	ds_read_b128 v[196:199], v145 offset:4096
	ds_read_b128 v[200:203], v145 offset:5120
	ds_read_b128 v[204:207], v145 offset:6144
	ds_read_b128 v[208:211], v145 offset:7168
	global_load_lds_dwordx4 v[140:141], off
	v_lshl_add_u64 v[140:141], s[58:59], 0, v[138:139]
	s_add_i32 m0, s57, 0xe000
	s_nop 0
	global_load_lds_dwordx4 v[140:141], off
	s_waitcnt vmcnt(8)
	s_waitcnt lgkmcnt(0)
	s_barrier
	s_setprio 1
	s_waitcnt lgkmcnt(0)
	v_mfma_f32_16x16x32_bf16 v[126:129], v[146:149], v[180:183], 0
	v_mfma_f32_16x16x32_bf16 v[122:125], v[154:157], v[180:183], 0
	v_mfma_f32_16x16x32_bf16 v[110:113], v[146:149], v[188:191], 0
	v_mfma_f32_16x16x32_bf16 v[106:109], v[154:157], v[188:191], 0
	v_mfma_f32_16x16x32_bf16 v[94:97], v[146:149], v[196:199], 0
	v_mfma_f32_16x16x32_bf16 v[90:93], v[154:157], v[196:199], 0
	v_mfma_f32_16x16x32_bf16 v[78:81], v[146:149], v[204:207], 0
	v_mfma_f32_16x16x32_bf16 v[74:77], v[154:157], v[204:207], 0
	v_mfma_f32_16x16x32_bf16 v[126:129], v[150:153], v[184:187], v[126:129]
	v_mfma_f32_16x16x32_bf16 v[122:125], v[158:161], v[184:187], v[122:125]
	v_mfma_f32_16x16x32_bf16 v[110:113], v[150:153], v[192:195], v[110:113]
	v_mfma_f32_16x16x32_bf16 v[106:109], v[158:161], v[192:195], v[106:109]
	v_mfma_f32_16x16x32_bf16 v[94:97], v[150:153], v[200:203], v[94:97]
	v_mfma_f32_16x16x32_bf16 v[90:93], v[158:161], v[200:203], v[90:93]
	v_mfma_f32_16x16x32_bf16 v[78:81], v[150:153], v[208:211], v[78:81]
	v_mfma_f32_16x16x32_bf16 v[74:77], v[158:161], v[208:211], v[74:77]
	s_setprio 0
	s_setprio 1
	v_mfma_f32_16x16x32_bf16 v[118:121], v[164:167], v[180:183], 0
	v_mfma_f32_16x16x32_bf16 v[114:117], v[172:175], v[180:183], 0
	v_mfma_f32_16x16x32_bf16 v[102:105], v[164:167], v[188:191], 0
	v_mfma_f32_16x16x32_bf16 v[98:101], v[172:175], v[188:191], 0
	v_mfma_f32_16x16x32_bf16 v[86:89], v[164:167], v[196:199], 0
	v_mfma_f32_16x16x32_bf16 v[82:85], v[172:175], v[196:199], 0
	v_mfma_f32_16x16x32_bf16 v[70:73], v[164:167], v[204:207], 0
	v_mfma_f32_16x16x32_bf16 v[66:69], v[172:175], v[204:207], 0
	v_mfma_f32_16x16x32_bf16 v[118:121], v[168:171], v[184:187], v[118:121]
	v_mfma_f32_16x16x32_bf16 v[114:117], v[176:179], v[184:187], v[114:117]
	v_mfma_f32_16x16x32_bf16 v[102:105], v[168:171], v[192:195], v[102:105]
	v_mfma_f32_16x16x32_bf16 v[98:101], v[176:179], v[192:195], v[98:101]
	v_mfma_f32_16x16x32_bf16 v[86:89], v[168:171], v[200:203], v[86:89]
	v_mfma_f32_16x16x32_bf16 v[82:85], v[176:179], v[200:203], v[82:85]
	v_mfma_f32_16x16x32_bf16 v[70:73], v[168:171], v[208:211], v[70:73]
	v_mfma_f32_16x16x32_bf16 v[66:69], v[176:179], v[208:211], v[66:69]
	s_setprio 0
	s_barrier
	s_add_i32 s5, s88, s70
	v_lshl_add_u64 v[140:141], s[60:61], 0, v[0:1]
	s_mov_b32 m0, s5
	ds_read_b128 v[180:183], v145 offset:16384
	ds_read_b128 v[184:187], v145 offset:17408
	ds_read_b128 v[188:191], v145 offset:18432
	ds_read_b128 v[192:195], v145 offset:19456
	ds_read_b128 v[196:199], v145 offset:20480
	ds_read_b128 v[200:203], v145 offset:21504
	ds_read_b128 v[204:207], v145 offset:22528
	ds_read_b128 v[208:211], v145 offset:23552
	global_load_lds_dwordx4 v[140:141], off
	s_add_i32 m0, s5, 0x2000
	s_add_u32 s88, s60, 0x40000
	v_lshl_add_u64 v[212:213], s[60:61], 0, v[134:135]
	s_addc_u32 s89, s61, 0
	s_add_i32 s4, s4, s70
	global_load_lds_dwordx4 v[212:213], off
	v_lshl_add_u64 v[214:215], s[88:89], 0, v[0:1]
	s_mov_b32 m0, s4
	v_lshl_add_u64 v[230:231], s[62:63], 0, v[132:133]
	global_load_lds_dwordx4 v[214:215], off
	v_lshl_add_u64 v[214:215], s[88:89], 0, v[134:135]
	s_add_i32 m0, s4, 0x2000
	s_nop 0
	global_load_lds_dwordx4 v[214:215], off
	v_lshl_add_u64 v[214:215], s[62:63], 0, v[130:131]
	s_mov_b32 m0, s57
	s_nop 0
	global_load_lds_dwordx4 v[214:215], off
	s_mov_b32 m0, s71
	s_nop 0
	global_load_lds_dwordx4 v[230:231], off
	s_waitcnt vmcnt(8)
	s_waitcnt lgkmcnt(0)
	s_barrier
; #define PG8_STAGE(bufoff, gbase, voff) do { _Pragma("unroll") for (int _i = 0; _i < 2; ++_i) \
;         __builtin_amdgcn_global_load_lds((const unsigned*)((const char*)(gbase) + (voff)[_i]), (LAS unsigned*)(lds + (bufoff) + ldsw + _i * 8192), 16, 0, 0); } while (0)
; #define PG8_LDA(dst, b, h) do { _Pragma("unroll") for (int m = 0; m < 4; ++m) _Pragma("unroll") for (int k = 0; k < 2; ++k) dst[m][k] = *(const LAS bf16x8*)(lds + PG8_SA(b, h) + aoff + m * 2048 + k * 1024); } while (0)
; #define PG8_LDB(dst, b, h) do { _Pragma("unroll") for (int n = 0; n < 2; ++n) _Pragma("unroll") for (int k = 0; k < 2; ++k) dst[n][k] = *(const LAS bf16x8*)(lds + PG8_SB(b, h) + boff + n * 2048 + k * 1024); } while (0)
; #define PG8_MMA(ai, bj, At, Bt) do { __builtin_amdgcn_s_setprio(1); _Pragma("unroll") for (int m = 0; m < 4; ++m) _Pragma("unroll") for (int n = 0; n < 2; ++n) _Pragma("unroll") for (int k = 0; k < 2; ++k) \
;         acc[ai][bj][m][n] = __builtin_amdgcn_mfma_f32_16x16x32_bf16(Bt[n][k], At[m][k], acc[ai][bj][m][n], 0, 0, 0); __builtin_amdgcn_s_setprio(0); } while (0)
; #define PG8_WAIT_V(n) asm volatile("s_waitcnt vmcnt(" #n ")" ::: "memory")
; #define PG8_WAIT_L(n) asm volatile("s_waitcnt lgkmcnt(" #n ")" ::: "memory")
; #define PG8_BAR __builtin_amdgcn_s_barrier()
; #define PG8_SCHED __builtin_amdgcn_sched_barrier(0)
; template <class Epi, bool MID = false>
; __device__ __forceinline__ void gemm_phase(LAS unsigned char* lds, const Gemm g, const StaticOrder& S, const Epi& E) {
;     ...
;             PG8_WAIT_V(8); PG8_WAIT_L(0); PG8_BAR; PG8_MMA(1, 0, At, B0); PG8_MMA(1, 1, At, B1); PG8_BAR; PG8_SCHED;
;             PG8_LDB(B0, 1, 0); PG8_LDB(B1, 1, 1); PG8_SCHED; PG8_LDA(At, 1, 0); PG8_STAGE(PG8_SA(0, 1), a2 + hstepA, voffA);
;             PG8_WAIT_V(8); PG8_WAIT_L(0); PG8_BAR; PG8_MMA(0, 0, At, B0); PG8_MMA(0, 1, At, B1); PG8_BAR; PG8_SCHED;
	s_setprio 1
	s_waitcnt lgkmcnt(0)
	v_mfma_f32_16x16x32_bf16 v[62:65], v[146:149], v[180:183], 0
	v_mfma_f32_16x16x32_bf16 v[58:61], v[154:157], v[180:183], 0
	v_mfma_f32_16x16x32_bf16 v[46:49], v[146:149], v[188:191], 0
	v_mfma_f32_16x16x32_bf16 v[42:45], v[154:157], v[188:191], 0
	v_mfma_f32_16x16x32_bf16 v[30:33], v[146:149], v[196:199], 0
	v_mfma_f32_16x16x32_bf16 v[26:29], v[154:157], v[196:199], 0
	v_mfma_f32_16x16x32_bf16 v[14:17], v[146:149], v[204:207], 0
	v_mfma_f32_16x16x32_bf16 v[10:13], v[154:157], v[204:207], 0
	v_mfma_f32_16x16x32_bf16 v[62:65], v[150:153], v[184:187], v[62:65]
	v_mfma_f32_16x16x32_bf16 v[58:61], v[158:161], v[184:187], v[58:61]
	v_mfma_f32_16x16x32_bf16 v[46:49], v[150:153], v[192:195], v[46:49]
	v_mfma_f32_16x16x32_bf16 v[42:45], v[158:161], v[192:195], v[42:45]
	v_mfma_f32_16x16x32_bf16 v[30:33], v[150:153], v[200:203], v[30:33]
	v_mfma_f32_16x16x32_bf16 v[26:29], v[158:161], v[200:203], v[26:29]
	v_mfma_f32_16x16x32_bf16 v[14:17], v[150:153], v[208:211], v[14:17]
	v_mfma_f32_16x16x32_bf16 v[10:13], v[158:161], v[208:211], v[10:13]
	s_setprio 0
	s_setprio 1
	v_mfma_f32_16x16x32_bf16 v[54:57], v[164:167], v[180:183], 0
	v_mfma_f32_16x16x32_bf16 v[50:53], v[172:175], v[180:183], 0
	v_mfma_f32_16x16x32_bf16 v[38:41], v[164:167], v[188:191], 0
	v_mfma_f32_16x16x32_bf16 v[34:37], v[172:175], v[188:191], 0
	v_mfma_f32_16x16x32_bf16 v[22:25], v[164:167], v[196:199], 0
	v_mfma_f32_16x16x32_bf16 v[18:21], v[172:175], v[196:199], 0
	v_mfma_f32_16x16x32_bf16 v[6:9], v[164:167], v[204:207], 0
	v_mfma_f32_16x16x32_bf16 v[2:5], v[172:175], v[204:207], 0
	v_mfma_f32_16x16x32_bf16 v[54:57], v[168:171], v[184:187], v[54:57]
	v_mfma_f32_16x16x32_bf16 v[50:53], v[176:179], v[184:187], v[50:53]
	v_mfma_f32_16x16x32_bf16 v[38:41], v[168:171], v[192:195], v[38:41]
	v_mfma_f32_16x16x32_bf16 v[34:37], v[176:179], v[192:195], v[34:37]
	v_mfma_f32_16x16x32_bf16 v[22:25], v[168:171], v[200:203], v[22:25]
	v_mfma_f32_16x16x32_bf16 v[18:21], v[176:179], v[200:203], v[18:21]
	v_mfma_f32_16x16x32_bf16 v[6:9], v[168:171], v[208:211], v[6:9]
	v_mfma_f32_16x16x32_bf16 v[2:5], v[176:179], v[208:211], v[2:5]
	s_setprio 0
	s_barrier
	s_add_i32 s4, 0, 0x18000
	s_add_i32 s5, 0, 0x1c000
	v_add_u32_e32 v158, s4, v143
	v_add_u32_e32 v176, s5, v143
	ds_read_b128 v[146:149], v158
	ds_read_b128 v[150:153], v158 offset:1024
	ds_read_b128 v[154:157], v158 offset:2048
	ds_read_b128 v[158:161], v158 offset:3072
	ds_read_b128 v[164:167], v176
	ds_read_b128 v[168:171], v176 offset:1024
	ds_read_b128 v[172:175], v176 offset:2048
	ds_read_b128 v[176:179], v176 offset:3072
	s_add_u32 s62, s62, 0x40000
	s_addc_u32 s63, s63, 0
	s_mov_b32 m0, s75
	v_lshl_add_u64 v[232:233], s[62:63], 0, v[130:131]
	ds_read_b128 v[180:183], v145 offset:32768
	ds_read_b128 v[184:187], v145 offset:33792
	ds_read_b128 v[188:191], v145 offset:34816
	ds_read_b128 v[192:195], v145 offset:35840
	ds_read_b128 v[196:199], v145 offset:36864
	ds_read_b128 v[200:203], v145 offset:37888
	ds_read_b128 v[204:207], v145 offset:38912
	ds_read_b128 v[208:211], v145 offset:39936
	global_load_lds_dwordx4 v[232:233], off
	v_lshl_add_u64 v[232:233], s[62:63], 0, v[132:133]
	s_mov_b32 m0, s78
	s_nop 0
	global_load_lds_dwordx4 v[232:233], off
	s_waitcnt vmcnt(8)
	s_waitcnt lgkmcnt(0)
	s_barrier
	s_setprio 1
	s_waitcnt lgkmcnt(0)
	v_mfma_f32_16x16x32_bf16 v[126:129], v[146:149], v[180:183], v[126:129]
	v_mfma_f32_16x16x32_bf16 v[122:125], v[154:157], v[180:183], v[122:125]
	v_mfma_f32_16x16x32_bf16 v[110:113], v[146:149], v[188:191], v[110:113]
	v_mfma_f32_16x16x32_bf16 v[106:109], v[154:157], v[188:191], v[106:109]
	v_mfma_f32_16x16x32_bf16 v[94:97], v[146:149], v[196:199], v[94:97]
	v_mfma_f32_16x16x32_bf16 v[90:93], v[154:157], v[196:199], v[90:93]
	v_mfma_f32_16x16x32_bf16 v[78:81], v[146:149], v[204:207], v[78:81]
	v_mfma_f32_16x16x32_bf16 v[74:77], v[154:157], v[204:207], v[74:77]
	v_mfma_f32_16x16x32_bf16 v[126:129], v[150:153], v[184:187], v[126:129]
	v_mfma_f32_16x16x32_bf16 v[122:125], v[158:161], v[184:187], v[122:125]
	v_mfma_f32_16x16x32_bf16 v[110:113], v[150:153], v[192:195], v[110:113]
	v_mfma_f32_16x16x32_bf16 v[106:109], v[158:161], v[192:195], v[106:109]
	v_mfma_f32_16x16x32_bf16 v[94:97], v[150:153], v[200:203], v[94:97]
	v_mfma_f32_16x16x32_bf16 v[90:93], v[158:161], v[200:203], v[90:93]
	v_mfma_f32_16x16x32_bf16 v[78:81], v[150:153], v[208:211], v[78:81]
	v_mfma_f32_16x16x32_bf16 v[74:77], v[158:161], v[208:211], v[74:77]
	s_setprio 0
	s_setprio 1
	v_mfma_f32_16x16x32_bf16 v[118:121], v[164:167], v[180:183], v[118:121]
	v_mfma_f32_16x16x32_bf16 v[114:117], v[172:175], v[180:183], v[114:117]
	v_mfma_f32_16x16x32_bf16 v[102:105], v[164:167], v[188:191], v[102:105]
	v_mfma_f32_16x16x32_bf16 v[98:101], v[172:175], v[188:191], v[98:101]
	v_mfma_f32_16x16x32_bf16 v[86:89], v[164:167], v[196:199], v[86:89]
	v_mfma_f32_16x16x32_bf16 v[82:85], v[172:175], v[196:199], v[82:85]
	v_mfma_f32_16x16x32_bf16 v[70:73], v[164:167], v[204:207], v[70:73]
	v_mfma_f32_16x16x32_bf16 v[66:69], v[172:175], v[204:207], v[66:69]
	v_mfma_f32_16x16x32_bf16 v[118:121], v[168:171], v[184:187], v[118:121]
	v_mfma_f32_16x16x32_bf16 v[114:117], v[176:179], v[184:187], v[114:117]
	v_mfma_f32_16x16x32_bf16 v[102:105], v[168:171], v[192:195], v[102:105]
	v_mfma_f32_16x16x32_bf16 v[98:101], v[176:179], v[192:195], v[98:101]
	v_mfma_f32_16x16x32_bf16 v[86:89], v[168:171], v[200:203], v[86:89]
	v_mfma_f32_16x16x32_bf16 v[82:85], v[176:179], v[200:203], v[82:85]
	v_mfma_f32_16x16x32_bf16 v[70:73], v[168:171], v[208:211], v[70:73]
	v_mfma_f32_16x16x32_bf16 v[66:69], v[176:179], v[208:211], v[66:69]
	s_setprio 0
	s_barrier
; #define PG8_STAGE(bufoff, gbase, voff) do { _Pragma("unroll") for (int _i = 0; _i < 2; ++_i) \
;         __builtin_amdgcn_global_load_lds((const unsigned*)((const char*)(gbase) + (voff)[_i]), (LAS unsigned*)(lds + (bufoff) + ldsw + _i * 8192), 16, 0, 0); } while (0)
; #define PG8_LDA(dst, b, h) do { _Pragma("unroll") for (int m = 0; m < 4; ++m) _Pragma("unroll") for (int k = 0; k < 2; ++k) dst[m][k] = *(const LAS bf16x8*)(lds + PG8_SA(b, h) + aoff + m * 2048 + k * 1024); } while (0)
; #define PG8_LDB(dst, b, h) do { _Pragma("unroll") for (int n = 0; n < 2; ++n) _Pragma("unroll") for (int k = 0; k < 2; ++k) dst[n][k] = *(const LAS bf16x8*)(lds + PG8_SB(b, h) + boff + n * 2048 + k * 1024); } while (0)
; #define PG8_MMA(ai, bj, At, Bt) do { __builtin_amdgcn_s_setprio(1); _Pragma("unroll") for (int m = 0; m < 4; ++m) _Pragma("unroll") for (int n = 0; n < 2; ++n) _Pragma("unroll") for (int k = 0; k < 2; ++k) \
;         acc[ai][bj][m][n] = __builtin_amdgcn_mfma_f32_16x16x32_bf16(Bt[n][k], At[m][k], acc[ai][bj][m][n], 0, 0, 0); __builtin_amdgcn_s_setprio(0); } while (0)
; #define PG8_WAIT_V(n) asm volatile("s_waitcnt vmcnt(" #n ")" ::: "memory")
; #define PG8_WAIT_L(n) asm volatile("s_waitcnt lgkmcnt(" #n ")" ::: "memory")
; #define PG8_BAR __builtin_amdgcn_s_barrier()
; #define PG8_SCHED __builtin_amdgcn_sched_barrier(0)
; template <class Epi, bool MID = false>
; __device__ __forceinline__ void gemm_phase(LAS unsigned char* lds, const Gemm g, const StaticOrder& S, const Epi& E) {
;     ...
;         for (int t = 0; t < nt; t += 2) {
;             const bool last = (t == nt - 2);
;             const char* a1 = cA + (size_t)(t + 1) * kstep;
;             const char* a2 = last ? nA : cA + (size_t)(t + 2) * kstep; const char* b2 = last ? nB : cB + (size_t)(t + 2) * kstep;
;             const char* a3 = a2 + kstep; const char* b3 = b2 + kstep;
;             PG8_LDB(B0, 0, 0); PG8_LDB(B1, 0, 1); PG8_SCHED; PG8_LDA(At, 0, 0); PG8_STAGE(PG8_SA(1, 1), a1 + hstepA, voffA);
;     ...
;             PG8_LDA(At, 1, 1); PG8_STAGE(PG8_SB(1, 0), b3, voffB); PG8_STAGE(PG8_SB(1, 1), b3 + hstepB, voffB); PG8_STAGE(PG8_SA(1, 0), a3, voffA);
;             PG8_WAIT_V(8); PG8_WAIT_L(0); PG8_BAR; PG8_MMA(1, 0, At, B0); PG8_MMA(1, 1, At, B1); PG8_BAR; PG8_SCHED;
	s_add_i32 s4, s4, s70
	v_lshl_add_u64 v[140:141], v[140:141], 0, s[24:25]
	s_mov_b32 m0, s4
	ds_read_b128 v[180:183], v145 offset:49152
	ds_read_b128 v[184:187], v145 offset:50176
	ds_read_b128 v[188:191], v145 offset:51200
	ds_read_b128 v[192:195], v145 offset:52224
	ds_read_b128 v[196:199], v145 offset:53248
	ds_read_b128 v[200:203], v145 offset:54272
	ds_read_b128 v[204:207], v145 offset:55296
	ds_read_b128 v[208:211], v145 offset:56320
	global_load_lds_dwordx4 v[140:141], off
	s_add_i32 m0, s4, 0x2000
	s_add_u32 s60, s60, 0x40080
	v_lshl_add_u64 v[140:141], v[212:213], 0, s[24:25]
	s_addc_u32 s61, s61, 0
	s_add_i32 s4, s5, s70
	global_load_lds_dwordx4 v[140:141], off
	v_lshl_add_u64 v[140:141], s[60:61], 0, v[0:1]
	s_mov_b32 m0, s4
	s_nop 0
	global_load_lds_dwordx4 v[140:141], off
	v_lshl_add_u64 v[140:141], s[60:61], 0, v[134:135]
	s_add_i32 m0, s4, 0x2000
	s_nop 0
	global_load_lds_dwordx4 v[140:141], off
	v_lshl_add_u64 v[140:141], v[214:215], 0, s[24:25]
	s_mov_b32 m0, s79
	s_nop 0
	global_load_lds_dwordx4 v[140:141], off
	v_lshl_add_u64 v[140:141], v[230:231], 0, s[24:25]
	s_mov_b32 m0, s80
	s_nop 0
	global_load_lds_dwordx4 v[140:141], off
	s_waitcnt vmcnt(8)
	s_waitcnt lgkmcnt(0)
	s_barrier
	s_setprio 1
	s_waitcnt lgkmcnt(0)
	v_mfma_f32_16x16x32_bf16 v[62:65], v[146:149], v[180:183], v[62:65]
	v_mfma_f32_16x16x32_bf16 v[58:61], v[154:157], v[180:183], v[58:61]
	v_mfma_f32_16x16x32_bf16 v[46:49], v[146:149], v[188:191], v[46:49]
	v_mfma_f32_16x16x32_bf16 v[42:45], v[154:157], v[188:191], v[42:45]
	v_mfma_f32_16x16x32_bf16 v[30:33], v[146:149], v[196:199], v[30:33]
	v_mfma_f32_16x16x32_bf16 v[26:29], v[154:157], v[196:199], v[26:29]
	v_mfma_f32_16x16x32_bf16 v[14:17], v[146:149], v[204:207], v[14:17]
	v_mfma_f32_16x16x32_bf16 v[10:13], v[154:157], v[204:207], v[10:13]
	v_mfma_f32_16x16x32_bf16 v[62:65], v[150:153], v[184:187], v[62:65]
	v_mfma_f32_16x16x32_bf16 v[58:61], v[158:161], v[184:187], v[58:61]
	v_mfma_f32_16x16x32_bf16 v[46:49], v[150:153], v[192:195], v[46:49]
	v_mfma_f32_16x16x32_bf16 v[42:45], v[158:161], v[192:195], v[42:45]
	v_mfma_f32_16x16x32_bf16 v[30:33], v[150:153], v[200:203], v[30:33]
	v_mfma_f32_16x16x32_bf16 v[26:29], v[158:161], v[200:203], v[26:29]
	v_mfma_f32_16x16x32_bf16 v[14:17], v[150:153], v[208:211], v[14:17]
	v_mfma_f32_16x16x32_bf16 v[10:13], v[158:161], v[208:211], v[10:13]
	s_setprio 0
	s_setprio 1
	v_mfma_f32_16x16x32_bf16 v[54:57], v[164:167], v[180:183], v[54:57]
	v_mfma_f32_16x16x32_bf16 v[50:53], v[172:175], v[180:183], v[50:53]
	v_mfma_f32_16x16x32_bf16 v[38:41], v[164:167], v[188:191], v[38:41]
	v_mfma_f32_16x16x32_bf16 v[34:37], v[172:175], v[188:191], v[34:37]
	v_mfma_f32_16x16x32_bf16 v[22:25], v[164:167], v[196:199], v[22:25]
	v_mfma_f32_16x16x32_bf16 v[18:21], v[172:175], v[196:199], v[18:21]
	v_mfma_f32_16x16x32_bf16 v[6:9], v[164:167], v[204:207], v[6:9]
	v_mfma_f32_16x16x32_bf16 v[2:5], v[172:175], v[204:207], v[2:5]
	v_mfma_f32_16x16x32_bf16 v[54:57], v[168:171], v[184:187], v[54:57]
	v_mfma_f32_16x16x32_bf16 v[50:53], v[176:179], v[184:187], v[50:53]
	v_mfma_f32_16x16x32_bf16 v[38:41], v[168:171], v[192:195], v[38:41]
	v_mfma_f32_16x16x32_bf16 v[34:37], v[176:179], v[192:195], v[34:37]
	v_mfma_f32_16x16x32_bf16 v[22:25], v[168:171], v[200:203], v[22:25]
	v_mfma_f32_16x16x32_bf16 v[18:21], v[176:179], v[200:203], v[18:21]
	v_mfma_f32_16x16x32_bf16 v[6:9], v[168:171], v[208:211], v[6:9]
	v_mfma_f32_16x16x32_bf16 v[2:5], v[176:179], v[208:211], v[2:5]
	s_setprio 0
	s_barrier
	s_add_u32 s58, s58, 0x100
	s_addc_u32 s59, s59, 0
	s_add_u32 s85, s85, 0x100
	s_addc_u32 s86, s86, 0
	s_cmp_ge_i32 s87, s65
	s_mov_b32 s60, s87
	s_cbranch_scc0 .LBB0_1459
	s_branch .Lpk_1459_exit
.LBB0_1459:
	s_add_i32 s87, s60, 2
	s_add_u32 s4, s58, 0xfffc0080
	s_addc_u32 s5, s59, -1
	s_add_i32 s88, 0, 0x10000
	s_cmp_eq_u32 s82, s60
	s_cselect_b32 s63, s47, s5
	s_cselect_b32 s62, s51, s4
	v_add_u32_e32 v140, s88, v143
	s_cselect_b32 s61, s73, s86
	s_cselect_b32 s60, s84, s85
	s_add_i32 s4, 0, 0x14000
	ds_read_b128 v[146:149], v140
	ds_read_b128 v[150:153], v140 offset:1024
	ds_read_b128 v[154:157], v140 offset:2048
	ds_read_b128 v[158:161], v140 offset:3072
	v_add_u32_e32 v140, s4, v143
	ds_read_b128 v[164:167], v140
	ds_read_b128 v[168:171], v140 offset:1024
	ds_read_b128 v[172:175], v140 offset:2048
	ds_read_b128 v[176:179], v140 offset:3072
	v_lshl_add_u64 v[140:141], s[58:59], 0, v[136:137]
	s_add_i32 m0, s57, 0xc000
	ds_read_b128 v[180:183], v145
	ds_read_b128 v[184:187], v145 offset:1024
	ds_read_b128 v[188:191], v145 offset:2048
	ds_read_b128 v[192:195], v145 offset:3072
	ds_read_b128 v[196:199], v145 offset:4096
	ds_read_b128 v[200:203], v145 offset:5120
	ds_read_b128 v[204:207], v145 offset:6144
	ds_read_b128 v[208:211], v145 offset:7168
	global_load_lds_dwordx4 v[140:141], off
	v_lshl_add_u64 v[140:141], s[58:59], 0, v[138:139]
	s_add_i32 m0, s57, 0xe000
	s_nop 0
	global_load_lds_dwordx4 v[140:141], off
	s_waitcnt vmcnt(8)
	s_waitcnt lgkmcnt(0)
	s_barrier
; #define PG8_STAGE(bufoff, gbase, voff) do { _Pragma("unroll") for (int _i = 0; _i < 2; ++_i) \
;         __builtin_amdgcn_global_load_lds((const unsigned*)((const char*)(gbase) + (voff)[_i]), (LAS unsigned*)(lds + (bufoff) + ldsw + _i * 8192), 16, 0, 0); } while (0)
; #define PG8_LDA(dst, b, h) do { _Pragma("unroll") for (int m = 0; m < 4; ++m) _Pragma("unroll") for (int k = 0; k < 2; ++k) dst[m][k] = *(const LAS bf16x8*)(lds + PG8_SA(b, h) + aoff + m * 2048 + k * 1024); } while (0)
; #define PG8_MMA(ai, bj, At, Bt) do { __builtin_amdgcn_s_setprio(1); _Pragma("unroll") for (int m = 0; m < 4; ++m) _Pragma("unroll") for (int n = 0; n < 2; ++n) _Pragma("unroll") for (int k = 0; k < 2; ++k) \
;         acc[ai][bj][m][n] = __builtin_amdgcn_mfma_f32_16x16x32_bf16(Bt[n][k], At[m][k], acc[ai][bj][m][n], 0, 0, 0); __builtin_amdgcn_s_setprio(0); } while (0)
; #define PG8_WAIT_V(n) asm volatile("s_waitcnt vmcnt(" #n ")" ::: "memory")
; #define PG8_WAIT_L(n) asm volatile("s_waitcnt lgkmcnt(" #n ")" ::: "memory")
; #define PG8_BAR __builtin_amdgcn_s_barrier()
; #define PG8_SCHED __builtin_amdgcn_sched_barrier(0)
; template <class Epi, bool MID = false>
; __device__ __forceinline__ void gemm_phase(LAS unsigned char* lds, const Gemm g, const StaticOrder& S, const Epi& E) {
;     ...
;             PG8_WAIT_V(8); PG8_WAIT_L(0); PG8_BAR; PG8_MMA(0, 0, At, B0); PG8_MMA(0, 1, At, B1); PG8_BAR; PG8_SCHED;
;             PG8_LDA(At, 0, 1); PG8_STAGE(PG8_SB(0, 0), b2, voffB); PG8_STAGE(PG8_SB(0, 1), b2 + hstepB, voffB); PG8_STAGE(PG8_SA(0, 0), a2, voffA);
;             PG8_WAIT_V(8); PG8_WAIT_L(0); PG8_BAR; PG8_MMA(1, 0, At, B0); PG8_MMA(1, 1, At, B1); PG8_BAR; PG8_SCHED;
	s_setprio 1
	s_waitcnt lgkmcnt(0)
	v_mfma_f32_16x16x32_bf16 v[126:129], v[146:149], v[180:183], v[126:129]
	v_mfma_f32_16x16x32_bf16 v[122:125], v[154:157], v[180:183], v[122:125]
	v_mfma_f32_16x16x32_bf16 v[110:113], v[146:149], v[188:191], v[110:113]
	v_mfma_f32_16x16x32_bf16 v[106:109], v[154:157], v[188:191], v[106:109]
	v_mfma_f32_16x16x32_bf16 v[94:97], v[146:149], v[196:199], v[94:97]
	v_mfma_f32_16x16x32_bf16 v[90:93], v[154:157], v[196:199], v[90:93]
	v_mfma_f32_16x16x32_bf16 v[78:81], v[146:149], v[204:207], v[78:81]
	v_mfma_f32_16x16x32_bf16 v[74:77], v[154:157], v[204:207], v[74:77]
	v_mfma_f32_16x16x32_bf16 v[126:129], v[150:153], v[184:187], v[126:129]
	v_mfma_f32_16x16x32_bf16 v[122:125], v[158:161], v[184:187], v[122:125]
	v_mfma_f32_16x16x32_bf16 v[110:113], v[150:153], v[192:195], v[110:113]
	v_mfma_f32_16x16x32_bf16 v[106:109], v[158:161], v[192:195], v[106:109]
	v_mfma_f32_16x16x32_bf16 v[94:97], v[150:153], v[200:203], v[94:97]
	v_mfma_f32_16x16x32_bf16 v[90:93], v[158:161], v[200:203], v[90:93]
	v_mfma_f32_16x16x32_bf16 v[78:81], v[150:153], v[208:211], v[78:81]
	v_mfma_f32_16x16x32_bf16 v[74:77], v[158:161], v[208:211], v[74:77]
	s_setprio 0
	s_setprio 1
	v_mfma_f32_16x16x32_bf16 v[118:121], v[164:167], v[180:183], v[118:121]
	v_mfma_f32_16x16x32_bf16 v[114:117], v[172:175], v[180:183], v[114:117]
	v_mfma_f32_16x16x32_bf16 v[102:105], v[164:167], v[188:191], v[102:105]
	v_mfma_f32_16x16x32_bf16 v[98:101], v[172:175], v[188:191], v[98:101]
	v_mfma_f32_16x16x32_bf16 v[86:89], v[164:167], v[196:199], v[86:89]
	v_mfma_f32_16x16x32_bf16 v[82:85], v[172:175], v[196:199], v[82:85]
	v_mfma_f32_16x16x32_bf16 v[70:73], v[164:167], v[204:207], v[70:73]
	v_mfma_f32_16x16x32_bf16 v[66:69], v[172:175], v[204:207], v[66:69]
	v_mfma_f32_16x16x32_bf16 v[118:121], v[168:171], v[184:187], v[118:121]
	v_mfma_f32_16x16x32_bf16 v[114:117], v[176:179], v[184:187], v[114:117]
	v_mfma_f32_16x16x32_bf16 v[102:105], v[168:171], v[192:195], v[102:105]
	v_mfma_f32_16x16x32_bf16 v[98:101], v[176:179], v[192:195], v[98:101]
	v_mfma_f32_16x16x32_bf16 v[86:89], v[168:171], v[200:203], v[86:89]
	v_mfma_f32_16x16x32_bf16 v[82:85], v[176:179], v[200:203], v[82:85]
	v_mfma_f32_16x16x32_bf16 v[70:73], v[168:171], v[208:211], v[70:73]
	v_mfma_f32_16x16x32_bf16 v[66:69], v[176:179], v[208:211], v[66:69]
	s_setprio 0
	s_barrier
	s_add_i32 s5, s88, s70
	v_lshl_add_u64 v[140:141], s[60:61], 0, v[0:1]
	s_mov_b32 m0, s5
	ds_read_b128 v[180:183], v145 offset:16384
	ds_read_b128 v[184:187], v145 offset:17408
	ds_read_b128 v[188:191], v145 offset:18432
	ds_read_b128 v[192:195], v145 offset:19456
	ds_read_b128 v[196:199], v145 offset:20480
	ds_read_b128 v[200:203], v145 offset:21504
	ds_read_b128 v[204:207], v145 offset:22528
	ds_read_b128 v[208:211], v145 offset:23552
	global_load_lds_dwordx4 v[140:141], off
	s_add_i32 m0, s5, 0x2000
	s_add_u32 s88, s60, 0x40000
	v_lshl_add_u64 v[212:213], s[60:61], 0, v[134:135]
	s_addc_u32 s89, s61, 0
	s_add_i32 s4, s4, s70
	global_load_lds_dwordx4 v[212:213], off
	v_lshl_add_u64 v[214:215], s[88:89], 0, v[0:1]
	s_mov_b32 m0, s4
	v_lshl_add_u64 v[230:231], s[62:63], 0, v[132:133]
	global_load_lds_dwordx4 v[214:215], off
	v_lshl_add_u64 v[214:215], s[88:89], 0, v[134:135]
	s_add_i32 m0, s4, 0x2000
	s_nop 0
	global_load_lds_dwordx4 v[214:215], off
	v_lshl_add_u64 v[214:215], s[62:63], 0, v[130:131]
	s_mov_b32 m0, s57
	s_nop 0
	global_load_lds_dwordx4 v[214:215], off
	s_mov_b32 m0, s71
	s_nop 0
	global_load_lds_dwordx4 v[230:231], off
	s_waitcnt vmcnt(8)
	s_waitcnt lgkmcnt(0)
	s_barrier
	s_setprio 1
	s_waitcnt lgkmcnt(0)
	v_mfma_f32_16x16x32_bf16 v[62:65], v[146:149], v[180:183], v[62:65]
	v_mfma_f32_16x16x32_bf16 v[58:61], v[154:157], v[180:183], v[58:61]
	v_mfma_f32_16x16x32_bf16 v[46:49], v[146:149], v[188:191], v[46:49]
	v_mfma_f32_16x16x32_bf16 v[42:45], v[154:157], v[188:191], v[42:45]
	v_mfma_f32_16x16x32_bf16 v[30:33], v[146:149], v[196:199], v[30:33]
	v_mfma_f32_16x16x32_bf16 v[26:29], v[154:157], v[196:199], v[26:29]
	v_mfma_f32_16x16x32_bf16 v[14:17], v[146:149], v[204:207], v[14:17]
	v_mfma_f32_16x16x32_bf16 v[10:13], v[154:157], v[204:207], v[10:13]
	v_mfma_f32_16x16x32_bf16 v[62:65], v[150:153], v[184:187], v[62:65]
	v_mfma_f32_16x16x32_bf16 v[58:61], v[158:161], v[184:187], v[58:61]
	v_mfma_f32_16x16x32_bf16 v[46:49], v[150:153], v[192:195], v[46:49]
	v_mfma_f32_16x16x32_bf16 v[42:45], v[158:161], v[192:195], v[42:45]
	v_mfma_f32_16x16x32_bf16 v[30:33], v[150:153], v[200:203], v[30:33]
	v_mfma_f32_16x16x32_bf16 v[26:29], v[158:161], v[200:203], v[26:29]
	v_mfma_f32_16x16x32_bf16 v[14:17], v[150:153], v[208:211], v[14:17]
	v_mfma_f32_16x16x32_bf16 v[10:13], v[158:161], v[208:211], v[10:13]
	s_setprio 0
	s_setprio 1
	v_mfma_f32_16x16x32_bf16 v[54:57], v[164:167], v[180:183], v[54:57]
	v_mfma_f32_16x16x32_bf16 v[50:53], v[172:175], v[180:183], v[50:53]
	v_mfma_f32_16x16x32_bf16 v[38:41], v[164:167], v[188:191], v[38:41]
	v_mfma_f32_16x16x32_bf16 v[34:37], v[172:175], v[188:191], v[34:37]
	v_mfma_f32_16x16x32_bf16 v[22:25], v[164:167], v[196:199], v[22:25]
	v_mfma_f32_16x16x32_bf16 v[18:21], v[172:175], v[196:199], v[18:21]
	v_mfma_f32_16x16x32_bf16 v[6:9], v[164:167], v[204:207], v[6:9]
	v_mfma_f32_16x16x32_bf16 v[2:5], v[172:175], v[204:207], v[2:5]
	v_mfma_f32_16x16x32_bf16 v[54:57], v[168:171], v[184:187], v[54:57]
	v_mfma_f32_16x16x32_bf16 v[50:53], v[176:179], v[184:187], v[50:53]
	v_mfma_f32_16x16x32_bf16 v[38:41], v[168:171], v[192:195], v[38:41]
	v_mfma_f32_16x16x32_bf16 v[34:37], v[176:179], v[192:195], v[34:37]
	v_mfma_f32_16x16x32_bf16 v[22:25], v[168:171], v[200:203], v[22:25]
	v_mfma_f32_16x16x32_bf16 v[18:21], v[176:179], v[200:203], v[18:21]
	v_mfma_f32_16x16x32_bf16 v[6:9], v[168:171], v[208:211], v[6:9]
	v_mfma_f32_16x16x32_bf16 v[2:5], v[176:179], v[208:211], v[2:5]
	s_setprio 0
	s_barrier
; #define PG8_STAGE(bufoff, gbase, voff) do { _Pragma("unroll") for (int _i = 0; _i < 2; ++_i) \
;         __builtin_amdgcn_global_load_lds((const unsigned*)((const char*)(gbase) + (voff)[_i]), (LAS unsigned*)(lds + (bufoff) + ldsw + _i * 8192), 16, 0, 0); } while (0)
; #define PG8_LDA(dst, b, h) do { _Pragma("unroll") for (int m = 0; m < 4; ++m) _Pragma("unroll") for (int k = 0; k < 2; ++k) dst[m][k] = *(const LAS bf16x8*)(lds + PG8_SA(b, h) + aoff + m * 2048 + k * 1024); } while (0)
; #define PG8_LDB(dst, b, h) do { _Pragma("unroll") for (int n = 0; n < 2; ++n) _Pragma("unroll") for (int k = 0; k < 2; ++k) dst[n][k] = *(const LAS bf16x8*)(lds + PG8_SB(b, h) + boff + n * 2048 + k * 1024); } while (0)
; #define PG8_MMA(ai, bj, At, Bt) do { __builtin_amdgcn_s_setprio(1); _Pragma("unroll") for (int m = 0; m < 4; ++m) _Pragma("unroll") for (int n = 0; n < 2; ++n) _Pragma("unroll") for (int k = 0; k < 2; ++k) \
;         acc[ai][bj][m][n] = __builtin_amdgcn_mfma_f32_16x16x32_bf16(Bt[n][k], At[m][k], acc[ai][bj][m][n], 0, 0, 0); __builtin_amdgcn_s_setprio(0); } while (0)
; #define PG8_WAIT_V(n) asm volatile("s_waitcnt vmcnt(" #n ")" ::: "memory")
; #define PG8_WAIT_L(n) asm volatile("s_waitcnt lgkmcnt(" #n ")" ::: "memory")
; #define PG8_BAR __builtin_amdgcn_s_barrier()
; #define PG8_SCHED __builtin_amdgcn_sched_barrier(0)
; template <class Epi, bool MID = false>
; __device__ __forceinline__ void gemm_phase(LAS unsigned char* lds, const Gemm g, const StaticOrder& S, const Epi& E) {
;     ...
;             PG8_LDB(B0, 1, 0); PG8_LDB(B1, 1, 1); PG8_SCHED; PG8_LDA(At, 1, 0); PG8_STAGE(PG8_SA(0, 1), a2 + hstepA, voffA);
;             PG8_WAIT_V(8); PG8_WAIT_L(0); PG8_BAR; PG8_MMA(0, 0, At, B0); PG8_MMA(0, 1, At, B1); PG8_BAR; PG8_SCHED;
;             PG8_LDA(At, 1, 1); PG8_STAGE(PG8_SB(1, 0), b3, voffB); PG8_STAGE(PG8_SB(1, 1), b3 + hstepB, voffB); PG8_STAGE(PG8_SA(1, 0), a3, voffA);
;             PG8_WAIT_V(8); PG8_WAIT_L(0); PG8_BAR; PG8_MMA(1, 0, At, B0); PG8_MMA(1, 1, At, B1); PG8_BAR; PG8_SCHED;
	s_add_i32 s4, 0, 0x18000
	s_add_i32 s5, 0, 0x1c000
	v_add_u32_e32 v158, s4, v143
	v_add_u32_e32 v176, s5, v143
	ds_read_b128 v[146:149], v158
	ds_read_b128 v[150:153], v158 offset:1024
	ds_read_b128 v[154:157], v158 offset:2048
	ds_read_b128 v[158:161], v158 offset:3072
	ds_read_b128 v[164:167], v176
	ds_read_b128 v[168:171], v176 offset:1024
	ds_read_b128 v[172:175], v176 offset:2048
	ds_read_b128 v[176:179], v176 offset:3072
	s_add_u32 s62, s62, 0x40000
	s_addc_u32 s63, s63, 0
	s_mov_b32 m0, s75
	v_lshl_add_u64 v[232:233], s[62:63], 0, v[130:131]
	ds_read_b128 v[180:183], v145 offset:32768
	ds_read_b128 v[184:187], v145 offset:33792
	ds_read_b128 v[188:191], v145 offset:34816
	ds_read_b128 v[192:195], v145 offset:35840
	ds_read_b128 v[196:199], v145 offset:36864
	ds_read_b128 v[200:203], v145 offset:37888
	ds_read_b128 v[204:207], v145 offset:38912
	ds_read_b128 v[208:211], v145 offset:39936
	global_load_lds_dwordx4 v[232:233], off
	v_lshl_add_u64 v[232:233], s[62:63], 0, v[132:133]
	s_mov_b32 m0, s78
	s_nop 0
	global_load_lds_dwordx4 v[232:233], off
	s_waitcnt vmcnt(8)
	s_waitcnt lgkmcnt(0)
	s_barrier
	s_setprio 1
	s_waitcnt lgkmcnt(0)
	v_mfma_f32_16x16x32_bf16 v[126:129], v[146:149], v[180:183], v[126:129]
	v_mfma_f32_16x16x32_bf16 v[122:125], v[154:157], v[180:183], v[122:125]
	v_mfma_f32_16x16x32_bf16 v[110:113], v[146:149], v[188:191], v[110:113]
	v_mfma_f32_16x16x32_bf16 v[106:109], v[154:157], v[188:191], v[106:109]
	v_mfma_f32_16x16x32_bf16 v[94:97], v[146:149], v[196:199], v[94:97]
	v_mfma_f32_16x16x32_bf16 v[90:93], v[154:157], v[196:199], v[90:93]
	v_mfma_f32_16x16x32_bf16 v[78:81], v[146:149], v[204:207], v[78:81]
	v_mfma_f32_16x16x32_bf16 v[74:77], v[154:157], v[204:207], v[74:77]
	v_mfma_f32_16x16x32_bf16 v[126:129], v[150:153], v[184:187], v[126:129]
	v_mfma_f32_16x16x32_bf16 v[122:125], v[158:161], v[184:187], v[122:125]
	v_mfma_f32_16x16x32_bf16 v[110:113], v[150:153], v[192:195], v[110:113]
	v_mfma_f32_16x16x32_bf16 v[106:109], v[158:161], v[192:195], v[106:109]
	v_mfma_f32_16x16x32_bf16 v[94:97], v[150:153], v[200:203], v[94:97]
	v_mfma_f32_16x16x32_bf16 v[90:93], v[158:161], v[200:203], v[90:93]
	v_mfma_f32_16x16x32_bf16 v[78:81], v[150:153], v[208:211], v[78:81]
	v_mfma_f32_16x16x32_bf16 v[74:77], v[158:161], v[208:211], v[74:77]
	s_setprio 0
	s_setprio 1
	v_mfma_f32_16x16x32_bf16 v[118:121], v[164:167], v[180:183], v[118:121]
	v_mfma_f32_16x16x32_bf16 v[114:117], v[172:175], v[180:183], v[114:117]
	v_mfma_f32_16x16x32_bf16 v[102:105], v[164:167], v[188:191], v[102:105]
	v_mfma_f32_16x16x32_bf16 v[98:101], v[172:175], v[188:191], v[98:101]
	v_mfma_f32_16x16x32_bf16 v[86:89], v[164:167], v[196:199], v[86:89]
	v_mfma_f32_16x16x32_bf16 v[82:85], v[172:175], v[196:199], v[82:85]
	v_mfma_f32_16x16x32_bf16 v[70:73], v[164:167], v[204:207], v[70:73]
	v_mfma_f32_16x16x32_bf16 v[66:69], v[172:175], v[204:207], v[66:69]
	v_mfma_f32_16x16x32_bf16 v[118:121], v[168:171], v[184:187], v[118:121]
	v_mfma_f32_16x16x32_bf16 v[114:117], v[176:179], v[184:187], v[114:117]
	v_mfma_f32_16x16x32_bf16 v[102:105], v[168:171], v[192:195], v[102:105]
	v_mfma_f32_16x16x32_bf16 v[98:101], v[176:179], v[192:195], v[98:101]
	v_mfma_f32_16x16x32_bf16 v[86:89], v[168:171], v[200:203], v[86:89]
	v_mfma_f32_16x16x32_bf16 v[82:85], v[176:179], v[200:203], v[82:85]
	v_mfma_f32_16x16x32_bf16 v[70:73], v[168:171], v[208:211], v[70:73]
	v_mfma_f32_16x16x32_bf16 v[66:69], v[176:179], v[208:211], v[66:69]
	s_setprio 0
	s_barrier
	s_add_i32 s4, s4, s70
	v_lshl_add_u64 v[140:141], v[140:141], 0, s[24:25]
	s_mov_b32 m0, s4
	ds_read_b128 v[180:183], v145 offset:49152
	ds_read_b128 v[184:187], v145 offset:50176
	ds_read_b128 v[188:191], v145 offset:51200
	ds_read_b128 v[192:195], v145 offset:52224
	ds_read_b128 v[196:199], v145 offset:53248
	ds_read_b128 v[200:203], v145 offset:54272
	ds_read_b128 v[204:207], v145 offset:55296
	ds_read_b128 v[208:211], v145 offset:56320
	global_load_lds_dwordx4 v[140:141], off
	s_add_i32 m0, s4, 0x2000
	s_add_u32 s60, s60, 0x40080
	v_lshl_add_u64 v[140:141], v[212:213], 0, s[24:25]
	s_addc_u32 s61, s61, 0
	s_add_i32 s4, s5, s70
	global_load_lds_dwordx4 v[140:141], off
	v_lshl_add_u64 v[140:141], s[60:61], 0, v[0:1]
	s_mov_b32 m0, s4
	s_nop 0
	global_load_lds_dwordx4 v[140:141], off
	v_lshl_add_u64 v[140:141], s[60:61], 0, v[134:135]
	s_add_i32 m0, s4, 0x2000
	s_nop 0
	global_load_lds_dwordx4 v[140:141], off
	v_lshl_add_u64 v[140:141], v[214:215], 0, s[24:25]
	s_mov_b32 m0, s79
	s_nop 0
	global_load_lds_dwordx4 v[140:141], off
	v_lshl_add_u64 v[140:141], v[230:231], 0, s[24:25]
	s_mov_b32 m0, s80
	s_nop 0
	global_load_lds_dwordx4 v[140:141], off
	s_waitcnt vmcnt(8)
	s_waitcnt lgkmcnt(0)
	s_barrier
; #define PG8_MMA(ai, bj, At, Bt) do { __builtin_amdgcn_s_setprio(1); _Pragma("unroll") for (int m = 0; m < 4; ++m) _Pragma("unroll") for (int n = 0; n < 2; ++n) _Pragma("unroll") for (int k = 0; k < 2; ++k) \
;         acc[ai][bj][m][n] = __builtin_amdgcn_mfma_f32_16x16x32_bf16(Bt[n][k], At[m][k], acc[ai][bj][m][n], 0, 0, 0); __builtin_amdgcn_s_setprio(0); } while (0)
; #define PG8_WAIT_V(n) asm volatile("s_waitcnt vmcnt(" #n ")" ::: "memory")
; #define PG8_WAIT_L(n) asm volatile("s_waitcnt lgkmcnt(" #n ")" ::: "memory")
; #define PG8_BAR __builtin_amdgcn_s_barrier()
; #define PG8_SCHED __builtin_amdgcn_sched_barrier(0)
; __device__ __forceinline__ u32x4 pack8(f32x4 a, f32x4 b) { u32x4 w; w.x = cvt_pk_bf16(a[0], a[1]); w.y = cvt_pk_bf16(a[2], a[3]); w.z = cvt_pk_bf16(b[0], b[1]); w.w = cvt_pk_bf16(b[2], b[3]); return w; }
; template <class Epi, bool MID = false>
; __device__ __forceinline__ void gemm_phase(LAS unsigned char* lds, const Gemm g, const StaticOrder& S, const Epi& E) {
;     ...
;             PG8_WAIT_V(8); PG8_WAIT_L(0); PG8_BAR; PG8_MMA(1, 0, At, B0); PG8_MMA(1, 1, At, B1); PG8_BAR; PG8_SCHED;
;             if constexpr (MID) { if (t == 6) E.mid(acc, cur, wr, wc, fr, fq); }
;         }
;         if (wr == 0) PG8_BAR;
;     __device__ __forceinline__ void operator()(const f32x4 (&acc)[2][2][4][2], const Unit& u, int wr, int wc, int fr, int fq) const {
;     ...
;                 for (int bj = 0; bj < 2; ++bj) {
;                     f32x4 v0 = acc[ai][bj][m][0], v1 = acc[ai][bj][m][1];
; #pragma unroll
;                     for (int i = 0; i < 4; ++i) { const float a = fmaxf(v0[i], 0.f), b = fmaxf(v1[i], 0.f); v0[i] = a * a; v1[i] = b * b; }
;                     *(u32x4*)(H + (size_t)row * FF + colb + bj * 128) = pack8(v0, v1);
	s_setprio 1
	s_waitcnt lgkmcnt(0)
	v_mfma_f32_16x16x32_bf16 v[62:65], v[146:149], v[180:183], v[62:65]
	v_mfma_f32_16x16x32_bf16 v[58:61], v[154:157], v[180:183], v[58:61]
	v_mfma_f32_16x16x32_bf16 v[46:49], v[146:149], v[188:191], v[46:49]
	v_mfma_f32_16x16x32_bf16 v[42:45], v[154:157], v[188:191], v[42:45]
	v_mfma_f32_16x16x32_bf16 v[30:33], v[146:149], v[196:199], v[30:33]
	v_mfma_f32_16x16x32_bf16 v[26:29], v[154:157], v[196:199], v[26:29]
	v_mfma_f32_16x16x32_bf16 v[14:17], v[146:149], v[204:207], v[14:17]
	v_mfma_f32_16x16x32_bf16 v[10:13], v[154:157], v[204:207], v[10:13]
	v_mfma_f32_16x16x32_bf16 v[62:65], v[150:153], v[184:187], v[62:65]
	v_mfma_f32_16x16x32_bf16 v[58:61], v[158:161], v[184:187], v[58:61]
	v_mfma_f32_16x16x32_bf16 v[46:49], v[150:153], v[192:195], v[46:49]
	v_mfma_f32_16x16x32_bf16 v[42:45], v[158:161], v[192:195], v[42:45]
	v_mfma_f32_16x16x32_bf16 v[30:33], v[150:153], v[200:203], v[30:33]
	v_mfma_f32_16x16x32_bf16 v[26:29], v[158:161], v[200:203], v[26:29]
	v_mfma_f32_16x16x32_bf16 v[14:17], v[150:153], v[208:211], v[14:17]
	v_mfma_f32_16x16x32_bf16 v[10:13], v[158:161], v[208:211], v[10:13]
	s_setprio 0
	s_setprio 1
	v_mfma_f32_16x16x32_bf16 v[54:57], v[164:167], v[180:183], v[54:57]
	v_mfma_f32_16x16x32_bf16 v[50:53], v[172:175], v[180:183], v[50:53]
	v_mfma_f32_16x16x32_bf16 v[38:41], v[164:167], v[188:191], v[38:41]
	v_mfma_f32_16x16x32_bf16 v[34:37], v[172:175], v[188:191], v[34:37]
	v_mfma_f32_16x16x32_bf16 v[22:25], v[164:167], v[196:199], v[22:25]
	v_mfma_f32_16x16x32_bf16 v[18:21], v[172:175], v[196:199], v[18:21]
	v_mfma_f32_16x16x32_bf16 v[6:9], v[164:167], v[204:207], v[6:9]
	v_mfma_f32_16x16x32_bf16 v[2:5], v[172:175], v[204:207], v[2:5]
	v_mfma_f32_16x16x32_bf16 v[54:57], v[168:171], v[184:187], v[54:57]
	v_mfma_f32_16x16x32_bf16 v[50:53], v[176:179], v[184:187], v[50:53]
	v_mfma_f32_16x16x32_bf16 v[38:41], v[168:171], v[192:195], v[38:41]
	v_mfma_f32_16x16x32_bf16 v[34:37], v[176:179], v[192:195], v[34:37]
	v_mfma_f32_16x16x32_bf16 v[22:25], v[168:171], v[200:203], v[22:25]
	v_mfma_f32_16x16x32_bf16 v[18:21], v[176:179], v[200:203], v[18:21]
	v_mfma_f32_16x16x32_bf16 v[6:9], v[168:171], v[208:211], v[6:9]
	v_mfma_f32_16x16x32_bf16 v[2:5], v[176:179], v[208:211], v[2:5]
	s_setprio 0
	s_barrier
	s_add_u32 s58, s58, 0x100
	s_addc_u32 s59, s59, 0
	s_add_u32 s85, s85, 0x100
	s_addc_u32 s86, s86, 0
	s_cmp_ge_i32 s87, s65
	s_mov_b32 s60, s87
	s_cbranch_scc0 .LBB0_1459
.Lpk_1459_exit:
	s_and_b64 vcc, exec, s[42:43]
	s_cbranch_vccz .LBB0_1462
.LBB0_1461:
	s_barrier
.LBB0_1462:
	v_lshl_add_u32 v140, s56, 8, v142
	v_ashrrev_i32_e32 v141, 31, v140
	v_max_f32_e32 v124, 0, v124
	v_lshlrev_b64 v[148:149], 13, v[140:141]
	v_mul_f32_e32 v141, v124, v124
	v_lshl_or_b32 v146, s72, 8, v144
	v_max_f32_e32 v126, 0, v126
	v_max_f32_e32 v122, 0, v122
	v_max_f32_e32 v123, 0, v123
	v_max_f32_e32 v128, 0, v128
	v_max_f32_e32 v124, 0, v129
	v_ashrrev_i32_e32 v147, 31, v146
	v_mul_f32_e32 v126, v126, v126
	v_mul_f32_e32 v122, v122, v122
	v_max_f32_e32 v127, 0, v127
	v_mul_f32_e32 v123, v123, v123
	v_mul_f32_e32 v128, v128, v128
	v_max_f32_e32 v125, 0, v125
	v_mul_f32_e32 v129, v124, v124
	v_mul_f32_e32 v127, v127, v127
	v_mul_f32_e32 v150, v125, v125
	v_cvt_pk_bf16_f32 v124, v126, v127
	v_cvt_pk_bf16_f32 v125, v128, v129
	v_cvt_pk_bf16_f32 v126, v122, v123
	v_lshl_add_u64 v[128:129], s[18:19], 0, v[148:149]
	v_lshlrev_b64 v[122:123], 1, v[146:147]
	v_lshl_add_u64 v[128:129], v[128:129], 0, v[122:123]
	v_max_f32_e32 v114, 0, v114
	v_max_f32_e32 v115, 0, v115
	v_max_f32_e32 v116, 0, v116
	v_cvt_pk_bf16_f32 v127, v141, v150
	global_store_dwordx4 v[128:129], v[124:127], off
	s_nop 1
	v_mul_f32_e32 v124, v114, v114
	v_max_f32_e32 v114, v119, v119
	v_mul_f32_e32 v119, v115, v115
	v_max_f32_e32 v115, v120, v120
	v_mul_f32_e32 v120, v116, v116
	v_max_f32_e32 v114, 0, v114
	v_max_f32_e32 v115, 0, v115
	v_max_f32_e32 v116, 0, v121
	v_max_f32_e32 v118, 0, v118
	v_mul_f32_e32 v114, v114, v114
	v_mul_f32_e32 v115, v115, v115
	v_max_f32_e32 v117, 0, v117
	v_mul_f32_e32 v116, v116, v116
	v_mul_f32_e32 v118, v118, v118
	v_mul_f32_e32 v117, v117, v117
	v_cvt_pk_bf16_f32 v114, v118, v114
	v_cvt_pk_bf16_f32 v115, v115, v116
	v_cvt_pk_bf16_f32 v116, v124, v119
	v_max_f32_e32 v106, 0, v106
	v_max_f32_e32 v107, 0, v107
	v_max_f32_e32 v108, 0, v108
	v_cvt_pk_bf16_f32 v117, v120, v117
	global_store_dwordx4 v[128:129], v[114:117], off offset:256
	s_nop 1
	v_max_f32_e32 v110, 0, v110
	v_or_b32_e32 v114, 16, v140
	v_mul_f32_e32 v116, v106, v106
	v_max_f32_e32 v106, v111, v111
	v_mul_f32_e32 v111, v107, v107
	v_max_f32_e32 v107, v112, v112
	v_mul_f32_e32 v112, v108, v108
	v_ashrrev_i32_e32 v115, 31, v114
	v_max_f32_e32 v106, 0, v106
	v_max_f32_e32 v107, 0, v107
	v_max_f32_e32 v108, 0, v113
	v_lshlrev_b64 v[114:115], 13, v[114:115]
	v_mul_f32_e32 v110, v110, v110
	v_mul_f32_e32 v106, v106, v106
	v_mul_f32_e32 v107, v107, v107
	v_mul_f32_e32 v108, v108, v108
	v_max_f32_e32 v109, 0, v109
	v_cvt_pk_bf16_f32 v106, v110, v106
	v_cvt_pk_bf16_f32 v107, v107, v108
	v_cvt_pk_bf16_f32 v108, v116, v111
	v_lshl_add_u64 v[110:111], s[18:19], 0, v[114:115]
	v_mul_f32_e32 v109, v109, v109
	v_lshl_add_u64 v[110:111], v[110:111], 0, v[122:123]
	v_max_f32_e32 v98, 0, v98
	v_max_f32_e32 v99, 0, v99
	v_max_f32_e32 v100, 0, v100
	v_cvt_pk_bf16_f32 v109, v112, v109
	global_store_dwordx4 v[110:111], v[106:109], off
	s_nop 1
	v_mul_f32_e32 v106, v98, v98
	v_max_f32_e32 v98, v103, v103
	v_mul_f32_e32 v103, v99, v99
	v_max_f32_e32 v99, v104, v104
	v_mul_f32_e32 v104, v100, v100
	v_max_f32_e32 v98, 0, v98
	v_max_f32_e32 v99, 0, v99
	v_max_f32_e32 v100, 0, v105
; __device__ __forceinline__ u32x4 pack8(f32x4 a, f32x4 b) { u32x4 w; w.x = cvt_pk_bf16(a[0], a[1]); w.y = cvt_pk_bf16(a[2], a[3]); w.z = cvt_pk_bf16(b[0], b[1]); w.w = cvt_pk_bf16(b[2], b[3]); return w; }
;     __device__ __forceinline__ void operator()(const f32x4 (&acc)[2][2][4][2], const Unit& u, int wr, int wc, int fr, int fq) const {
;     ...
;         for (int ai = 0; ai < 2; ++ai)
; #pragma unroll
;             for (int m = 0; m < 4; ++m) {
;                 const int row = u.pm * 256 + ai * 128 + wr * 64 + m * 16 + fr;
; #pragma unroll
;                 for (int bj = 0; bj < 2; ++bj) {
;                     f32x4 v0 = acc[ai][bj][m][0], v1 = acc[ai][bj][m][1];
; #pragma unroll
;                     for (int i = 0; i < 4; ++i) { const float a = fmaxf(v0[i], 0.f), b = fmaxf(v1[i], 0.f); v0[i] = a * a; v1[i] = b * b; }
;                     *(u32x4*)(H + (size_t)row * FF + colb + bj * 128) = pack8(v0, v1);
	v_max_f32_e32 v102, 0, v102
	v_mul_f32_e32 v98, v98, v98
	v_mul_f32_e32 v99, v99, v99
	v_max_f32_e32 v101, 0, v101
	v_mul_f32_e32 v100, v100, v100
	v_mul_f32_e32 v102, v102, v102
	v_mul_f32_e32 v101, v101, v101
	v_cvt_pk_bf16_f32 v98, v102, v98
	v_cvt_pk_bf16_f32 v99, v99, v100
	v_cvt_pk_bf16_f32 v100, v106, v103
	v_max_f32_e32 v90, 0, v90
	v_max_f32_e32 v91, 0, v91
	v_max_f32_e32 v92, 0, v92
	v_cvt_pk_bf16_f32 v101, v104, v101
	global_store_dwordx4 v[110:111], v[98:101], off offset:256
	s_nop 1
	v_max_f32_e32 v94, 0, v94
	v_or_b32_e32 v98, 32, v140
	v_mul_f32_e32 v100, v90, v90
	v_max_f32_e32 v90, v95, v95
	v_mul_f32_e32 v95, v91, v91
	v_max_f32_e32 v91, v96, v96
	v_mul_f32_e32 v96, v92, v92
	v_ashrrev_i32_e32 v99, 31, v98
	v_max_f32_e32 v90, 0, v90
	v_max_f32_e32 v91, 0, v91
	v_max_f32_e32 v92, 0, v97
	v_lshlrev_b64 v[98:99], 13, v[98:99]
	v_mul_f32_e32 v94, v94, v94
	v_mul_f32_e32 v90, v90, v90
	v_mul_f32_e32 v91, v91, v91
	v_mul_f32_e32 v92, v92, v92
	v_max_f32_e32 v93, 0, v93
	v_cvt_pk_bf16_f32 v90, v94, v90
	v_cvt_pk_bf16_f32 v91, v91, v92
	v_cvt_pk_bf16_f32 v92, v100, v95
	v_lshl_add_u64 v[94:95], s[18:19], 0, v[98:99]
	v_mul_f32_e32 v93, v93, v93
	v_lshl_add_u64 v[94:95], v[94:95], 0, v[122:123]
	v_max_f32_e32 v82, 0, v82
	v_max_f32_e32 v83, 0, v83
	v_max_f32_e32 v84, 0, v84
	v_cvt_pk_bf16_f32 v93, v96, v93
	global_store_dwordx4 v[94:95], v[90:93], off
	s_nop 1
	v_mul_f32_e32 v90, v82, v82
	v_max_f32_e32 v82, v87, v87
	v_mul_f32_e32 v87, v83, v83
	v_max_f32_e32 v83, v88, v88
	v_mul_f32_e32 v88, v84, v84
	v_max_f32_e32 v82, 0, v82
	v_max_f32_e32 v83, 0, v83
	v_max_f32_e32 v84, 0, v89
	v_max_f32_e32 v86, 0, v86
	v_mul_f32_e32 v82, v82, v82
	v_mul_f32_e32 v83, v83, v83
	v_max_f32_e32 v85, 0, v85
	v_mul_f32_e32 v84, v84, v84
	v_mul_f32_e32 v86, v86, v86
	v_mul_f32_e32 v85, v85, v85
	v_cvt_pk_bf16_f32 v82, v86, v82
	v_cvt_pk_bf16_f32 v83, v83, v84
	v_cvt_pk_bf16_f32 v84, v90, v87
	v_max_f32_e32 v74, 0, v74
	v_max_f32_e32 v75, 0, v75
	v_max_f32_e32 v76, 0, v76
	v_cvt_pk_bf16_f32 v85, v88, v85
	global_store_dwordx4 v[94:95], v[82:85], off offset:256
	s_nop 1
	v_max_f32_e32 v78, 0, v78
	v_or_b32_e32 v82, 48, v140
	v_mul_f32_e32 v84, v74, v74
	v_max_f32_e32 v74, v79, v79
	v_mul_f32_e32 v79, v75, v75
	v_max_f32_e32 v75, v80, v80
	v_mul_f32_e32 v80, v76, v76
	v_ashrrev_i32_e32 v83, 31, v82
	v_max_f32_e32 v74, 0, v74
	v_max_f32_e32 v75, 0, v75
	v_max_f32_e32 v76, 0, v81
	v_lshlrev_b64 v[82:83], 13, v[82:83]
	v_mul_f32_e32 v78, v78, v78
	v_mul_f32_e32 v74, v74, v74
	v_mul_f32_e32 v75, v75, v75
	v_mul_f32_e32 v76, v76, v76
	v_max_f32_e32 v77, 0, v77
	v_cvt_pk_bf16_f32 v74, v78, v74
	v_cvt_pk_bf16_f32 v75, v75, v76
	v_cvt_pk_bf16_f32 v76, v84, v79
	v_lshl_add_u64 v[78:79], s[18:19], 0, v[82:83]
	v_mul_f32_e32 v77, v77, v77
	v_lshl_add_u64 v[78:79], v[78:79], 0, v[122:123]
	v_max_f32_e32 v66, 0, v66
	v_max_f32_e32 v67, 0, v67
	v_max_f32_e32 v68, 0, v68
	v_cvt_pk_bf16_f32 v77, v80, v77
	global_store_dwordx4 v[78:79], v[74:77], off
	s_nop 1
	v_mul_f32_e32 v74, v66, v66
	v_max_f32_e32 v66, v71, v71
	v_mul_f32_e32 v71, v67, v67
	v_max_f32_e32 v67, v72, v72
	v_mul_f32_e32 v72, v68, v68
	v_max_f32_e32 v66, 0, v66
	v_max_f32_e32 v67, 0, v67
	v_max_f32_e32 v68, 0, v73
	v_max_f32_e32 v70, 0, v70
	v_mul_f32_e32 v66, v66, v66
	v_mul_f32_e32 v67, v67, v67
	v_max_f32_e32 v69, 0, v69
	v_mul_f32_e32 v68, v68, v68
	v_mul_f32_e32 v70, v70, v70
	v_mul_f32_e32 v69, v69, v69
	v_cvt_pk_bf16_f32 v66, v70, v66
	v_cvt_pk_bf16_f32 v67, v67, v68
	v_cvt_pk_bf16_f32 v68, v74, v71
	v_max_f32_e32 v58, 0, v58
	v_max_f32_e32 v59, 0, v59
	v_max_f32_e32 v60, 0, v60
	v_cvt_pk_bf16_f32 v69, v72, v69
	global_store_dwordx4 v[78:79], v[66:69], off offset:256
	s_nop 1
	v_max_f32_e32 v62, 0, v62
	v_add_u32_e32 v66, 0x80, v140
	v_mul_f32_e32 v68, v58, v58
	v_max_f32_e32 v58, v63, v63
	v_mul_f32_e32 v63, v59, v59
	v_max_f32_e32 v59, v64, v64
	v_mul_f32_e32 v64, v60, v60
	v_ashrrev_i32_e32 v67, 31, v66
	v_max_f32_e32 v58, 0, v58
	v_max_f32_e32 v59, 0, v59
	v_max_f32_e32 v60, 0, v65
	v_lshlrev_b64 v[66:67], 13, v[66:67]
	v_mul_f32_e32 v62, v62, v62
	v_mul_f32_e32 v58, v58, v58
	v_mul_f32_e32 v59, v59, v59
	v_mul_f32_e32 v60, v60, v60
	v_max_f32_e32 v61, 0, v61
	v_cvt_pk_bf16_f32 v58, v62, v58
	v_cvt_pk_bf16_f32 v59, v59, v60
	v_cvt_pk_bf16_f32 v60, v68, v63
	v_lshl_add_u64 v[62:63], s[18:19], 0, v[66:67]
	v_mul_f32_e32 v61, v61, v61
	v_lshl_add_u64 v[62:63], v[62:63], 0, v[122:123]
	v_max_f32_e32 v50, 0, v50
	v_max_f32_e32 v51, 0, v51
	v_max_f32_e32 v52, 0, v52
	v_cvt_pk_bf16_f32 v61, v64, v61
	global_store_dwordx4 v[62:63], v[58:61], off
	s_nop 1
	v_mul_f32_e32 v58, v50, v50
	v_max_f32_e32 v50, v55, v55
	v_mul_f32_e32 v55, v51, v51
	v_max_f32_e32 v51, v56, v56
	v_mul_f32_e32 v56, v52, v52
	v_max_f32_e32 v50, 0, v50
	v_max_f32_e32 v51, 0, v51
	v_max_f32_e32 v52, 0, v57
	v_max_f32_e32 v54, 0, v54
	v_mul_f32_e32 v50, v50, v50
	v_mul_f32_e32 v51, v51, v51
	v_max_f32_e32 v53, 0, v53
	v_mul_f32_e32 v52, v52, v52
	v_mul_f32_e32 v54, v54, v54
	v_mul_f32_e32 v53, v53, v53
	v_cvt_pk_bf16_f32 v50, v54, v50
; __device__ __forceinline__ u32x4 pack8(f32x4 a, f32x4 b) { u32x4 w; w.x = cvt_pk_bf16(a[0], a[1]); w.y = cvt_pk_bf16(a[2], a[3]); w.z = cvt_pk_bf16(b[0], b[1]); w.w = cvt_pk_bf16(b[2], b[3]); return w; }
;     __device__ __forceinline__ void operator()(const f32x4 (&acc)[2][2][4][2], const Unit& u, int wr, int wc, int fr, int fq) const {
;     ...
;         for (int ai = 0; ai < 2; ++ai)
; #pragma unroll
;             for (int m = 0; m < 4; ++m) {
;                 const int row = u.pm * 256 + ai * 128 + wr * 64 + m * 16 + fr;
; #pragma unroll
;                 for (int bj = 0; bj < 2; ++bj) {
;                     f32x4 v0 = acc[ai][bj][m][0], v1 = acc[ai][bj][m][1];
; #pragma unroll
;                     for (int i = 0; i < 4; ++i) { const float a = fmaxf(v0[i], 0.f), b = fmaxf(v1[i], 0.f); v0[i] = a * a; v1[i] = b * b; }
;                     *(u32x4*)(H + (size_t)row * FF + colb + bj * 128) = pack8(v0, v1);
	v_cvt_pk_bf16_f32 v51, v51, v52
	v_cvt_pk_bf16_f32 v52, v58, v55
	v_max_f32_e32 v42, 0, v42
	v_max_f32_e32 v43, 0, v43
	v_max_f32_e32 v44, 0, v44
	v_cvt_pk_bf16_f32 v53, v56, v53
	global_store_dwordx4 v[62:63], v[50:53], off offset:256
	s_nop 1
	v_max_f32_e32 v46, 0, v46
	v_add_u32_e32 v50, 0x90, v140
	v_mul_f32_e32 v52, v42, v42
	v_max_f32_e32 v42, v47, v47
	v_mul_f32_e32 v47, v43, v43
	v_max_f32_e32 v43, v48, v48
	v_mul_f32_e32 v48, v44, v44
	v_ashrrev_i32_e32 v51, 31, v50
	v_max_f32_e32 v42, 0, v42
	v_max_f32_e32 v43, 0, v43
	v_max_f32_e32 v44, 0, v49
	v_lshlrev_b64 v[50:51], 13, v[50:51]
	v_mul_f32_e32 v46, v46, v46
	v_mul_f32_e32 v42, v42, v42
	v_mul_f32_e32 v43, v43, v43
	v_mul_f32_e32 v44, v44, v44
	v_max_f32_e32 v45, 0, v45
	v_cvt_pk_bf16_f32 v42, v46, v42
	v_cvt_pk_bf16_f32 v43, v43, v44
	v_cvt_pk_bf16_f32 v44, v52, v47
	v_lshl_add_u64 v[46:47], s[18:19], 0, v[50:51]
	v_mul_f32_e32 v45, v45, v45
	v_lshl_add_u64 v[46:47], v[46:47], 0, v[122:123]
	v_max_f32_e32 v34, 0, v34
	v_max_f32_e32 v35, 0, v35
	v_max_f32_e32 v36, 0, v36
	v_cvt_pk_bf16_f32 v45, v48, v45
	global_store_dwordx4 v[46:47], v[42:45], off
	s_nop 1
	v_mul_f32_e32 v42, v34, v34
	v_max_f32_e32 v34, v39, v39
	v_mul_f32_e32 v39, v35, v35
	v_max_f32_e32 v35, v40, v40
	v_mul_f32_e32 v40, v36, v36
	v_max_f32_e32 v34, 0, v34
	v_max_f32_e32 v35, 0, v35
	v_max_f32_e32 v36, 0, v41
	v_max_f32_e32 v38, 0, v38
	v_mul_f32_e32 v34, v34, v34
	v_mul_f32_e32 v35, v35, v35
	v_max_f32_e32 v37, 0, v37
	v_mul_f32_e32 v36, v36, v36
	v_mul_f32_e32 v38, v38, v38
	v_mul_f32_e32 v37, v37, v37
	v_cvt_pk_bf16_f32 v34, v38, v34
	v_cvt_pk_bf16_f32 v35, v35, v36
	v_cvt_pk_bf16_f32 v36, v42, v39
	v_max_f32_e32 v26, 0, v26
	v_max_f32_e32 v27, 0, v27
	v_max_f32_e32 v28, 0, v28
	v_cvt_pk_bf16_f32 v37, v40, v37
	global_store_dwordx4 v[46:47], v[34:37], off offset:256
	s_nop 1
	v_max_f32_e32 v30, 0, v30
	v_add_u32_e32 v34, 0xa0, v140
	v_mul_f32_e32 v36, v26, v26
	v_max_f32_e32 v26, v31, v31
	v_mul_f32_e32 v31, v27, v27
	v_max_f32_e32 v27, v32, v32
	v_mul_f32_e32 v32, v28, v28
	v_ashrrev_i32_e32 v35, 31, v34
	v_max_f32_e32 v26, 0, v26
	v_max_f32_e32 v27, 0, v27
	v_max_f32_e32 v28, 0, v33
	v_lshlrev_b64 v[34:35], 13, v[34:35]
	v_mul_f32_e32 v30, v30, v30
	v_mul_f32_e32 v26, v26, v26
	v_mul_f32_e32 v27, v27, v27
	v_mul_f32_e32 v28, v28, v28
	v_max_f32_e32 v29, 0, v29
	v_cvt_pk_bf16_f32 v26, v30, v26
	v_cvt_pk_bf16_f32 v27, v27, v28
	v_cvt_pk_bf16_f32 v28, v36, v31
	v_lshl_add_u64 v[30:31], s[18:19], 0, v[34:35]
	v_mul_f32_e32 v29, v29, v29
	v_lshl_add_u64 v[30:31], v[30:31], 0, v[122:123]
	v_max_f32_e32 v18, 0, v18
	v_max_f32_e32 v19, 0, v19
	v_max_f32_e32 v20, 0, v20
	v_cvt_pk_bf16_f32 v29, v32, v29
	global_store_dwordx4 v[30:31], v[26:29], off
	s_nop 1
	v_mul_f32_e32 v26, v18, v18
	v_max_f32_e32 v18, v23, v23
	v_mul_f32_e32 v23, v19, v19
	v_max_f32_e32 v19, v24, v24
	v_mul_f32_e32 v24, v20, v20
	v_max_f32_e32 v18, 0, v18
	v_max_f32_e32 v19, 0, v19
	v_max_f32_e32 v20, 0, v25
	v_max_f32_e32 v22, 0, v22
	v_mul_f32_e32 v18, v18, v18
	v_mul_f32_e32 v19, v19, v19
	v_max_f32_e32 v21, 0, v21
	v_mul_f32_e32 v20, v20, v20
	v_mul_f32_e32 v22, v22, v22
	v_mul_f32_e32 v21, v21, v21
	v_cvt_pk_bf16_f32 v18, v22, v18
	v_cvt_pk_bf16_f32 v19, v19, v20
	v_cvt_pk_bf16_f32 v20, v26, v23
	v_max_f32_e32 v10, 0, v10
	v_max_f32_e32 v11, 0, v11
	v_max_f32_e32 v12, 0, v12
	v_cvt_pk_bf16_f32 v21, v24, v21
	global_store_dwordx4 v[30:31], v[18:21], off offset:256
	s_nop 1
	v_max_f32_e32 v14, 0, v14
	v_add_u32_e32 v18, 0xb0, v140
	v_mul_f32_e32 v20, v10, v10
	v_max_f32_e32 v10, v15, v15
	v_mul_f32_e32 v15, v11, v11
	v_max_f32_e32 v11, v16, v16
	v_mul_f32_e32 v16, v12, v12
	v_ashrrev_i32_e32 v19, 31, v18
	v_max_f32_e32 v10, 0, v10
	v_max_f32_e32 v11, 0, v11
	v_max_f32_e32 v12, 0, v17
	v_lshlrev_b64 v[18:19], 13, v[18:19]
	v_mul_f32_e32 v14, v14, v14
	v_mul_f32_e32 v10, v10, v10
	v_mul_f32_e32 v11, v11, v11
	v_mul_f32_e32 v12, v12, v12
	v_max_f32_e32 v13, 0, v13
	v_cvt_pk_bf16_f32 v10, v14, v10
	v_cvt_pk_bf16_f32 v11, v11, v12
	v_cvt_pk_bf16_f32 v12, v20, v15
	v_lshl_add_u64 v[14:15], s[18:19], 0, v[18:19]
	v_mul_f32_e32 v13, v13, v13
	v_lshl_add_u64 v[14:15], v[14:15], 0, v[122:123]
	v_max_f32_e32 v2, 0, v2
	v_max_f32_e32 v3, 0, v3
	v_max_f32_e32 v4, 0, v4
	v_cvt_pk_bf16_f32 v13, v16, v13
	global_store_dwordx4 v[14:15], v[10:13], off
	s_nop 1
	v_mul_f32_e32 v10, v2, v2
	v_max_f32_e32 v2, v7, v7
	v_mul_f32_e32 v7, v3, v3
	v_max_f32_e32 v3, v8, v8
	v_mul_f32_e32 v8, v4, v4
	v_max_f32_e32 v2, 0, v2
	v_max_f32_e32 v3, 0, v3
	v_max_f32_e32 v4, 0, v9
	v_max_f32_e32 v5, 0, v5
	v_max_f32_e32 v6, 0, v6
	v_mul_f32_e32 v2, v2, v2
	v_mul_f32_e32 v3, v3, v3
	v_mul_f32_e32 v4, v4, v4
	v_mul_f32_e32 v5, v5, v5
	s_andn2_b64 vcc, exec, s[38:39]
	s_mov_b64 s[38:39], -1
	v_mul_f32_e32 v6, v6, v6
	v_cvt_pk_bf16_f32 v2, v6, v2
	v_cvt_pk_bf16_f32 v3, v3, v4
	v_cvt_pk_bf16_f32 v4, v10, v7
	v_cvt_pk_bf16_f32 v5, v8, v5
	global_store_dwordx4 v[14:15], v[2:5], off offset:256
	s_nop 1
	s_cbranch_vccnz .LBB0_1450
	s_andn2_b64 vcc, exec, s[0:1]
	s_cbranch_vccnz .LBB0_1449
	s_barrier
	s_branch .LBB0_1449

; #define PG8_STAGE(bufoff, gbase, voff) do { _Pragma("unroll") for (int _i = 0; _i < 2; ++_i) \
;         __builtin_amdgcn_global_load_lds((const unsigned*)((const char*)(gbase) + (voff)[_i]), (LAS unsigned*)(lds + (bufoff) + ldsw + _i * 8192), 16, 0, 0); } while (0)
; #define PG8_LDA(dst, b, h) do { _Pragma("unroll") for (int m = 0; m < 4; ++m) _Pragma("unroll") for (int k = 0; k < 2; ++k) dst[m][k] = *(const LAS bf16x8*)(lds + PG8_SA(b, h) + aoff + m * 2048 + k * 1024); } while (0)
; #define PG8_LDB(dst, b, h) do { _Pragma("unroll") for (int n = 0; n < 2; ++n) _Pragma("unroll") for (int k = 0; k < 2; ++k) dst[n][k] = *(const LAS bf16x8*)(lds + PG8_SB(b, h) + boff + n * 2048 + k * 1024); } while (0)
; #define PG8_MMA(ai, bj, At, Bt) do { __builtin_amdgcn_s_setprio(1); _Pragma("unroll") for (int m = 0; m < 4; ++m) _Pragma("unroll") for (int n = 0; n < 2; ++n) _Pragma("unroll") for (int k = 0; k < 2; ++k) \
;         acc[ai][bj][m][n] = __builtin_amdgcn_mfma_f32_16x16x32_bf16(Bt[n][k], At[m][k], acc[ai][bj][m][n], 0, 0, 0); __builtin_amdgcn_s_setprio(0); } while (0)
; #define PG8_BAR __builtin_amdgcn_s_barrier()
; template <class Epi, bool MID = false>
; __device__ __forceinline__ void gemm_phase(LAS unsigned char* lds, const Gemm g, const StaticOrder& S, const Epi& E) {
;     ...
;         const bool has_next = S.next(ui + 1, nxt);
;         const char* nA = has_next ? (const char*)g.A + (size_t)nxt.pm * tstepA : cA; const char* nB = has_next ? (const char*)g.Bt + (size_t)nxt.pn * tstepB : cB;
; #pragma nounroll
;         for (int t = 0; t < nt; t += 2) {
;             const bool last = (t == nt - 2);
;             const char* a1 = cA + (size_t)(t + 1) * kstep;
;             const char* a2 = last ? nA : cA + (size_t)(t + 2) * kstep; const char* b2 = last ? nB : cB + (size_t)(t + 2) * kstep;
;             const char* a3 = a2 + kstep; const char* b3 = b2 + kstep;
;             PG8_LDB(B0, 0, 0); PG8_LDB(B1, 0, 1); PG8_SCHED; PG8_LDA(At, 0, 0); PG8_STAGE(PG8_SA(1, 1), a1 + hstepA, voffA);
;             PG8_WAIT_V(8); PG8_WAIT_L(0); PG8_BAR; PG8_MMA(0, 0, At, B0); PG8_MMA(0, 1, At, B1); PG8_BAR; PG8_SCHED;
;             PG8_LDA(At, 0, 1); PG8_STAGE(PG8_SB(0, 0), b2, voffB); PG8_STAGE(PG8_SB(0, 1), b2 + hstepB, voffB); PG8_STAGE(PG8_SA(0, 0), a2, voffA);
;             PG8_WAIT_V(8); PG8_WAIT_L(0); PG8_BAR; PG8_MMA(1, 0, At, B0); PG8_MMA(1, 1, At, B1); PG8_BAR; PG8_SCHED;
.LBB0_1561:
	s_ashr_i32 s59, s58, 31
	s_lshl_b64 s[60:61], s[58:59], 21
	s_add_u32 s60, s80, s60
	s_addc_u32 s61, s82, s61
	s_ashr_i32 s57, s56, 31
	s_lshl_b64 s[62:63], s[56:57], 21
	s_add_u32 s62, s83, s62
	s_addc_u32 s63, s84, s63
	s_andn2_b64 vcc, exec, s[46:47]
	s_cbranch_vccnz .LBB0_1585
	s_and_b64 s[70:71], s[40:41], exec
	s_cselect_b32 s43, s61, s67
	s_cselect_b32 s48, s60, s66
	s_cselect_b32 s57, s63, s69
	s_cselect_b32 s59, s62, s68
	s_add_u32 s66, s66, 0x100080
	s_addc_u32 s67, s67, 0
	s_add_u32 s65, s68, 0x100
	s_addc_u32 s72, s69, 0
	s_mov_b32 s68, 0
	s_add_i32 s73, s68, 2
	s_add_u32 s4, s66, 0xfff00080
	s_addc_u32 s5, s67, -1
	s_add_i32 s81, 0, 0x10000
	s_cmp_eq_u32 s93, s68
	s_cselect_b32 s71, s43, s5
	s_cselect_b32 s70, s48, s4
	s_cselect_b32 s69, s57, s72
	s_cselect_b32 s68, s59, s65
	s_add_i32 s4, 0, 0x14000
	v_add_u32_e32 v142, s81, v231
	v_add_u32_e32 v172, s4, v231
	ds_read_b128 v[130:133], v142
	ds_read_b128 v[134:137], v142 offset:1024
	ds_read_b128 v[138:141], v142 offset:2048
	ds_read_b128 v[142:145], v142 offset:3072
	ds_read_b128 v[146:149], v172
	ds_read_b128 v[150:153], v172 offset:1024
	ds_read_b128 v[168:171], v172 offset:2048
	ds_read_b128 v[172:175], v172 offset:3072
	v_lshl_add_u64 v[208:209], s[66:67], 0, v[164:165]
	s_add_i32 m0, s86, 0xc000
	ds_read_b128 v[176:179], v233
	ds_read_b128 v[180:183], v233 offset:1024
	ds_read_b128 v[184:187], v233 offset:2048
	ds_read_b128 v[188:191], v233 offset:3072
	ds_read_b128 v[192:195], v233 offset:4096
	ds_read_b128 v[196:199], v233 offset:5120
	ds_read_b128 v[200:203], v233 offset:6144
	ds_read_b128 v[204:207], v233 offset:7168
	global_load_lds_dwordx4 v[208:209], off
	v_lshl_add_u64 v[208:209], s[66:67], 0, v[166:167]
	s_add_i32 m0, s86, 0xe000
	s_nop 0
	global_load_lds_dwordx4 v[208:209], off
	s_waitcnt vmcnt(8)
	s_waitcnt lgkmcnt(0)
	s_barrier
	s_setprio 1
	s_waitcnt lgkmcnt(0)
	v_mfma_f32_16x16x32_bf16 v[126:129], v[130:133], v[176:179], 0
	v_mfma_f32_16x16x32_bf16 v[122:125], v[138:141], v[176:179], 0
	v_mfma_f32_16x16x32_bf16 v[110:113], v[130:133], v[184:187], 0
	v_mfma_f32_16x16x32_bf16 v[106:109], v[138:141], v[184:187], 0
	v_mfma_f32_16x16x32_bf16 v[94:97], v[130:133], v[192:195], 0
	v_mfma_f32_16x16x32_bf16 v[90:93], v[138:141], v[192:195], 0
	v_mfma_f32_16x16x32_bf16 v[78:81], v[130:133], v[200:203], 0
	v_mfma_f32_16x16x32_bf16 v[74:77], v[138:141], v[200:203], 0
	v_mfma_f32_16x16x32_bf16 v[126:129], v[134:137], v[180:183], v[126:129]
	v_mfma_f32_16x16x32_bf16 v[122:125], v[142:145], v[180:183], v[122:125]
	v_mfma_f32_16x16x32_bf16 v[110:113], v[134:137], v[188:191], v[110:113]
	v_mfma_f32_16x16x32_bf16 v[106:109], v[142:145], v[188:191], v[106:109]
	v_mfma_f32_16x16x32_bf16 v[94:97], v[134:137], v[196:199], v[94:97]
	v_mfma_f32_16x16x32_bf16 v[90:93], v[142:145], v[196:199], v[90:93]
	v_mfma_f32_16x16x32_bf16 v[78:81], v[134:137], v[204:207], v[78:81]
	v_mfma_f32_16x16x32_bf16 v[74:77], v[142:145], v[204:207], v[74:77]
	s_setprio 0
	s_setprio 1
	v_mfma_f32_16x16x32_bf16 v[118:121], v[146:149], v[176:179], 0
	v_mfma_f32_16x16x32_bf16 v[114:117], v[168:171], v[176:179], 0
	v_mfma_f32_16x16x32_bf16 v[102:105], v[146:149], v[184:187], 0
	v_mfma_f32_16x16x32_bf16 v[98:101], v[168:171], v[184:187], 0
	v_mfma_f32_16x16x32_bf16 v[86:89], v[146:149], v[192:195], 0
	v_mfma_f32_16x16x32_bf16 v[82:85], v[168:171], v[192:195], 0
	v_mfma_f32_16x16x32_bf16 v[70:73], v[146:149], v[200:203], 0
	v_mfma_f32_16x16x32_bf16 v[66:69], v[168:171], v[200:203], 0
	v_mfma_f32_16x16x32_bf16 v[118:121], v[150:153], v[180:183], v[118:121]
	v_mfma_f32_16x16x32_bf16 v[114:117], v[172:175], v[180:183], v[114:117]
	v_mfma_f32_16x16x32_bf16 v[102:105], v[150:153], v[188:191], v[102:105]
	v_mfma_f32_16x16x32_bf16 v[98:101], v[172:175], v[188:191], v[98:101]
	v_mfma_f32_16x16x32_bf16 v[86:89], v[150:153], v[196:199], v[86:89]
	v_mfma_f32_16x16x32_bf16 v[82:85], v[172:175], v[196:199], v[82:85]
	v_mfma_f32_16x16x32_bf16 v[70:73], v[150:153], v[204:207], v[70:73]
	v_mfma_f32_16x16x32_bf16 v[66:69], v[172:175], v[204:207], v[66:69]
	s_setprio 0
	s_barrier
	s_add_i32 s5, s81, s85
	v_lshl_add_u64 v[208:209], s[68:69], 0, v[0:1]
	s_mov_b32 m0, s5
	ds_read_b128 v[176:179], v233 offset:16384
	ds_read_b128 v[180:183], v233 offset:17408
	ds_read_b128 v[184:187], v233 offset:18432
	ds_read_b128 v[188:191], v233 offset:19456
	ds_read_b128 v[192:195], v233 offset:20480
	ds_read_b128 v[196:199], v233 offset:21504
	ds_read_b128 v[200:203], v233 offset:22528
	ds_read_b128 v[204:207], v233 offset:23552
	global_load_lds_dwordx4 v[208:209], off
	s_add_i32 m0, s5, 0x2000
	s_add_u32 vcc_lo, s68, 0x100000
	v_lshl_add_u64 v[210:211], s[68:69], 0, v[158:159]
	s_addc_u32 vcc_hi, s69, 0
	s_add_i32 s4, s4, s85
	global_load_lds_dwordx4 v[210:211], off
	v_lshl_add_u64 v[212:213], vcc, 0, v[0:1]
	s_mov_b32 m0, s4
	v_lshl_add_u64 v[214:215], s[70:71], 0, v[156:157]
	global_load_lds_dwordx4 v[212:213], off
	v_lshl_add_u64 v[212:213], vcc, 0, v[158:159]
	s_add_i32 m0, s4, 0x2000
	s_nop 0
	global_load_lds_dwordx4 v[212:213], off
	v_lshl_add_u64 v[212:213], s[70:71], 0, v[154:155]
	s_mov_b32 m0, s86
	s_nop 0
	global_load_lds_dwordx4 v[212:213], off
	s_mov_b32 m0, s87
	s_nop 0
	global_load_lds_dwordx4 v[214:215], off
	s_waitcnt vmcnt(8)
	s_waitcnt lgkmcnt(0)
	s_barrier
; #define PG8_STAGE(bufoff, gbase, voff) do { _Pragma("unroll") for (int _i = 0; _i < 2; ++_i) \
;         __builtin_amdgcn_global_load_lds((const unsigned*)((const char*)(gbase) + (voff)[_i]), (LAS unsigned*)(lds + (bufoff) + ldsw + _i * 8192), 16, 0, 0); } while (0)
; #define PG8_LDA(dst, b, h) do { _Pragma("unroll") for (int m = 0; m < 4; ++m) _Pragma("unroll") for (int k = 0; k < 2; ++k) dst[m][k] = *(const LAS bf16x8*)(lds + PG8_SA(b, h) + aoff + m * 2048 + k * 1024); } while (0)
; #define PG8_LDB(dst, b, h) do { _Pragma("unroll") for (int n = 0; n < 2; ++n) _Pragma("unroll") for (int k = 0; k < 2; ++k) dst[n][k] = *(const LAS bf16x8*)(lds + PG8_SB(b, h) + boff + n * 2048 + k * 1024); } while (0)
; #define PG8_MMA(ai, bj, At, Bt) do { __builtin_amdgcn_s_setprio(1); _Pragma("unroll") for (int m = 0; m < 4; ++m) _Pragma("unroll") for (int n = 0; n < 2; ++n) _Pragma("unroll") for (int k = 0; k < 2; ++k) \
;         acc[ai][bj][m][n] = __builtin_amdgcn_mfma_f32_16x16x32_bf16(Bt[n][k], At[m][k], acc[ai][bj][m][n], 0, 0, 0); __builtin_amdgcn_s_setprio(0); } while (0)
; #define PG8_WAIT_V(n) asm volatile("s_waitcnt vmcnt(" #n ")" ::: "memory")
; #define PG8_WAIT_L(n) asm volatile("s_waitcnt lgkmcnt(" #n ")" ::: "memory")
; #define PG8_BAR __builtin_amdgcn_s_barrier()
; #define PG8_SCHED __builtin_amdgcn_sched_barrier(0)
; template <class Epi, bool MID = false>
; __device__ __forceinline__ void gemm_phase(LAS unsigned char* lds, const Gemm g, const StaticOrder& S, const Epi& E) {
;     ...
;             PG8_WAIT_V(8); PG8_WAIT_L(0); PG8_BAR; PG8_MMA(1, 0, At, B0); PG8_MMA(1, 1, At, B1); PG8_BAR; PG8_SCHED;
;             PG8_LDB(B0, 1, 0); PG8_LDB(B1, 1, 1); PG8_SCHED; PG8_LDA(At, 1, 0); PG8_STAGE(PG8_SA(0, 1), a2 + hstepA, voffA);
;             PG8_WAIT_V(8); PG8_WAIT_L(0); PG8_BAR; PG8_MMA(0, 0, At, B0); PG8_MMA(0, 1, At, B1); PG8_BAR; PG8_SCHED;
	s_setprio 1
	s_waitcnt lgkmcnt(0)
	v_mfma_f32_16x16x32_bf16 v[62:65], v[130:133], v[176:179], 0
	v_mfma_f32_16x16x32_bf16 v[58:61], v[138:141], v[176:179], 0
	v_mfma_f32_16x16x32_bf16 v[46:49], v[130:133], v[184:187], 0
	v_mfma_f32_16x16x32_bf16 v[42:45], v[138:141], v[184:187], 0
	v_mfma_f32_16x16x32_bf16 v[30:33], v[130:133], v[192:195], 0
	v_mfma_f32_16x16x32_bf16 v[26:29], v[138:141], v[192:195], 0
	v_mfma_f32_16x16x32_bf16 v[14:17], v[130:133], v[200:203], 0
	v_mfma_f32_16x16x32_bf16 v[10:13], v[138:141], v[200:203], 0
	v_mfma_f32_16x16x32_bf16 v[62:65], v[134:137], v[180:183], v[62:65]
	v_mfma_f32_16x16x32_bf16 v[58:61], v[142:145], v[180:183], v[58:61]
	v_mfma_f32_16x16x32_bf16 v[46:49], v[134:137], v[188:191], v[46:49]
	v_mfma_f32_16x16x32_bf16 v[42:45], v[142:145], v[188:191], v[42:45]
	v_mfma_f32_16x16x32_bf16 v[30:33], v[134:137], v[196:199], v[30:33]
	v_mfma_f32_16x16x32_bf16 v[26:29], v[142:145], v[196:199], v[26:29]
	v_mfma_f32_16x16x32_bf16 v[14:17], v[134:137], v[204:207], v[14:17]
	v_mfma_f32_16x16x32_bf16 v[10:13], v[142:145], v[204:207], v[10:13]
	s_setprio 0
	s_setprio 1
	v_mfma_f32_16x16x32_bf16 v[54:57], v[146:149], v[176:179], 0
	v_mfma_f32_16x16x32_bf16 v[50:53], v[168:171], v[176:179], 0
	v_mfma_f32_16x16x32_bf16 v[38:41], v[146:149], v[184:187], 0
	v_mfma_f32_16x16x32_bf16 v[34:37], v[168:171], v[184:187], 0
	v_mfma_f32_16x16x32_bf16 v[22:25], v[146:149], v[192:195], 0
	v_mfma_f32_16x16x32_bf16 v[18:21], v[168:171], v[192:195], 0
	v_mfma_f32_16x16x32_bf16 v[6:9], v[146:149], v[200:203], 0
	v_mfma_f32_16x16x32_bf16 v[2:5], v[168:171], v[200:203], 0
	v_mfma_f32_16x16x32_bf16 v[54:57], v[150:153], v[180:183], v[54:57]
	v_mfma_f32_16x16x32_bf16 v[50:53], v[172:175], v[180:183], v[50:53]
	v_mfma_f32_16x16x32_bf16 v[38:41], v[150:153], v[188:191], v[38:41]
	v_mfma_f32_16x16x32_bf16 v[34:37], v[172:175], v[188:191], v[34:37]
	v_mfma_f32_16x16x32_bf16 v[22:25], v[150:153], v[196:199], v[22:25]
	v_mfma_f32_16x16x32_bf16 v[18:21], v[172:175], v[196:199], v[18:21]
	v_mfma_f32_16x16x32_bf16 v[6:9], v[150:153], v[204:207], v[6:9]
	v_mfma_f32_16x16x32_bf16 v[2:5], v[172:175], v[204:207], v[2:5]
	s_setprio 0
	s_barrier
	s_add_i32 s4, 0, 0x18000
	s_add_i32 s5, 0, 0x1c000
	v_add_u32_e32 v142, s4, v231
	v_add_u32_e32 v172, s5, v231
	ds_read_b128 v[130:133], v142
	ds_read_b128 v[134:137], v142 offset:1024
	ds_read_b128 v[138:141], v142 offset:2048
	ds_read_b128 v[142:145], v142 offset:3072
	ds_read_b128 v[146:149], v172
	ds_read_b128 v[150:153], v172 offset:1024
	ds_read_b128 v[168:171], v172 offset:2048
	ds_read_b128 v[172:175], v172 offset:3072
	s_add_u32 s70, s70, 0x100000
	s_addc_u32 s71, s71, 0
	s_mov_b32 m0, s88
	v_lshl_add_u64 v[234:235], s[70:71], 0, v[154:155]
	ds_read_b128 v[176:179], v233 offset:32768
	ds_read_b128 v[180:183], v233 offset:33792
	ds_read_b128 v[184:187], v233 offset:34816
	ds_read_b128 v[188:191], v233 offset:35840
	ds_read_b128 v[192:195], v233 offset:36864
	ds_read_b128 v[196:199], v233 offset:37888
	ds_read_b128 v[200:203], v233 offset:38912
	ds_read_b128 v[204:207], v233 offset:39936
	global_load_lds_dwordx4 v[234:235], off
	v_lshl_add_u64 v[234:235], s[70:71], 0, v[156:157]
	s_mov_b32 m0, s89
	s_nop 0
	global_load_lds_dwordx4 v[234:235], off
	s_waitcnt vmcnt(8)
	s_waitcnt lgkmcnt(0)
	s_barrier
	s_setprio 1
	s_waitcnt lgkmcnt(0)
	v_mfma_f32_16x16x32_bf16 v[126:129], v[130:133], v[176:179], v[126:129]
	v_mfma_f32_16x16x32_bf16 v[122:125], v[138:141], v[176:179], v[122:125]
	v_mfma_f32_16x16x32_bf16 v[110:113], v[130:133], v[184:187], v[110:113]
	v_mfma_f32_16x16x32_bf16 v[106:109], v[138:141], v[184:187], v[106:109]
	v_mfma_f32_16x16x32_bf16 v[94:97], v[130:133], v[192:195], v[94:97]
	v_mfma_f32_16x16x32_bf16 v[90:93], v[138:141], v[192:195], v[90:93]
	v_mfma_f32_16x16x32_bf16 v[78:81], v[130:133], v[200:203], v[78:81]
	v_mfma_f32_16x16x32_bf16 v[74:77], v[138:141], v[200:203], v[74:77]
	v_mfma_f32_16x16x32_bf16 v[126:129], v[134:137], v[180:183], v[126:129]
	v_mfma_f32_16x16x32_bf16 v[122:125], v[142:145], v[180:183], v[122:125]
	v_mfma_f32_16x16x32_bf16 v[110:113], v[134:137], v[188:191], v[110:113]
	v_mfma_f32_16x16x32_bf16 v[106:109], v[142:145], v[188:191], v[106:109]
	v_mfma_f32_16x16x32_bf16 v[94:97], v[134:137], v[196:199], v[94:97]
	v_mfma_f32_16x16x32_bf16 v[90:93], v[142:145], v[196:199], v[90:93]
	v_mfma_f32_16x16x32_bf16 v[78:81], v[134:137], v[204:207], v[78:81]
	v_mfma_f32_16x16x32_bf16 v[74:77], v[142:145], v[204:207], v[74:77]
	s_setprio 0
	s_setprio 1
	v_mfma_f32_16x16x32_bf16 v[118:121], v[146:149], v[176:179], v[118:121]
	v_mfma_f32_16x16x32_bf16 v[114:117], v[168:171], v[176:179], v[114:117]
	v_mfma_f32_16x16x32_bf16 v[102:105], v[146:149], v[184:187], v[102:105]
	v_mfma_f32_16x16x32_bf16 v[98:101], v[168:171], v[184:187], v[98:101]
	v_mfma_f32_16x16x32_bf16 v[86:89], v[146:149], v[192:195], v[86:89]
	v_mfma_f32_16x16x32_bf16 v[82:85], v[168:171], v[192:195], v[82:85]
	v_mfma_f32_16x16x32_bf16 v[70:73], v[146:149], v[200:203], v[70:73]
	v_mfma_f32_16x16x32_bf16 v[66:69], v[168:171], v[200:203], v[66:69]
	v_mfma_f32_16x16x32_bf16 v[118:121], v[150:153], v[180:183], v[118:121]
	v_mfma_f32_16x16x32_bf16 v[114:117], v[172:175], v[180:183], v[114:117]
	v_mfma_f32_16x16x32_bf16 v[102:105], v[150:153], v[188:191], v[102:105]
	v_mfma_f32_16x16x32_bf16 v[98:101], v[172:175], v[188:191], v[98:101]
	v_mfma_f32_16x16x32_bf16 v[86:89], v[150:153], v[196:199], v[86:89]
	v_mfma_f32_16x16x32_bf16 v[82:85], v[172:175], v[196:199], v[82:85]
	v_mfma_f32_16x16x32_bf16 v[70:73], v[150:153], v[204:207], v[70:73]
	v_mfma_f32_16x16x32_bf16 v[66:69], v[172:175], v[204:207], v[66:69]
	s_setprio 0
	s_barrier
; #define PG8_STAGE(bufoff, gbase, voff) do { _Pragma("unroll") for (int _i = 0; _i < 2; ++_i) \
;         __builtin_amdgcn_global_load_lds((const unsigned*)((const char*)(gbase) + (voff)[_i]), (LAS unsigned*)(lds + (bufoff) + ldsw + _i * 8192), 16, 0, 0); } while (0)
; #define PG8_LDA(dst, b, h) do { _Pragma("unroll") for (int m = 0; m < 4; ++m) _Pragma("unroll") for (int k = 0; k < 2; ++k) dst[m][k] = *(const LAS bf16x8*)(lds + PG8_SA(b, h) + aoff + m * 2048 + k * 1024); } while (0)
; #define PG8_LDB(dst, b, h) do { _Pragma("unroll") for (int n = 0; n < 2; ++n) _Pragma("unroll") for (int k = 0; k < 2; ++k) dst[n][k] = *(const LAS bf16x8*)(lds + PG8_SB(b, h) + boff + n * 2048 + k * 1024); } while (0)
; #define PG8_MMA(ai, bj, At, Bt) do { __builtin_amdgcn_s_setprio(1); _Pragma("unroll") for (int m = 0; m < 4; ++m) _Pragma("unroll") for (int n = 0; n < 2; ++n) _Pragma("unroll") for (int k = 0; k < 2; ++k) \
;         acc[ai][bj][m][n] = __builtin_amdgcn_mfma_f32_16x16x32_bf16(Bt[n][k], At[m][k], acc[ai][bj][m][n], 0, 0, 0); __builtin_amdgcn_s_setprio(0); } while (0)
; #define PG8_WAIT_V(n) asm volatile("s_waitcnt vmcnt(" #n ")" ::: "memory")
; #define PG8_WAIT_L(n) asm volatile("s_waitcnt lgkmcnt(" #n ")" ::: "memory")
; #define PG8_BAR __builtin_amdgcn_s_barrier()
; #define PG8_SCHED __builtin_amdgcn_sched_barrier(0)
; template <class Epi, bool MID = false>
; __device__ __forceinline__ void gemm_phase(LAS unsigned char* lds, const Gemm g, const StaticOrder& S, const Epi& E) {
;     ...
;         for (int t = 0; t < nt; t += 2) {
;             const bool last = (t == nt - 2);
;             const char* a1 = cA + (size_t)(t + 1) * kstep;
;             const char* a2 = last ? nA : cA + (size_t)(t + 2) * kstep; const char* b2 = last ? nB : cB + (size_t)(t + 2) * kstep;
;             const char* a3 = a2 + kstep; const char* b3 = b2 + kstep;
;             PG8_LDB(B0, 0, 0); PG8_LDB(B1, 0, 1); PG8_SCHED; PG8_LDA(At, 0, 0); PG8_STAGE(PG8_SA(1, 1), a1 + hstepA, voffA);
;     ...
;             PG8_LDA(At, 1, 1); PG8_STAGE(PG8_SB(1, 0), b3, voffB); PG8_STAGE(PG8_SB(1, 1), b3 + hstepB, voffB); PG8_STAGE(PG8_SA(1, 0), a3, voffA);
;             PG8_WAIT_V(8); PG8_WAIT_L(0); PG8_BAR; PG8_MMA(1, 0, At, B0); PG8_MMA(1, 1, At, B1); PG8_BAR; PG8_SCHED;
	s_add_i32 s4, s4, s85
	v_lshl_add_u64 v[208:209], v[208:209], 0, s[24:25]
	s_mov_b32 m0, s4
	ds_read_b128 v[176:179], v233 offset:49152
	ds_read_b128 v[180:183], v233 offset:50176
	ds_read_b128 v[184:187], v233 offset:51200
	ds_read_b128 v[188:191], v233 offset:52224
	ds_read_b128 v[192:195], v233 offset:53248
	ds_read_b128 v[196:199], v233 offset:54272
	ds_read_b128 v[200:203], v233 offset:55296
	ds_read_b128 v[204:207], v233 offset:56320
	global_load_lds_dwordx4 v[208:209], off
	s_add_i32 m0, s4, 0x2000
	s_add_u32 s68, s68, 0x100080
	v_lshl_add_u64 v[208:209], v[210:211], 0, s[24:25]
	s_addc_u32 s69, s69, 0
	s_add_i32 s4, s5, s85
	global_load_lds_dwordx4 v[208:209], off
	v_lshl_add_u64 v[208:209], s[68:69], 0, v[0:1]
	s_mov_b32 m0, s4
	s_nop 0
	global_load_lds_dwordx4 v[208:209], off
	v_lshl_add_u64 v[208:209], s[68:69], 0, v[158:159]
	s_add_i32 m0, s4, 0x2000
	s_nop 0
	global_load_lds_dwordx4 v[208:209], off
	v_lshl_add_u64 v[208:209], v[212:213], 0, s[24:25]
	s_mov_b32 m0, s91
	s_nop 0
	global_load_lds_dwordx4 v[208:209], off
	v_lshl_add_u64 v[208:209], v[214:215], 0, s[24:25]
	s_mov_b32 m0, s92
	s_nop 0
	global_load_lds_dwordx4 v[208:209], off
	s_waitcnt vmcnt(8)
	s_waitcnt lgkmcnt(0)
	s_barrier
	s_setprio 1
	s_waitcnt lgkmcnt(0)
	v_mfma_f32_16x16x32_bf16 v[62:65], v[130:133], v[176:179], v[62:65]
	v_mfma_f32_16x16x32_bf16 v[58:61], v[138:141], v[176:179], v[58:61]
	v_mfma_f32_16x16x32_bf16 v[46:49], v[130:133], v[184:187], v[46:49]
	v_mfma_f32_16x16x32_bf16 v[42:45], v[138:141], v[184:187], v[42:45]
	v_mfma_f32_16x16x32_bf16 v[30:33], v[130:133], v[192:195], v[30:33]
	v_mfma_f32_16x16x32_bf16 v[26:29], v[138:141], v[192:195], v[26:29]
	v_mfma_f32_16x16x32_bf16 v[14:17], v[130:133], v[200:203], v[14:17]
	v_mfma_f32_16x16x32_bf16 v[10:13], v[138:141], v[200:203], v[10:13]
	v_mfma_f32_16x16x32_bf16 v[62:65], v[134:137], v[180:183], v[62:65]
	v_mfma_f32_16x16x32_bf16 v[58:61], v[142:145], v[180:183], v[58:61]
	v_mfma_f32_16x16x32_bf16 v[46:49], v[134:137], v[188:191], v[46:49]
	v_mfma_f32_16x16x32_bf16 v[42:45], v[142:145], v[188:191], v[42:45]
	v_mfma_f32_16x16x32_bf16 v[30:33], v[134:137], v[196:199], v[30:33]
	v_mfma_f32_16x16x32_bf16 v[26:29], v[142:145], v[196:199], v[26:29]
	v_mfma_f32_16x16x32_bf16 v[14:17], v[134:137], v[204:207], v[14:17]
	v_mfma_f32_16x16x32_bf16 v[10:13], v[142:145], v[204:207], v[10:13]
	s_setprio 0
	s_setprio 1
	v_mfma_f32_16x16x32_bf16 v[54:57], v[146:149], v[176:179], v[54:57]
	v_mfma_f32_16x16x32_bf16 v[50:53], v[168:171], v[176:179], v[50:53]
	v_mfma_f32_16x16x32_bf16 v[38:41], v[146:149], v[184:187], v[38:41]
	v_mfma_f32_16x16x32_bf16 v[34:37], v[168:171], v[184:187], v[34:37]
	v_mfma_f32_16x16x32_bf16 v[22:25], v[146:149], v[192:195], v[22:25]
	v_mfma_f32_16x16x32_bf16 v[18:21], v[168:171], v[192:195], v[18:21]
	v_mfma_f32_16x16x32_bf16 v[6:9], v[146:149], v[200:203], v[6:9]
	v_mfma_f32_16x16x32_bf16 v[2:5], v[168:171], v[200:203], v[2:5]
	v_mfma_f32_16x16x32_bf16 v[54:57], v[150:153], v[180:183], v[54:57]
	v_mfma_f32_16x16x32_bf16 v[50:53], v[172:175], v[180:183], v[50:53]
	v_mfma_f32_16x16x32_bf16 v[38:41], v[150:153], v[188:191], v[38:41]
	v_mfma_f32_16x16x32_bf16 v[34:37], v[172:175], v[188:191], v[34:37]
	v_mfma_f32_16x16x32_bf16 v[22:25], v[150:153], v[196:199], v[22:25]
	v_mfma_f32_16x16x32_bf16 v[18:21], v[172:175], v[196:199], v[18:21]
	v_mfma_f32_16x16x32_bf16 v[6:9], v[150:153], v[204:207], v[6:9]
	v_mfma_f32_16x16x32_bf16 v[2:5], v[172:175], v[204:207], v[2:5]
	s_setprio 0
	s_barrier
	s_add_u32 s66, s66, 0x100
	s_addc_u32 s67, s67, 0
	s_add_u32 s65, s65, 0x100
	s_addc_u32 s72, s72, 0
	s_cmp_ge_i32 s73, s79
	s_mov_b32 s68, s73
	s_cbranch_scc0 .LBB0_1563
	s_branch .Lpk_1563_exit
.LBB0_1563:
	s_add_i32 s73, s68, 2
	s_add_u32 s4, s66, 0xfff00080
	s_addc_u32 s5, s67, -1
	s_add_i32 s81, 0, 0x10000
	s_cmp_eq_u32 s93, s68
	s_cselect_b32 s71, s43, s5
	s_cselect_b32 s70, s48, s4
	s_cselect_b32 s69, s57, s72
	s_cselect_b32 s68, s59, s65
	s_add_i32 s4, 0, 0x14000
	v_add_u32_e32 v142, s81, v231
	v_add_u32_e32 v172, s4, v231
	ds_read_b128 v[130:133], v142
	ds_read_b128 v[134:137], v142 offset:1024
	ds_read_b128 v[138:141], v142 offset:2048
	ds_read_b128 v[142:145], v142 offset:3072
	ds_read_b128 v[146:149], v172
	ds_read_b128 v[150:153], v172 offset:1024
	ds_read_b128 v[168:171], v172 offset:2048
	ds_read_b128 v[172:175], v172 offset:3072
	v_lshl_add_u64 v[208:209], s[66:67], 0, v[164:165]
	s_add_i32 m0, s86, 0xc000
	ds_read_b128 v[176:179], v233
	ds_read_b128 v[180:183], v233 offset:1024
	ds_read_b128 v[184:187], v233 offset:2048
	ds_read_b128 v[188:191], v233 offset:3072
	ds_read_b128 v[192:195], v233 offset:4096
	ds_read_b128 v[196:199], v233 offset:5120
	ds_read_b128 v[200:203], v233 offset:6144
	ds_read_b128 v[204:207], v233 offset:7168
	global_load_lds_dwordx4 v[208:209], off
	v_lshl_add_u64 v[208:209], s[66:67], 0, v[166:167]
	s_add_i32 m0, s86, 0xe000
	s_nop 0
	global_load_lds_dwordx4 v[208:209], off
	s_waitcnt vmcnt(8)
	s_waitcnt lgkmcnt(0)
	s_barrier
; #define PG8_STAGE(bufoff, gbase, voff) do { _Pragma("unroll") for (int _i = 0; _i < 2; ++_i) \
;         __builtin_amdgcn_global_load_lds((const unsigned*)((const char*)(gbase) + (voff)[_i]), (LAS unsigned*)(lds + (bufoff) + ldsw + _i * 8192), 16, 0, 0); } while (0)
; #define PG8_LDA(dst, b, h) do { _Pragma("unroll") for (int m = 0; m < 4; ++m) _Pragma("unroll") for (int k = 0; k < 2; ++k) dst[m][k] = *(const LAS bf16x8*)(lds + PG8_SA(b, h) + aoff + m * 2048 + k * 1024); } while (0)
; #define PG8_MMA(ai, bj, At, Bt) do { __builtin_amdgcn_s_setprio(1); _Pragma("unroll") for (int m = 0; m < 4; ++m) _Pragma("unroll") for (int n = 0; n < 2; ++n) _Pragma("unroll") for (int k = 0; k < 2; ++k) \
;         acc[ai][bj][m][n] = __builtin_amdgcn_mfma_f32_16x16x32_bf16(Bt[n][k], At[m][k], acc[ai][bj][m][n], 0, 0, 0); __builtin_amdgcn_s_setprio(0); } while (0)
; #define PG8_WAIT_V(n) asm volatile("s_waitcnt vmcnt(" #n ")" ::: "memory")
; #define PG8_WAIT_L(n) asm volatile("s_waitcnt lgkmcnt(" #n ")" ::: "memory")
; #define PG8_BAR __builtin_amdgcn_s_barrier()
; #define PG8_SCHED __builtin_amdgcn_sched_barrier(0)
; template <class Epi, bool MID = false>
; __device__ __forceinline__ void gemm_phase(LAS unsigned char* lds, const Gemm g, const StaticOrder& S, const Epi& E) {
;     ...
;             PG8_WAIT_V(8); PG8_WAIT_L(0); PG8_BAR; PG8_MMA(0, 0, At, B0); PG8_MMA(0, 1, At, B1); PG8_BAR; PG8_SCHED;
;             PG8_LDA(At, 0, 1); PG8_STAGE(PG8_SB(0, 0), b2, voffB); PG8_STAGE(PG8_SB(0, 1), b2 + hstepB, voffB); PG8_STAGE(PG8_SA(0, 0), a2, voffA);
;             PG8_WAIT_V(8); PG8_WAIT_L(0); PG8_BAR; PG8_MMA(1, 0, At, B0); PG8_MMA(1, 1, At, B1); PG8_BAR; PG8_SCHED;
	s_setprio 1
	s_waitcnt lgkmcnt(0)
	v_mfma_f32_16x16x32_bf16 v[126:129], v[130:133], v[176:179], v[126:129]
	v_mfma_f32_16x16x32_bf16 v[122:125], v[138:141], v[176:179], v[122:125]
	v_mfma_f32_16x16x32_bf16 v[110:113], v[130:133], v[184:187], v[110:113]
	v_mfma_f32_16x16x32_bf16 v[106:109], v[138:141], v[184:187], v[106:109]
	v_mfma_f32_16x16x32_bf16 v[94:97], v[130:133], v[192:195], v[94:97]
	v_mfma_f32_16x16x32_bf16 v[90:93], v[138:141], v[192:195], v[90:93]
	v_mfma_f32_16x16x32_bf16 v[78:81], v[130:133], v[200:203], v[78:81]
	v_mfma_f32_16x16x32_bf16 v[74:77], v[138:141], v[200:203], v[74:77]
	v_mfma_f32_16x16x32_bf16 v[126:129], v[134:137], v[180:183], v[126:129]
	v_mfma_f32_16x16x32_bf16 v[122:125], v[142:145], v[180:183], v[122:125]
	v_mfma_f32_16x16x32_bf16 v[110:113], v[134:137], v[188:191], v[110:113]
	v_mfma_f32_16x16x32_bf16 v[106:109], v[142:145], v[188:191], v[106:109]
	v_mfma_f32_16x16x32_bf16 v[94:97], v[134:137], v[196:199], v[94:97]
	v_mfma_f32_16x16x32_bf16 v[90:93], v[142:145], v[196:199], v[90:93]
	v_mfma_f32_16x16x32_bf16 v[78:81], v[134:137], v[204:207], v[78:81]
	v_mfma_f32_16x16x32_bf16 v[74:77], v[142:145], v[204:207], v[74:77]
	s_setprio 0
	s_setprio 1
	v_mfma_f32_16x16x32_bf16 v[118:121], v[146:149], v[176:179], v[118:121]
	v_mfma_f32_16x16x32_bf16 v[114:117], v[168:171], v[176:179], v[114:117]
	v_mfma_f32_16x16x32_bf16 v[102:105], v[146:149], v[184:187], v[102:105]
	v_mfma_f32_16x16x32_bf16 v[98:101], v[168:171], v[184:187], v[98:101]
	v_mfma_f32_16x16x32_bf16 v[86:89], v[146:149], v[192:195], v[86:89]
	v_mfma_f32_16x16x32_bf16 v[82:85], v[168:171], v[192:195], v[82:85]
	v_mfma_f32_16x16x32_bf16 v[70:73], v[146:149], v[200:203], v[70:73]
	v_mfma_f32_16x16x32_bf16 v[66:69], v[168:171], v[200:203], v[66:69]
	v_mfma_f32_16x16x32_bf16 v[118:121], v[150:153], v[180:183], v[118:121]
	v_mfma_f32_16x16x32_bf16 v[114:117], v[172:175], v[180:183], v[114:117]
	v_mfma_f32_16x16x32_bf16 v[102:105], v[150:153], v[188:191], v[102:105]
	v_mfma_f32_16x16x32_bf16 v[98:101], v[172:175], v[188:191], v[98:101]
	v_mfma_f32_16x16x32_bf16 v[86:89], v[150:153], v[196:199], v[86:89]
	v_mfma_f32_16x16x32_bf16 v[82:85], v[172:175], v[196:199], v[82:85]
	v_mfma_f32_16x16x32_bf16 v[70:73], v[150:153], v[204:207], v[70:73]
	v_mfma_f32_16x16x32_bf16 v[66:69], v[172:175], v[204:207], v[66:69]
	s_setprio 0
	s_barrier
	s_add_i32 s5, s81, s85
	v_lshl_add_u64 v[208:209], s[68:69], 0, v[0:1]
	s_mov_b32 m0, s5
	ds_read_b128 v[176:179], v233 offset:16384
	ds_read_b128 v[180:183], v233 offset:17408
	ds_read_b128 v[184:187], v233 offset:18432
	ds_read_b128 v[188:191], v233 offset:19456
	ds_read_b128 v[192:195], v233 offset:20480
	ds_read_b128 v[196:199], v233 offset:21504
	ds_read_b128 v[200:203], v233 offset:22528
	ds_read_b128 v[204:207], v233 offset:23552
	global_load_lds_dwordx4 v[208:209], off
	s_add_i32 m0, s5, 0x2000
	s_add_u32 vcc_lo, s68, 0x100000
	v_lshl_add_u64 v[210:211], s[68:69], 0, v[158:159]
	s_addc_u32 vcc_hi, s69, 0
	s_add_i32 s4, s4, s85
	global_load_lds_dwordx4 v[210:211], off
	v_lshl_add_u64 v[212:213], vcc, 0, v[0:1]
	s_mov_b32 m0, s4
	v_lshl_add_u64 v[214:215], s[70:71], 0, v[156:157]
	global_load_lds_dwordx4 v[212:213], off
	v_lshl_add_u64 v[212:213], vcc, 0, v[158:159]
	s_add_i32 m0, s4, 0x2000
	s_nop 0
	global_load_lds_dwordx4 v[212:213], off
	v_lshl_add_u64 v[212:213], s[70:71], 0, v[154:155]
	s_mov_b32 m0, s86
	s_nop 0
	global_load_lds_dwordx4 v[212:213], off
	s_mov_b32 m0, s87
	s_nop 0
	global_load_lds_dwordx4 v[214:215], off
	s_waitcnt vmcnt(8)
	s_waitcnt lgkmcnt(0)
	s_barrier
	s_setprio 1
	s_waitcnt lgkmcnt(0)
	v_mfma_f32_16x16x32_bf16 v[62:65], v[130:133], v[176:179], v[62:65]
	v_mfma_f32_16x16x32_bf16 v[58:61], v[138:141], v[176:179], v[58:61]
	v_mfma_f32_16x16x32_bf16 v[46:49], v[130:133], v[184:187], v[46:49]
	v_mfma_f32_16x16x32_bf16 v[42:45], v[138:141], v[184:187], v[42:45]
	v_mfma_f32_16x16x32_bf16 v[30:33], v[130:133], v[192:195], v[30:33]
	v_mfma_f32_16x16x32_bf16 v[26:29], v[138:141], v[192:195], v[26:29]
	v_mfma_f32_16x16x32_bf16 v[14:17], v[130:133], v[200:203], v[14:17]
	v_mfma_f32_16x16x32_bf16 v[10:13], v[138:141], v[200:203], v[10:13]
	v_mfma_f32_16x16x32_bf16 v[62:65], v[134:137], v[180:183], v[62:65]
	v_mfma_f32_16x16x32_bf16 v[58:61], v[142:145], v[180:183], v[58:61]
	v_mfma_f32_16x16x32_bf16 v[46:49], v[134:137], v[188:191], v[46:49]
	v_mfma_f32_16x16x32_bf16 v[42:45], v[142:145], v[188:191], v[42:45]
	v_mfma_f32_16x16x32_bf16 v[30:33], v[134:137], v[196:199], v[30:33]
	v_mfma_f32_16x16x32_bf16 v[26:29], v[142:145], v[196:199], v[26:29]
	v_mfma_f32_16x16x32_bf16 v[14:17], v[134:137], v[204:207], v[14:17]
	v_mfma_f32_16x16x32_bf16 v[10:13], v[142:145], v[204:207], v[10:13]
	s_setprio 0
	s_setprio 1
	v_mfma_f32_16x16x32_bf16 v[54:57], v[146:149], v[176:179], v[54:57]
	v_mfma_f32_16x16x32_bf16 v[50:53], v[168:171], v[176:179], v[50:53]
	v_mfma_f32_16x16x32_bf16 v[38:41], v[146:149], v[184:187], v[38:41]
	v_mfma_f32_16x16x32_bf16 v[34:37], v[168:171], v[184:187], v[34:37]
	v_mfma_f32_16x16x32_bf16 v[22:25], v[146:149], v[192:195], v[22:25]
	v_mfma_f32_16x16x32_bf16 v[18:21], v[168:171], v[192:195], v[18:21]
	v_mfma_f32_16x16x32_bf16 v[6:9], v[146:149], v[200:203], v[6:9]
	v_mfma_f32_16x16x32_bf16 v[2:5], v[168:171], v[200:203], v[2:5]
	v_mfma_f32_16x16x32_bf16 v[54:57], v[150:153], v[180:183], v[54:57]
	v_mfma_f32_16x16x32_bf16 v[50:53], v[172:175], v[180:183], v[50:53]
	v_mfma_f32_16x16x32_bf16 v[38:41], v[150:153], v[188:191], v[38:41]
	v_mfma_f32_16x16x32_bf16 v[34:37], v[172:175], v[188:191], v[34:37]
	v_mfma_f32_16x16x32_bf16 v[22:25], v[150:153], v[196:199], v[22:25]
	v_mfma_f32_16x16x32_bf16 v[18:21], v[172:175], v[196:199], v[18:21]
	v_mfma_f32_16x16x32_bf16 v[6:9], v[150:153], v[204:207], v[6:9]
	v_mfma_f32_16x16x32_bf16 v[2:5], v[172:175], v[204:207], v[2:5]
	s_setprio 0
	s_barrier
; #define PG8_STAGE(bufoff, gbase, voff) do { _Pragma("unroll") for (int _i = 0; _i < 2; ++_i) \
;         __builtin_amdgcn_global_load_lds((const unsigned*)((const char*)(gbase) + (voff)[_i]), (LAS unsigned*)(lds + (bufoff) + ldsw + _i * 8192), 16, 0, 0); } while (0)
; #define PG8_LDA(dst, b, h) do { _Pragma("unroll") for (int m = 0; m < 4; ++m) _Pragma("unroll") for (int k = 0; k < 2; ++k) dst[m][k] = *(const LAS bf16x8*)(lds + PG8_SA(b, h) + aoff + m * 2048 + k * 1024); } while (0)
; #define PG8_LDB(dst, b, h) do { _Pragma("unroll") for (int n = 0; n < 2; ++n) _Pragma("unroll") for (int k = 0; k < 2; ++k) dst[n][k] = *(const LAS bf16x8*)(lds + PG8_SB(b, h) + boff + n * 2048 + k * 1024); } while (0)
; #define PG8_MMA(ai, bj, At, Bt) do { __builtin_amdgcn_s_setprio(1); _Pragma("unroll") for (int m = 0; m < 4; ++m) _Pragma("unroll") for (int n = 0; n < 2; ++n) _Pragma("unroll") for (int k = 0; k < 2; ++k) \
;         acc[ai][bj][m][n] = __builtin_amdgcn_mfma_f32_16x16x32_bf16(Bt[n][k], At[m][k], acc[ai][bj][m][n], 0, 0, 0); __builtin_amdgcn_s_setprio(0); } while (0)
; #define PG8_WAIT_V(n) asm volatile("s_waitcnt vmcnt(" #n ")" ::: "memory")
; #define PG8_WAIT_L(n) asm volatile("s_waitcnt lgkmcnt(" #n ")" ::: "memory")
; #define PG8_BAR __builtin_amdgcn_s_barrier()
; #define PG8_SCHED __builtin_amdgcn_sched_barrier(0)
; template <class Epi, bool MID = false>
; __device__ __forceinline__ void gemm_phase(LAS unsigned char* lds, const Gemm g, const StaticOrder& S, const Epi& E) {
;     ...
;             PG8_LDB(B0, 1, 0); PG8_LDB(B1, 1, 1); PG8_SCHED; PG8_LDA(At, 1, 0); PG8_STAGE(PG8_SA(0, 1), a2 + hstepA, voffA);
;             PG8_WAIT_V(8); PG8_WAIT_L(0); PG8_BAR; PG8_MMA(0, 0, At, B0); PG8_MMA(0, 1, At, B1); PG8_BAR; PG8_SCHED;
	s_add_i32 s4, 0, 0x18000
	s_add_i32 s5, 0, 0x1c000
	v_add_u32_e32 v142, s4, v231
	v_add_u32_e32 v172, s5, v231
	ds_read_b128 v[130:133], v142
	ds_read_b128 v[134:137], v142 offset:1024
	ds_read_b128 v[138:141], v142 offset:2048
	ds_read_b128 v[142:145], v142 offset:3072
	ds_read_b128 v[146:149], v172
	ds_read_b128 v[150:153], v172 offset:1024
	ds_read_b128 v[168:171], v172 offset:2048
	ds_read_b128 v[172:175], v172 offset:3072
	s_add_u32 s70, s70, 0x100000
	s_addc_u32 s71, s71, 0
	s_mov_b32 m0, s88
	v_lshl_add_u64 v[234:235], s[70:71], 0, v[154:155]
	ds_read_b128 v[176:179], v233 offset:32768
	ds_read_b128 v[180:183], v233 offset:33792
	ds_read_b128 v[184:187], v233 offset:34816
	ds_read_b128 v[188:191], v233 offset:35840
	ds_read_b128 v[192:195], v233 offset:36864
	ds_read_b128 v[196:199], v233 offset:37888
	ds_read_b128 v[200:203], v233 offset:38912
	ds_read_b128 v[204:207], v233 offset:39936
	global_load_lds_dwordx4 v[234:235], off
	v_lshl_add_u64 v[234:235], s[70:71], 0, v[156:157]
	s_mov_b32 m0, s89
	s_nop 0
	global_load_lds_dwordx4 v[234:235], off
	s_waitcnt vmcnt(8)
	s_waitcnt lgkmcnt(0)
	s_barrier
	s_setprio 1
	s_waitcnt lgkmcnt(0)
	v_mfma_f32_16x16x32_bf16 v[126:129], v[130:133], v[176:179], v[126:129]
	v_mfma_f32_16x16x32_bf16 v[122:125], v[138:141], v[176:179], v[122:125]
	v_mfma_f32_16x16x32_bf16 v[110:113], v[130:133], v[184:187], v[110:113]
	v_mfma_f32_16x16x32_bf16 v[106:109], v[138:141], v[184:187], v[106:109]
	v_mfma_f32_16x16x32_bf16 v[94:97], v[130:133], v[192:195], v[94:97]
	v_mfma_f32_16x16x32_bf16 v[90:93], v[138:141], v[192:195], v[90:93]
	v_mfma_f32_16x16x32_bf16 v[78:81], v[130:133], v[200:203], v[78:81]
	v_mfma_f32_16x16x32_bf16 v[74:77], v[138:141], v[200:203], v[74:77]
	v_mfma_f32_16x16x32_bf16 v[126:129], v[134:137], v[180:183], v[126:129]
	v_mfma_f32_16x16x32_bf16 v[122:125], v[142:145], v[180:183], v[122:125]
	v_mfma_f32_16x16x32_bf16 v[110:113], v[134:137], v[188:191], v[110:113]
	v_mfma_f32_16x16x32_bf16 v[106:109], v[142:145], v[188:191], v[106:109]
	v_mfma_f32_16x16x32_bf16 v[94:97], v[134:137], v[196:199], v[94:97]
	v_mfma_f32_16x16x32_bf16 v[90:93], v[142:145], v[196:199], v[90:93]
	v_mfma_f32_16x16x32_bf16 v[78:81], v[134:137], v[204:207], v[78:81]
	v_mfma_f32_16x16x32_bf16 v[74:77], v[142:145], v[204:207], v[74:77]
	s_setprio 0
	s_setprio 1
	v_mfma_f32_16x16x32_bf16 v[118:121], v[146:149], v[176:179], v[118:121]
	v_mfma_f32_16x16x32_bf16 v[114:117], v[168:171], v[176:179], v[114:117]
	v_mfma_f32_16x16x32_bf16 v[102:105], v[146:149], v[184:187], v[102:105]
	v_mfma_f32_16x16x32_bf16 v[98:101], v[168:171], v[184:187], v[98:101]
	v_mfma_f32_16x16x32_bf16 v[86:89], v[146:149], v[192:195], v[86:89]
	v_mfma_f32_16x16x32_bf16 v[82:85], v[168:171], v[192:195], v[82:85]
	v_mfma_f32_16x16x32_bf16 v[70:73], v[146:149], v[200:203], v[70:73]
	v_mfma_f32_16x16x32_bf16 v[66:69], v[168:171], v[200:203], v[66:69]
	v_mfma_f32_16x16x32_bf16 v[118:121], v[150:153], v[180:183], v[118:121]
	v_mfma_f32_16x16x32_bf16 v[114:117], v[172:175], v[180:183], v[114:117]
	v_mfma_f32_16x16x32_bf16 v[102:105], v[150:153], v[188:191], v[102:105]
	v_mfma_f32_16x16x32_bf16 v[98:101], v[172:175], v[188:191], v[98:101]
	v_mfma_f32_16x16x32_bf16 v[86:89], v[150:153], v[196:199], v[86:89]
	v_mfma_f32_16x16x32_bf16 v[82:85], v[172:175], v[196:199], v[82:85]
	v_mfma_f32_16x16x32_bf16 v[70:73], v[150:153], v[204:207], v[70:73]
	v_mfma_f32_16x16x32_bf16 v[66:69], v[172:175], v[204:207], v[66:69]
	s_setprio 0
	s_barrier
; #define PG8_STAGE(bufoff, gbase, voff) do { _Pragma("unroll") for (int _i = 0; _i < 2; ++_i) \
;         __builtin_amdgcn_global_load_lds((const unsigned*)((const char*)(gbase) + (voff)[_i]), (LAS unsigned*)(lds + (bufoff) + ldsw + _i * 8192), 16, 0, 0); } while (0)
; #define PG8_LDA(dst, b, h) do { _Pragma("unroll") for (int m = 0; m < 4; ++m) _Pragma("unroll") for (int k = 0; k < 2; ++k) dst[m][k] = *(const LAS bf16x8*)(lds + PG8_SA(b, h) + aoff + m * 2048 + k * 1024); } while (0)
; #define PG8_MMA(ai, bj, At, Bt) do { __builtin_amdgcn_s_setprio(1); _Pragma("unroll") for (int m = 0; m < 4; ++m) _Pragma("unroll") for (int n = 0; n < 2; ++n) _Pragma("unroll") for (int k = 0; k < 2; ++k) \
;         acc[ai][bj][m][n] = __builtin_amdgcn_mfma_f32_16x16x32_bf16(Bt[n][k], At[m][k], acc[ai][bj][m][n], 0, 0, 0); __builtin_amdgcn_s_setprio(0); } while (0)
; #define PG8_WAIT_V(n) asm volatile("s_waitcnt vmcnt(" #n ")" ::: "memory")
; #define PG8_WAIT_L(n) asm volatile("s_waitcnt lgkmcnt(" #n ")" ::: "memory")
; #define PG8_BAR __builtin_amdgcn_s_barrier()
; #define PG8_SCHED __builtin_amdgcn_sched_barrier(0)
; template <class Epi, bool MID = false>
; __device__ __forceinline__ void gemm_phase(LAS unsigned char* lds, const Gemm g, const StaticOrder& S, const Epi& E) {
;     ...
;             PG8_LDA(At, 1, 1); PG8_STAGE(PG8_SB(1, 0), b3, voffB); PG8_STAGE(PG8_SB(1, 1), b3 + hstepB, voffB); PG8_STAGE(PG8_SA(1, 0), a3, voffA);
;             PG8_WAIT_V(8); PG8_WAIT_L(0); PG8_BAR; PG8_MMA(1, 0, At, B0); PG8_MMA(1, 1, At, B1); PG8_BAR; PG8_SCHED;
;             if constexpr (MID) { if (t == 6) E.mid(acc, cur, wr, wc, fr, fq); }
;         }
;         if (wr == 0) PG8_BAR;
	s_add_i32 s4, s4, s85
	v_lshl_add_u64 v[208:209], v[208:209], 0, s[24:25]
	s_mov_b32 m0, s4
	ds_read_b128 v[176:179], v233 offset:49152
	ds_read_b128 v[180:183], v233 offset:50176
	ds_read_b128 v[184:187], v233 offset:51200
	ds_read_b128 v[188:191], v233 offset:52224
	ds_read_b128 v[192:195], v233 offset:53248
	ds_read_b128 v[196:199], v233 offset:54272
	ds_read_b128 v[200:203], v233 offset:55296
	ds_read_b128 v[204:207], v233 offset:56320
	global_load_lds_dwordx4 v[208:209], off
	s_add_i32 m0, s4, 0x2000
	s_add_u32 s68, s68, 0x100080
	v_lshl_add_u64 v[208:209], v[210:211], 0, s[24:25]
	s_addc_u32 s69, s69, 0
	s_add_i32 s4, s5, s85
	global_load_lds_dwordx4 v[208:209], off
	v_lshl_add_u64 v[208:209], s[68:69], 0, v[0:1]
	s_mov_b32 m0, s4
	s_nop 0
	global_load_lds_dwordx4 v[208:209], off
	v_lshl_add_u64 v[208:209], s[68:69], 0, v[158:159]
	s_add_i32 m0, s4, 0x2000
	s_nop 0
	global_load_lds_dwordx4 v[208:209], off
	v_lshl_add_u64 v[208:209], v[212:213], 0, s[24:25]
	s_mov_b32 m0, s91
	s_nop 0
	global_load_lds_dwordx4 v[208:209], off
	v_lshl_add_u64 v[208:209], v[214:215], 0, s[24:25]
	s_mov_b32 m0, s92
	s_nop 0
	global_load_lds_dwordx4 v[208:209], off
	s_waitcnt vmcnt(8)
	s_waitcnt lgkmcnt(0)
	s_barrier
	s_setprio 1
	s_waitcnt lgkmcnt(0)
	v_mfma_f32_16x16x32_bf16 v[62:65], v[130:133], v[176:179], v[62:65]
	v_mfma_f32_16x16x32_bf16 v[58:61], v[138:141], v[176:179], v[58:61]
	v_mfma_f32_16x16x32_bf16 v[46:49], v[130:133], v[184:187], v[46:49]
	v_mfma_f32_16x16x32_bf16 v[42:45], v[138:141], v[184:187], v[42:45]
	v_mfma_f32_16x16x32_bf16 v[30:33], v[130:133], v[192:195], v[30:33]
	v_mfma_f32_16x16x32_bf16 v[26:29], v[138:141], v[192:195], v[26:29]
	v_mfma_f32_16x16x32_bf16 v[14:17], v[130:133], v[200:203], v[14:17]
	v_mfma_f32_16x16x32_bf16 v[10:13], v[138:141], v[200:203], v[10:13]
	v_mfma_f32_16x16x32_bf16 v[62:65], v[134:137], v[180:183], v[62:65]
	v_mfma_f32_16x16x32_bf16 v[58:61], v[142:145], v[180:183], v[58:61]
	v_mfma_f32_16x16x32_bf16 v[46:49], v[134:137], v[188:191], v[46:49]
	v_mfma_f32_16x16x32_bf16 v[42:45], v[142:145], v[188:191], v[42:45]
	v_mfma_f32_16x16x32_bf16 v[30:33], v[134:137], v[196:199], v[30:33]
	v_mfma_f32_16x16x32_bf16 v[26:29], v[142:145], v[196:199], v[26:29]
	v_mfma_f32_16x16x32_bf16 v[14:17], v[134:137], v[204:207], v[14:17]
	v_mfma_f32_16x16x32_bf16 v[10:13], v[142:145], v[204:207], v[10:13]
	s_setprio 0
	s_setprio 1
	v_mfma_f32_16x16x32_bf16 v[54:57], v[146:149], v[176:179], v[54:57]
	v_mfma_f32_16x16x32_bf16 v[50:53], v[168:171], v[176:179], v[50:53]
	v_mfma_f32_16x16x32_bf16 v[38:41], v[146:149], v[184:187], v[38:41]
	v_mfma_f32_16x16x32_bf16 v[34:37], v[168:171], v[184:187], v[34:37]
	v_mfma_f32_16x16x32_bf16 v[22:25], v[146:149], v[192:195], v[22:25]
	v_mfma_f32_16x16x32_bf16 v[18:21], v[168:171], v[192:195], v[18:21]
	v_mfma_f32_16x16x32_bf16 v[6:9], v[146:149], v[200:203], v[6:9]
	v_mfma_f32_16x16x32_bf16 v[2:5], v[168:171], v[200:203], v[2:5]
	v_mfma_f32_16x16x32_bf16 v[54:57], v[150:153], v[180:183], v[54:57]
	v_mfma_f32_16x16x32_bf16 v[50:53], v[172:175], v[180:183], v[50:53]
	v_mfma_f32_16x16x32_bf16 v[38:41], v[150:153], v[188:191], v[38:41]
	v_mfma_f32_16x16x32_bf16 v[34:37], v[172:175], v[188:191], v[34:37]
	v_mfma_f32_16x16x32_bf16 v[22:25], v[150:153], v[196:199], v[22:25]
	v_mfma_f32_16x16x32_bf16 v[18:21], v[172:175], v[196:199], v[18:21]
	v_mfma_f32_16x16x32_bf16 v[6:9], v[150:153], v[204:207], v[6:9]
	v_mfma_f32_16x16x32_bf16 v[2:5], v[172:175], v[204:207], v[2:5]
	s_setprio 0
	s_barrier
	s_add_u32 s66, s66, 0x100
	s_addc_u32 s67, s67, 0
	s_add_u32 s65, s65, 0x100
	s_addc_u32 s72, s72, 0
	s_cmp_ge_i32 s73, s79
	s_mov_b32 s68, s73
	s_cbranch_scc0 .LBB0_1563
.Lpk_1563_exit:
	s_and_b64 vcc, exec, s[50:51]
	s_cbranch_vccz .LBB0_1566
.LBB0_1565:
	s_barrier

; #define PG8_STAGE(bufoff, gbase, voff) do { _Pragma("unroll") for (int _i = 0; _i < 2; ++_i) \
;         __builtin_amdgcn_global_load_lds((const unsigned*)((const char*)(gbase) + (voff)[_i]), (LAS unsigned*)(lds + (bufoff) + ldsw + _i * 8192), 16, 0, 0); } while (0)
; #define PG8_LDA(dst, b, h) do { _Pragma("unroll") for (int m = 0; m < 4; ++m) _Pragma("unroll") for (int k = 0; k < 2; ++k) dst[m][k] = *(const LAS bf16x8*)(lds + PG8_SA(b, h) + aoff + m * 2048 + k * 1024); } while (0)
; #define PG8_LDB(dst, b, h) do { _Pragma("unroll") for (int n = 0; n < 2; ++n) _Pragma("unroll") for (int k = 0; k < 2; ++k) dst[n][k] = *(const LAS bf16x8*)(lds + PG8_SB(b, h) + boff + n * 2048 + k * 1024); } while (0)
; #define PG8_MMA(ai, bj, At, Bt) do { __builtin_amdgcn_s_setprio(1); _Pragma("unroll") for (int m = 0; m < 4; ++m) _Pragma("unroll") for (int n = 0; n < 2; ++n) _Pragma("unroll") for (int k = 0; k < 2; ++k) \
;         acc[ai][bj][m][n] = __builtin_amdgcn_mfma_f32_16x16x32_bf16(Bt[n][k], At[m][k], acc[ai][bj][m][n], 0, 0, 0); __builtin_amdgcn_s_setprio(0); } while (0)
; #define PG8_BAR __builtin_amdgcn_s_barrier()
; template <class Epi, bool MID = false>
; __device__ __forceinline__ void gemm_phase(LAS unsigned char* lds, const Gemm g, const StaticOrder& S, const Epi& E) {
;     ...
;         const bool has_next = S.next(ui + 1, nxt);
;         const char* nA = has_next ? (const char*)g.A + (size_t)nxt.pm * tstepA : cA; const char* nB = has_next ? (const char*)g.Bt + (size_t)nxt.pn * tstepB : cB;
; #pragma nounroll
;         for (int t = 0; t < nt; t += 2) {
;             const bool last = (t == nt - 2);
;             const char* a1 = cA + (size_t)(t + 1) * kstep;
;             const char* a2 = last ? nA : cA + (size_t)(t + 2) * kstep; const char* b2 = last ? nB : cB + (size_t)(t + 2) * kstep;
;             const char* a3 = a2 + kstep; const char* b3 = b2 + kstep;
;             PG8_LDB(B0, 0, 0); PG8_LDB(B1, 0, 1); PG8_SCHED; PG8_LDA(At, 0, 0); PG8_STAGE(PG8_SA(1, 1), a1 + hstepA, voffA);
;             PG8_WAIT_V(8); PG8_WAIT_L(0); PG8_BAR; PG8_MMA(0, 0, At, B0); PG8_MMA(0, 1, At, B1); PG8_BAR; PG8_SCHED;
;             PG8_LDA(At, 0, 1); PG8_STAGE(PG8_SB(0, 0), b2, voffB); PG8_STAGE(PG8_SB(0, 1), b2 + hstepB, voffB); PG8_STAGE(PG8_SA(0, 0), a2, voffA);
;             PG8_WAIT_V(8); PG8_WAIT_L(0); PG8_BAR; PG8_MMA(1, 0, At, B0); PG8_MMA(1, 1, At, B1); PG8_BAR; PG8_SCHED;
.LBB0_1733:
	s_ashr_i32 s53, s52, 31
	s_lshl_b64 s[54:55], s[52:53], 17
	s_add_u32 s54, s66, s54
	s_addc_u32 s55, s67, s55
	s_ashr_i32 s51, s50, 31
	s_lshl_b64 s[56:57], s[50:51], 17
	s_add_u32 s56, s68, s56
	s_addc_u32 s57, s69, s57
	s_andn2_b64 vcc, exec, s[38:39]
	s_cbranch_vccnz .LBB0_1741
	s_and_b64 s[62:63], s[40:41], exec
	s_cselect_b32 s51, s55, s59
	s_cselect_b32 s53, s54, s58
	s_cselect_b32 s83, s57, s61
	s_cselect_b32 s84, s56, s60
	s_add_u32 s58, s58, 0x10080
	s_addc_u32 s59, s59, 0
	s_add_u32 s85, s60, 0x100
	s_addc_u32 s86, s61, 0
	s_mov_b32 s60, 0
	s_add_i32 s87, s60, 2
	s_add_u32 s4, s58, 0xffff0080
	s_addc_u32 s5, s59, -1
	s_add_i32 s88, 0, 0x10000
	s_cmp_eq_u32 s80, s60
	s_cselect_b32 s63, s51, s5
	s_cselect_b32 s62, s53, s4
	s_cselect_b32 s61, s83, s86
	s_cselect_b32 s60, s84, s85
	s_add_i32 s4, 0, 0x14000
	v_add_u32_e32 v156, s88, v141
	v_add_u32_e32 v160, s4, v141
	ds_read_b128 v[144:147], v156
	ds_read_b128 v[148:151], v156 offset:1024
	ds_read_b128 v[152:155], v156 offset:2048
	ds_read_b128 v[156:159], v156 offset:3072
	ds_read_b128 v[164:167], v160
	ds_read_b128 v[168:171], v160 offset:1024
	ds_read_b128 v[172:175], v160 offset:2048
	ds_read_b128 v[176:179], v160 offset:3072
	v_lshl_add_u64 v[160:161], s[58:59], 0, v[136:137]
	s_add_i32 m0, s47, 0xc000
	ds_read_b128 v[180:183], v143
	ds_read_b128 v[184:187], v143 offset:1024
	ds_read_b128 v[188:191], v143 offset:2048
	ds_read_b128 v[192:195], v143 offset:3072
	ds_read_b128 v[196:199], v143 offset:4096
	ds_read_b128 v[200:203], v143 offset:5120
	ds_read_b128 v[204:207], v143 offset:6144
	ds_read_b128 v[208:211], v143 offset:7168
	global_load_lds_dwordx4 v[160:161], off
	v_lshl_add_u64 v[160:161], s[58:59], 0, v[138:139]
	s_add_i32 m0, s47, 0xe000
	s_nop 0
	global_load_lds_dwordx4 v[160:161], off
	s_waitcnt vmcnt(8)
	s_waitcnt lgkmcnt(0)
	s_barrier
	s_setprio 1
	s_waitcnt lgkmcnt(0)
	v_mfma_f32_16x16x32_bf16 v[126:129], v[144:147], v[180:183], 0
	v_mfma_f32_16x16x32_bf16 v[122:125], v[152:155], v[180:183], 0
	v_mfma_f32_16x16x32_bf16 v[110:113], v[144:147], v[188:191], 0
	v_mfma_f32_16x16x32_bf16 v[106:109], v[152:155], v[188:191], 0
	v_mfma_f32_16x16x32_bf16 v[94:97], v[144:147], v[196:199], 0
	v_mfma_f32_16x16x32_bf16 v[90:93], v[152:155], v[196:199], 0
	v_mfma_f32_16x16x32_bf16 v[78:81], v[144:147], v[204:207], 0
	v_mfma_f32_16x16x32_bf16 v[74:77], v[152:155], v[204:207], 0
	v_mfma_f32_16x16x32_bf16 v[126:129], v[148:151], v[184:187], v[126:129]
	v_mfma_f32_16x16x32_bf16 v[122:125], v[156:159], v[184:187], v[122:125]
	v_mfma_f32_16x16x32_bf16 v[110:113], v[148:151], v[192:195], v[110:113]
	v_mfma_f32_16x16x32_bf16 v[106:109], v[156:159], v[192:195], v[106:109]
	v_mfma_f32_16x16x32_bf16 v[94:97], v[148:151], v[200:203], v[94:97]
	v_mfma_f32_16x16x32_bf16 v[90:93], v[156:159], v[200:203], v[90:93]
	v_mfma_f32_16x16x32_bf16 v[78:81], v[148:151], v[208:211], v[78:81]
	v_mfma_f32_16x16x32_bf16 v[74:77], v[156:159], v[208:211], v[74:77]
	s_setprio 0
	s_setprio 1
	v_mfma_f32_16x16x32_bf16 v[118:121], v[164:167], v[180:183], 0
	v_mfma_f32_16x16x32_bf16 v[114:117], v[172:175], v[180:183], 0
	v_mfma_f32_16x16x32_bf16 v[102:105], v[164:167], v[188:191], 0
	v_mfma_f32_16x16x32_bf16 v[98:101], v[172:175], v[188:191], 0
	v_mfma_f32_16x16x32_bf16 v[86:89], v[164:167], v[196:199], 0
	v_mfma_f32_16x16x32_bf16 v[82:85], v[172:175], v[196:199], 0
	v_mfma_f32_16x16x32_bf16 v[70:73], v[164:167], v[204:207], 0
	v_mfma_f32_16x16x32_bf16 v[66:69], v[172:175], v[204:207], 0
	v_mfma_f32_16x16x32_bf16 v[118:121], v[168:171], v[184:187], v[118:121]
	v_mfma_f32_16x16x32_bf16 v[114:117], v[176:179], v[184:187], v[114:117]
	v_mfma_f32_16x16x32_bf16 v[102:105], v[168:171], v[192:195], v[102:105]
	v_mfma_f32_16x16x32_bf16 v[98:101], v[176:179], v[192:195], v[98:101]
	v_mfma_f32_16x16x32_bf16 v[86:89], v[168:171], v[200:203], v[86:89]
	v_mfma_f32_16x16x32_bf16 v[82:85], v[176:179], v[200:203], v[82:85]
	v_mfma_f32_16x16x32_bf16 v[70:73], v[168:171], v[208:211], v[70:73]
	v_mfma_f32_16x16x32_bf16 v[66:69], v[176:179], v[208:211], v[66:69]
	s_setprio 0
	s_barrier
	s_add_i32 s5, s88, s70
	v_lshl_add_u64 v[160:161], s[60:61], 0, v[0:1]
	s_mov_b32 m0, s5
	ds_read_b128 v[180:183], v143 offset:16384
	ds_read_b128 v[184:187], v143 offset:17408
	ds_read_b128 v[188:191], v143 offset:18432
	ds_read_b128 v[192:195], v143 offset:19456
	ds_read_b128 v[196:199], v143 offset:20480
	ds_read_b128 v[200:203], v143 offset:21504
	ds_read_b128 v[204:207], v143 offset:22528
	ds_read_b128 v[208:211], v143 offset:23552
	global_load_lds_dwordx4 v[160:161], off
	s_add_i32 m0, s5, 0x2000
	s_add_u32 s88, s60, 0x10000
	v_lshl_add_u64 v[212:213], s[60:61], 0, v[134:135]
	s_addc_u32 s89, s61, 0
	s_add_i32 s4, s4, s70
	global_load_lds_dwordx4 v[212:213], off
	v_lshl_add_u64 v[214:215], s[88:89], 0, v[0:1]
	s_mov_b32 m0, s4
	v_lshl_add_u64 v[222:223], s[62:63], 0, v[132:133]
	global_load_lds_dwordx4 v[214:215], off
	v_lshl_add_u64 v[214:215], s[88:89], 0, v[134:135]
	s_add_i32 m0, s4, 0x2000
	s_nop 0
	global_load_lds_dwordx4 v[214:215], off
	v_lshl_add_u64 v[214:215], s[62:63], 0, v[130:131]
	s_mov_b32 m0, s47
	s_nop 0
	global_load_lds_dwordx4 v[214:215], off
	s_mov_b32 m0, s71
	s_nop 0
	global_load_lds_dwordx4 v[222:223], off
	s_waitcnt vmcnt(8)
	s_waitcnt lgkmcnt(0)
	s_barrier
; #define PG8_STAGE(bufoff, gbase, voff) do { _Pragma("unroll") for (int _i = 0; _i < 2; ++_i) \
;         __builtin_amdgcn_global_load_lds((const unsigned*)((const char*)(gbase) + (voff)[_i]), (LAS unsigned*)(lds + (bufoff) + ldsw + _i * 8192), 16, 0, 0); } while (0)
; #define PG8_LDA(dst, b, h) do { _Pragma("unroll") for (int m = 0; m < 4; ++m) _Pragma("unroll") for (int k = 0; k < 2; ++k) dst[m][k] = *(const LAS bf16x8*)(lds + PG8_SA(b, h) + aoff + m * 2048 + k * 1024); } while (0)
; #define PG8_LDB(dst, b, h) do { _Pragma("unroll") for (int n = 0; n < 2; ++n) _Pragma("unroll") for (int k = 0; k < 2; ++k) dst[n][k] = *(const LAS bf16x8*)(lds + PG8_SB(b, h) + boff + n * 2048 + k * 1024); } while (0)
; #define PG8_MMA(ai, bj, At, Bt) do { __builtin_amdgcn_s_setprio(1); _Pragma("unroll") for (int m = 0; m < 4; ++m) _Pragma("unroll") for (int n = 0; n < 2; ++n) _Pragma("unroll") for (int k = 0; k < 2; ++k) \
;         acc[ai][bj][m][n] = __builtin_amdgcn_mfma_f32_16x16x32_bf16(Bt[n][k], At[m][k], acc[ai][bj][m][n], 0, 0, 0); __builtin_amdgcn_s_setprio(0); } while (0)
; #define PG8_WAIT_V(n) asm volatile("s_waitcnt vmcnt(" #n ")" ::: "memory")
; #define PG8_WAIT_L(n) asm volatile("s_waitcnt lgkmcnt(" #n ")" ::: "memory")
; #define PG8_BAR __builtin_amdgcn_s_barrier()
; #define PG8_SCHED __builtin_amdgcn_sched_barrier(0)
; template <class Epi, bool MID = false>
; __device__ __forceinline__ void gemm_phase(LAS unsigned char* lds, const Gemm g, const StaticOrder& S, const Epi& E) {
;     ...
;             PG8_WAIT_V(8); PG8_WAIT_L(0); PG8_BAR; PG8_MMA(1, 0, At, B0); PG8_MMA(1, 1, At, B1); PG8_BAR; PG8_SCHED;
;             PG8_LDB(B0, 1, 0); PG8_LDB(B1, 1, 1); PG8_SCHED; PG8_LDA(At, 1, 0); PG8_STAGE(PG8_SA(0, 1), a2 + hstepA, voffA);
;             PG8_WAIT_V(8); PG8_WAIT_L(0); PG8_BAR; PG8_MMA(0, 0, At, B0); PG8_MMA(0, 1, At, B1); PG8_BAR; PG8_SCHED;
	s_setprio 1
	s_waitcnt lgkmcnt(0)
	v_mfma_f32_16x16x32_bf16 v[62:65], v[144:147], v[180:183], 0
	v_mfma_f32_16x16x32_bf16 v[58:61], v[152:155], v[180:183], 0
	v_mfma_f32_16x16x32_bf16 v[46:49], v[144:147], v[188:191], 0
	v_mfma_f32_16x16x32_bf16 v[42:45], v[152:155], v[188:191], 0
	v_mfma_f32_16x16x32_bf16 v[30:33], v[144:147], v[196:199], 0
	v_mfma_f32_16x16x32_bf16 v[26:29], v[152:155], v[196:199], 0
	v_mfma_f32_16x16x32_bf16 v[14:17], v[144:147], v[204:207], 0
	v_mfma_f32_16x16x32_bf16 v[10:13], v[152:155], v[204:207], 0
	v_mfma_f32_16x16x32_bf16 v[62:65], v[148:151], v[184:187], v[62:65]
	v_mfma_f32_16x16x32_bf16 v[58:61], v[156:159], v[184:187], v[58:61]
	v_mfma_f32_16x16x32_bf16 v[46:49], v[148:151], v[192:195], v[46:49]
	v_mfma_f32_16x16x32_bf16 v[42:45], v[156:159], v[192:195], v[42:45]
	v_mfma_f32_16x16x32_bf16 v[30:33], v[148:151], v[200:203], v[30:33]
	v_mfma_f32_16x16x32_bf16 v[26:29], v[156:159], v[200:203], v[26:29]
	v_mfma_f32_16x16x32_bf16 v[14:17], v[148:151], v[208:211], v[14:17]
	v_mfma_f32_16x16x32_bf16 v[10:13], v[156:159], v[208:211], v[10:13]
	s_setprio 0
	s_setprio 1
	v_mfma_f32_16x16x32_bf16 v[54:57], v[164:167], v[180:183], 0
	v_mfma_f32_16x16x32_bf16 v[50:53], v[172:175], v[180:183], 0
	v_mfma_f32_16x16x32_bf16 v[38:41], v[164:167], v[188:191], 0
	v_mfma_f32_16x16x32_bf16 v[34:37], v[172:175], v[188:191], 0
	v_mfma_f32_16x16x32_bf16 v[22:25], v[164:167], v[196:199], 0
	v_mfma_f32_16x16x32_bf16 v[18:21], v[172:175], v[196:199], 0
	v_mfma_f32_16x16x32_bf16 v[6:9], v[164:167], v[204:207], 0
	v_mfma_f32_16x16x32_bf16 v[2:5], v[172:175], v[204:207], 0
	v_mfma_f32_16x16x32_bf16 v[54:57], v[168:171], v[184:187], v[54:57]
	v_mfma_f32_16x16x32_bf16 v[50:53], v[176:179], v[184:187], v[50:53]
	v_mfma_f32_16x16x32_bf16 v[38:41], v[168:171], v[192:195], v[38:41]
	v_mfma_f32_16x16x32_bf16 v[34:37], v[176:179], v[192:195], v[34:37]
	v_mfma_f32_16x16x32_bf16 v[22:25], v[168:171], v[200:203], v[22:25]
	v_mfma_f32_16x16x32_bf16 v[18:21], v[176:179], v[200:203], v[18:21]
	v_mfma_f32_16x16x32_bf16 v[6:9], v[168:171], v[208:211], v[6:9]
	v_mfma_f32_16x16x32_bf16 v[2:5], v[176:179], v[208:211], v[2:5]
	s_setprio 0
	s_barrier
	s_add_i32 s4, 0, 0x18000
	s_add_i32 s5, 0, 0x1c000
	v_add_u32_e32 v156, s4, v141
	v_add_u32_e32 v176, s5, v141
	ds_read_b128 v[144:147], v156
	ds_read_b128 v[148:151], v156 offset:1024
	ds_read_b128 v[152:155], v156 offset:2048
	ds_read_b128 v[156:159], v156 offset:3072
	ds_read_b128 v[164:167], v176
	ds_read_b128 v[168:171], v176 offset:1024
	ds_read_b128 v[172:175], v176 offset:2048
	ds_read_b128 v[176:179], v176 offset:3072
	s_add_u32 s62, s62, 0x10000
	s_addc_u32 s63, s63, 0
	s_mov_b32 m0, s72
	v_lshl_add_u64 v[230:231], s[62:63], 0, v[130:131]
	ds_read_b128 v[180:183], v143 offset:32768
	ds_read_b128 v[184:187], v143 offset:33792
	ds_read_b128 v[188:191], v143 offset:34816
	ds_read_b128 v[192:195], v143 offset:35840
	ds_read_b128 v[196:199], v143 offset:36864
	ds_read_b128 v[200:203], v143 offset:37888
	ds_read_b128 v[204:207], v143 offset:38912
	ds_read_b128 v[208:211], v143 offset:39936
	global_load_lds_dwordx4 v[230:231], off
	v_lshl_add_u64 v[230:231], s[62:63], 0, v[132:133]
	s_mov_b32 m0, s73
	s_nop 0
	global_load_lds_dwordx4 v[230:231], off
	s_waitcnt vmcnt(8)
	s_waitcnt lgkmcnt(0)
	s_barrier
	s_setprio 1
	s_waitcnt lgkmcnt(0)
	v_mfma_f32_16x16x32_bf16 v[126:129], v[144:147], v[180:183], v[126:129]
	v_mfma_f32_16x16x32_bf16 v[122:125], v[152:155], v[180:183], v[122:125]
	v_mfma_f32_16x16x32_bf16 v[110:113], v[144:147], v[188:191], v[110:113]
	v_mfma_f32_16x16x32_bf16 v[106:109], v[152:155], v[188:191], v[106:109]
	v_mfma_f32_16x16x32_bf16 v[94:97], v[144:147], v[196:199], v[94:97]
	v_mfma_f32_16x16x32_bf16 v[90:93], v[152:155], v[196:199], v[90:93]
	v_mfma_f32_16x16x32_bf16 v[78:81], v[144:147], v[204:207], v[78:81]
	v_mfma_f32_16x16x32_bf16 v[74:77], v[152:155], v[204:207], v[74:77]
	v_mfma_f32_16x16x32_bf16 v[126:129], v[148:151], v[184:187], v[126:129]
	v_mfma_f32_16x16x32_bf16 v[122:125], v[156:159], v[184:187], v[122:125]
	v_mfma_f32_16x16x32_bf16 v[110:113], v[148:151], v[192:195], v[110:113]
	v_mfma_f32_16x16x32_bf16 v[106:109], v[156:159], v[192:195], v[106:109]
	v_mfma_f32_16x16x32_bf16 v[94:97], v[148:151], v[200:203], v[94:97]
	v_mfma_f32_16x16x32_bf16 v[90:93], v[156:159], v[200:203], v[90:93]
	v_mfma_f32_16x16x32_bf16 v[78:81], v[148:151], v[208:211], v[78:81]
	v_mfma_f32_16x16x32_bf16 v[74:77], v[156:159], v[208:211], v[74:77]
	s_setprio 0
	s_setprio 1
	v_mfma_f32_16x16x32_bf16 v[118:121], v[164:167], v[180:183], v[118:121]
	v_mfma_f32_16x16x32_bf16 v[114:117], v[172:175], v[180:183], v[114:117]
	v_mfma_f32_16x16x32_bf16 v[102:105], v[164:167], v[188:191], v[102:105]
	v_mfma_f32_16x16x32_bf16 v[98:101], v[172:175], v[188:191], v[98:101]
	v_mfma_f32_16x16x32_bf16 v[86:89], v[164:167], v[196:199], v[86:89]
	v_mfma_f32_16x16x32_bf16 v[82:85], v[172:175], v[196:199], v[82:85]
	v_mfma_f32_16x16x32_bf16 v[70:73], v[164:167], v[204:207], v[70:73]
	v_mfma_f32_16x16x32_bf16 v[66:69], v[172:175], v[204:207], v[66:69]
	v_mfma_f32_16x16x32_bf16 v[118:121], v[168:171], v[184:187], v[118:121]
	v_mfma_f32_16x16x32_bf16 v[114:117], v[176:179], v[184:187], v[114:117]
	v_mfma_f32_16x16x32_bf16 v[102:105], v[168:171], v[192:195], v[102:105]
	v_mfma_f32_16x16x32_bf16 v[98:101], v[176:179], v[192:195], v[98:101]
	v_mfma_f32_16x16x32_bf16 v[86:89], v[168:171], v[200:203], v[86:89]
	v_mfma_f32_16x16x32_bf16 v[82:85], v[176:179], v[200:203], v[82:85]
	v_mfma_f32_16x16x32_bf16 v[70:73], v[168:171], v[208:211], v[70:73]
	v_mfma_f32_16x16x32_bf16 v[66:69], v[176:179], v[208:211], v[66:69]
	s_setprio 0
	s_barrier
; #define PG8_STAGE(bufoff, gbase, voff) do { _Pragma("unroll") for (int _i = 0; _i < 2; ++_i) \
;         __builtin_amdgcn_global_load_lds((const unsigned*)((const char*)(gbase) + (voff)[_i]), (LAS unsigned*)(lds + (bufoff) + ldsw + _i * 8192), 16, 0, 0); } while (0)
; #define PG8_LDA(dst, b, h) do { _Pragma("unroll") for (int m = 0; m < 4; ++m) _Pragma("unroll") for (int k = 0; k < 2; ++k) dst[m][k] = *(const LAS bf16x8*)(lds + PG8_SA(b, h) + aoff + m * 2048 + k * 1024); } while (0)
; #define PG8_LDB(dst, b, h) do { _Pragma("unroll") for (int n = 0; n < 2; ++n) _Pragma("unroll") for (int k = 0; k < 2; ++k) dst[n][k] = *(const LAS bf16x8*)(lds + PG8_SB(b, h) + boff + n * 2048 + k * 1024); } while (0)
; #define PG8_MMA(ai, bj, At, Bt) do { __builtin_amdgcn_s_setprio(1); _Pragma("unroll") for (int m = 0; m < 4; ++m) _Pragma("unroll") for (int n = 0; n < 2; ++n) _Pragma("unroll") for (int k = 0; k < 2; ++k) \
;         acc[ai][bj][m][n] = __builtin_amdgcn_mfma_f32_16x16x32_bf16(Bt[n][k], At[m][k], acc[ai][bj][m][n], 0, 0, 0); __builtin_amdgcn_s_setprio(0); } while (0)
; #define PG8_WAIT_V(n) asm volatile("s_waitcnt vmcnt(" #n ")" ::: "memory")
; #define PG8_WAIT_L(n) asm volatile("s_waitcnt lgkmcnt(" #n ")" ::: "memory")
; #define PG8_BAR __builtin_amdgcn_s_barrier()
; #define PG8_SCHED __builtin_amdgcn_sched_barrier(0)
; template <class Epi, bool MID = false>
; __device__ __forceinline__ void gemm_phase(LAS unsigned char* lds, const Gemm g, const StaticOrder& S, const Epi& E) {
;     ...
;         for (int t = 0; t < nt; t += 2) {
;             const bool last = (t == nt - 2);
;             const char* a1 = cA + (size_t)(t + 1) * kstep;
;             const char* a2 = last ? nA : cA + (size_t)(t + 2) * kstep; const char* b2 = last ? nB : cB + (size_t)(t + 2) * kstep;
;             const char* a3 = a2 + kstep; const char* b3 = b2 + kstep;
;             PG8_LDB(B0, 0, 0); PG8_LDB(B1, 0, 1); PG8_SCHED; PG8_LDA(At, 0, 0); PG8_STAGE(PG8_SA(1, 1), a1 + hstepA, voffA);
;     ...
;             PG8_LDA(At, 1, 1); PG8_STAGE(PG8_SB(1, 0), b3, voffB); PG8_STAGE(PG8_SB(1, 1), b3 + hstepB, voffB); PG8_STAGE(PG8_SA(1, 0), a3, voffA);
;             PG8_WAIT_V(8); PG8_WAIT_L(0); PG8_BAR; PG8_MMA(1, 0, At, B0); PG8_MMA(1, 1, At, B1); PG8_BAR; PG8_SCHED;
	s_add_i32 s4, s4, s70
	v_lshl_add_u64 v[160:161], v[160:161], 0, s[24:25]
	s_mov_b32 m0, s4
	ds_read_b128 v[180:183], v143 offset:49152
	ds_read_b128 v[184:187], v143 offset:50176
	ds_read_b128 v[188:191], v143 offset:51200
	ds_read_b128 v[192:195], v143 offset:52224
	ds_read_b128 v[196:199], v143 offset:53248
	ds_read_b128 v[200:203], v143 offset:54272
	ds_read_b128 v[204:207], v143 offset:55296
	ds_read_b128 v[208:211], v143 offset:56320
	global_load_lds_dwordx4 v[160:161], off
	s_add_i32 m0, s4, 0x2000
	s_add_u32 s60, s60, 0x10080
	v_lshl_add_u64 v[160:161], v[212:213], 0, s[24:25]
	s_addc_u32 s61, s61, 0
	s_add_i32 s4, s5, s70
	global_load_lds_dwordx4 v[160:161], off
	v_lshl_add_u64 v[160:161], s[60:61], 0, v[0:1]
	s_mov_b32 m0, s4
	s_nop 0
	global_load_lds_dwordx4 v[160:161], off
	v_lshl_add_u64 v[160:161], s[60:61], 0, v[134:135]
	s_add_i32 m0, s4, 0x2000
	s_nop 0
	global_load_lds_dwordx4 v[160:161], off
	v_lshl_add_u64 v[160:161], v[214:215], 0, s[24:25]
	s_mov_b32 m0, s75
	s_nop 0
	global_load_lds_dwordx4 v[160:161], off
	v_lshl_add_u64 v[160:161], v[222:223], 0, s[24:25]
	s_mov_b32 m0, s78
	s_nop 0
	global_load_lds_dwordx4 v[160:161], off
	s_waitcnt vmcnt(8)
	s_waitcnt lgkmcnt(0)
	s_barrier
	s_setprio 1
	s_waitcnt lgkmcnt(0)
	v_mfma_f32_16x16x32_bf16 v[62:65], v[144:147], v[180:183], v[62:65]
	v_mfma_f32_16x16x32_bf16 v[58:61], v[152:155], v[180:183], v[58:61]
	v_mfma_f32_16x16x32_bf16 v[46:49], v[144:147], v[188:191], v[46:49]
	v_mfma_f32_16x16x32_bf16 v[42:45], v[152:155], v[188:191], v[42:45]
	v_mfma_f32_16x16x32_bf16 v[30:33], v[144:147], v[196:199], v[30:33]
	v_mfma_f32_16x16x32_bf16 v[26:29], v[152:155], v[196:199], v[26:29]
	v_mfma_f32_16x16x32_bf16 v[14:17], v[144:147], v[204:207], v[14:17]
	v_mfma_f32_16x16x32_bf16 v[10:13], v[152:155], v[204:207], v[10:13]
	v_mfma_f32_16x16x32_bf16 v[62:65], v[148:151], v[184:187], v[62:65]
	v_mfma_f32_16x16x32_bf16 v[58:61], v[156:159], v[184:187], v[58:61]
	v_mfma_f32_16x16x32_bf16 v[46:49], v[148:151], v[192:195], v[46:49]
	v_mfma_f32_16x16x32_bf16 v[42:45], v[156:159], v[192:195], v[42:45]
	v_mfma_f32_16x16x32_bf16 v[30:33], v[148:151], v[200:203], v[30:33]
	v_mfma_f32_16x16x32_bf16 v[26:29], v[156:159], v[200:203], v[26:29]
	v_mfma_f32_16x16x32_bf16 v[14:17], v[148:151], v[208:211], v[14:17]
	v_mfma_f32_16x16x32_bf16 v[10:13], v[156:159], v[208:211], v[10:13]
	s_setprio 0
	s_setprio 1
	v_mfma_f32_16x16x32_bf16 v[54:57], v[164:167], v[180:183], v[54:57]
	v_mfma_f32_16x16x32_bf16 v[50:53], v[172:175], v[180:183], v[50:53]
	v_mfma_f32_16x16x32_bf16 v[38:41], v[164:167], v[188:191], v[38:41]
	v_mfma_f32_16x16x32_bf16 v[34:37], v[172:175], v[188:191], v[34:37]
	v_mfma_f32_16x16x32_bf16 v[22:25], v[164:167], v[196:199], v[22:25]
	v_mfma_f32_16x16x32_bf16 v[18:21], v[172:175], v[196:199], v[18:21]
	v_mfma_f32_16x16x32_bf16 v[6:9], v[164:167], v[204:207], v[6:9]
	v_mfma_f32_16x16x32_bf16 v[2:5], v[172:175], v[204:207], v[2:5]
	v_mfma_f32_16x16x32_bf16 v[54:57], v[168:171], v[184:187], v[54:57]
	v_mfma_f32_16x16x32_bf16 v[50:53], v[176:179], v[184:187], v[50:53]
	v_mfma_f32_16x16x32_bf16 v[38:41], v[168:171], v[192:195], v[38:41]
	v_mfma_f32_16x16x32_bf16 v[34:37], v[176:179], v[192:195], v[34:37]
	v_mfma_f32_16x16x32_bf16 v[22:25], v[168:171], v[200:203], v[22:25]
	v_mfma_f32_16x16x32_bf16 v[18:21], v[176:179], v[200:203], v[18:21]
	v_mfma_f32_16x16x32_bf16 v[6:9], v[168:171], v[208:211], v[6:9]
	v_mfma_f32_16x16x32_bf16 v[2:5], v[176:179], v[208:211], v[2:5]
	s_setprio 0
	s_barrier
	s_add_u32 s58, s58, 0x100
	s_addc_u32 s59, s59, 0
	s_add_u32 s85, s85, 0x100
	s_addc_u32 s86, s86, 0
	s_cmp_ge_i32 s87, s65
	s_mov_b32 s60, s87
	s_cbranch_scc0 .LBB0_1735
	s_branch .Lpk_1735_exit
.LBB0_1735:
	s_add_i32 s87, s60, 2
	s_add_u32 s4, s58, 0xffff0080
	s_addc_u32 s5, s59, -1
	s_add_i32 s88, 0, 0x10000
	s_cmp_eq_u32 s80, s60
	s_cselect_b32 s63, s51, s5
	s_cselect_b32 s62, s53, s4
	s_cselect_b32 s61, s83, s86
	s_cselect_b32 s60, s84, s85
	s_add_i32 s4, 0, 0x14000
	v_add_u32_e32 v156, s88, v141
	v_add_u32_e32 v160, s4, v141
	ds_read_b128 v[144:147], v156
	ds_read_b128 v[148:151], v156 offset:1024
	ds_read_b128 v[152:155], v156 offset:2048
	ds_read_b128 v[156:159], v156 offset:3072
	ds_read_b128 v[164:167], v160
	ds_read_b128 v[168:171], v160 offset:1024
	ds_read_b128 v[172:175], v160 offset:2048
	ds_read_b128 v[176:179], v160 offset:3072
	v_lshl_add_u64 v[160:161], s[58:59], 0, v[136:137]
	s_add_i32 m0, s47, 0xc000
	ds_read_b128 v[180:183], v143
	ds_read_b128 v[184:187], v143 offset:1024
	ds_read_b128 v[188:191], v143 offset:2048
	ds_read_b128 v[192:195], v143 offset:3072
	ds_read_b128 v[196:199], v143 offset:4096
	ds_read_b128 v[200:203], v143 offset:5120
	ds_read_b128 v[204:207], v143 offset:6144
	ds_read_b128 v[208:211], v143 offset:7168
	global_load_lds_dwordx4 v[160:161], off
	v_lshl_add_u64 v[160:161], s[58:59], 0, v[138:139]
	s_add_i32 m0, s47, 0xe000
	s_nop 0
	global_load_lds_dwordx4 v[160:161], off
	s_waitcnt vmcnt(8)
	s_waitcnt lgkmcnt(0)
	s_barrier
; #define PG8_STAGE(bufoff, gbase, voff) do { _Pragma("unroll") for (int _i = 0; _i < 2; ++_i) \
;         __builtin_amdgcn_global_load_lds((const unsigned*)((const char*)(gbase) + (voff)[_i]), (LAS unsigned*)(lds + (bufoff) + ldsw + _i * 8192), 16, 0, 0); } while (0)
; #define PG8_LDA(dst, b, h) do { _Pragma("unroll") for (int m = 0; m < 4; ++m) _Pragma("unroll") for (int k = 0; k < 2; ++k) dst[m][k] = *(const LAS bf16x8*)(lds + PG8_SA(b, h) + aoff + m * 2048 + k * 1024); } while (0)
; #define PG8_MMA(ai, bj, At, Bt) do { __builtin_amdgcn_s_setprio(1); _Pragma("unroll") for (int m = 0; m < 4; ++m) _Pragma("unroll") for (int n = 0; n < 2; ++n) _Pragma("unroll") for (int k = 0; k < 2; ++k) \
;         acc[ai][bj][m][n] = __builtin_amdgcn_mfma_f32_16x16x32_bf16(Bt[n][k], At[m][k], acc[ai][bj][m][n], 0, 0, 0); __builtin_amdgcn_s_setprio(0); } while (0)
; #define PG8_WAIT_V(n) asm volatile("s_waitcnt vmcnt(" #n ")" ::: "memory")
; #define PG8_WAIT_L(n) asm volatile("s_waitcnt lgkmcnt(" #n ")" ::: "memory")
; #define PG8_BAR __builtin_amdgcn_s_barrier()
; #define PG8_SCHED __builtin_amdgcn_sched_barrier(0)
; template <class Epi, bool MID = false>
; __device__ __forceinline__ void gemm_phase(LAS unsigned char* lds, const Gemm g, const StaticOrder& S, const Epi& E) {
;     ...
;             PG8_WAIT_V(8); PG8_WAIT_L(0); PG8_BAR; PG8_MMA(0, 0, At, B0); PG8_MMA(0, 1, At, B1); PG8_BAR; PG8_SCHED;
;             PG8_LDA(At, 0, 1); PG8_STAGE(PG8_SB(0, 0), b2, voffB); PG8_STAGE(PG8_SB(0, 1), b2 + hstepB, voffB); PG8_STAGE(PG8_SA(0, 0), a2, voffA);
;             PG8_WAIT_V(8); PG8_WAIT_L(0); PG8_BAR; PG8_MMA(1, 0, At, B0); PG8_MMA(1, 1, At, B1); PG8_BAR; PG8_SCHED;
	s_setprio 1
	s_waitcnt lgkmcnt(0)
	v_mfma_f32_16x16x32_bf16 v[126:129], v[144:147], v[180:183], v[126:129]
	v_mfma_f32_16x16x32_bf16 v[122:125], v[152:155], v[180:183], v[122:125]
	v_mfma_f32_16x16x32_bf16 v[110:113], v[144:147], v[188:191], v[110:113]
	v_mfma_f32_16x16x32_bf16 v[106:109], v[152:155], v[188:191], v[106:109]
	v_mfma_f32_16x16x32_bf16 v[94:97], v[144:147], v[196:199], v[94:97]
	v_mfma_f32_16x16x32_bf16 v[90:93], v[152:155], v[196:199], v[90:93]
	v_mfma_f32_16x16x32_bf16 v[78:81], v[144:147], v[204:207], v[78:81]
	v_mfma_f32_16x16x32_bf16 v[74:77], v[152:155], v[204:207], v[74:77]
	v_mfma_f32_16x16x32_bf16 v[126:129], v[148:151], v[184:187], v[126:129]
	v_mfma_f32_16x16x32_bf16 v[122:125], v[156:159], v[184:187], v[122:125]
	v_mfma_f32_16x16x32_bf16 v[110:113], v[148:151], v[192:195], v[110:113]
	v_mfma_f32_16x16x32_bf16 v[106:109], v[156:159], v[192:195], v[106:109]
	v_mfma_f32_16x16x32_bf16 v[94:97], v[148:151], v[200:203], v[94:97]
	v_mfma_f32_16x16x32_bf16 v[90:93], v[156:159], v[200:203], v[90:93]
	v_mfma_f32_16x16x32_bf16 v[78:81], v[148:151], v[208:211], v[78:81]
	v_mfma_f32_16x16x32_bf16 v[74:77], v[156:159], v[208:211], v[74:77]
	s_setprio 0
	s_setprio 1
	v_mfma_f32_16x16x32_bf16 v[118:121], v[164:167], v[180:183], v[118:121]
	v_mfma_f32_16x16x32_bf16 v[114:117], v[172:175], v[180:183], v[114:117]
	v_mfma_f32_16x16x32_bf16 v[102:105], v[164:167], v[188:191], v[102:105]
	v_mfma_f32_16x16x32_bf16 v[98:101], v[172:175], v[188:191], v[98:101]
	v_mfma_f32_16x16x32_bf16 v[86:89], v[164:167], v[196:199], v[86:89]
	v_mfma_f32_16x16x32_bf16 v[82:85], v[172:175], v[196:199], v[82:85]
	v_mfma_f32_16x16x32_bf16 v[70:73], v[164:167], v[204:207], v[70:73]
	v_mfma_f32_16x16x32_bf16 v[66:69], v[172:175], v[204:207], v[66:69]
	v_mfma_f32_16x16x32_bf16 v[118:121], v[168:171], v[184:187], v[118:121]
	v_mfma_f32_16x16x32_bf16 v[114:117], v[176:179], v[184:187], v[114:117]
	v_mfma_f32_16x16x32_bf16 v[102:105], v[168:171], v[192:195], v[102:105]
	v_mfma_f32_16x16x32_bf16 v[98:101], v[176:179], v[192:195], v[98:101]
	v_mfma_f32_16x16x32_bf16 v[86:89], v[168:171], v[200:203], v[86:89]
	v_mfma_f32_16x16x32_bf16 v[82:85], v[176:179], v[200:203], v[82:85]
	v_mfma_f32_16x16x32_bf16 v[70:73], v[168:171], v[208:211], v[70:73]
	v_mfma_f32_16x16x32_bf16 v[66:69], v[176:179], v[208:211], v[66:69]
	s_setprio 0
	s_barrier
	s_add_i32 s5, s88, s70
	v_lshl_add_u64 v[160:161], s[60:61], 0, v[0:1]
	s_mov_b32 m0, s5
	ds_read_b128 v[180:183], v143 offset:16384
	ds_read_b128 v[184:187], v143 offset:17408
	ds_read_b128 v[188:191], v143 offset:18432
	ds_read_b128 v[192:195], v143 offset:19456
	ds_read_b128 v[196:199], v143 offset:20480
	ds_read_b128 v[200:203], v143 offset:21504
	ds_read_b128 v[204:207], v143 offset:22528
	ds_read_b128 v[208:211], v143 offset:23552
	global_load_lds_dwordx4 v[160:161], off
	s_add_i32 m0, s5, 0x2000
	s_add_u32 s88, s60, 0x10000
	v_lshl_add_u64 v[212:213], s[60:61], 0, v[134:135]
	s_addc_u32 s89, s61, 0
	s_add_i32 s4, s4, s70
	global_load_lds_dwordx4 v[212:213], off
	v_lshl_add_u64 v[214:215], s[88:89], 0, v[0:1]
	s_mov_b32 m0, s4
	v_lshl_add_u64 v[222:223], s[62:63], 0, v[132:133]
	global_load_lds_dwordx4 v[214:215], off
	v_lshl_add_u64 v[214:215], s[88:89], 0, v[134:135]
	s_add_i32 m0, s4, 0x2000
	s_nop 0
	global_load_lds_dwordx4 v[214:215], off
	v_lshl_add_u64 v[214:215], s[62:63], 0, v[130:131]
	s_mov_b32 m0, s47
	s_nop 0
	global_load_lds_dwordx4 v[214:215], off
	s_mov_b32 m0, s71
	s_nop 0
	global_load_lds_dwordx4 v[222:223], off
	s_waitcnt vmcnt(8)
	s_waitcnt lgkmcnt(0)
	s_barrier
	s_setprio 1
	s_waitcnt lgkmcnt(0)
	v_mfma_f32_16x16x32_bf16 v[62:65], v[144:147], v[180:183], v[62:65]
	v_mfma_f32_16x16x32_bf16 v[58:61], v[152:155], v[180:183], v[58:61]
	v_mfma_f32_16x16x32_bf16 v[46:49], v[144:147], v[188:191], v[46:49]
	v_mfma_f32_16x16x32_bf16 v[42:45], v[152:155], v[188:191], v[42:45]
	v_mfma_f32_16x16x32_bf16 v[30:33], v[144:147], v[196:199], v[30:33]
	v_mfma_f32_16x16x32_bf16 v[26:29], v[152:155], v[196:199], v[26:29]
	v_mfma_f32_16x16x32_bf16 v[14:17], v[144:147], v[204:207], v[14:17]
	v_mfma_f32_16x16x32_bf16 v[10:13], v[152:155], v[204:207], v[10:13]
	v_mfma_f32_16x16x32_bf16 v[62:65], v[148:151], v[184:187], v[62:65]
	v_mfma_f32_16x16x32_bf16 v[58:61], v[156:159], v[184:187], v[58:61]
	v_mfma_f32_16x16x32_bf16 v[46:49], v[148:151], v[192:195], v[46:49]
	v_mfma_f32_16x16x32_bf16 v[42:45], v[156:159], v[192:195], v[42:45]
	v_mfma_f32_16x16x32_bf16 v[30:33], v[148:151], v[200:203], v[30:33]
	v_mfma_f32_16x16x32_bf16 v[26:29], v[156:159], v[200:203], v[26:29]
	v_mfma_f32_16x16x32_bf16 v[14:17], v[148:151], v[208:211], v[14:17]
	v_mfma_f32_16x16x32_bf16 v[10:13], v[156:159], v[208:211], v[10:13]
	s_setprio 0
	s_setprio 1
	v_mfma_f32_16x16x32_bf16 v[54:57], v[164:167], v[180:183], v[54:57]
	v_mfma_f32_16x16x32_bf16 v[50:53], v[172:175], v[180:183], v[50:53]
	v_mfma_f32_16x16x32_bf16 v[38:41], v[164:167], v[188:191], v[38:41]
	v_mfma_f32_16x16x32_bf16 v[34:37], v[172:175], v[188:191], v[34:37]
	v_mfma_f32_16x16x32_bf16 v[22:25], v[164:167], v[196:199], v[22:25]
	v_mfma_f32_16x16x32_bf16 v[18:21], v[172:175], v[196:199], v[18:21]
	v_mfma_f32_16x16x32_bf16 v[6:9], v[164:167], v[204:207], v[6:9]
	v_mfma_f32_16x16x32_bf16 v[2:5], v[172:175], v[204:207], v[2:5]
	v_mfma_f32_16x16x32_bf16 v[54:57], v[168:171], v[184:187], v[54:57]
	v_mfma_f32_16x16x32_bf16 v[50:53], v[176:179], v[184:187], v[50:53]
	v_mfma_f32_16x16x32_bf16 v[38:41], v[168:171], v[192:195], v[38:41]
	v_mfma_f32_16x16x32_bf16 v[34:37], v[176:179], v[192:195], v[34:37]
	v_mfma_f32_16x16x32_bf16 v[22:25], v[168:171], v[200:203], v[22:25]
	v_mfma_f32_16x16x32_bf16 v[18:21], v[176:179], v[200:203], v[18:21]
	v_mfma_f32_16x16x32_bf16 v[6:9], v[168:171], v[208:211], v[6:9]
	v_mfma_f32_16x16x32_bf16 v[2:5], v[176:179], v[208:211], v[2:5]
	s_setprio 0
	s_barrier
; #define PG8_STAGE(bufoff, gbase, voff) do { _Pragma("unroll") for (int _i = 0; _i < 2; ++_i) \
;         __builtin_amdgcn_global_load_lds((const unsigned*)((const char*)(gbase) + (voff)[_i]), (LAS unsigned*)(lds + (bufoff) + ldsw + _i * 8192), 16, 0, 0); } while (0)
; #define PG8_LDA(dst, b, h) do { _Pragma("unroll") for (int m = 0; m < 4; ++m) _Pragma("unroll") for (int k = 0; k < 2; ++k) dst[m][k] = *(const LAS bf16x8*)(lds + PG8_SA(b, h) + aoff + m * 2048 + k * 1024); } while (0)
; #define PG8_LDB(dst, b, h) do { _Pragma("unroll") for (int n = 0; n < 2; ++n) _Pragma("unroll") for (int k = 0; k < 2; ++k) dst[n][k] = *(const LAS bf16x8*)(lds + PG8_SB(b, h) + boff + n * 2048 + k * 1024); } while (0)
; #define PG8_MMA(ai, bj, At, Bt) do { __builtin_amdgcn_s_setprio(1); _Pragma("unroll") for (int m = 0; m < 4; ++m) _Pragma("unroll") for (int n = 0; n < 2; ++n) _Pragma("unroll") for (int k = 0; k < 2; ++k) \
;         acc[ai][bj][m][n] = __builtin_amdgcn_mfma_f32_16x16x32_bf16(Bt[n][k], At[m][k], acc[ai][bj][m][n], 0, 0, 0); __builtin_amdgcn_s_setprio(0); } while (0)
; #define PG8_WAIT_V(n) asm volatile("s_waitcnt vmcnt(" #n ")" ::: "memory")
; #define PG8_WAIT_L(n) asm volatile("s_waitcnt lgkmcnt(" #n ")" ::: "memory")
; #define PG8_BAR __builtin_amdgcn_s_barrier()
; #define PG8_SCHED __builtin_amdgcn_sched_barrier(0)
; template <class Epi, bool MID = false>
; __device__ __forceinline__ void gemm_phase(LAS unsigned char* lds, const Gemm g, const StaticOrder& S, const Epi& E) {
;     ...
;             PG8_LDB(B0, 1, 0); PG8_LDB(B1, 1, 1); PG8_SCHED; PG8_LDA(At, 1, 0); PG8_STAGE(PG8_SA(0, 1), a2 + hstepA, voffA);
;             PG8_WAIT_V(8); PG8_WAIT_L(0); PG8_BAR; PG8_MMA(0, 0, At, B0); PG8_MMA(0, 1, At, B1); PG8_BAR; PG8_SCHED;
	s_add_i32 s4, 0, 0x18000
	s_add_i32 s5, 0, 0x1c000
	v_add_u32_e32 v156, s4, v141
	v_add_u32_e32 v176, s5, v141
	ds_read_b128 v[144:147], v156
	ds_read_b128 v[148:151], v156 offset:1024
	ds_read_b128 v[152:155], v156 offset:2048
	ds_read_b128 v[156:159], v156 offset:3072
	ds_read_b128 v[164:167], v176
	ds_read_b128 v[168:171], v176 offset:1024
	ds_read_b128 v[172:175], v176 offset:2048
	ds_read_b128 v[176:179], v176 offset:3072
	s_add_u32 s62, s62, 0x10000
	s_addc_u32 s63, s63, 0
	s_mov_b32 m0, s72
	v_lshl_add_u64 v[230:231], s[62:63], 0, v[130:131]
	ds_read_b128 v[180:183], v143 offset:32768
	ds_read_b128 v[184:187], v143 offset:33792
	ds_read_b128 v[188:191], v143 offset:34816
	ds_read_b128 v[192:195], v143 offset:35840
	ds_read_b128 v[196:199], v143 offset:36864
	ds_read_b128 v[200:203], v143 offset:37888
	ds_read_b128 v[204:207], v143 offset:38912
	ds_read_b128 v[208:211], v143 offset:39936
	global_load_lds_dwordx4 v[230:231], off
	v_lshl_add_u64 v[230:231], s[62:63], 0, v[132:133]
	s_mov_b32 m0, s73
	s_nop 0
	global_load_lds_dwordx4 v[230:231], off
	s_waitcnt vmcnt(8)
	s_waitcnt lgkmcnt(0)
	s_barrier
	s_setprio 1
	s_waitcnt lgkmcnt(0)
	v_mfma_f32_16x16x32_bf16 v[126:129], v[144:147], v[180:183], v[126:129]
	v_mfma_f32_16x16x32_bf16 v[122:125], v[152:155], v[180:183], v[122:125]
	v_mfma_f32_16x16x32_bf16 v[110:113], v[144:147], v[188:191], v[110:113]
	v_mfma_f32_16x16x32_bf16 v[106:109], v[152:155], v[188:191], v[106:109]
	v_mfma_f32_16x16x32_bf16 v[94:97], v[144:147], v[196:199], v[94:97]
	v_mfma_f32_16x16x32_bf16 v[90:93], v[152:155], v[196:199], v[90:93]
	v_mfma_f32_16x16x32_bf16 v[78:81], v[144:147], v[204:207], v[78:81]
	v_mfma_f32_16x16x32_bf16 v[74:77], v[152:155], v[204:207], v[74:77]
	v_mfma_f32_16x16x32_bf16 v[126:129], v[148:151], v[184:187], v[126:129]
	v_mfma_f32_16x16x32_bf16 v[122:125], v[156:159], v[184:187], v[122:125]
	v_mfma_f32_16x16x32_bf16 v[110:113], v[148:151], v[192:195], v[110:113]
	v_mfma_f32_16x16x32_bf16 v[106:109], v[156:159], v[192:195], v[106:109]
	v_mfma_f32_16x16x32_bf16 v[94:97], v[148:151], v[200:203], v[94:97]
	v_mfma_f32_16x16x32_bf16 v[90:93], v[156:159], v[200:203], v[90:93]
	v_mfma_f32_16x16x32_bf16 v[78:81], v[148:151], v[208:211], v[78:81]
	v_mfma_f32_16x16x32_bf16 v[74:77], v[156:159], v[208:211], v[74:77]
	s_setprio 0
	s_setprio 1
	v_mfma_f32_16x16x32_bf16 v[118:121], v[164:167], v[180:183], v[118:121]
	v_mfma_f32_16x16x32_bf16 v[114:117], v[172:175], v[180:183], v[114:117]
	v_mfma_f32_16x16x32_bf16 v[102:105], v[164:167], v[188:191], v[102:105]
	v_mfma_f32_16x16x32_bf16 v[98:101], v[172:175], v[188:191], v[98:101]
	v_mfma_f32_16x16x32_bf16 v[86:89], v[164:167], v[196:199], v[86:89]
	v_mfma_f32_16x16x32_bf16 v[82:85], v[172:175], v[196:199], v[82:85]
	v_mfma_f32_16x16x32_bf16 v[70:73], v[164:167], v[204:207], v[70:73]
	v_mfma_f32_16x16x32_bf16 v[66:69], v[172:175], v[204:207], v[66:69]
	v_mfma_f32_16x16x32_bf16 v[118:121], v[168:171], v[184:187], v[118:121]
	v_mfma_f32_16x16x32_bf16 v[114:117], v[176:179], v[184:187], v[114:117]
	v_mfma_f32_16x16x32_bf16 v[102:105], v[168:171], v[192:195], v[102:105]
	v_mfma_f32_16x16x32_bf16 v[98:101], v[176:179], v[192:195], v[98:101]
	v_mfma_f32_16x16x32_bf16 v[86:89], v[168:171], v[200:203], v[86:89]
	v_mfma_f32_16x16x32_bf16 v[82:85], v[176:179], v[200:203], v[82:85]
	v_mfma_f32_16x16x32_bf16 v[70:73], v[168:171], v[208:211], v[70:73]
	v_mfma_f32_16x16x32_bf16 v[66:69], v[176:179], v[208:211], v[66:69]
	s_setprio 0
	s_barrier
; #define PG8_STAGE(bufoff, gbase, voff) do { _Pragma("unroll") for (int _i = 0; _i < 2; ++_i) \
;         __builtin_amdgcn_global_load_lds((const unsigned*)((const char*)(gbase) + (voff)[_i]), (LAS unsigned*)(lds + (bufoff) + ldsw + _i * 8192), 16, 0, 0); } while (0)
; #define PG8_LDA(dst, b, h) do { _Pragma("unroll") for (int m = 0; m < 4; ++m) _Pragma("unroll") for (int k = 0; k < 2; ++k) dst[m][k] = *(const LAS bf16x8*)(lds + PG8_SA(b, h) + aoff + m * 2048 + k * 1024); } while (0)
; #define PG8_MMA(ai, bj, At, Bt) do { __builtin_amdgcn_s_setprio(1); _Pragma("unroll") for (int m = 0; m < 4; ++m) _Pragma("unroll") for (int n = 0; n < 2; ++n) _Pragma("unroll") for (int k = 0; k < 2; ++k) \
;         acc[ai][bj][m][n] = __builtin_amdgcn_mfma_f32_16x16x32_bf16(Bt[n][k], At[m][k], acc[ai][bj][m][n], 0, 0, 0); __builtin_amdgcn_s_setprio(0); } while (0)
; #define PG8_WAIT_V(n) asm volatile("s_waitcnt vmcnt(" #n ")" ::: "memory")
; #define PG8_WAIT_L(n) asm volatile("s_waitcnt lgkmcnt(" #n ")" ::: "memory")
; #define PG8_BAR __builtin_amdgcn_s_barrier()
; #define PG8_SCHED __builtin_amdgcn_sched_barrier(0)
; template <class Epi, bool MID = false>
; __device__ __forceinline__ void gemm_phase(LAS unsigned char* lds, const Gemm g, const StaticOrder& S, const Epi& E) {
;     ...
;             PG8_LDA(At, 1, 1); PG8_STAGE(PG8_SB(1, 0), b3, voffB); PG8_STAGE(PG8_SB(1, 1), b3 + hstepB, voffB); PG8_STAGE(PG8_SA(1, 0), a3, voffA);
;             PG8_WAIT_V(8); PG8_WAIT_L(0); PG8_BAR; PG8_MMA(1, 0, At, B0); PG8_MMA(1, 1, At, B1); PG8_BAR; PG8_SCHED;
;             if constexpr (MID) { if (t == 6) E.mid(acc, cur, wr, wc, fr, fq); }
;         }
;         if (wr == 0) PG8_BAR;
	s_add_i32 s4, s4, s70
	v_lshl_add_u64 v[160:161], v[160:161], 0, s[24:25]
	s_mov_b32 m0, s4
	ds_read_b128 v[180:183], v143 offset:49152
	ds_read_b128 v[184:187], v143 offset:50176
	ds_read_b128 v[188:191], v143 offset:51200
	ds_read_b128 v[192:195], v143 offset:52224
	ds_read_b128 v[196:199], v143 offset:53248
	ds_read_b128 v[200:203], v143 offset:54272
	ds_read_b128 v[204:207], v143 offset:55296
	ds_read_b128 v[208:211], v143 offset:56320
	global_load_lds_dwordx4 v[160:161], off
	s_add_i32 m0, s4, 0x2000
	s_add_u32 s60, s60, 0x10080
	v_lshl_add_u64 v[160:161], v[212:213], 0, s[24:25]
	s_addc_u32 s61, s61, 0
	s_add_i32 s4, s5, s70
	global_load_lds_dwordx4 v[160:161], off
	v_lshl_add_u64 v[160:161], s[60:61], 0, v[0:1]
	s_mov_b32 m0, s4
	s_nop 0
	global_load_lds_dwordx4 v[160:161], off
	v_lshl_add_u64 v[160:161], s[60:61], 0, v[134:135]
	s_add_i32 m0, s4, 0x2000
	s_nop 0
	global_load_lds_dwordx4 v[160:161], off
	v_lshl_add_u64 v[160:161], v[214:215], 0, s[24:25]
	s_mov_b32 m0, s75
	s_nop 0
	global_load_lds_dwordx4 v[160:161], off
	v_lshl_add_u64 v[160:161], v[222:223], 0, s[24:25]
	s_mov_b32 m0, s78
	s_nop 0
	global_load_lds_dwordx4 v[160:161], off
	s_waitcnt vmcnt(8)
	s_waitcnt lgkmcnt(0)
	s_barrier
	s_setprio 1
	s_waitcnt lgkmcnt(0)
	v_mfma_f32_16x16x32_bf16 v[62:65], v[144:147], v[180:183], v[62:65]
	v_mfma_f32_16x16x32_bf16 v[58:61], v[152:155], v[180:183], v[58:61]
	v_mfma_f32_16x16x32_bf16 v[46:49], v[144:147], v[188:191], v[46:49]
	v_mfma_f32_16x16x32_bf16 v[42:45], v[152:155], v[188:191], v[42:45]
	v_mfma_f32_16x16x32_bf16 v[30:33], v[144:147], v[196:199], v[30:33]
	v_mfma_f32_16x16x32_bf16 v[26:29], v[152:155], v[196:199], v[26:29]
	v_mfma_f32_16x16x32_bf16 v[14:17], v[144:147], v[204:207], v[14:17]
	v_mfma_f32_16x16x32_bf16 v[10:13], v[152:155], v[204:207], v[10:13]
	v_mfma_f32_16x16x32_bf16 v[62:65], v[148:151], v[184:187], v[62:65]
	v_mfma_f32_16x16x32_bf16 v[58:61], v[156:159], v[184:187], v[58:61]
	v_mfma_f32_16x16x32_bf16 v[46:49], v[148:151], v[192:195], v[46:49]
	v_mfma_f32_16x16x32_bf16 v[42:45], v[156:159], v[192:195], v[42:45]
	v_mfma_f32_16x16x32_bf16 v[30:33], v[148:151], v[200:203], v[30:33]
	v_mfma_f32_16x16x32_bf16 v[26:29], v[156:159], v[200:203], v[26:29]
	v_mfma_f32_16x16x32_bf16 v[14:17], v[148:151], v[208:211], v[14:17]
	v_mfma_f32_16x16x32_bf16 v[10:13], v[156:159], v[208:211], v[10:13]
	s_setprio 0
	s_setprio 1
	v_mfma_f32_16x16x32_bf16 v[54:57], v[164:167], v[180:183], v[54:57]
	v_mfma_f32_16x16x32_bf16 v[50:53], v[172:175], v[180:183], v[50:53]
	v_mfma_f32_16x16x32_bf16 v[38:41], v[164:167], v[188:191], v[38:41]
	v_mfma_f32_16x16x32_bf16 v[34:37], v[172:175], v[188:191], v[34:37]
	v_mfma_f32_16x16x32_bf16 v[22:25], v[164:167], v[196:199], v[22:25]
	v_mfma_f32_16x16x32_bf16 v[18:21], v[172:175], v[196:199], v[18:21]
	v_mfma_f32_16x16x32_bf16 v[6:9], v[164:167], v[204:207], v[6:9]
	v_mfma_f32_16x16x32_bf16 v[2:5], v[172:175], v[204:207], v[2:5]
	v_mfma_f32_16x16x32_bf16 v[54:57], v[168:171], v[184:187], v[54:57]
	v_mfma_f32_16x16x32_bf16 v[50:53], v[176:179], v[184:187], v[50:53]
	v_mfma_f32_16x16x32_bf16 v[38:41], v[168:171], v[192:195], v[38:41]
	v_mfma_f32_16x16x32_bf16 v[34:37], v[176:179], v[192:195], v[34:37]
	v_mfma_f32_16x16x32_bf16 v[22:25], v[168:171], v[200:203], v[22:25]
	v_mfma_f32_16x16x32_bf16 v[18:21], v[176:179], v[200:203], v[18:21]
	v_mfma_f32_16x16x32_bf16 v[6:9], v[168:171], v[208:211], v[6:9]
	v_mfma_f32_16x16x32_bf16 v[2:5], v[176:179], v[208:211], v[2:5]
	s_setprio 0
	s_barrier
	s_add_u32 s58, s58, 0x100
	s_addc_u32 s59, s59, 0
	s_add_u32 s85, s85, 0x100
	s_addc_u32 s86, s86, 0
	s_cmp_ge_i32 s87, s65
	s_mov_b32 s60, s87
	s_cbranch_scc0 .LBB0_1735
.Lpk_1735_exit:
	s_and_b64 vcc, exec, s[42:43]
	s_cbranch_vccz .LBB0_1738
.LBB0_1737:
	s_barrier

; #define PG8_STAGE(bufoff, gbase, voff) do { _Pragma("unroll") for (int _i = 0; _i < 2; ++_i) \
;         __builtin_amdgcn_global_load_lds((const unsigned*)((const char*)(gbase) + (voff)[_i]), (LAS unsigned*)(lds + (bufoff) + ldsw + _i * 8192), 16, 0, 0); } while (0)
; #define PG8_LDA(dst, b, h) do { _Pragma("unroll") for (int m = 0; m < 4; ++m) _Pragma("unroll") for (int k = 0; k < 2; ++k) dst[m][k] = *(const LAS bf16x8*)(lds + PG8_SA(b, h) + aoff + m * 2048 + k * 1024); } while (0)
; #define PG8_LDB(dst, b, h) do { _Pragma("unroll") for (int n = 0; n < 2; ++n) _Pragma("unroll") for (int k = 0; k < 2; ++k) dst[n][k] = *(const LAS bf16x8*)(lds + PG8_SB(b, h) + boff + n * 2048 + k * 1024); } while (0)
; #define PG8_MMA(ai, bj, At, Bt) do { __builtin_amdgcn_s_setprio(1); _Pragma("unroll") for (int m = 0; m < 4; ++m) _Pragma("unroll") for (int n = 0; n < 2; ++n) _Pragma("unroll") for (int k = 0; k < 2; ++k) \
;         acc[ai][bj][m][n] = __builtin_amdgcn_mfma_f32_16x16x32_bf16(Bt[n][k], At[m][k], acc[ai][bj][m][n], 0, 0, 0); __builtin_amdgcn_s_setprio(0); } while (0)
; #define PG8_BAR __builtin_amdgcn_s_barrier()
; template <class Epi, bool MID = false>
; __device__ __forceinline__ void gemm_phase(LAS unsigned char* lds, const Gemm g, const StaticOrder& S, const Epi& E) {
;     ...
;         const bool has_next = S.next(ui + 1, nxt);
;         const char* nA = has_next ? (const char*)g.A + (size_t)nxt.pm * tstepA : cA; const char* nB = has_next ? (const char*)g.Bt + (size_t)nxt.pn * tstepB : cB;
; #pragma nounroll
;         for (int t = 0; t < nt; t += 2) {
;             const bool last = (t == nt - 2);
;             const char* a1 = cA + (size_t)(t + 1) * kstep;
;             const char* a2 = last ? nA : cA + (size_t)(t + 2) * kstep; const char* b2 = last ? nB : cB + (size_t)(t + 2) * kstep;
;             const char* a3 = a2 + kstep; const char* b3 = b2 + kstep;
;             PG8_LDB(B0, 0, 0); PG8_LDB(B1, 0, 1); PG8_SCHED; PG8_LDA(At, 0, 0); PG8_STAGE(PG8_SA(1, 1), a1 + hstepA, voffA);
;             PG8_WAIT_V(8); PG8_WAIT_L(0); PG8_BAR; PG8_MMA(0, 0, At, B0); PG8_MMA(0, 1, At, B1); PG8_BAR; PG8_SCHED;
;             PG8_LDA(At, 0, 1); PG8_STAGE(PG8_SB(0, 0), b2, voffB); PG8_STAGE(PG8_SB(0, 1), b2 + hstepB, voffB); PG8_STAGE(PG8_SA(0, 0), a2, voffA);
;             PG8_WAIT_V(8); PG8_WAIT_L(0); PG8_BAR; PG8_MMA(1, 0, At, B0); PG8_MMA(1, 1, At, B1); PG8_BAR; PG8_SCHED;
.LBB0_1762:
	s_ashr_i32 s67, s66, 31
	s_lshl_b64 s[70:71], s[66:67], 19
	s_add_u32 s80, s46, s70
	s_addc_u32 s81, s47, s71
	s_ashr_i32 s65, s64, 31
	s_lshl_b64 s[70:71], s[64:65], 19
	s_add_u32 s70, s83, s70
	s_addc_u32 s71, s84, s71
	s_andn2_b64 vcc, exec, s[58:59]
	s_cbranch_vccnz .LBB0_1786
	s_and_b64 s[72:73], s[42:43], exec
	s_cselect_b32 s39, s81, s69
	s_cselect_b32 s45, s80, s68
	s_cselect_b32 s48, s71, s79
	s_cselect_b32 s65, s70, s78
	s_add_u32 vcc_lo, s68, 0x40080
	s_addc_u32 vcc_hi, s69, 0
	s_add_u32 s67, s78, 0x100
	s_addc_u32 s72, s79, 0
	s_mov_b32 s68, 0
	s_add_i32 s73, s68, 2
	s_add_u32 s4, vcc_lo, 0xfffc0080
	s_addc_u32 s5, vcc_hi, -1
	s_add_i32 s97, 0, 0x10000
	s_cmp_eq_u32 s95, s68
	s_cselect_b32 s79, s39, s5
	s_cselect_b32 s78, s45, s4
	s_cselect_b32 s69, s48, s72
	s_cselect_b32 s68, s65, s67
	s_add_i32 s6, 0, 0x14000
	v_add_u32_e32 v142, s97, v209
	v_add_u32_e32 v172, s6, v209
	ds_read_b128 v[130:133], v142
	ds_read_b128 v[134:137], v142 offset:1024
	ds_read_b128 v[138:141], v142 offset:2048
	ds_read_b128 v[142:145], v142 offset:3072
	ds_read_b128 v[158:161], v172
	ds_read_b128 v[164:167], v172 offset:1024
	ds_read_b128 v[168:171], v172 offset:2048
	ds_read_b128 v[172:175], v172 offset:3072
	v_lshl_add_u64 v[212:213], vcc, 0, v[154:155]
	s_add_i32 m0, s87, 0xc000
	ds_read_b128 v[176:179], v211
	ds_read_b128 v[180:183], v211 offset:1024
	ds_read_b128 v[184:187], v211 offset:2048
	ds_read_b128 v[188:191], v211 offset:3072
	ds_read_b128 v[192:195], v211 offset:4096
	ds_read_b128 v[196:199], v211 offset:5120
	ds_read_b128 v[200:203], v211 offset:6144
	ds_read_b128 v[204:207], v211 offset:7168
	global_load_lds_dwordx4 v[212:213], off
	v_lshl_add_u64 v[212:213], vcc, 0, v[156:157]
	s_add_i32 m0, s87, 0xe000
	s_nop 0
	global_load_lds_dwordx4 v[212:213], off
	s_waitcnt vmcnt(8)
	s_waitcnt lgkmcnt(0)
	s_barrier
	s_setprio 1
	s_waitcnt lgkmcnt(0)
	v_mfma_f32_16x16x32_bf16 v[126:129], v[130:133], v[176:179], 0
	v_mfma_f32_16x16x32_bf16 v[122:125], v[138:141], v[176:179], 0
	v_mfma_f32_16x16x32_bf16 v[110:113], v[130:133], v[184:187], 0
	v_mfma_f32_16x16x32_bf16 v[106:109], v[138:141], v[184:187], 0
	v_mfma_f32_16x16x32_bf16 v[94:97], v[130:133], v[192:195], 0
	v_mfma_f32_16x16x32_bf16 v[90:93], v[138:141], v[192:195], 0
	v_mfma_f32_16x16x32_bf16 v[78:81], v[130:133], v[200:203], 0
	v_mfma_f32_16x16x32_bf16 v[74:77], v[138:141], v[200:203], 0
	v_mfma_f32_16x16x32_bf16 v[126:129], v[134:137], v[180:183], v[126:129]
	v_mfma_f32_16x16x32_bf16 v[122:125], v[142:145], v[180:183], v[122:125]
	v_mfma_f32_16x16x32_bf16 v[110:113], v[134:137], v[188:191], v[110:113]
	v_mfma_f32_16x16x32_bf16 v[106:109], v[142:145], v[188:191], v[106:109]
	v_mfma_f32_16x16x32_bf16 v[94:97], v[134:137], v[196:199], v[94:97]
	v_mfma_f32_16x16x32_bf16 v[90:93], v[142:145], v[196:199], v[90:93]
	v_mfma_f32_16x16x32_bf16 v[78:81], v[134:137], v[204:207], v[78:81]
	v_mfma_f32_16x16x32_bf16 v[74:77], v[142:145], v[204:207], v[74:77]
	s_setprio 0
	s_setprio 1
	v_mfma_f32_16x16x32_bf16 v[118:121], v[158:161], v[176:179], 0
	v_mfma_f32_16x16x32_bf16 v[114:117], v[168:171], v[176:179], 0
	v_mfma_f32_16x16x32_bf16 v[102:105], v[158:161], v[184:187], 0
	v_mfma_f32_16x16x32_bf16 v[98:101], v[168:171], v[184:187], 0
	v_mfma_f32_16x16x32_bf16 v[86:89], v[158:161], v[192:195], 0
	v_mfma_f32_16x16x32_bf16 v[82:85], v[168:171], v[192:195], 0
	v_mfma_f32_16x16x32_bf16 v[70:73], v[158:161], v[200:203], 0
	v_mfma_f32_16x16x32_bf16 v[66:69], v[168:171], v[200:203], 0
	v_mfma_f32_16x16x32_bf16 v[118:121], v[164:167], v[180:183], v[118:121]
	v_mfma_f32_16x16x32_bf16 v[114:117], v[172:175], v[180:183], v[114:117]
	v_mfma_f32_16x16x32_bf16 v[102:105], v[164:167], v[188:191], v[102:105]
	v_mfma_f32_16x16x32_bf16 v[98:101], v[172:175], v[188:191], v[98:101]
	v_mfma_f32_16x16x32_bf16 v[86:89], v[164:167], v[196:199], v[86:89]
	v_mfma_f32_16x16x32_bf16 v[82:85], v[172:175], v[196:199], v[82:85]
	v_mfma_f32_16x16x32_bf16 v[70:73], v[164:167], v[204:207], v[70:73]
	v_mfma_f32_16x16x32_bf16 v[66:69], v[172:175], v[204:207], v[66:69]
	s_setprio 0
	s_barrier
	s_add_i32 s4, s97, s86
	v_lshl_add_u64 v[212:213], s[68:69], 0, v[0:1]
	s_mov_b32 m0, s4
	ds_read_b128 v[176:179], v211 offset:16384
	ds_read_b128 v[180:183], v211 offset:17408
	ds_read_b128 v[184:187], v211 offset:18432
	ds_read_b128 v[188:191], v211 offset:19456
	ds_read_b128 v[192:195], v211 offset:20480
	ds_read_b128 v[196:199], v211 offset:21504
	ds_read_b128 v[200:203], v211 offset:22528
	ds_read_b128 v[204:207], v211 offset:23552
	global_load_lds_dwordx4 v[212:213], off
	s_add_i32 m0, s4, 0x2000
	s_add_u32 s4, s68, 0x40000
	v_lshl_add_u64 v[214:215], s[68:69], 0, v[150:151]
	s_addc_u32 s5, s69, 0
	s_add_i32 s6, s6, s86
	global_load_lds_dwordx4 v[214:215], off
	v_lshl_add_u64 v[222:223], s[4:5], 0, v[0:1]
	s_mov_b32 m0, s6
	v_lshl_add_u64 v[230:231], s[78:79], 0, v[148:149]
	global_load_lds_dwordx4 v[222:223], off
	v_lshl_add_u64 v[222:223], s[4:5], 0, v[150:151]
	s_add_i32 m0, s6, 0x2000
	s_nop 0
	global_load_lds_dwordx4 v[222:223], off
	v_lshl_add_u64 v[222:223], s[78:79], 0, v[146:147]
	s_mov_b32 m0, s87
	s_nop 0
	global_load_lds_dwordx4 v[222:223], off
	s_mov_b32 m0, s88
	s_nop 0
	global_load_lds_dwordx4 v[230:231], off
	s_waitcnt vmcnt(8)
	s_waitcnt lgkmcnt(0)
	s_barrier
; #define PG8_STAGE(bufoff, gbase, voff) do { _Pragma("unroll") for (int _i = 0; _i < 2; ++_i) \
;         __builtin_amdgcn_global_load_lds((const unsigned*)((const char*)(gbase) + (voff)[_i]), (LAS unsigned*)(lds + (bufoff) + ldsw + _i * 8192), 16, 0, 0); } while (0)
; #define PG8_LDA(dst, b, h) do { _Pragma("unroll") for (int m = 0; m < 4; ++m) _Pragma("unroll") for (int k = 0; k < 2; ++k) dst[m][k] = *(const LAS bf16x8*)(lds + PG8_SA(b, h) + aoff + m * 2048 + k * 1024); } while (0)
; #define PG8_LDB(dst, b, h) do { _Pragma("unroll") for (int n = 0; n < 2; ++n) _Pragma("unroll") for (int k = 0; k < 2; ++k) dst[n][k] = *(const LAS bf16x8*)(lds + PG8_SB(b, h) + boff + n * 2048 + k * 1024); } while (0)
; #define PG8_WAIT_V(n) asm volatile("s_waitcnt vmcnt(" #n ")" ::: "memory")
; #define PG8_BAR __builtin_amdgcn_s_barrier()
; template <class Epi, bool MID = false>
; __device__ __forceinline__ void gemm_phase(LAS unsigned char* lds, const Gemm g, const StaticOrder& S, const Epi& E) {
;     ...
;         for (int t = 0; t < nt; t += 2) {
;             const bool last = (t == nt - 2);
;             const char* a1 = cA + (size_t)(t + 1) * kstep;
;             const char* a2 = last ? nA : cA + (size_t)(t + 2) * kstep; const char* b2 = last ? nB : cB + (size_t)(t + 2) * kstep;
;             const char* a3 = a2 + kstep; const char* b3 = b2 + kstep;
;             PG8_LDB(B0, 0, 0); PG8_LDB(B1, 0, 1); PG8_SCHED; PG8_LDA(At, 0, 0); PG8_STAGE(PG8_SA(1, 1), a1 + hstepA, voffA);
;             PG8_WAIT_V(8); PG8_WAIT_L(0); PG8_BAR; PG8_MMA(0, 0, At, B0); PG8_MMA(0, 1, At, B1); PG8_BAR; PG8_SCHED;
;             PG8_LDA(At, 0, 1); PG8_STAGE(PG8_SB(0, 0), b2, voffB); PG8_STAGE(PG8_SB(0, 1), b2 + hstepB, voffB); PG8_STAGE(PG8_SA(0, 0), a2, voffA);
;             PG8_WAIT_V(8); PG8_WAIT_L(0); PG8_BAR; PG8_MMA(1, 0, At, B0); PG8_MMA(1, 1, At, B1); PG8_BAR; PG8_SCHED;
;             PG8_LDB(B0, 1, 0); PG8_LDB(B1, 1, 1); PG8_SCHED; PG8_LDA(At, 1, 0); PG8_STAGE(PG8_SA(0, 1), a2 + hstepA, voffA);
;             PG8_WAIT_V(8); PG8_WAIT_L(0); PG8_BAR; PG8_MMA(0, 0, At, B0); PG8_MMA(0, 1, At, B1); PG8_BAR; PG8_SCHED;
;             PG8_LDA(At, 1, 1); PG8_STAGE(PG8_SB(1, 0), b3, voffB); PG8_STAGE(PG8_SB(1, 1), b3 + hstepB, voffB); PG8_STAGE(PG8_SA(1, 0), a3, voffA);
;             PG8_WAIT_V(8); PG8_WAIT_L(0); PG8_BAR; PG8_MMA(1, 0, At, B0); PG8_MMA(1, 1, At, B1); PG8_BAR; PG8_SCHED;
	s_setprio 1
	s_waitcnt lgkmcnt(0)
	v_mfma_f32_16x16x32_bf16 v[62:65], v[130:133], v[176:179], 0
	v_mfma_f32_16x16x32_bf16 v[58:61], v[138:141], v[176:179], 0
	v_mfma_f32_16x16x32_bf16 v[46:49], v[130:133], v[184:187], 0
	v_mfma_f32_16x16x32_bf16 v[42:45], v[138:141], v[184:187], 0
	v_mfma_f32_16x16x32_bf16 v[30:33], v[130:133], v[192:195], 0
	v_mfma_f32_16x16x32_bf16 v[26:29], v[138:141], v[192:195], 0
	v_mfma_f32_16x16x32_bf16 v[14:17], v[130:133], v[200:203], 0
	v_mfma_f32_16x16x32_bf16 v[10:13], v[138:141], v[200:203], 0
	v_mfma_f32_16x16x32_bf16 v[62:65], v[134:137], v[180:183], v[62:65]
	v_mfma_f32_16x16x32_bf16 v[58:61], v[142:145], v[180:183], v[58:61]
	v_mfma_f32_16x16x32_bf16 v[46:49], v[134:137], v[188:191], v[46:49]
	v_mfma_f32_16x16x32_bf16 v[42:45], v[142:145], v[188:191], v[42:45]
	v_mfma_f32_16x16x32_bf16 v[30:33], v[134:137], v[196:199], v[30:33]
	v_mfma_f32_16x16x32_bf16 v[26:29], v[142:145], v[196:199], v[26:29]
	v_mfma_f32_16x16x32_bf16 v[14:17], v[134:137], v[204:207], v[14:17]
	v_mfma_f32_16x16x32_bf16 v[10:13], v[142:145], v[204:207], v[10:13]
	s_setprio 0
	s_setprio 1
	v_mfma_f32_16x16x32_bf16 v[54:57], v[158:161], v[176:179], 0
	v_mfma_f32_16x16x32_bf16 v[50:53], v[168:171], v[176:179], 0
	v_mfma_f32_16x16x32_bf16 v[38:41], v[158:161], v[184:187], 0
	v_mfma_f32_16x16x32_bf16 v[34:37], v[168:171], v[184:187], 0
	v_mfma_f32_16x16x32_bf16 v[22:25], v[158:161], v[192:195], 0
	v_mfma_f32_16x16x32_bf16 v[18:21], v[168:171], v[192:195], 0
	v_mfma_f32_16x16x32_bf16 v[6:9], v[158:161], v[200:203], 0
	v_mfma_f32_16x16x32_bf16 v[2:5], v[168:171], v[200:203], 0
	v_mfma_f32_16x16x32_bf16 v[54:57], v[164:167], v[180:183], v[54:57]
	v_mfma_f32_16x16x32_bf16 v[50:53], v[172:175], v[180:183], v[50:53]
	v_mfma_f32_16x16x32_bf16 v[38:41], v[164:167], v[188:191], v[38:41]
	v_mfma_f32_16x16x32_bf16 v[34:37], v[172:175], v[188:191], v[34:37]
	v_mfma_f32_16x16x32_bf16 v[22:25], v[164:167], v[196:199], v[22:25]
	v_mfma_f32_16x16x32_bf16 v[18:21], v[172:175], v[196:199], v[18:21]
	v_mfma_f32_16x16x32_bf16 v[6:9], v[164:167], v[204:207], v[6:9]
	v_mfma_f32_16x16x32_bf16 v[2:5], v[172:175], v[204:207], v[2:5]
	s_setprio 0
	s_barrier
	s_add_i32 s6, 0, 0x18000
	s_add_i32 s7, 0, 0x1c000
	v_add_u32_e32 v142, s6, v209
	v_add_u32_e32 v172, s7, v209
	ds_read_b128 v[130:133], v142
	ds_read_b128 v[134:137], v142 offset:1024
	ds_read_b128 v[138:141], v142 offset:2048
	ds_read_b128 v[142:145], v142 offset:3072
	ds_read_b128 v[158:161], v172
	ds_read_b128 v[164:167], v172 offset:1024
	ds_read_b128 v[168:171], v172 offset:2048
	ds_read_b128 v[172:175], v172 offset:3072
	s_add_u32 s4, s78, 0x40000
	s_addc_u32 s5, s79, 0
	s_mov_b32 m0, s89
	v_lshl_add_u64 v[232:233], s[4:5], 0, v[146:147]
	ds_read_b128 v[176:179], v211 offset:32768
	ds_read_b128 v[180:183], v211 offset:33792
	ds_read_b128 v[184:187], v211 offset:34816
	ds_read_b128 v[188:191], v211 offset:35840
	ds_read_b128 v[192:195], v211 offset:36864
	ds_read_b128 v[196:199], v211 offset:37888
	ds_read_b128 v[200:203], v211 offset:38912
	ds_read_b128 v[204:207], v211 offset:39936
	global_load_lds_dwordx4 v[232:233], off
	v_lshl_add_u64 v[232:233], s[4:5], 0, v[148:149]
	s_mov_b32 m0, s90
	s_nop 0
	global_load_lds_dwordx4 v[232:233], off
	s_waitcnt vmcnt(8)
	s_waitcnt lgkmcnt(0)
	s_barrier
	s_setprio 1
	s_waitcnt lgkmcnt(0)
	v_mfma_f32_16x16x32_bf16 v[126:129], v[130:133], v[176:179], v[126:129]
	v_mfma_f32_16x16x32_bf16 v[122:125], v[138:141], v[176:179], v[122:125]
	v_mfma_f32_16x16x32_bf16 v[110:113], v[130:133], v[184:187], v[110:113]
	v_mfma_f32_16x16x32_bf16 v[106:109], v[138:141], v[184:187], v[106:109]
	v_mfma_f32_16x16x32_bf16 v[94:97], v[130:133], v[192:195], v[94:97]
	v_mfma_f32_16x16x32_bf16 v[90:93], v[138:141], v[192:195], v[90:93]
	v_mfma_f32_16x16x32_bf16 v[78:81], v[130:133], v[200:203], v[78:81]
	v_mfma_f32_16x16x32_bf16 v[74:77], v[138:141], v[200:203], v[74:77]
	v_mfma_f32_16x16x32_bf16 v[126:129], v[134:137], v[180:183], v[126:129]
	v_mfma_f32_16x16x32_bf16 v[122:125], v[142:145], v[180:183], v[122:125]
	v_mfma_f32_16x16x32_bf16 v[110:113], v[134:137], v[188:191], v[110:113]
	v_mfma_f32_16x16x32_bf16 v[106:109], v[142:145], v[188:191], v[106:109]
	v_mfma_f32_16x16x32_bf16 v[94:97], v[134:137], v[196:199], v[94:97]
	v_mfma_f32_16x16x32_bf16 v[90:93], v[142:145], v[196:199], v[90:93]
	v_mfma_f32_16x16x32_bf16 v[78:81], v[134:137], v[204:207], v[78:81]
	v_mfma_f32_16x16x32_bf16 v[74:77], v[142:145], v[204:207], v[74:77]
	s_setprio 0
	s_setprio 1
	v_mfma_f32_16x16x32_bf16 v[118:121], v[158:161], v[176:179], v[118:121]
	v_mfma_f32_16x16x32_bf16 v[114:117], v[168:171], v[176:179], v[114:117]
	v_mfma_f32_16x16x32_bf16 v[102:105], v[158:161], v[184:187], v[102:105]
	v_mfma_f32_16x16x32_bf16 v[98:101], v[168:171], v[184:187], v[98:101]
	v_mfma_f32_16x16x32_bf16 v[86:89], v[158:161], v[192:195], v[86:89]
	v_mfma_f32_16x16x32_bf16 v[82:85], v[168:171], v[192:195], v[82:85]
	v_mfma_f32_16x16x32_bf16 v[70:73], v[158:161], v[200:203], v[70:73]
	v_mfma_f32_16x16x32_bf16 v[66:69], v[168:171], v[200:203], v[66:69]
	v_mfma_f32_16x16x32_bf16 v[118:121], v[164:167], v[180:183], v[118:121]
	v_mfma_f32_16x16x32_bf16 v[114:117], v[172:175], v[180:183], v[114:117]
	v_mfma_f32_16x16x32_bf16 v[102:105], v[164:167], v[188:191], v[102:105]
	v_mfma_f32_16x16x32_bf16 v[98:101], v[172:175], v[188:191], v[98:101]
	v_mfma_f32_16x16x32_bf16 v[86:89], v[164:167], v[196:199], v[86:89]
	v_mfma_f32_16x16x32_bf16 v[82:85], v[172:175], v[196:199], v[82:85]
	v_mfma_f32_16x16x32_bf16 v[70:73], v[164:167], v[204:207], v[70:73]
	v_mfma_f32_16x16x32_bf16 v[66:69], v[172:175], v[204:207], v[66:69]
	s_setprio 0
	s_barrier
; #define PG8_STAGE(bufoff, gbase, voff) do { _Pragma("unroll") for (int _i = 0; _i < 2; ++_i) \
;         __builtin_amdgcn_global_load_lds((const unsigned*)((const char*)(gbase) + (voff)[_i]), (LAS unsigned*)(lds + (bufoff) + ldsw + _i * 8192), 16, 0, 0); } while (0)
; #define PG8_LDA(dst, b, h) do { _Pragma("unroll") for (int m = 0; m < 4; ++m) _Pragma("unroll") for (int k = 0; k < 2; ++k) dst[m][k] = *(const LAS bf16x8*)(lds + PG8_SA(b, h) + aoff + m * 2048 + k * 1024); } while (0)
; #define PG8_LDB(dst, b, h) do { _Pragma("unroll") for (int n = 0; n < 2; ++n) _Pragma("unroll") for (int k = 0; k < 2; ++k) dst[n][k] = *(const LAS bf16x8*)(lds + PG8_SB(b, h) + boff + n * 2048 + k * 1024); } while (0)
; #define PG8_WAIT_V(n) asm volatile("s_waitcnt vmcnt(" #n ")" ::: "memory")
; #define PG8_BAR __builtin_amdgcn_s_barrier()
; template <class Epi, bool MID = false>
; __device__ __forceinline__ void gemm_phase(LAS unsigned char* lds, const Gemm g, const StaticOrder& S, const Epi& E) {
;     ...
;         for (int t = 0; t < nt; t += 2) {
;             const bool last = (t == nt - 2);
;             const char* a1 = cA + (size_t)(t + 1) * kstep;
;             const char* a2 = last ? nA : cA + (size_t)(t + 2) * kstep; const char* b2 = last ? nB : cB + (size_t)(t + 2) * kstep;
;             const char* a3 = a2 + kstep; const char* b3 = b2 + kstep;
;             PG8_LDB(B0, 0, 0); PG8_LDB(B1, 0, 1); PG8_SCHED; PG8_LDA(At, 0, 0); PG8_STAGE(PG8_SA(1, 1), a1 + hstepA, voffA);
;             PG8_WAIT_V(8); PG8_WAIT_L(0); PG8_BAR; PG8_MMA(0, 0, At, B0); PG8_MMA(0, 1, At, B1); PG8_BAR; PG8_SCHED;
;             PG8_LDA(At, 0, 1); PG8_STAGE(PG8_SB(0, 0), b2, voffB); PG8_STAGE(PG8_SB(0, 1), b2 + hstepB, voffB); PG8_STAGE(PG8_SA(0, 0), a2, voffA);
;             PG8_WAIT_V(8); PG8_WAIT_L(0); PG8_BAR; PG8_MMA(1, 0, At, B0); PG8_MMA(1, 1, At, B1); PG8_BAR; PG8_SCHED;
;             PG8_LDB(B0, 1, 0); PG8_LDB(B1, 1, 1); PG8_SCHED; PG8_LDA(At, 1, 0); PG8_STAGE(PG8_SA(0, 1), a2 + hstepA, voffA);
;             PG8_WAIT_V(8); PG8_WAIT_L(0); PG8_BAR; PG8_MMA(0, 0, At, B0); PG8_MMA(0, 1, At, B1); PG8_BAR; PG8_SCHED;
;             PG8_LDA(At, 1, 1); PG8_STAGE(PG8_SB(1, 0), b3, voffB); PG8_STAGE(PG8_SB(1, 1), b3 + hstepB, voffB); PG8_STAGE(PG8_SA(1, 0), a3, voffA);
;             PG8_WAIT_V(8); PG8_WAIT_L(0); PG8_BAR; PG8_MMA(1, 0, At, B0); PG8_MMA(1, 1, At, B1); PG8_BAR; PG8_SCHED;
	s_add_i32 s4, s6, s86
	v_lshl_add_u64 v[212:213], v[212:213], 0, s[24:25]
	s_mov_b32 m0, s4
	ds_read_b128 v[176:179], v211 offset:49152
	ds_read_b128 v[180:183], v211 offset:50176
	ds_read_b128 v[184:187], v211 offset:51200
	ds_read_b128 v[188:191], v211 offset:52224
	ds_read_b128 v[192:195], v211 offset:53248
	ds_read_b128 v[196:199], v211 offset:54272
	ds_read_b128 v[200:203], v211 offset:55296
	ds_read_b128 v[204:207], v211 offset:56320
	global_load_lds_dwordx4 v[212:213], off
	s_add_i32 m0, s4, 0x2000
	s_add_u32 s4, s68, 0x40080
	v_lshl_add_u64 v[212:213], v[214:215], 0, s[24:25]
	s_addc_u32 s5, s69, 0
	s_add_i32 s6, s7, s86
	global_load_lds_dwordx4 v[212:213], off
	v_lshl_add_u64 v[212:213], s[4:5], 0, v[0:1]
	s_mov_b32 m0, s6
	s_nop 0
	global_load_lds_dwordx4 v[212:213], off
	v_lshl_add_u64 v[212:213], s[4:5], 0, v[150:151]
	s_add_i32 m0, s6, 0x2000
	s_nop 0
	global_load_lds_dwordx4 v[212:213], off
	v_lshl_add_u64 v[212:213], v[222:223], 0, s[24:25]
	s_mov_b32 m0, s92
	s_nop 0
	global_load_lds_dwordx4 v[212:213], off
	v_lshl_add_u64 v[212:213], v[230:231], 0, s[24:25]
	s_mov_b32 m0, s93
	s_nop 0
	global_load_lds_dwordx4 v[212:213], off
	s_waitcnt vmcnt(8)
	s_waitcnt lgkmcnt(0)
	s_barrier
	s_setprio 1
	s_waitcnt lgkmcnt(0)
	v_mfma_f32_16x16x32_bf16 v[62:65], v[130:133], v[176:179], v[62:65]
	v_mfma_f32_16x16x32_bf16 v[58:61], v[138:141], v[176:179], v[58:61]
	v_mfma_f32_16x16x32_bf16 v[46:49], v[130:133], v[184:187], v[46:49]
	v_mfma_f32_16x16x32_bf16 v[42:45], v[138:141], v[184:187], v[42:45]
	v_mfma_f32_16x16x32_bf16 v[30:33], v[130:133], v[192:195], v[30:33]
	v_mfma_f32_16x16x32_bf16 v[26:29], v[138:141], v[192:195], v[26:29]
	v_mfma_f32_16x16x32_bf16 v[14:17], v[130:133], v[200:203], v[14:17]
	v_mfma_f32_16x16x32_bf16 v[10:13], v[138:141], v[200:203], v[10:13]
	v_mfma_f32_16x16x32_bf16 v[62:65], v[134:137], v[180:183], v[62:65]
	v_mfma_f32_16x16x32_bf16 v[58:61], v[142:145], v[180:183], v[58:61]
	v_mfma_f32_16x16x32_bf16 v[46:49], v[134:137], v[188:191], v[46:49]
	v_mfma_f32_16x16x32_bf16 v[42:45], v[142:145], v[188:191], v[42:45]
	v_mfma_f32_16x16x32_bf16 v[30:33], v[134:137], v[196:199], v[30:33]
	v_mfma_f32_16x16x32_bf16 v[26:29], v[142:145], v[196:199], v[26:29]
	v_mfma_f32_16x16x32_bf16 v[14:17], v[134:137], v[204:207], v[14:17]
	v_mfma_f32_16x16x32_bf16 v[10:13], v[142:145], v[204:207], v[10:13]
	s_setprio 0
	s_setprio 1
	v_mfma_f32_16x16x32_bf16 v[54:57], v[158:161], v[176:179], v[54:57]
	v_mfma_f32_16x16x32_bf16 v[50:53], v[168:171], v[176:179], v[50:53]
	v_mfma_f32_16x16x32_bf16 v[38:41], v[158:161], v[184:187], v[38:41]
	v_mfma_f32_16x16x32_bf16 v[34:37], v[168:171], v[184:187], v[34:37]
	v_mfma_f32_16x16x32_bf16 v[22:25], v[158:161], v[192:195], v[22:25]
	v_mfma_f32_16x16x32_bf16 v[18:21], v[168:171], v[192:195], v[18:21]
	v_mfma_f32_16x16x32_bf16 v[6:9], v[158:161], v[200:203], v[6:9]
	v_mfma_f32_16x16x32_bf16 v[2:5], v[168:171], v[200:203], v[2:5]
	v_mfma_f32_16x16x32_bf16 v[54:57], v[164:167], v[180:183], v[54:57]
	v_mfma_f32_16x16x32_bf16 v[50:53], v[172:175], v[180:183], v[50:53]
	v_mfma_f32_16x16x32_bf16 v[38:41], v[164:167], v[188:191], v[38:41]
	v_mfma_f32_16x16x32_bf16 v[34:37], v[172:175], v[188:191], v[34:37]
	v_mfma_f32_16x16x32_bf16 v[22:25], v[164:167], v[196:199], v[22:25]
	v_mfma_f32_16x16x32_bf16 v[18:21], v[172:175], v[196:199], v[18:21]
	v_mfma_f32_16x16x32_bf16 v[6:9], v[164:167], v[204:207], v[6:9]
	v_mfma_f32_16x16x32_bf16 v[2:5], v[172:175], v[204:207], v[2:5]
	s_setprio 0
	s_barrier
	s_add_u32 vcc_lo, vcc_lo, 0x100
	s_addc_u32 vcc_hi, vcc_hi, 0
	s_add_u32 s67, s67, 0x100
	s_addc_u32 s72, s72, 0
	s_cmp_ge_i32 s73, s85
	s_mov_b32 s68, s73
	s_cbranch_scc0 .LBB0_1764
	s_branch .Lpk_1764_exit

; #define PG8_BAR __builtin_amdgcn_s_barrier()
; template <class Epi, bool MID = false>
; __device__ __forceinline__ void gemm_phase(LAS unsigned char* lds, const Gemm g, const StaticOrder& S, const Epi& E) {
;     ...
;         if (wr == 0) PG8_BAR;
.Lpk_1764_exit:
	s_and_b64 vcc, exec, s[60:61]
	s_cbranch_vccz .LBB0_1767

; #define PG8_STAGE(bufoff, gbase, voff) do { _Pragma("unroll") for (int _i = 0; _i < 2; ++_i) \
;         __builtin_amdgcn_global_load_lds((const unsigned*)((const char*)(gbase) + (voff)[_i]), (LAS unsigned*)(lds + (bufoff) + ldsw + _i * 8192), 16, 0, 0); } while (0)
; #define PG8_LDA(dst, b, h) do { _Pragma("unroll") for (int m = 0; m < 4; ++m) _Pragma("unroll") for (int k = 0; k < 2; ++k) dst[m][k] = *(const LAS bf16x8*)(lds + PG8_SA(b, h) + aoff + m * 2048 + k * 1024); } while (0)
; #define PG8_LDB(dst, b, h) do { _Pragma("unroll") for (int n = 0; n < 2; ++n) _Pragma("unroll") for (int k = 0; k < 2; ++k) dst[n][k] = *(const LAS bf16x8*)(lds + PG8_SB(b, h) + boff + n * 2048 + k * 1024); } while (0)
; #define PG8_WAIT_V(n) asm volatile("s_waitcnt vmcnt(" #n ")" ::: "memory")
; #define PG8_WAIT_L(n) asm volatile("s_waitcnt lgkmcnt(" #n ")" ::: "memory")
; #define PG8_BAR __builtin_amdgcn_s_barrier()
; template <class Epi, bool MID = false>
; __device__ __forceinline__ void gemm_phase(LAS unsigned char* lds, const Gemm g, const StaticOrder& S, const Epi& E) {
;     ...
;         const bool has_next = S.next(ui + 1, nxt);
;         const char* nA = has_next ? (const char*)g.A + (size_t)nxt.pm * tstepA : cA; const char* nB = has_next ? (const char*)g.Bt + (size_t)nxt.pn * tstepB : cB;
; #pragma nounroll
;         for (int t = 0; t < nt; t += 2) {
;             const bool last = (t == nt - 2);
;             const char* a1 = cA + (size_t)(t + 1) * kstep;
;             const char* a2 = last ? nA : cA + (size_t)(t + 2) * kstep; const char* b2 = last ? nB : cB + (size_t)(t + 2) * kstep;
;             const char* a3 = a2 + kstep; const char* b3 = b2 + kstep;
;             PG8_LDB(B0, 0, 0); PG8_LDB(B1, 0, 1); PG8_SCHED; PG8_LDA(At, 0, 0); PG8_STAGE(PG8_SA(1, 1), a1 + hstepA, voffA);
;             PG8_WAIT_V(8); PG8_WAIT_L(0); PG8_BAR; PG8_MMA(0, 0, At, B0); PG8_MMA(0, 1, At, B1); PG8_BAR; PG8_SCHED;
;             PG8_LDA(At, 0, 1); PG8_STAGE(PG8_SB(0, 0), b2, voffB); PG8_STAGE(PG8_SB(0, 1), b2 + hstepB, voffB); PG8_STAGE(PG8_SA(0, 0), a2, voffA);
;     ...
; #pragma unroll
;         for (int a = 0; a < 2; ++a)
; #pragma unroll
;             for (int b = 0; b < 2; ++b)
; #pragma unroll
;                 for (int m = 0; m < 4; ++m)
; #pragma unroll
;                     for (int n = 0; n < 2; ++n) acc[a][b][m][n] = (f32x4){0.f, 0.f, 0.f, 0.f};
.LBB0_1806:
	s_ashr_i32 s59, s58, 31
	s_lshl_b64 s[4:5], s[58:59], 19
	s_add_u32 s60, s46, s4
	s_addc_u32 s61, s47, s5
	s_ashr_i32 s57, s56, 31
	s_lshl_b64 s[4:5], s[56:57], 19
	s_add_u32 s62, s83, s4
	s_addc_u32 s63, s84, s5
	s_andn2_b64 vcc, exec, s[44:45]
	s_cbranch_vccnz .LBB0_1814
	s_and_b64 s[4:5], s[40:41], exec
	s_cselect_b32 s57, s61, s43
	s_cselect_b32 s59, s60, s42
	s_cselect_b32 s72, s63, s65
	s_cselect_b32 s73, s62, s64
	s_add_u32 s42, s42, 0x40080
	s_addc_u32 s43, s43, 0
	s_add_u32 s87, s64, 0x100
	s_addc_u32 s88, s65, 0
	s_mov_b32 s64, 0
	s_add_i32 s89, s64, 2
	s_add_u32 s4, s42, 0xfffc0080
	s_addc_u32 s5, s43, -1
	s_add_i32 s6, 0, 0x10000
	s_cmp_eq_u32 s85, s64
	s_cselect_b32 s67, s57, s5
	s_cselect_b32 s66, s59, s4
	s_cselect_b32 s65, s72, s88
	s_cselect_b32 s64, s73, s87
	s_add_i32 s7, 0, 0x14000
	v_add_u32_e32 v142, s6, v199
	v_add_u32_e32 v158, s7, v199
	ds_read_b128 v[130:133], v142
	ds_read_b128 v[134:137], v142 offset:1024
	ds_read_b128 v[138:141], v142 offset:2048
	ds_read_b128 v[142:145], v142 offset:3072
	ds_read_b128 v[146:149], v158
	ds_read_b128 v[150:153], v158 offset:1024
	ds_read_b128 v[154:157], v158 offset:2048
	ds_read_b128 v[158:161], v158 offset:3072
	v_lshl_add_u64 v[196:197], s[42:43], 0, v[172:173]
	s_add_i32 m0, s69, 0xc000
	ds_read_b128 v[176:179], v201
	ds_read_b128 v[180:183], v201 offset:1024
	ds_read_b128 v[184:187], v201 offset:2048
	ds_read_b128 v[188:191], v201 offset:3072
	ds_read_b128 v[192:195], v201 offset:4096
	ds_read_b128 v[202:205], v201 offset:5120
	ds_read_b128 v[206:209], v201 offset:6144
	ds_read_b128 v[210:213], v201 offset:7168
	global_load_lds_dwordx4 v[196:197], off
	v_lshl_add_u64 v[196:197], s[42:43], 0, v[174:175]
	s_add_i32 m0, s69, 0xe000
	s_nop 0
	global_load_lds_dwordx4 v[196:197], off
	s_waitcnt vmcnt(8)
	s_waitcnt lgkmcnt(0)
	s_barrier
	s_setprio 1
	s_waitcnt lgkmcnt(0)
	v_mfma_f32_16x16x32_bf16 v[126:129], v[130:133], v[176:179], 0
	v_mfma_f32_16x16x32_bf16 v[122:125], v[138:141], v[176:179], 0
	v_mfma_f32_16x16x32_bf16 v[110:113], v[130:133], v[184:187], 0
	v_mfma_f32_16x16x32_bf16 v[106:109], v[138:141], v[184:187], 0
	v_mfma_f32_16x16x32_bf16 v[94:97], v[130:133], v[192:195], 0
	v_mfma_f32_16x16x32_bf16 v[90:93], v[138:141], v[192:195], 0
	v_mfma_f32_16x16x32_bf16 v[78:81], v[130:133], v[206:209], 0
	v_mfma_f32_16x16x32_bf16 v[74:77], v[138:141], v[206:209], 0
	v_mfma_f32_16x16x32_bf16 v[126:129], v[134:137], v[180:183], v[126:129]
	v_mfma_f32_16x16x32_bf16 v[122:125], v[142:145], v[180:183], v[122:125]
	v_mfma_f32_16x16x32_bf16 v[110:113], v[134:137], v[188:191], v[110:113]
	v_mfma_f32_16x16x32_bf16 v[106:109], v[142:145], v[188:191], v[106:109]
	v_mfma_f32_16x16x32_bf16 v[94:97], v[134:137], v[202:205], v[94:97]
	v_mfma_f32_16x16x32_bf16 v[90:93], v[142:145], v[202:205], v[90:93]
	v_mfma_f32_16x16x32_bf16 v[78:81], v[134:137], v[210:213], v[78:81]
	v_mfma_f32_16x16x32_bf16 v[74:77], v[142:145], v[210:213], v[74:77]
	s_setprio 0
	s_setprio 1
	v_mfma_f32_16x16x32_bf16 v[118:121], v[146:149], v[176:179], 0
	v_mfma_f32_16x16x32_bf16 v[114:117], v[154:157], v[176:179], 0
	v_mfma_f32_16x16x32_bf16 v[102:105], v[146:149], v[184:187], 0
	v_mfma_f32_16x16x32_bf16 v[98:101], v[154:157], v[184:187], 0
	v_mfma_f32_16x16x32_bf16 v[86:89], v[146:149], v[192:195], 0
	v_mfma_f32_16x16x32_bf16 v[82:85], v[154:157], v[192:195], 0
	v_mfma_f32_16x16x32_bf16 v[70:73], v[146:149], v[206:209], 0
	v_mfma_f32_16x16x32_bf16 v[66:69], v[154:157], v[206:209], 0
	v_mfma_f32_16x16x32_bf16 v[118:121], v[150:153], v[180:183], v[118:121]
	v_mfma_f32_16x16x32_bf16 v[114:117], v[158:161], v[180:183], v[114:117]
	v_mfma_f32_16x16x32_bf16 v[102:105], v[150:153], v[188:191], v[102:105]
	v_mfma_f32_16x16x32_bf16 v[98:101], v[158:161], v[188:191], v[98:101]
	v_mfma_f32_16x16x32_bf16 v[86:89], v[150:153], v[202:205], v[86:89]
	v_mfma_f32_16x16x32_bf16 v[82:85], v[158:161], v[202:205], v[82:85]
	v_mfma_f32_16x16x32_bf16 v[70:73], v[150:153], v[210:213], v[70:73]
	v_mfma_f32_16x16x32_bf16 v[66:69], v[158:161], v[210:213], v[66:69]
	s_setprio 0
	s_barrier
	s_add_i32 s4, s6, s68
	v_lshl_add_u64 v[196:197], s[64:65], 0, v[0:1]
	s_mov_b32 m0, s4
	ds_read_b128 v[176:179], v201 offset:16384
	ds_read_b128 v[180:183], v201 offset:17408
	ds_read_b128 v[184:187], v201 offset:18432
	ds_read_b128 v[188:191], v201 offset:19456
	ds_read_b128 v[192:195], v201 offset:20480
	ds_read_b128 v[202:205], v201 offset:21504
	ds_read_b128 v[206:209], v201 offset:22528
	ds_read_b128 v[210:213], v201 offset:23552
	global_load_lds_dwordx4 v[196:197], off
	s_add_i32 m0, s4, 0x2000
	s_add_u32 s4, s64, 0x40000
	v_lshl_add_u64 v[214:215], s[64:65], 0, v[168:169]
	s_addc_u32 s5, s65, 0
	s_add_i32 s6, s7, s68
	global_load_lds_dwordx4 v[214:215], off
	v_lshl_add_u64 v[222:223], s[4:5], 0, v[0:1]
	s_mov_b32 m0, s6
	v_lshl_add_u64 v[230:231], s[66:67], 0, v[166:167]
	global_load_lds_dwordx4 v[222:223], off
	v_lshl_add_u64 v[222:223], s[4:5], 0, v[168:169]
	s_add_i32 m0, s6, 0x2000
	s_nop 0
	global_load_lds_dwordx4 v[222:223], off
	v_lshl_add_u64 v[222:223], s[66:67], 0, v[164:165]
	s_mov_b32 m0, s69
	s_nop 0
	global_load_lds_dwordx4 v[222:223], off
	s_mov_b32 m0, s70
	s_nop 0
	global_load_lds_dwordx4 v[230:231], off
	s_waitcnt vmcnt(8)
	s_waitcnt lgkmcnt(0)
	s_barrier
; #define PG8_STAGE(bufoff, gbase, voff) do { _Pragma("unroll") for (int _i = 0; _i < 2; ++_i) \
;         __builtin_amdgcn_global_load_lds((const unsigned*)((const char*)(gbase) + (voff)[_i]), (LAS unsigned*)(lds + (bufoff) + ldsw + _i * 8192), 16, 0, 0); } while (0)
; #define PG8_LDA(dst, b, h) do { _Pragma("unroll") for (int m = 0; m < 4; ++m) _Pragma("unroll") for (int k = 0; k < 2; ++k) dst[m][k] = *(const LAS bf16x8*)(lds + PG8_SA(b, h) + aoff + m * 2048 + k * 1024); } while (0)
; #define PG8_LDB(dst, b, h) do { _Pragma("unroll") for (int n = 0; n < 2; ++n) _Pragma("unroll") for (int k = 0; k < 2; ++k) dst[n][k] = *(const LAS bf16x8*)(lds + PG8_SB(b, h) + boff + n * 2048 + k * 1024); } while (0)
; #define PG8_MMA(ai, bj, At, Bt) do { __builtin_amdgcn_s_setprio(1); _Pragma("unroll") for (int m = 0; m < 4; ++m) _Pragma("unroll") for (int n = 0; n < 2; ++n) _Pragma("unroll") for (int k = 0; k < 2; ++k) \
;         acc[ai][bj][m][n] = __builtin_amdgcn_mfma_f32_16x16x32_bf16(Bt[n][k], At[m][k], acc[ai][bj][m][n], 0, 0, 0); __builtin_amdgcn_s_setprio(0); } while (0)
; #define PG8_WAIT_V(n) asm volatile("s_waitcnt vmcnt(" #n ")" ::: "memory")
; #define PG8_WAIT_L(n) asm volatile("s_waitcnt lgkmcnt(" #n ")" ::: "memory")
; #define PG8_BAR __builtin_amdgcn_s_barrier()
; template <class Epi, bool MID = false>
; __device__ __forceinline__ void gemm_phase(LAS unsigned char* lds, const Gemm g, const StaticOrder& S, const Epi& E) {
;     ...
;             PG8_WAIT_V(8); PG8_WAIT_L(0); PG8_BAR; PG8_MMA(0, 0, At, B0); PG8_MMA(0, 1, At, B1); PG8_BAR; PG8_SCHED;
;             PG8_LDA(At, 0, 1); PG8_STAGE(PG8_SB(0, 0), b2, voffB); PG8_STAGE(PG8_SB(0, 1), b2 + hstepB, voffB); PG8_STAGE(PG8_SA(0, 0), a2, voffA);
;             PG8_WAIT_V(8); PG8_WAIT_L(0); PG8_BAR; PG8_MMA(1, 0, At, B0); PG8_MMA(1, 1, At, B1); PG8_BAR; PG8_SCHED;
;             PG8_LDB(B0, 1, 0); PG8_LDB(B1, 1, 1); PG8_SCHED; PG8_LDA(At, 1, 0); PG8_STAGE(PG8_SA(0, 1), a2 + hstepA, voffA);
;             PG8_WAIT_V(8); PG8_WAIT_L(0); PG8_BAR; PG8_MMA(0, 0, At, B0); PG8_MMA(0, 1, At, B1); PG8_BAR; PG8_SCHED;
;             PG8_LDA(At, 1, 1); PG8_STAGE(PG8_SB(1, 0), b3, voffB); PG8_STAGE(PG8_SB(1, 1), b3 + hstepB, voffB); PG8_STAGE(PG8_SA(1, 0), a3, voffA);
;             PG8_WAIT_V(8); PG8_WAIT_L(0); PG8_BAR; PG8_MMA(1, 0, At, B0); PG8_MMA(1, 1, At, B1); PG8_BAR; PG8_SCHED;
	s_setprio 1
	s_waitcnt lgkmcnt(0)
	v_mfma_f32_16x16x32_bf16 v[62:65], v[130:133], v[176:179], 0
	v_mfma_f32_16x16x32_bf16 v[58:61], v[138:141], v[176:179], 0
	v_mfma_f32_16x16x32_bf16 v[46:49], v[130:133], v[184:187], 0
	v_mfma_f32_16x16x32_bf16 v[42:45], v[138:141], v[184:187], 0
	v_mfma_f32_16x16x32_bf16 v[30:33], v[130:133], v[192:195], 0
	v_mfma_f32_16x16x32_bf16 v[26:29], v[138:141], v[192:195], 0
	v_mfma_f32_16x16x32_bf16 v[14:17], v[130:133], v[206:209], 0
	v_mfma_f32_16x16x32_bf16 v[10:13], v[138:141], v[206:209], 0
	v_mfma_f32_16x16x32_bf16 v[62:65], v[134:137], v[180:183], v[62:65]
	v_mfma_f32_16x16x32_bf16 v[58:61], v[142:145], v[180:183], v[58:61]
	v_mfma_f32_16x16x32_bf16 v[46:49], v[134:137], v[188:191], v[46:49]
	v_mfma_f32_16x16x32_bf16 v[42:45], v[142:145], v[188:191], v[42:45]
	v_mfma_f32_16x16x32_bf16 v[30:33], v[134:137], v[202:205], v[30:33]
	v_mfma_f32_16x16x32_bf16 v[26:29], v[142:145], v[202:205], v[26:29]
	v_mfma_f32_16x16x32_bf16 v[14:17], v[134:137], v[210:213], v[14:17]
	v_mfma_f32_16x16x32_bf16 v[10:13], v[142:145], v[210:213], v[10:13]
	s_setprio 0
	s_setprio 1
	v_mfma_f32_16x16x32_bf16 v[54:57], v[146:149], v[176:179], 0
	v_mfma_f32_16x16x32_bf16 v[50:53], v[154:157], v[176:179], 0
	v_mfma_f32_16x16x32_bf16 v[38:41], v[146:149], v[184:187], 0
	v_mfma_f32_16x16x32_bf16 v[34:37], v[154:157], v[184:187], 0
	v_mfma_f32_16x16x32_bf16 v[22:25], v[146:149], v[192:195], 0
	v_mfma_f32_16x16x32_bf16 v[18:21], v[154:157], v[192:195], 0
	v_mfma_f32_16x16x32_bf16 v[6:9], v[146:149], v[206:209], 0
	v_mfma_f32_16x16x32_bf16 v[2:5], v[154:157], v[206:209], 0
	v_mfma_f32_16x16x32_bf16 v[54:57], v[150:153], v[180:183], v[54:57]
	v_mfma_f32_16x16x32_bf16 v[50:53], v[158:161], v[180:183], v[50:53]
	v_mfma_f32_16x16x32_bf16 v[38:41], v[150:153], v[188:191], v[38:41]
	v_mfma_f32_16x16x32_bf16 v[34:37], v[158:161], v[188:191], v[34:37]
	v_mfma_f32_16x16x32_bf16 v[22:25], v[150:153], v[202:205], v[22:25]
	v_mfma_f32_16x16x32_bf16 v[18:21], v[158:161], v[202:205], v[18:21]
	v_mfma_f32_16x16x32_bf16 v[6:9], v[150:153], v[210:213], v[6:9]
	v_mfma_f32_16x16x32_bf16 v[2:5], v[158:161], v[210:213], v[2:5]
	s_setprio 0
	s_barrier
	s_add_i32 s6, 0, 0x18000
	s_add_i32 s7, 0, 0x1c000
	v_add_u32_e32 v142, s6, v199
	v_add_u32_e32 v158, s7, v199
	ds_read_b128 v[130:133], v142
	ds_read_b128 v[134:137], v142 offset:1024
	ds_read_b128 v[138:141], v142 offset:2048
	ds_read_b128 v[142:145], v142 offset:3072
	ds_read_b128 v[146:149], v158
	ds_read_b128 v[150:153], v158 offset:1024
	ds_read_b128 v[154:157], v158 offset:2048
	ds_read_b128 v[158:161], v158 offset:3072
	s_add_u32 s4, s66, 0x40000
	s_addc_u32 s5, s67, 0
	s_mov_b32 m0, s71
	v_lshl_add_u64 v[232:233], s[4:5], 0, v[164:165]
	ds_read_b128 v[176:179], v201 offset:32768
	ds_read_b128 v[180:183], v201 offset:33792
	ds_read_b128 v[184:187], v201 offset:34816
	ds_read_b128 v[188:191], v201 offset:35840
	ds_read_b128 v[192:195], v201 offset:36864
	ds_read_b128 v[202:205], v201 offset:37888
	ds_read_b128 v[206:209], v201 offset:38912
	ds_read_b128 v[210:213], v201 offset:39936
	global_load_lds_dwordx4 v[232:233], off
	v_lshl_add_u64 v[232:233], s[4:5], 0, v[166:167]
	s_mov_b32 m0, s78
	s_nop 0
	global_load_lds_dwordx4 v[232:233], off
	s_waitcnt vmcnt(8)
	s_waitcnt lgkmcnt(0)
	s_barrier
	s_setprio 1
	s_waitcnt lgkmcnt(0)
	v_mfma_f32_16x16x32_bf16 v[126:129], v[130:133], v[176:179], v[126:129]
	v_mfma_f32_16x16x32_bf16 v[122:125], v[138:141], v[176:179], v[122:125]
	v_mfma_f32_16x16x32_bf16 v[110:113], v[130:133], v[184:187], v[110:113]
	v_mfma_f32_16x16x32_bf16 v[106:109], v[138:141], v[184:187], v[106:109]
	v_mfma_f32_16x16x32_bf16 v[94:97], v[130:133], v[192:195], v[94:97]
	v_mfma_f32_16x16x32_bf16 v[90:93], v[138:141], v[192:195], v[90:93]
	v_mfma_f32_16x16x32_bf16 v[78:81], v[130:133], v[206:209], v[78:81]
	v_mfma_f32_16x16x32_bf16 v[74:77], v[138:141], v[206:209], v[74:77]
	v_mfma_f32_16x16x32_bf16 v[126:129], v[134:137], v[180:183], v[126:129]
	v_mfma_f32_16x16x32_bf16 v[122:125], v[142:145], v[180:183], v[122:125]
	v_mfma_f32_16x16x32_bf16 v[110:113], v[134:137], v[188:191], v[110:113]
	v_mfma_f32_16x16x32_bf16 v[106:109], v[142:145], v[188:191], v[106:109]
	v_mfma_f32_16x16x32_bf16 v[94:97], v[134:137], v[202:205], v[94:97]
	v_mfma_f32_16x16x32_bf16 v[90:93], v[142:145], v[202:205], v[90:93]
	v_mfma_f32_16x16x32_bf16 v[78:81], v[134:137], v[210:213], v[78:81]
	v_mfma_f32_16x16x32_bf16 v[74:77], v[142:145], v[210:213], v[74:77]
	s_setprio 0
	s_setprio 1
	v_mfma_f32_16x16x32_bf16 v[118:121], v[146:149], v[176:179], v[118:121]
	v_mfma_f32_16x16x32_bf16 v[114:117], v[154:157], v[176:179], v[114:117]
	v_mfma_f32_16x16x32_bf16 v[102:105], v[146:149], v[184:187], v[102:105]
	v_mfma_f32_16x16x32_bf16 v[98:101], v[154:157], v[184:187], v[98:101]
	v_mfma_f32_16x16x32_bf16 v[86:89], v[146:149], v[192:195], v[86:89]
	v_mfma_f32_16x16x32_bf16 v[82:85], v[154:157], v[192:195], v[82:85]
	v_mfma_f32_16x16x32_bf16 v[70:73], v[146:149], v[206:209], v[70:73]
	v_mfma_f32_16x16x32_bf16 v[66:69], v[154:157], v[206:209], v[66:69]
	v_mfma_f32_16x16x32_bf16 v[118:121], v[150:153], v[180:183], v[118:121]
	v_mfma_f32_16x16x32_bf16 v[114:117], v[158:161], v[180:183], v[114:117]
	v_mfma_f32_16x16x32_bf16 v[102:105], v[150:153], v[188:191], v[102:105]
	v_mfma_f32_16x16x32_bf16 v[98:101], v[158:161], v[188:191], v[98:101]
	v_mfma_f32_16x16x32_bf16 v[86:89], v[150:153], v[202:205], v[86:89]
	v_mfma_f32_16x16x32_bf16 v[82:85], v[158:161], v[202:205], v[82:85]
	v_mfma_f32_16x16x32_bf16 v[70:73], v[150:153], v[210:213], v[70:73]
	v_mfma_f32_16x16x32_bf16 v[66:69], v[158:161], v[210:213], v[66:69]
	s_setprio 0
	s_barrier
; #define PG8_STAGE(bufoff, gbase, voff) do { _Pragma("unroll") for (int _i = 0; _i < 2; ++_i) \
;         __builtin_amdgcn_global_load_lds((const unsigned*)((const char*)(gbase) + (voff)[_i]), (LAS unsigned*)(lds + (bufoff) + ldsw + _i * 8192), 16, 0, 0); } while (0)
; #define PG8_LDA(dst, b, h) do { _Pragma("unroll") for (int m = 0; m < 4; ++m) _Pragma("unroll") for (int k = 0; k < 2; ++k) dst[m][k] = *(const LAS bf16x8*)(lds + PG8_SA(b, h) + aoff + m * 2048 + k * 1024); } while (0)
; #define PG8_LDB(dst, b, h) do { _Pragma("unroll") for (int n = 0; n < 2; ++n) _Pragma("unroll") for (int k = 0; k < 2; ++k) dst[n][k] = *(const LAS bf16x8*)(lds + PG8_SB(b, h) + boff + n * 2048 + k * 1024); } while (0)
; #define PG8_WAIT_V(n) asm volatile("s_waitcnt vmcnt(" #n ")" ::: "memory")
; #define PG8_BAR __builtin_amdgcn_s_barrier()
; template <class Epi, bool MID = false>
; __device__ __forceinline__ void gemm_phase(LAS unsigned char* lds, const Gemm g, const StaticOrder& S, const Epi& E) {
;     ...
;         for (int t = 0; t < nt; t += 2) {
;             const bool last = (t == nt - 2);
;             const char* a1 = cA + (size_t)(t + 1) * kstep;
;             const char* a2 = last ? nA : cA + (size_t)(t + 2) * kstep; const char* b2 = last ? nB : cB + (size_t)(t + 2) * kstep;
;             const char* a3 = a2 + kstep; const char* b3 = b2 + kstep;
;             PG8_LDB(B0, 0, 0); PG8_LDB(B1, 0, 1); PG8_SCHED; PG8_LDA(At, 0, 0); PG8_STAGE(PG8_SA(1, 1), a1 + hstepA, voffA);
;             PG8_WAIT_V(8); PG8_WAIT_L(0); PG8_BAR; PG8_MMA(0, 0, At, B0); PG8_MMA(0, 1, At, B1); PG8_BAR; PG8_SCHED;
;             PG8_LDA(At, 0, 1); PG8_STAGE(PG8_SB(0, 0), b2, voffB); PG8_STAGE(PG8_SB(0, 1), b2 + hstepB, voffB); PG8_STAGE(PG8_SA(0, 0), a2, voffA);
;             PG8_WAIT_V(8); PG8_WAIT_L(0); PG8_BAR; PG8_MMA(1, 0, At, B0); PG8_MMA(1, 1, At, B1); PG8_BAR; PG8_SCHED;
;             PG8_LDB(B0, 1, 0); PG8_LDB(B1, 1, 1); PG8_SCHED; PG8_LDA(At, 1, 0); PG8_STAGE(PG8_SA(0, 1), a2 + hstepA, voffA);
;             PG8_WAIT_V(8); PG8_WAIT_L(0); PG8_BAR; PG8_MMA(0, 0, At, B0); PG8_MMA(0, 1, At, B1); PG8_BAR; PG8_SCHED;
;             PG8_LDA(At, 1, 1); PG8_STAGE(PG8_SB(1, 0), b3, voffB); PG8_STAGE(PG8_SB(1, 1), b3 + hstepB, voffB); PG8_STAGE(PG8_SA(1, 0), a3, voffA);
;             PG8_WAIT_V(8); PG8_WAIT_L(0); PG8_BAR; PG8_MMA(1, 0, At, B0); PG8_MMA(1, 1, At, B1); PG8_BAR; PG8_SCHED;
	s_add_i32 s4, s6, s68
	v_lshl_add_u64 v[196:197], v[196:197], 0, s[24:25]
	s_mov_b32 m0, s4
	ds_read_b128 v[176:179], v201 offset:49152
	ds_read_b128 v[180:183], v201 offset:50176
	ds_read_b128 v[184:187], v201 offset:51200
	ds_read_b128 v[188:191], v201 offset:52224
	ds_read_b128 v[192:195], v201 offset:53248
	ds_read_b128 v[202:205], v201 offset:54272
	ds_read_b128 v[206:209], v201 offset:55296
	ds_read_b128 v[210:213], v201 offset:56320
	global_load_lds_dwordx4 v[196:197], off
	s_add_i32 m0, s4, 0x2000
	s_add_u32 s4, s64, 0x40080
	v_lshl_add_u64 v[196:197], v[214:215], 0, s[24:25]
	s_addc_u32 s5, s65, 0
	s_add_i32 s6, s7, s68
	global_load_lds_dwordx4 v[196:197], off
	v_lshl_add_u64 v[196:197], s[4:5], 0, v[0:1]
	s_mov_b32 m0, s6
	s_nop 0
	global_load_lds_dwordx4 v[196:197], off
	v_lshl_add_u64 v[196:197], s[4:5], 0, v[168:169]
	s_add_i32 m0, s6, 0x2000
	s_nop 0
	global_load_lds_dwordx4 v[196:197], off
	v_lshl_add_u64 v[196:197], v[222:223], 0, s[24:25]
	s_mov_b32 m0, s79
	s_nop 0
	global_load_lds_dwordx4 v[196:197], off
	v_lshl_add_u64 v[196:197], v[230:231], 0, s[24:25]
	s_mov_b32 m0, s80
	s_nop 0
	global_load_lds_dwordx4 v[196:197], off
	s_waitcnt vmcnt(8)
	s_waitcnt lgkmcnt(0)
	s_barrier
	s_setprio 1
	s_waitcnt lgkmcnt(0)
	v_mfma_f32_16x16x32_bf16 v[62:65], v[130:133], v[176:179], v[62:65]
	v_mfma_f32_16x16x32_bf16 v[58:61], v[138:141], v[176:179], v[58:61]
	v_mfma_f32_16x16x32_bf16 v[46:49], v[130:133], v[184:187], v[46:49]
	v_mfma_f32_16x16x32_bf16 v[42:45], v[138:141], v[184:187], v[42:45]
	v_mfma_f32_16x16x32_bf16 v[30:33], v[130:133], v[192:195], v[30:33]
	v_mfma_f32_16x16x32_bf16 v[26:29], v[138:141], v[192:195], v[26:29]
	v_mfma_f32_16x16x32_bf16 v[14:17], v[130:133], v[206:209], v[14:17]
	v_mfma_f32_16x16x32_bf16 v[10:13], v[138:141], v[206:209], v[10:13]
	v_mfma_f32_16x16x32_bf16 v[62:65], v[134:137], v[180:183], v[62:65]
	v_mfma_f32_16x16x32_bf16 v[58:61], v[142:145], v[180:183], v[58:61]
	v_mfma_f32_16x16x32_bf16 v[46:49], v[134:137], v[188:191], v[46:49]
	v_mfma_f32_16x16x32_bf16 v[42:45], v[142:145], v[188:191], v[42:45]
	v_mfma_f32_16x16x32_bf16 v[30:33], v[134:137], v[202:205], v[30:33]
	v_mfma_f32_16x16x32_bf16 v[26:29], v[142:145], v[202:205], v[26:29]
	v_mfma_f32_16x16x32_bf16 v[14:17], v[134:137], v[210:213], v[14:17]
	v_mfma_f32_16x16x32_bf16 v[10:13], v[142:145], v[210:213], v[10:13]
	s_setprio 0
	s_setprio 1
	v_mfma_f32_16x16x32_bf16 v[54:57], v[146:149], v[176:179], v[54:57]
	v_mfma_f32_16x16x32_bf16 v[50:53], v[154:157], v[176:179], v[50:53]
	v_mfma_f32_16x16x32_bf16 v[38:41], v[146:149], v[184:187], v[38:41]
	v_mfma_f32_16x16x32_bf16 v[34:37], v[154:157], v[184:187], v[34:37]
	v_mfma_f32_16x16x32_bf16 v[22:25], v[146:149], v[192:195], v[22:25]
	v_mfma_f32_16x16x32_bf16 v[18:21], v[154:157], v[192:195], v[18:21]
	v_mfma_f32_16x16x32_bf16 v[6:9], v[146:149], v[206:209], v[6:9]
	v_mfma_f32_16x16x32_bf16 v[2:5], v[154:157], v[206:209], v[2:5]
	v_mfma_f32_16x16x32_bf16 v[54:57], v[150:153], v[180:183], v[54:57]
	v_mfma_f32_16x16x32_bf16 v[50:53], v[158:161], v[180:183], v[50:53]
	v_mfma_f32_16x16x32_bf16 v[38:41], v[150:153], v[188:191], v[38:41]
	v_mfma_f32_16x16x32_bf16 v[34:37], v[158:161], v[188:191], v[34:37]
	v_mfma_f32_16x16x32_bf16 v[22:25], v[150:153], v[202:205], v[22:25]
	v_mfma_f32_16x16x32_bf16 v[18:21], v[158:161], v[202:205], v[18:21]
	v_mfma_f32_16x16x32_bf16 v[6:9], v[150:153], v[210:213], v[6:9]
	v_mfma_f32_16x16x32_bf16 v[2:5], v[158:161], v[210:213], v[2:5]
	s_setprio 0
	s_barrier
	s_add_u32 s42, s42, 0x100
	s_addc_u32 s43, s43, 0
	s_add_u32 s87, s87, 0x100
	s_addc_u32 s88, s88, 0
	s_cmp_ge_i32 s89, s48
	s_mov_b32 s64, s89
	s_cbranch_scc0 .LBB0_1808
	s_branch .Lpk_1808_exit
.LBB0_1808:
	s_add_i32 s89, s64, 2
	s_add_u32 s4, s42, 0xfffc0080
	s_addc_u32 s5, s43, -1
	s_add_i32 s6, 0, 0x10000
	s_cmp_eq_u32 s85, s64
	s_cselect_b32 s67, s57, s5
	s_cselect_b32 s66, s59, s4
	s_cselect_b32 s65, s72, s88
	s_cselect_b32 s64, s73, s87
	s_add_i32 s7, 0, 0x14000
	v_add_u32_e32 v142, s6, v199
	v_add_u32_e32 v158, s7, v199
	ds_read_b128 v[130:133], v142
	ds_read_b128 v[134:137], v142 offset:1024
	ds_read_b128 v[138:141], v142 offset:2048
	ds_read_b128 v[142:145], v142 offset:3072
	ds_read_b128 v[146:149], v158
	ds_read_b128 v[150:153], v158 offset:1024
	ds_read_b128 v[154:157], v158 offset:2048
	ds_read_b128 v[158:161], v158 offset:3072
	v_lshl_add_u64 v[196:197], s[42:43], 0, v[172:173]
	s_add_i32 m0, s69, 0xc000
	ds_read_b128 v[176:179], v201
	ds_read_b128 v[180:183], v201 offset:1024
	ds_read_b128 v[184:187], v201 offset:2048
	ds_read_b128 v[188:191], v201 offset:3072
	ds_read_b128 v[192:195], v201 offset:4096
	ds_read_b128 v[202:205], v201 offset:5120
	ds_read_b128 v[206:209], v201 offset:6144
	ds_read_b128 v[210:213], v201 offset:7168
	global_load_lds_dwordx4 v[196:197], off
	v_lshl_add_u64 v[196:197], s[42:43], 0, v[174:175]
	s_add_i32 m0, s69, 0xe000
	s_nop 0
	global_load_lds_dwordx4 v[196:197], off
	s_waitcnt vmcnt(8)
	s_waitcnt lgkmcnt(0)
	s_barrier
; #define PG8_STAGE(bufoff, gbase, voff) do { _Pragma("unroll") for (int _i = 0; _i < 2; ++_i) \
;         __builtin_amdgcn_global_load_lds((const unsigned*)((const char*)(gbase) + (voff)[_i]), (LAS unsigned*)(lds + (bufoff) + ldsw + _i * 8192), 16, 0, 0); } while (0)
; #define PG8_LDA(dst, b, h) do { _Pragma("unroll") for (int m = 0; m < 4; ++m) _Pragma("unroll") for (int k = 0; k < 2; ++k) dst[m][k] = *(const LAS bf16x8*)(lds + PG8_SA(b, h) + aoff + m * 2048 + k * 1024); } while (0)
; #define PG8_LDB(dst, b, h) do { _Pragma("unroll") for (int n = 0; n < 2; ++n) _Pragma("unroll") for (int k = 0; k < 2; ++k) dst[n][k] = *(const LAS bf16x8*)(lds + PG8_SB(b, h) + boff + n * 2048 + k * 1024); } while (0)
; #define PG8_MMA(ai, bj, At, Bt) do { __builtin_amdgcn_s_setprio(1); _Pragma("unroll") for (int m = 0; m < 4; ++m) _Pragma("unroll") for (int n = 0; n < 2; ++n) _Pragma("unroll") for (int k = 0; k < 2; ++k) \
;         acc[ai][bj][m][n] = __builtin_amdgcn_mfma_f32_16x16x32_bf16(Bt[n][k], At[m][k], acc[ai][bj][m][n], 0, 0, 0); __builtin_amdgcn_s_setprio(0); } while (0)
; #define PG8_WAIT_V(n) asm volatile("s_waitcnt vmcnt(" #n ")" ::: "memory")
; #define PG8_WAIT_L(n) asm volatile("s_waitcnt lgkmcnt(" #n ")" ::: "memory")
; #define PG8_BAR __builtin_amdgcn_s_barrier()
; #define PG8_SCHED __builtin_amdgcn_sched_barrier(0)
; template <class Epi, bool MID = false>
; __device__ __forceinline__ void gemm_phase(LAS unsigned char* lds, const Gemm g, const StaticOrder& S, const Epi& E) {
;     ...
;             PG8_LDB(B0, 0, 0); PG8_LDB(B1, 0, 1); PG8_SCHED; PG8_LDA(At, 0, 0); PG8_STAGE(PG8_SA(1, 1), a1 + hstepA, voffA);
;             PG8_WAIT_V(8); PG8_WAIT_L(0); PG8_BAR; PG8_MMA(0, 0, At, B0); PG8_MMA(0, 1, At, B1); PG8_BAR; PG8_SCHED;
;             PG8_LDA(At, 0, 1); PG8_STAGE(PG8_SB(0, 0), b2, voffB); PG8_STAGE(PG8_SB(0, 1), b2 + hstepB, voffB); PG8_STAGE(PG8_SA(0, 0), a2, voffA);
;             PG8_WAIT_V(8); PG8_WAIT_L(0); PG8_BAR; PG8_MMA(1, 0, At, B0); PG8_MMA(1, 1, At, B1); PG8_BAR; PG8_SCHED;
;             PG8_LDB(B0, 1, 0); PG8_LDB(B1, 1, 1); PG8_SCHED; PG8_LDA(At, 1, 0); PG8_STAGE(PG8_SA(0, 1), a2 + hstepA, voffA);
;             PG8_WAIT_V(8); PG8_WAIT_L(0); PG8_BAR; PG8_MMA(0, 0, At, B0); PG8_MMA(0, 1, At, B1); PG8_BAR; PG8_SCHED;
	s_setprio 1
	s_waitcnt lgkmcnt(0)
	v_mfma_f32_16x16x32_bf16 v[126:129], v[130:133], v[176:179], v[126:129]
	v_mfma_f32_16x16x32_bf16 v[122:125], v[138:141], v[176:179], v[122:125]
	v_mfma_f32_16x16x32_bf16 v[110:113], v[130:133], v[184:187], v[110:113]
	v_mfma_f32_16x16x32_bf16 v[106:109], v[138:141], v[184:187], v[106:109]
	v_mfma_f32_16x16x32_bf16 v[94:97], v[130:133], v[192:195], v[94:97]
	v_mfma_f32_16x16x32_bf16 v[90:93], v[138:141], v[192:195], v[90:93]
	v_mfma_f32_16x16x32_bf16 v[78:81], v[130:133], v[206:209], v[78:81]
	v_mfma_f32_16x16x32_bf16 v[74:77], v[138:141], v[206:209], v[74:77]
	v_mfma_f32_16x16x32_bf16 v[126:129], v[134:137], v[180:183], v[126:129]
	v_mfma_f32_16x16x32_bf16 v[122:125], v[142:145], v[180:183], v[122:125]
	v_mfma_f32_16x16x32_bf16 v[110:113], v[134:137], v[188:191], v[110:113]
	v_mfma_f32_16x16x32_bf16 v[106:109], v[142:145], v[188:191], v[106:109]
	v_mfma_f32_16x16x32_bf16 v[94:97], v[134:137], v[202:205], v[94:97]
	v_mfma_f32_16x16x32_bf16 v[90:93], v[142:145], v[202:205], v[90:93]
	v_mfma_f32_16x16x32_bf16 v[78:81], v[134:137], v[210:213], v[78:81]
	v_mfma_f32_16x16x32_bf16 v[74:77], v[142:145], v[210:213], v[74:77]
	s_setprio 0
	s_setprio 1
	v_mfma_f32_16x16x32_bf16 v[118:121], v[146:149], v[176:179], v[118:121]
	v_mfma_f32_16x16x32_bf16 v[114:117], v[154:157], v[176:179], v[114:117]
	v_mfma_f32_16x16x32_bf16 v[102:105], v[146:149], v[184:187], v[102:105]
	v_mfma_f32_16x16x32_bf16 v[98:101], v[154:157], v[184:187], v[98:101]
	v_mfma_f32_16x16x32_bf16 v[86:89], v[146:149], v[192:195], v[86:89]
	v_mfma_f32_16x16x32_bf16 v[82:85], v[154:157], v[192:195], v[82:85]
	v_mfma_f32_16x16x32_bf16 v[70:73], v[146:149], v[206:209], v[70:73]
	v_mfma_f32_16x16x32_bf16 v[66:69], v[154:157], v[206:209], v[66:69]
	v_mfma_f32_16x16x32_bf16 v[118:121], v[150:153], v[180:183], v[118:121]
	v_mfma_f32_16x16x32_bf16 v[114:117], v[158:161], v[180:183], v[114:117]
	v_mfma_f32_16x16x32_bf16 v[102:105], v[150:153], v[188:191], v[102:105]
	v_mfma_f32_16x16x32_bf16 v[98:101], v[158:161], v[188:191], v[98:101]
	v_mfma_f32_16x16x32_bf16 v[86:89], v[150:153], v[202:205], v[86:89]
	v_mfma_f32_16x16x32_bf16 v[82:85], v[158:161], v[202:205], v[82:85]
	v_mfma_f32_16x16x32_bf16 v[70:73], v[150:153], v[210:213], v[70:73]
	v_mfma_f32_16x16x32_bf16 v[66:69], v[158:161], v[210:213], v[66:69]
	s_setprio 0
	s_barrier
	s_add_i32 s4, s6, s68
	v_lshl_add_u64 v[196:197], s[64:65], 0, v[0:1]
	s_mov_b32 m0, s4
	ds_read_b128 v[176:179], v201 offset:16384
	ds_read_b128 v[180:183], v201 offset:17408
	ds_read_b128 v[184:187], v201 offset:18432
	ds_read_b128 v[188:191], v201 offset:19456
	ds_read_b128 v[192:195], v201 offset:20480
	ds_read_b128 v[202:205], v201 offset:21504
	ds_read_b128 v[206:209], v201 offset:22528
	ds_read_b128 v[210:213], v201 offset:23552
	global_load_lds_dwordx4 v[196:197], off
	s_add_i32 m0, s4, 0x2000
	s_add_u32 s4, s64, 0x40000
	v_lshl_add_u64 v[214:215], s[64:65], 0, v[168:169]
	s_addc_u32 s5, s65, 0
	s_add_i32 s6, s7, s68
	global_load_lds_dwordx4 v[214:215], off
	v_lshl_add_u64 v[222:223], s[4:5], 0, v[0:1]
	s_mov_b32 m0, s6
	v_lshl_add_u64 v[230:231], s[66:67], 0, v[166:167]
	global_load_lds_dwordx4 v[222:223], off
	v_lshl_add_u64 v[222:223], s[4:5], 0, v[168:169]
	s_add_i32 m0, s6, 0x2000
	s_nop 0
	global_load_lds_dwordx4 v[222:223], off
	v_lshl_add_u64 v[222:223], s[66:67], 0, v[164:165]
	s_mov_b32 m0, s69
	s_nop 0
	global_load_lds_dwordx4 v[222:223], off
	s_mov_b32 m0, s70
	s_nop 0
	global_load_lds_dwordx4 v[230:231], off
	s_waitcnt vmcnt(8)
	s_waitcnt lgkmcnt(0)
	s_barrier
	s_setprio 1
	s_waitcnt lgkmcnt(0)
	v_mfma_f32_16x16x32_bf16 v[62:65], v[130:133], v[176:179], v[62:65]
	v_mfma_f32_16x16x32_bf16 v[58:61], v[138:141], v[176:179], v[58:61]
	v_mfma_f32_16x16x32_bf16 v[46:49], v[130:133], v[184:187], v[46:49]
	v_mfma_f32_16x16x32_bf16 v[42:45], v[138:141], v[184:187], v[42:45]
	v_mfma_f32_16x16x32_bf16 v[30:33], v[130:133], v[192:195], v[30:33]
	v_mfma_f32_16x16x32_bf16 v[26:29], v[138:141], v[192:195], v[26:29]
	v_mfma_f32_16x16x32_bf16 v[14:17], v[130:133], v[206:209], v[14:17]
	v_mfma_f32_16x16x32_bf16 v[10:13], v[138:141], v[206:209], v[10:13]
	v_mfma_f32_16x16x32_bf16 v[62:65], v[134:137], v[180:183], v[62:65]
	v_mfma_f32_16x16x32_bf16 v[58:61], v[142:145], v[180:183], v[58:61]
	v_mfma_f32_16x16x32_bf16 v[46:49], v[134:137], v[188:191], v[46:49]
	v_mfma_f32_16x16x32_bf16 v[42:45], v[142:145], v[188:191], v[42:45]
	v_mfma_f32_16x16x32_bf16 v[30:33], v[134:137], v[202:205], v[30:33]
	v_mfma_f32_16x16x32_bf16 v[26:29], v[142:145], v[202:205], v[26:29]
	v_mfma_f32_16x16x32_bf16 v[14:17], v[134:137], v[210:213], v[14:17]
	v_mfma_f32_16x16x32_bf16 v[10:13], v[142:145], v[210:213], v[10:13]
	s_setprio 0
	s_setprio 1
	v_mfma_f32_16x16x32_bf16 v[54:57], v[146:149], v[176:179], v[54:57]
	v_mfma_f32_16x16x32_bf16 v[50:53], v[154:157], v[176:179], v[50:53]
	v_mfma_f32_16x16x32_bf16 v[38:41], v[146:149], v[184:187], v[38:41]
	v_mfma_f32_16x16x32_bf16 v[34:37], v[154:157], v[184:187], v[34:37]
	v_mfma_f32_16x16x32_bf16 v[22:25], v[146:149], v[192:195], v[22:25]
	v_mfma_f32_16x16x32_bf16 v[18:21], v[154:157], v[192:195], v[18:21]
	v_mfma_f32_16x16x32_bf16 v[6:9], v[146:149], v[206:209], v[6:9]
	v_mfma_f32_16x16x32_bf16 v[2:5], v[154:157], v[206:209], v[2:5]
	v_mfma_f32_16x16x32_bf16 v[54:57], v[150:153], v[180:183], v[54:57]
	v_mfma_f32_16x16x32_bf16 v[50:53], v[158:161], v[180:183], v[50:53]
	v_mfma_f32_16x16x32_bf16 v[38:41], v[150:153], v[188:191], v[38:41]
	v_mfma_f32_16x16x32_bf16 v[34:37], v[158:161], v[188:191], v[34:37]
	v_mfma_f32_16x16x32_bf16 v[22:25], v[150:153], v[202:205], v[22:25]
	v_mfma_f32_16x16x32_bf16 v[18:21], v[158:161], v[202:205], v[18:21]
	v_mfma_f32_16x16x32_bf16 v[6:9], v[150:153], v[210:213], v[6:9]
	v_mfma_f32_16x16x32_bf16 v[2:5], v[158:161], v[210:213], v[2:5]
	s_setprio 0
	s_barrier
; #define PG8_STAGE(bufoff, gbase, voff) do { _Pragma("unroll") for (int _i = 0; _i < 2; ++_i) \
;         __builtin_amdgcn_global_load_lds((const unsigned*)((const char*)(gbase) + (voff)[_i]), (LAS unsigned*)(lds + (bufoff) + ldsw + _i * 8192), 16, 0, 0); } while (0)
; #define PG8_LDA(dst, b, h) do { _Pragma("unroll") for (int m = 0; m < 4; ++m) _Pragma("unroll") for (int k = 0; k < 2; ++k) dst[m][k] = *(const LAS bf16x8*)(lds + PG8_SA(b, h) + aoff + m * 2048 + k * 1024); } while (0)
; #define PG8_MMA(ai, bj, At, Bt) do { __builtin_amdgcn_s_setprio(1); _Pragma("unroll") for (int m = 0; m < 4; ++m) _Pragma("unroll") for (int n = 0; n < 2; ++n) _Pragma("unroll") for (int k = 0; k < 2; ++k) \
;         acc[ai][bj][m][n] = __builtin_amdgcn_mfma_f32_16x16x32_bf16(Bt[n][k], At[m][k], acc[ai][bj][m][n], 0, 0, 0); __builtin_amdgcn_s_setprio(0); } while (0)
; #define PG8_WAIT_V(n) asm volatile("s_waitcnt vmcnt(" #n ")" ::: "memory")
; #define PG8_WAIT_L(n) asm volatile("s_waitcnt lgkmcnt(" #n ")" ::: "memory")
; #define PG8_BAR __builtin_amdgcn_s_barrier()
; #define PG8_SCHED __builtin_amdgcn_sched_barrier(0)
; template <class Epi, bool MID = false>
; __device__ __forceinline__ void gemm_phase(LAS unsigned char* lds, const Gemm g, const StaticOrder& S, const Epi& E) {
;     ...
;             PG8_LDA(At, 1, 1); PG8_STAGE(PG8_SB(1, 0), b3, voffB); PG8_STAGE(PG8_SB(1, 1), b3 + hstepB, voffB); PG8_STAGE(PG8_SA(1, 0), a3, voffA);
;             PG8_WAIT_V(8); PG8_WAIT_L(0); PG8_BAR; PG8_MMA(1, 0, At, B0); PG8_MMA(1, 1, At, B1); PG8_BAR; PG8_SCHED;
	s_add_i32 s6, 0, 0x18000
	s_add_i32 s7, 0, 0x1c000
	v_add_u32_e32 v142, s6, v199
	v_add_u32_e32 v158, s7, v199
	ds_read_b128 v[130:133], v142
	ds_read_b128 v[134:137], v142 offset:1024
	ds_read_b128 v[138:141], v142 offset:2048
	ds_read_b128 v[142:145], v142 offset:3072
	ds_read_b128 v[146:149], v158
	ds_read_b128 v[150:153], v158 offset:1024
	ds_read_b128 v[154:157], v158 offset:2048
	ds_read_b128 v[158:161], v158 offset:3072
	s_add_u32 s4, s66, 0x40000
	s_addc_u32 s5, s67, 0
	s_mov_b32 m0, s71
	v_lshl_add_u64 v[232:233], s[4:5], 0, v[164:165]
	ds_read_b128 v[176:179], v201 offset:32768
	ds_read_b128 v[180:183], v201 offset:33792
	ds_read_b128 v[184:187], v201 offset:34816
	ds_read_b128 v[188:191], v201 offset:35840
	ds_read_b128 v[192:195], v201 offset:36864
	ds_read_b128 v[202:205], v201 offset:37888
	ds_read_b128 v[206:209], v201 offset:38912
	ds_read_b128 v[210:213], v201 offset:39936
	global_load_lds_dwordx4 v[232:233], off
	v_lshl_add_u64 v[232:233], s[4:5], 0, v[166:167]
	s_mov_b32 m0, s78
	s_nop 0
	global_load_lds_dwordx4 v[232:233], off
	s_waitcnt vmcnt(8)
	s_waitcnt lgkmcnt(0)
	s_barrier
	s_setprio 1
	s_waitcnt lgkmcnt(0)
	v_mfma_f32_16x16x32_bf16 v[126:129], v[130:133], v[176:179], v[126:129]
	v_mfma_f32_16x16x32_bf16 v[122:125], v[138:141], v[176:179], v[122:125]
	v_mfma_f32_16x16x32_bf16 v[110:113], v[130:133], v[184:187], v[110:113]
	v_mfma_f32_16x16x32_bf16 v[106:109], v[138:141], v[184:187], v[106:109]
	v_mfma_f32_16x16x32_bf16 v[94:97], v[130:133], v[192:195], v[94:97]
	v_mfma_f32_16x16x32_bf16 v[90:93], v[138:141], v[192:195], v[90:93]
	v_mfma_f32_16x16x32_bf16 v[78:81], v[130:133], v[206:209], v[78:81]
	v_mfma_f32_16x16x32_bf16 v[74:77], v[138:141], v[206:209], v[74:77]
	v_mfma_f32_16x16x32_bf16 v[126:129], v[134:137], v[180:183], v[126:129]
	v_mfma_f32_16x16x32_bf16 v[122:125], v[142:145], v[180:183], v[122:125]
	v_mfma_f32_16x16x32_bf16 v[110:113], v[134:137], v[188:191], v[110:113]
	v_mfma_f32_16x16x32_bf16 v[106:109], v[142:145], v[188:191], v[106:109]
	v_mfma_f32_16x16x32_bf16 v[94:97], v[134:137], v[202:205], v[94:97]
	v_mfma_f32_16x16x32_bf16 v[90:93], v[142:145], v[202:205], v[90:93]
	v_mfma_f32_16x16x32_bf16 v[78:81], v[134:137], v[210:213], v[78:81]
	v_mfma_f32_16x16x32_bf16 v[74:77], v[142:145], v[210:213], v[74:77]
	s_setprio 0
	s_setprio 1
	v_mfma_f32_16x16x32_bf16 v[118:121], v[146:149], v[176:179], v[118:121]
	v_mfma_f32_16x16x32_bf16 v[114:117], v[154:157], v[176:179], v[114:117]
	v_mfma_f32_16x16x32_bf16 v[102:105], v[146:149], v[184:187], v[102:105]
	v_mfma_f32_16x16x32_bf16 v[98:101], v[154:157], v[184:187], v[98:101]
	v_mfma_f32_16x16x32_bf16 v[86:89], v[146:149], v[192:195], v[86:89]
	v_mfma_f32_16x16x32_bf16 v[82:85], v[154:157], v[192:195], v[82:85]
	v_mfma_f32_16x16x32_bf16 v[70:73], v[146:149], v[206:209], v[70:73]
	v_mfma_f32_16x16x32_bf16 v[66:69], v[154:157], v[206:209], v[66:69]
	v_mfma_f32_16x16x32_bf16 v[118:121], v[150:153], v[180:183], v[118:121]
	v_mfma_f32_16x16x32_bf16 v[114:117], v[158:161], v[180:183], v[114:117]
	v_mfma_f32_16x16x32_bf16 v[102:105], v[150:153], v[188:191], v[102:105]
	v_mfma_f32_16x16x32_bf16 v[98:101], v[158:161], v[188:191], v[98:101]
	v_mfma_f32_16x16x32_bf16 v[86:89], v[150:153], v[202:205], v[86:89]
	v_mfma_f32_16x16x32_bf16 v[82:85], v[158:161], v[202:205], v[82:85]
	v_mfma_f32_16x16x32_bf16 v[70:73], v[150:153], v[210:213], v[70:73]
	v_mfma_f32_16x16x32_bf16 v[66:69], v[158:161], v[210:213], v[66:69]
	s_setprio 0
	s_barrier
; #define PG8_STAGE(bufoff, gbase, voff) do { _Pragma("unroll") for (int _i = 0; _i < 2; ++_i) \
;         __builtin_amdgcn_global_load_lds((const unsigned*)((const char*)(gbase) + (voff)[_i]), (LAS unsigned*)(lds + (bufoff) + ldsw + _i * 8192), 16, 0, 0); } while (0)
; #define PG8_LDA(dst, b, h) do { _Pragma("unroll") for (int m = 0; m < 4; ++m) _Pragma("unroll") for (int k = 0; k < 2; ++k) dst[m][k] = *(const LAS bf16x8*)(lds + PG8_SA(b, h) + aoff + m * 2048 + k * 1024); } while (0)
; #define PG8_MMA(ai, bj, At, Bt) do { __builtin_amdgcn_s_setprio(1); _Pragma("unroll") for (int m = 0; m < 4; ++m) _Pragma("unroll") for (int n = 0; n < 2; ++n) _Pragma("unroll") for (int k = 0; k < 2; ++k) \
;         acc[ai][bj][m][n] = __builtin_amdgcn_mfma_f32_16x16x32_bf16(Bt[n][k], At[m][k], acc[ai][bj][m][n], 0, 0, 0); __builtin_amdgcn_s_setprio(0); } while (0)
; #define PG8_WAIT_V(n) asm volatile("s_waitcnt vmcnt(" #n ")" ::: "memory")
; #define PG8_WAIT_L(n) asm volatile("s_waitcnt lgkmcnt(" #n ")" ::: "memory")
; #define PG8_BAR __builtin_amdgcn_s_barrier()
; #define PG8_SCHED __builtin_amdgcn_sched_barrier(0)
; template <class Epi, bool MID = false>
; __device__ __forceinline__ void gemm_phase(LAS unsigned char* lds, const Gemm g, const StaticOrder& S, const Epi& E) {
;     ...
;             PG8_LDA(At, 1, 1); PG8_STAGE(PG8_SB(1, 0), b3, voffB); PG8_STAGE(PG8_SB(1, 1), b3 + hstepB, voffB); PG8_STAGE(PG8_SA(1, 0), a3, voffA);
;             PG8_WAIT_V(8); PG8_WAIT_L(0); PG8_BAR; PG8_MMA(1, 0, At, B0); PG8_MMA(1, 1, At, B1); PG8_BAR; PG8_SCHED;
;             if constexpr (MID) { if (t == 6) E.mid(acc, cur, wr, wc, fr, fq); }
;         }
;         if (wr == 0) PG8_BAR;
	s_add_i32 s4, s6, s68
	v_lshl_add_u64 v[196:197], v[196:197], 0, s[24:25]
	s_mov_b32 m0, s4
	ds_read_b128 v[176:179], v201 offset:49152
	ds_read_b128 v[180:183], v201 offset:50176
	ds_read_b128 v[184:187], v201 offset:51200
	ds_read_b128 v[188:191], v201 offset:52224
	ds_read_b128 v[192:195], v201 offset:53248
	ds_read_b128 v[202:205], v201 offset:54272
	ds_read_b128 v[206:209], v201 offset:55296
	ds_read_b128 v[210:213], v201 offset:56320
	global_load_lds_dwordx4 v[196:197], off
	s_add_i32 m0, s4, 0x2000
	s_add_u32 s4, s64, 0x40080
	v_lshl_add_u64 v[196:197], v[214:215], 0, s[24:25]
	s_addc_u32 s5, s65, 0
	s_add_i32 s6, s7, s68
	global_load_lds_dwordx4 v[196:197], off
	v_lshl_add_u64 v[196:197], s[4:5], 0, v[0:1]
	s_mov_b32 m0, s6
	s_nop 0
	global_load_lds_dwordx4 v[196:197], off
	v_lshl_add_u64 v[196:197], s[4:5], 0, v[168:169]
	s_add_i32 m0, s6, 0x2000
	s_nop 0
	global_load_lds_dwordx4 v[196:197], off
	v_lshl_add_u64 v[196:197], v[222:223], 0, s[24:25]
	s_mov_b32 m0, s79
	s_nop 0
	global_load_lds_dwordx4 v[196:197], off
	v_lshl_add_u64 v[196:197], v[230:231], 0, s[24:25]
	s_mov_b32 m0, s80
	s_nop 0
	global_load_lds_dwordx4 v[196:197], off
	s_waitcnt vmcnt(8)
	s_waitcnt lgkmcnt(0)
	s_barrier
	s_setprio 1
	s_waitcnt lgkmcnt(0)
	v_mfma_f32_16x16x32_bf16 v[62:65], v[130:133], v[176:179], v[62:65]
	v_mfma_f32_16x16x32_bf16 v[58:61], v[138:141], v[176:179], v[58:61]
	v_mfma_f32_16x16x32_bf16 v[46:49], v[130:133], v[184:187], v[46:49]
	v_mfma_f32_16x16x32_bf16 v[42:45], v[138:141], v[184:187], v[42:45]
	v_mfma_f32_16x16x32_bf16 v[30:33], v[130:133], v[192:195], v[30:33]
	v_mfma_f32_16x16x32_bf16 v[26:29], v[138:141], v[192:195], v[26:29]
	v_mfma_f32_16x16x32_bf16 v[14:17], v[130:133], v[206:209], v[14:17]
	v_mfma_f32_16x16x32_bf16 v[10:13], v[138:141], v[206:209], v[10:13]
	v_mfma_f32_16x16x32_bf16 v[62:65], v[134:137], v[180:183], v[62:65]
	v_mfma_f32_16x16x32_bf16 v[58:61], v[142:145], v[180:183], v[58:61]
	v_mfma_f32_16x16x32_bf16 v[46:49], v[134:137], v[188:191], v[46:49]
	v_mfma_f32_16x16x32_bf16 v[42:45], v[142:145], v[188:191], v[42:45]
	v_mfma_f32_16x16x32_bf16 v[30:33], v[134:137], v[202:205], v[30:33]
	v_mfma_f32_16x16x32_bf16 v[26:29], v[142:145], v[202:205], v[26:29]
	v_mfma_f32_16x16x32_bf16 v[14:17], v[134:137], v[210:213], v[14:17]
	v_mfma_f32_16x16x32_bf16 v[10:13], v[142:145], v[210:213], v[10:13]
	s_setprio 0
	s_setprio 1
	v_mfma_f32_16x16x32_bf16 v[54:57], v[146:149], v[176:179], v[54:57]
	v_mfma_f32_16x16x32_bf16 v[50:53], v[154:157], v[176:179], v[50:53]
	v_mfma_f32_16x16x32_bf16 v[38:41], v[146:149], v[184:187], v[38:41]
	v_mfma_f32_16x16x32_bf16 v[34:37], v[154:157], v[184:187], v[34:37]
	v_mfma_f32_16x16x32_bf16 v[22:25], v[146:149], v[192:195], v[22:25]
	v_mfma_f32_16x16x32_bf16 v[18:21], v[154:157], v[192:195], v[18:21]
	v_mfma_f32_16x16x32_bf16 v[6:9], v[146:149], v[206:209], v[6:9]
	v_mfma_f32_16x16x32_bf16 v[2:5], v[154:157], v[206:209], v[2:5]
	v_mfma_f32_16x16x32_bf16 v[54:57], v[150:153], v[180:183], v[54:57]
	v_mfma_f32_16x16x32_bf16 v[50:53], v[158:161], v[180:183], v[50:53]
	v_mfma_f32_16x16x32_bf16 v[38:41], v[150:153], v[188:191], v[38:41]
	v_mfma_f32_16x16x32_bf16 v[34:37], v[158:161], v[188:191], v[34:37]
	v_mfma_f32_16x16x32_bf16 v[22:25], v[150:153], v[202:205], v[22:25]
	v_mfma_f32_16x16x32_bf16 v[18:21], v[158:161], v[202:205], v[18:21]
	v_mfma_f32_16x16x32_bf16 v[6:9], v[150:153], v[210:213], v[6:9]
	v_mfma_f32_16x16x32_bf16 v[2:5], v[158:161], v[210:213], v[2:5]
	s_setprio 0
	s_barrier
	s_add_u32 s42, s42, 0x100
	s_addc_u32 s43, s43, 0
	s_add_u32 s87, s87, 0x100
	s_addc_u32 s88, s88, 0
	s_cmp_ge_i32 s89, s48
	s_mov_b32 s64, s89
	s_cbranch_scc0 .LBB0_1808
.Lpk_1808_exit:
	s_and_b64 vcc, exec, s[50:51]
	s_cbranch_vccz .LBB0_1811
.LBB0_1810:
	s_barrier
